# GEMM K-loops: 8 of 16 LDS-DMA loads per iteration use scalar-base (saddr) addressing, removing their 64-bit VALU address adds
# speedup vs baseline: 1.0058x; 1.0058x over previous
; #define PG8_STAGE(bufoff, gbase, voff) do { _Pragma("unroll") for (int _i = 0; _i < 2; ++_i) \
;         __builtin_amdgcn_global_load_lds((const unsigned*)((const char*)(gbase) + (voff)[_i]), (LAS unsigned*)(lds + (bufoff) + ldsw + _i * 8192), 16, 0, 0); } while (0)
; #define PG8_LDA(dst, b, h) do { _Pragma("unroll") for (int m = 0; m < 4; ++m) _Pragma("unroll") for (int k = 0; k < 2; ++k) dst[m][k] = *(const LAS bf16x8*)(lds + PG8_SA(b, h) + aoff + m * 2048 + k * 1024); } while (0)
; #define PG8_LDB(dst, b, h) do { _Pragma("unroll") for (int n = 0; n < 2; ++n) _Pragma("unroll") for (int k = 0; k < 2; ++k) dst[n][k] = *(const LAS bf16x8*)(lds + PG8_SB(b, h) + boff + n * 2048 + k * 1024); } while (0)
; #define PG8_MMA(ai, bj, At, Bt) do { __builtin_amdgcn_s_setprio(1); _Pragma("unroll") for (int m = 0; m < 4; ++m) _Pragma("unroll") for (int n = 0; n < 2; ++n) _Pragma("unroll") for (int k = 0; k < 2; ++k) \
;         acc[ai][bj][m][n] = __builtin_amdgcn_mfma_f32_16x16x32_bf16(Bt[n][k], At[m][k], acc[ai][bj][m][n], 0, 0, 0); __builtin_amdgcn_s_setprio(0); } while (0)
; #define PG8_WAIT_V(n) asm volatile("s_waitcnt vmcnt(" #n ")" ::: "memory")
; #define PG8_WAIT_L(n) asm volatile("s_waitcnt lgkmcnt(" #n ")" ::: "memory")
; #define PG8_BAR __builtin_amdgcn_s_barrier()
; #define PG8_SCHED __builtin_amdgcn_sched_barrier(0)
; template <class Map, class Epi>
; DI void gemm_phase(LAS unsigned char* lds, const Map& MP, const Epi& E, const int nM, const int nN, const int K, const int lda, const int ldb) {
;     ...
;             PG8_LDB(B0, 0, 0); PG8_SCHED; PG8_LDA(At, 0, 0); PG8_STAGE(PG8_SA(1, 1), a1 + hstepA, voffA);
;             PG8_WAIT_L(8); PG8_BAR; PG8_WAIT_L(0); PG8_MMA(0, 0, At, B0); PG8_BAR; PG8_SCHED;
;             PG8_LDB(B1, 0, 1); PG8_STAGE(PG8_SB(0, 0), b2, voffB);
;             PG8_BAR; PG8_WAIT_L(0); PG8_MMA(0, 1, At, B1); PG8_BAR;
;             PG8_LDA(At, 0, 1); PG8_STAGE(PG8_SA(0, 0), a2, voffA);
;             PG8_BAR; PG8_WAIT_L(0); PG8_MMA(1, 0, At, B0); PG8_BAR; PG8_SCHED;
;             PG8_STAGE(PG8_SB(0, 1), b2 + hstepB, voffB);
;             PG8_WAIT_V(6); PG8_BAR; PG8_MMA(1, 1, At, B1); PG8_BAR;
.LBB1_229:
	ds_read_b128 v[72:75], v167
	ds_read_b128 v[76:79], v167 offset:1024
	ds_read_b128 v[80:83], v167 offset:2048
	ds_read_b128 v[84:87], v167 offset:3072
	s_add_u32 s26, s24, 0xfff80080
	s_addc_u32 s27, s25, -1
	s_cmp_eq_u32 s57, 4
	s_cselect_b32 s29, s17, s27
	s_cselect_b32 s28, s43, s26
	s_cselect_b32 s27, s53, s56
	s_cselect_b32 s26, s54, s55
	s_add_i32 m0, s2, 0xc000
	ds_read_b128 v[160:163], v168
	ds_read_b128 v[170:173], v168 offset:1024
	ds_read_b128 v[174:177], v168 offset:2048
	ds_read_b128 v[178:181], v168 offset:3072
	ds_read_b128 v[182:185], v168 offset:4096
	ds_read_b128 v[186:189], v168 offset:5120
	ds_read_b128 v[190:193], v168 offset:6144
	ds_read_b128 v[198:201], v168 offset:7168
	global_load_lds_dwordx4 v154, s[24:25]
	s_add_i32 m0, s2, 0xe000
	s_nop 0
	global_load_lds_dwordx4 v152, s[24:25]
	s_waitcnt lgkmcnt(8)
	s_barrier
	s_setprio 1
	s_waitcnt lgkmcnt(7)
	v_mfma_f32_16x16x32_bf16 v[140:143], v[72:75], v[160:163], v[140:143]
	v_mfma_f32_16x16x32_bf16 v[136:139], v[80:83], v[160:163], v[136:139]
	s_waitcnt lgkmcnt(5)
	v_mfma_f32_16x16x32_bf16 v[124:127], v[72:75], v[174:177], v[124:127]
	v_mfma_f32_16x16x32_bf16 v[120:123], v[80:83], v[174:177], v[120:123]
	s_waitcnt lgkmcnt(3)
	v_mfma_f32_16x16x32_bf16 v[108:111], v[72:75], v[182:185], v[108:111]
	v_mfma_f32_16x16x32_bf16 v[104:107], v[80:83], v[182:185], v[104:107]
	s_waitcnt lgkmcnt(1)
	v_mfma_f32_16x16x32_bf16 v[92:95], v[72:75], v[190:193], v[92:95]
	v_mfma_f32_16x16x32_bf16 v[88:91], v[80:83], v[190:193], v[88:91]
	v_mfma_f32_16x16x32_bf16 v[140:143], v[76:79], v[170:173], v[140:143]
	v_mfma_f32_16x16x32_bf16 v[136:139], v[84:87], v[170:173], v[136:139]
	v_mfma_f32_16x16x32_bf16 v[124:127], v[76:79], v[178:181], v[124:127]
	v_mfma_f32_16x16x32_bf16 v[120:123], v[84:87], v[178:181], v[120:123]
	v_mfma_f32_16x16x32_bf16 v[108:111], v[76:79], v[186:189], v[108:111]
	v_mfma_f32_16x16x32_bf16 v[104:107], v[84:87], v[186:189], v[104:107]
	s_waitcnt lgkmcnt(0)
	v_mfma_f32_16x16x32_bf16 v[92:95], v[76:79], v[198:201], v[92:95]
	v_mfma_f32_16x16x32_bf16 v[88:91], v[84:87], v[198:201], v[88:91]
	s_setprio 0
	s_barrier
	s_add_i32 s58, s48, s34
	v_lshl_add_u64 v[194:195], s[26:27], 0, v[148:149]
	s_mov_b32 m0, s58
	ds_read_b128 v[202:205], v169
	ds_read_b128 v[206:209], v169 offset:1024
	ds_read_b128 v[210:213], v169 offset:2048
	ds_read_b128 v[214:217], v169 offset:3072
	global_load_lds_dwordx4 v[194:195], off
	v_lshl_add_u64 v[218:219], s[26:27], 0, v[144:145]
	s_add_i32 m0, s58, 0x2000
	s_nop 0
	global_load_lds_dwordx4 v[218:219], off
	s_barrier
	s_setprio 1
	s_waitcnt lgkmcnt(3)
	v_mfma_f32_16x16x32_bf16 v[132:135], v[202:205], v[160:163], v[132:135]
	s_waitcnt lgkmcnt(1)
	v_mfma_f32_16x16x32_bf16 v[128:131], v[210:213], v[160:163], v[128:131]
	v_mfma_f32_16x16x32_bf16 v[116:119], v[202:205], v[174:177], v[116:119]
	v_mfma_f32_16x16x32_bf16 v[112:115], v[210:213], v[174:177], v[112:115]
	v_mfma_f32_16x16x32_bf16 v[100:103], v[202:205], v[182:185], v[100:103]
	v_mfma_f32_16x16x32_bf16 v[96:99], v[210:213], v[182:185], v[96:99]
	v_mfma_f32_16x16x32_bf16 v[68:71], v[202:205], v[190:193], v[68:71]
	v_mfma_f32_16x16x32_bf16 v[64:67], v[210:213], v[190:193], v[64:67]
	v_mfma_f32_16x16x32_bf16 v[132:135], v[206:209], v[170:173], v[132:135]
	s_waitcnt lgkmcnt(0)
	v_mfma_f32_16x16x32_bf16 v[128:131], v[214:217], v[170:173], v[128:131]
	v_mfma_f32_16x16x32_bf16 v[116:119], v[206:209], v[178:181], v[116:119]
	v_mfma_f32_16x16x32_bf16 v[112:115], v[214:217], v[178:181], v[112:115]
	v_mfma_f32_16x16x32_bf16 v[100:103], v[206:209], v[186:189], v[100:103]
	v_mfma_f32_16x16x32_bf16 v[96:99], v[214:217], v[186:189], v[96:99]
	v_mfma_f32_16x16x32_bf16 v[68:71], v[206:209], v[198:201], v[68:71]
	v_mfma_f32_16x16x32_bf16 v[64:67], v[214:217], v[198:201], v[64:67]
	s_setprio 0
	s_mov_b32 m0, s2
	v_lshl_add_u64 v[220:221], s[28:29], 0, v[150:151]
	s_barrier
	ds_read_b128 v[160:163], v168 offset:16384
	ds_read_b128 v[170:173], v168 offset:17408
	ds_read_b128 v[174:177], v168 offset:18432
	ds_read_b128 v[178:181], v168 offset:19456
	ds_read_b128 v[182:185], v168 offset:20480
	ds_read_b128 v[186:189], v168 offset:21504
	ds_read_b128 v[190:193], v168 offset:22528
	ds_read_b128 v[198:201], v168 offset:23552
	global_load_lds_dwordx4 v[220:221], off
	v_lshl_add_u64 v[222:223], s[28:29], 0, v[146:147]
	s_mov_b32 m0, s4
	s_nop 0
	global_load_lds_dwordx4 v[222:223], off
	s_barrier
	s_setprio 1
	s_waitcnt lgkmcnt(7)
	v_mfma_f32_16x16x32_bf16 v[60:63], v[72:75], v[160:163], v[60:63]
	v_mfma_f32_16x16x32_bf16 v[56:59], v[80:83], v[160:163], v[56:59]
	s_waitcnt lgkmcnt(5)
	v_mfma_f32_16x16x32_bf16 v[44:47], v[72:75], v[174:177], v[44:47]
	v_mfma_f32_16x16x32_bf16 v[40:43], v[80:83], v[174:177], v[40:43]
	s_waitcnt lgkmcnt(3)
	v_mfma_f32_16x16x32_bf16 v[28:31], v[72:75], v[182:185], v[28:31]
	v_mfma_f32_16x16x32_bf16 v[24:27], v[80:83], v[182:185], v[24:27]
	s_waitcnt lgkmcnt(1)
	v_mfma_f32_16x16x32_bf16 v[12:15], v[72:75], v[190:193], v[12:15]
	v_mfma_f32_16x16x32_bf16 v[8:11], v[80:83], v[190:193], v[8:11]
	v_mfma_f32_16x16x32_bf16 v[60:63], v[76:79], v[170:173], v[60:63]
	v_mfma_f32_16x16x32_bf16 v[56:59], v[84:87], v[170:173], v[56:59]
	v_mfma_f32_16x16x32_bf16 v[44:47], v[76:79], v[178:181], v[44:47]
	v_mfma_f32_16x16x32_bf16 v[40:43], v[84:87], v[178:181], v[40:43]
	v_mfma_f32_16x16x32_bf16 v[28:31], v[76:79], v[186:189], v[28:31]
	v_mfma_f32_16x16x32_bf16 v[24:27], v[84:87], v[186:189], v[24:27]
	s_waitcnt lgkmcnt(0)
	v_mfma_f32_16x16x32_bf16 v[12:15], v[76:79], v[198:201], v[12:15]
	v_mfma_f32_16x16x32_bf16 v[8:11], v[84:87], v[198:201], v[8:11]
	s_setprio 0
	s_barrier
; #define PG8_STAGE(bufoff, gbase, voff) do { _Pragma("unroll") for (int _i = 0; _i < 2; ++_i) \
;         __builtin_amdgcn_global_load_lds((const unsigned*)((const char*)(gbase) + (voff)[_i]), (LAS unsigned*)(lds + (bufoff) + ldsw + _i * 8192), 16, 0, 0); } while (0)
; #define PG8_LDA(dst, b, h) do { _Pragma("unroll") for (int m = 0; m < 4; ++m) _Pragma("unroll") for (int k = 0; k < 2; ++k) dst[m][k] = *(const LAS bf16x8*)(lds + PG8_SA(b, h) + aoff + m * 2048 + k * 1024); } while (0)
; #define PG8_LDB(dst, b, h) do { _Pragma("unroll") for (int n = 0; n < 2; ++n) _Pragma("unroll") for (int k = 0; k < 2; ++k) dst[n][k] = *(const LAS bf16x8*)(lds + PG8_SB(b, h) + boff + n * 2048 + k * 1024); } while (0)
; #define PG8_MMA(ai, bj, At, Bt) do { __builtin_amdgcn_s_setprio(1); _Pragma("unroll") for (int m = 0; m < 4; ++m) _Pragma("unroll") for (int n = 0; n < 2; ++n) _Pragma("unroll") for (int k = 0; k < 2; ++k) \
;         acc[ai][bj][m][n] = __builtin_amdgcn_mfma_f32_16x16x32_bf16(Bt[n][k], At[m][k], acc[ai][bj][m][n], 0, 0, 0); __builtin_amdgcn_s_setprio(0); } while (0)
; #define PG8_WAIT_V(n) asm volatile("s_waitcnt vmcnt(" #n ")" ::: "memory")
; #define PG8_WAIT_L(n) asm volatile("s_waitcnt lgkmcnt(" #n ")" ::: "memory")
; #define PG8_BAR __builtin_amdgcn_s_barrier()
; #define PG8_SCHED __builtin_amdgcn_sched_barrier(0)
; template <class Map, class Epi>
; DI void gemm_phase(LAS unsigned char* lds, const Map& MP, const Epi& E, const int nM, const int nN, const int K, const int lda, const int ldb) {
;     ...
;             PG8_STAGE(PG8_SB(0, 1), b2 + hstepB, voffB);
;             PG8_WAIT_V(6); PG8_BAR; PG8_MMA(1, 1, At, B1); PG8_BAR;
;             PG8_LDB(B0, 1, 0); PG8_SCHED; PG8_LDA(At, 1, 0); PG8_STAGE(PG8_SA(0, 1), a2 + hstepA, voffA);
;             PG8_WAIT_L(8); PG8_BAR; PG8_WAIT_L(0); PG8_MMA(0, 0, At, B0); PG8_BAR; PG8_SCHED;
;             PG8_LDB(B1, 1, 1); PG8_STAGE(PG8_SB(1, 0), b3, voffB);
	s_add_u32 s58, s26, 0x20000
	s_addc_u32 s59, s27, 0
	s_add_i32 s60, s49, s34
	s_mov_b32 m0, s60
	s_nop 0
	global_load_lds_dwordx4 v148, s[58:59]
	s_add_i32 m0, s60, 0x2000
	s_nop 0
	global_load_lds_dwordx4 v144, s[58:59]
	s_waitcnt vmcnt(6)
	s_barrier
	s_setprio 1
	v_mfma_f32_16x16x32_bf16 v[52:55], v[202:205], v[160:163], v[52:55]
	v_mfma_f32_16x16x32_bf16 v[48:51], v[210:213], v[160:163], v[48:51]
	v_mfma_f32_16x16x32_bf16 v[36:39], v[202:205], v[174:177], v[36:39]
	v_mfma_f32_16x16x32_bf16 v[32:35], v[210:213], v[174:177], v[32:35]
	v_mfma_f32_16x16x32_bf16 v[20:23], v[202:205], v[182:185], v[20:23]
	v_mfma_f32_16x16x32_bf16 v[16:19], v[210:213], v[182:185], v[16:19]
	v_mfma_f32_16x16x32_bf16 v[4:7], v[202:205], v[190:193], v[4:7]
	v_mfma_f32_16x16x32_bf16 v[0:3], v[210:213], v[190:193], v[0:3]
	v_mfma_f32_16x16x32_bf16 v[52:55], v[206:209], v[170:173], v[52:55]
	v_mfma_f32_16x16x32_bf16 v[48:51], v[214:217], v[170:173], v[48:51]
	v_mfma_f32_16x16x32_bf16 v[36:39], v[206:209], v[178:181], v[36:39]
	v_mfma_f32_16x16x32_bf16 v[32:35], v[214:217], v[178:181], v[32:35]
	v_mfma_f32_16x16x32_bf16 v[20:23], v[206:209], v[186:189], v[20:23]
	v_mfma_f32_16x16x32_bf16 v[16:19], v[214:217], v[186:189], v[16:19]
	v_mfma_f32_16x16x32_bf16 v[4:7], v[206:209], v[198:201], v[4:7]
	v_mfma_f32_16x16x32_bf16 v[0:3], v[214:217], v[198:201], v[0:3]
	s_setprio 0
	s_add_i32 s58, 0, 0x18000
	v_add_u32_e32 v84, s58, v166
	s_barrier
	ds_read_b128 v[72:75], v84
	ds_read_b128 v[76:79], v84 offset:1024
	ds_read_b128 v[80:83], v84 offset:2048
	ds_read_b128 v[84:87], v84 offset:3072
	s_add_u32 s28, s28, 0x80000
	s_addc_u32 s29, s29, 0
	s_mov_b32 m0, s5
	ds_read_b128 v[160:163], v168 offset:32768
	ds_read_b128 v[170:173], v168 offset:33792
	ds_read_b128 v[174:177], v168 offset:34816
	ds_read_b128 v[178:181], v168 offset:35840
	ds_read_b128 v[182:185], v168 offset:36864
	ds_read_b128 v[186:189], v168 offset:37888
	ds_read_b128 v[190:193], v168 offset:38912
	ds_read_b128 v[198:201], v168 offset:39936
	global_load_lds_dwordx4 v150, s[28:29]
	s_mov_b32 m0, s23
	s_nop 0
	global_load_lds_dwordx4 v146, s[28:29]
	s_waitcnt lgkmcnt(8)
	s_barrier
	s_setprio 1
	s_waitcnt lgkmcnt(7)
	v_mfma_f32_16x16x32_bf16 v[140:143], v[72:75], v[160:163], v[140:143]
	v_mfma_f32_16x16x32_bf16 v[136:139], v[80:83], v[160:163], v[136:139]
	s_waitcnt lgkmcnt(5)
	v_mfma_f32_16x16x32_bf16 v[124:127], v[72:75], v[174:177], v[124:127]
	v_mfma_f32_16x16x32_bf16 v[120:123], v[80:83], v[174:177], v[120:123]
	s_waitcnt lgkmcnt(3)
	v_mfma_f32_16x16x32_bf16 v[108:111], v[72:75], v[182:185], v[108:111]
	v_mfma_f32_16x16x32_bf16 v[104:107], v[80:83], v[182:185], v[104:107]
	s_waitcnt lgkmcnt(1)
	v_mfma_f32_16x16x32_bf16 v[92:95], v[72:75], v[190:193], v[92:95]
	v_mfma_f32_16x16x32_bf16 v[88:91], v[80:83], v[190:193], v[88:91]
	v_mfma_f32_16x16x32_bf16 v[140:143], v[76:79], v[170:173], v[140:143]
	v_mfma_f32_16x16x32_bf16 v[136:139], v[84:87], v[170:173], v[136:139]
	v_mfma_f32_16x16x32_bf16 v[124:127], v[76:79], v[178:181], v[124:127]
	v_mfma_f32_16x16x32_bf16 v[120:123], v[84:87], v[178:181], v[120:123]
	v_mfma_f32_16x16x32_bf16 v[108:111], v[76:79], v[186:189], v[108:111]
	v_mfma_f32_16x16x32_bf16 v[104:107], v[84:87], v[186:189], v[104:107]
	s_waitcnt lgkmcnt(0)
	v_mfma_f32_16x16x32_bf16 v[92:95], v[76:79], v[198:201], v[92:95]
	v_mfma_f32_16x16x32_bf16 v[88:91], v[84:87], v[198:201], v[88:91]
	s_setprio 0
	s_barrier
	s_add_i32 s28, 0, 0x1c000
	s_add_i32 s29, s58, s34
	v_add_u32_e32 v196, s28, v166
	v_lshl_add_u64 v[194:195], v[194:195], 0, s[12:13]
	s_mov_b32 m0, s29
	ds_read_b128 v[202:205], v196
	ds_read_b128 v[206:209], v196 offset:1024
	ds_read_b128 v[210:213], v196 offset:2048
	ds_read_b128 v[214:217], v196 offset:3072
	global_load_lds_dwordx4 v[194:195], off
	v_lshl_add_u64 v[194:195], v[218:219], 0, s[12:13]
	s_add_i32 m0, s29, 0x2000
	s_nop 0
	global_load_lds_dwordx4 v[194:195], off
	s_barrier
; #define PG8_STAGE(bufoff, gbase, voff) do { _Pragma("unroll") for (int _i = 0; _i < 2; ++_i) \
;         __builtin_amdgcn_global_load_lds((const unsigned*)((const char*)(gbase) + (voff)[_i]), (LAS unsigned*)(lds + (bufoff) + ldsw + _i * 8192), 16, 0, 0); } while (0)
; #define PG8_LDA(dst, b, h) do { _Pragma("unroll") for (int m = 0; m < 4; ++m) _Pragma("unroll") for (int k = 0; k < 2; ++k) dst[m][k] = *(const LAS bf16x8*)(lds + PG8_SA(b, h) + aoff + m * 2048 + k * 1024); } while (0)
; #define PG8_MMA(ai, bj, At, Bt) do { __builtin_amdgcn_s_setprio(1); _Pragma("unroll") for (int m = 0; m < 4; ++m) _Pragma("unroll") for (int n = 0; n < 2; ++n) _Pragma("unroll") for (int k = 0; k < 2; ++k) \
;         acc[ai][bj][m][n] = __builtin_amdgcn_mfma_f32_16x16x32_bf16(Bt[n][k], At[m][k], acc[ai][bj][m][n], 0, 0, 0); __builtin_amdgcn_s_setprio(0); } while (0)
; #define PG8_WAIT_V(n) asm volatile("s_waitcnt vmcnt(" #n ")" ::: "memory")
; #define PG8_WAIT_L(n) asm volatile("s_waitcnt lgkmcnt(" #n ")" ::: "memory")
; #define PG8_BAR __builtin_amdgcn_s_barrier()
; #define PG8_SCHED __builtin_amdgcn_sched_barrier(0)
;     DI void operator()(const f32x4 (&acc)[2][2][4][2], const Unit& u, int wr, int wc, int fr, int fq) const {
;         const int row0 = u.pm * BM + wr * 64 + fr, col0 = u.pn * BM + wc * 32 + 8 * fq;
;         f32x4 sc[2][2];
; #pragma unroll
;         for (int bj = 0; bj < 2; ++bj)
; #pragma unroll
;             for (int n = 0; n < 2; ++n) sc[bj][n] = scale ? *(const f32x4*)(scale + col0 + bj * HALF + 4 * n) : (f32x4){1.f, 1.f, 1.f, 1.f};
; template <class Map, class Epi>
; DI void gemm_phase(LAS unsigned char* lds, const Map& MP, const Epi& E, const int nM, const int nN, const int K, const int lda, const int ldb) {
;     ...
;             PG8_BAR; PG8_WAIT_L(0); PG8_MMA(0, 1, At, B1); PG8_BAR;
;             PG8_LDA(At, 1, 1); PG8_STAGE(PG8_SA(1, 0), a3, voffA);
;             PG8_BAR; PG8_WAIT_L(0); PG8_MMA(1, 0, At, B0); PG8_BAR; PG8_SCHED;
;             PG8_STAGE(PG8_SB(1, 1), b3 + hstepB, voffB);
;             PG8_WAIT_V(6); PG8_BAR; PG8_MMA(1, 1, At, B1); PG8_BAR;
	s_setprio 1
	s_waitcnt lgkmcnt(3)
	v_mfma_f32_16x16x32_bf16 v[132:135], v[202:205], v[160:163], v[132:135]
	s_waitcnt lgkmcnt(1)
	v_mfma_f32_16x16x32_bf16 v[128:131], v[210:213], v[160:163], v[128:131]
	v_mfma_f32_16x16x32_bf16 v[116:119], v[202:205], v[174:177], v[116:119]
	v_mfma_f32_16x16x32_bf16 v[112:115], v[210:213], v[174:177], v[112:115]
	v_mfma_f32_16x16x32_bf16 v[100:103], v[202:205], v[182:185], v[100:103]
	v_mfma_f32_16x16x32_bf16 v[96:99], v[210:213], v[182:185], v[96:99]
	v_mfma_f32_16x16x32_bf16 v[68:71], v[202:205], v[190:193], v[68:71]
	v_mfma_f32_16x16x32_bf16 v[64:67], v[210:213], v[190:193], v[64:67]
	v_mfma_f32_16x16x32_bf16 v[132:135], v[206:209], v[170:173], v[132:135]
	s_waitcnt lgkmcnt(0)
	v_mfma_f32_16x16x32_bf16 v[128:131], v[214:217], v[170:173], v[128:131]
	v_mfma_f32_16x16x32_bf16 v[116:119], v[206:209], v[178:181], v[116:119]
	v_mfma_f32_16x16x32_bf16 v[112:115], v[214:217], v[178:181], v[112:115]
	v_mfma_f32_16x16x32_bf16 v[100:103], v[206:209], v[186:189], v[100:103]
	v_mfma_f32_16x16x32_bf16 v[96:99], v[214:217], v[186:189], v[96:99]
	v_mfma_f32_16x16x32_bf16 v[68:71], v[206:209], v[198:201], v[68:71]
	v_mfma_f32_16x16x32_bf16 v[64:67], v[214:217], v[198:201], v[64:67]
	s_setprio 0
	s_mov_b32 m0, s39
	v_lshl_add_u64 v[194:195], v[220:221], 0, s[12:13]
	s_barrier
	ds_read_b128 v[160:163], v168 offset:49152
	ds_read_b128 v[170:173], v168 offset:50176
	ds_read_b128 v[174:177], v168 offset:51200
	ds_read_b128 v[178:181], v168 offset:52224
	ds_read_b128 v[182:185], v168 offset:53248
	ds_read_b128 v[186:189], v168 offset:54272
	ds_read_b128 v[190:193], v168 offset:55296
	ds_read_b128 v[198:201], v168 offset:56320
	global_load_lds_dwordx4 v[194:195], off
	v_lshl_add_u64 v[194:195], v[222:223], 0, s[12:13]
	s_mov_b32 m0, s46
	s_nop 0
	global_load_lds_dwordx4 v[194:195], off
	s_barrier
	s_setprio 1
	s_waitcnt lgkmcnt(7)
	v_mfma_f32_16x16x32_bf16 v[60:63], v[72:75], v[160:163], v[60:63]
	v_mfma_f32_16x16x32_bf16 v[56:59], v[80:83], v[160:163], v[56:59]
	s_waitcnt lgkmcnt(5)
	v_mfma_f32_16x16x32_bf16 v[44:47], v[72:75], v[174:177], v[44:47]
	v_mfma_f32_16x16x32_bf16 v[40:43], v[80:83], v[174:177], v[40:43]
	s_waitcnt lgkmcnt(3)
	v_mfma_f32_16x16x32_bf16 v[28:31], v[72:75], v[182:185], v[28:31]
	v_mfma_f32_16x16x32_bf16 v[24:27], v[80:83], v[182:185], v[24:27]
	s_waitcnt lgkmcnt(1)
	v_mfma_f32_16x16x32_bf16 v[12:15], v[72:75], v[190:193], v[12:15]
	v_mfma_f32_16x16x32_bf16 v[8:11], v[80:83], v[190:193], v[8:11]
	v_mfma_f32_16x16x32_bf16 v[60:63], v[76:79], v[170:173], v[60:63]
	v_mfma_f32_16x16x32_bf16 v[56:59], v[84:87], v[170:173], v[56:59]
	v_mfma_f32_16x16x32_bf16 v[44:47], v[76:79], v[178:181], v[44:47]
	v_mfma_f32_16x16x32_bf16 v[40:43], v[84:87], v[178:181], v[40:43]
	v_mfma_f32_16x16x32_bf16 v[28:31], v[76:79], v[186:189], v[28:31]
	v_mfma_f32_16x16x32_bf16 v[24:27], v[84:87], v[186:189], v[24:27]
	s_waitcnt lgkmcnt(0)
	v_mfma_f32_16x16x32_bf16 v[12:15], v[76:79], v[198:201], v[12:15]
	v_mfma_f32_16x16x32_bf16 v[8:11], v[84:87], v[198:201], v[8:11]
	s_setprio 0
	s_barrier
	s_add_u32 s26, s26, 0x20080
	s_addc_u32 s27, s27, 0
	s_add_i32 s28, s28, s34
	s_mov_b32 m0, s28
	s_nop 0
	global_load_lds_dwordx4 v148, s[26:27]
	s_add_i32 m0, s28, 0x2000
	s_nop 0
	global_load_lds_dwordx4 v144, s[26:27]
	s_waitcnt vmcnt(6)
	s_barrier
	s_setprio 1
	v_mfma_f32_16x16x32_bf16 v[52:55], v[202:205], v[160:163], v[52:55]
	v_mfma_f32_16x16x32_bf16 v[48:51], v[210:213], v[160:163], v[48:51]
	v_mfma_f32_16x16x32_bf16 v[36:39], v[202:205], v[174:177], v[36:39]
	v_mfma_f32_16x16x32_bf16 v[32:35], v[210:213], v[174:177], v[32:35]
	v_mfma_f32_16x16x32_bf16 v[20:23], v[202:205], v[182:185], v[20:23]
	v_mfma_f32_16x16x32_bf16 v[16:19], v[210:213], v[182:185], v[16:19]
	v_mfma_f32_16x16x32_bf16 v[4:7], v[202:205], v[190:193], v[4:7]
	v_mfma_f32_16x16x32_bf16 v[0:3], v[210:213], v[190:193], v[0:3]
	v_mfma_f32_16x16x32_bf16 v[52:55], v[206:209], v[170:173], v[52:55]
	v_mfma_f32_16x16x32_bf16 v[48:51], v[214:217], v[170:173], v[48:51]
	v_mfma_f32_16x16x32_bf16 v[36:39], v[206:209], v[178:181], v[36:39]
	v_mfma_f32_16x16x32_bf16 v[32:35], v[214:217], v[178:181], v[32:35]
	v_mfma_f32_16x16x32_bf16 v[20:23], v[206:209], v[186:189], v[20:23]
	v_mfma_f32_16x16x32_bf16 v[16:19], v[214:217], v[186:189], v[16:19]
	v_mfma_f32_16x16x32_bf16 v[4:7], v[206:209], v[198:201], v[4:7]
	v_mfma_f32_16x16x32_bf16 v[0:3], v[214:217], v[198:201], v[0:3]
	s_setprio 0
	s_add_i32 s57, s57, 2
	s_add_u32 s55, s55, 0x100
	s_addc_u32 s56, s56, 0
	s_add_u32 s24, s24, 0x100
	s_addc_u32 s25, s25, 0
	s_cmp_gt_u32 s57, 5
	s_barrier
	s_cbranch_scc0 .LBB1_229
	s_lshl_b32 s17, s42, 8
	v_mov_b32_e32 v170, v164
	v_mov_b32_e32 v72, v165
	s_or_b32 s17, s17, s38
	v_mov_b32_e32 v80, 1.0
	v_lshl_add_u32 v160, v72, 3, s17
	v_ashrrev_i32_e32 v161, 31, v160
	v_cndmask_b32_e64 v72, 0, 1, s[14:15]
	v_lshl_add_u64 v[162:163], v[160:161], 2, s[8:9]
	v_cmp_ne_u32_e64 s[42:43], 1, v72
	s_andn2_b64 vcc, exec, s[14:15]
	v_mov_b32_e32 v84, 1.0
	v_mov_b32_e32 v85, 1.0
	v_mov_b32_e32 v86, 1.0
	v_mov_b32_e32 v87, 1.0
	s_cbranch_vccnz .LBB1_232
	global_load_dwordx4 v[84:87], v[162:163], off

; #define PG8_STAGE(bufoff, gbase, voff) do { _Pragma("unroll") for (int _i = 0; _i < 2; ++_i) \
;         __builtin_amdgcn_global_load_lds((const unsigned*)((const char*)(gbase) + (voff)[_i]), (LAS unsigned*)(lds + (bufoff) + ldsw + _i * 8192), 16, 0, 0); } while (0)
; #define PG8_LDA(dst, b, h) do { _Pragma("unroll") for (int m = 0; m < 4; ++m) _Pragma("unroll") for (int k = 0; k < 2; ++k) dst[m][k] = *(const LAS bf16x8*)(lds + PG8_SA(b, h) + aoff + m * 2048 + k * 1024); } while (0)
; #define PG8_LDB(dst, b, h) do { _Pragma("unroll") for (int n = 0; n < 2; ++n) _Pragma("unroll") for (int k = 0; k < 2; ++k) dst[n][k] = *(const LAS bf16x8*)(lds + PG8_SB(b, h) + boff + n * 2048 + k * 1024); } while (0)
; #define PG8_MMA(ai, bj, At, Bt) do { __builtin_amdgcn_s_setprio(1); _Pragma("unroll") for (int m = 0; m < 4; ++m) _Pragma("unroll") for (int n = 0; n < 2; ++n) _Pragma("unroll") for (int k = 0; k < 2; ++k) \
;         acc[ai][bj][m][n] = __builtin_amdgcn_mfma_f32_16x16x32_bf16(Bt[n][k], At[m][k], acc[ai][bj][m][n], 0, 0, 0); __builtin_amdgcn_s_setprio(0); } while (0)
; #define PG8_WAIT_V(n) asm volatile("s_waitcnt vmcnt(" #n ")" ::: "memory")
; #define PG8_WAIT_L(n) asm volatile("s_waitcnt lgkmcnt(" #n ")" ::: "memory")
; #define PG8_BAR __builtin_amdgcn_s_barrier()
; #define PG8_SCHED __builtin_amdgcn_sched_barrier(0)
; template <class Map, class Epi>
; DI void gemm_phase(LAS unsigned char* lds, const Map& MP, const Epi& E, const int nM, const int nN, const int K, const int lda, const int ldb) {
;     ...
;             PG8_LDB(B0, 0, 0); PG8_SCHED; PG8_LDA(At, 0, 0); PG8_STAGE(PG8_SA(1, 1), a1 + hstepA, voffA);
;             PG8_WAIT_L(8); PG8_BAR; PG8_WAIT_L(0); PG8_MMA(0, 0, At, B0); PG8_BAR; PG8_SCHED;
;             PG8_LDB(B1, 0, 1); PG8_STAGE(PG8_SB(0, 0), b2, voffB);
;             PG8_BAR; PG8_WAIT_L(0); PG8_MMA(0, 1, At, B1); PG8_BAR;
;             PG8_LDA(At, 0, 1); PG8_STAGE(PG8_SA(0, 0), a2, voffA);
;             PG8_BAR; PG8_WAIT_L(0); PG8_MMA(1, 0, At, B0); PG8_BAR; PG8_SCHED;
;             PG8_STAGE(PG8_SB(0, 1), b2 + hstepB, voffB);
;             PG8_WAIT_V(6); PG8_BAR; PG8_MMA(1, 1, At, B1); PG8_BAR;
.LBB1_380:
	ds_read_b128 v[80:83], v189
	ds_read_b128 v[84:87], v189 offset:1024
	ds_read_b128 v[88:91], v189 offset:2048
	ds_read_b128 v[92:95], v189 offset:3072
	s_add_u32 s28, s44, 0xfff80080
	s_addc_u32 s29, s45, -1
	s_cmp_eq_u32 vcc_hi, 28
	s_cselect_b32 s47, s23, s29
	s_cselect_b32 s46, s61, s28
	s_cselect_b32 s29, s21, vcc_lo
	s_cselect_b32 s28, s58, s59
	s_add_i32 m0, s38, 0xc000
	ds_read_b128 v[96:99], v190
	ds_read_b128 v[100:103], v190 offset:1024
	ds_read_b128 v[108:111], v190 offset:2048
	ds_read_b128 v[112:115], v190 offset:3072
	ds_read_b128 v[160:163], v190 offset:4096
	ds_read_b128 v[164:167], v190 offset:5120
	ds_read_b128 v[198:201], v190 offset:6144
	ds_read_b128 v[202:205], v190 offset:7168
	global_load_lds_dwordx4 v178, s[44:45]
	s_add_i32 m0, s38, 0xe000
	s_nop 0
	global_load_lds_dwordx4 v176, s[44:45]
	s_waitcnt lgkmcnt(8)
	s_barrier
	s_setprio 1
	s_waitcnt lgkmcnt(7)
	v_mfma_f32_16x16x32_bf16 v[148:151], v[80:83], v[96:99], v[148:151]
	v_mfma_f32_16x16x32_bf16 v[144:147], v[88:91], v[96:99], v[144:147]
	s_waitcnt lgkmcnt(5)
	v_mfma_f32_16x16x32_bf16 v[136:139], v[80:83], v[108:111], v[136:139]
	v_mfma_f32_16x16x32_bf16 v[128:131], v[88:91], v[108:111], v[128:131]
	s_waitcnt lgkmcnt(3)
	v_mfma_f32_16x16x32_bf16 v[120:123], v[80:83], v[160:163], v[120:123]
	v_mfma_f32_16x16x32_bf16 v[104:107], v[88:91], v[160:163], v[104:107]
	s_waitcnt lgkmcnt(1)
	v_mfma_f32_16x16x32_bf16 v[76:79], v[80:83], v[198:201], v[76:79]
	v_mfma_f32_16x16x32_bf16 v[72:75], v[88:91], v[198:201], v[72:75]
	v_mfma_f32_16x16x32_bf16 v[148:151], v[84:87], v[100:103], v[148:151]
	v_mfma_f32_16x16x32_bf16 v[144:147], v[92:95], v[100:103], v[144:147]
	v_mfma_f32_16x16x32_bf16 v[136:139], v[84:87], v[112:115], v[136:139]
	v_mfma_f32_16x16x32_bf16 v[128:131], v[92:95], v[112:115], v[128:131]
	v_mfma_f32_16x16x32_bf16 v[120:123], v[84:87], v[164:167], v[120:123]
	v_mfma_f32_16x16x32_bf16 v[104:107], v[92:95], v[164:167], v[104:107]
	s_waitcnt lgkmcnt(0)
	v_mfma_f32_16x16x32_bf16 v[76:79], v[84:87], v[202:205], v[76:79]
	v_mfma_f32_16x16x32_bf16 v[72:75], v[92:95], v[202:205], v[72:75]
	s_setprio 0
	s_barrier
	s_add_i32 s68, s5, s37
	v_lshl_add_u64 v[184:185], s[28:29], 0, v[172:173]
	s_mov_b32 m0, s68
	ds_read_b128 v[206:209], v191
	ds_read_b128 v[210:213], v191 offset:1024
	ds_read_b128 v[214:217], v191 offset:2048
	ds_read_b128 v[218:221], v191 offset:3072
	global_load_lds_dwordx4 v[184:185], off
	v_lshl_add_u64 v[194:195], s[28:29], 0, v[168:169]
	s_add_i32 m0, s68, 0x2000
	s_nop 0
	global_load_lds_dwordx4 v[194:195], off
	s_barrier
	s_setprio 1
	s_waitcnt lgkmcnt(3)
	v_mfma_f32_16x16x32_bf16 v[156:159], v[206:209], v[96:99], v[156:159]
	s_waitcnt lgkmcnt(1)
	v_mfma_f32_16x16x32_bf16 v[96:99], v[214:217], v[96:99], v[152:155]
	v_mfma_f32_16x16x32_bf16 v[156:159], v[210:213], v[100:103], v[156:159]
	s_waitcnt lgkmcnt(0)
	v_mfma_f32_16x16x32_bf16 v[96:99], v[218:221], v[100:103], v[96:99]
	v_mfma_f32_16x16x32_bf16 v[100:103], v[206:209], v[108:111], v[140:143]
	v_mfma_f32_16x16x32_bf16 v[108:111], v[214:217], v[108:111], v[132:135]
	v_mfma_f32_16x16x32_bf16 v[116:119], v[214:217], v[160:163], v[116:119]
	v_mfma_f32_16x16x32_bf16 v[68:71], v[206:209], v[198:201], v[68:71]
	v_mfma_f32_16x16x32_bf16 v[64:67], v[214:217], v[198:201], v[64:67]
	v_mfma_f32_16x16x32_bf16 v[100:103], v[210:213], v[112:115], v[100:103]
	v_mfma_f32_16x16x32_bf16 v[108:111], v[218:221], v[112:115], v[108:111]
	v_mfma_f32_16x16x32_bf16 v[112:115], v[206:209], v[160:163], v[124:127]
	v_mfma_f32_16x16x32_bf16 v[116:119], v[218:221], v[164:167], v[116:119]
	v_mfma_f32_16x16x32_bf16 v[68:71], v[210:213], v[202:205], v[68:71]
	v_mfma_f32_16x16x32_bf16 v[64:67], v[218:221], v[202:205], v[64:67]
	v_mfma_f32_16x16x32_bf16 v[112:115], v[210:213], v[164:167], v[112:115]
	s_setprio 0
	s_mov_b32 m0, s38
	v_lshl_add_u64 v[226:227], s[46:47], 0, v[174:175]
	s_barrier
	ds_read_b128 v[124:127], v190 offset:16384
	ds_read_b128 v[132:135], v190 offset:17408
	ds_read_b128 v[140:143], v190 offset:18432
	ds_read_b128 v[152:155], v190 offset:19456
	ds_read_b128 v[160:163], v190 offset:20480
	ds_read_b128 v[164:167], v190 offset:21504
	ds_read_b128 v[198:201], v190 offset:22528
	ds_read_b128 v[202:205], v190 offset:23552
	global_load_lds_dwordx4 v[226:227], off
	v_lshl_add_u64 v[234:235], s[46:47], 0, v[170:171]
	s_mov_b32 m0, s39
	s_nop 0
	global_load_lds_dwordx4 v[234:235], off
	s_barrier
	s_setprio 1
	s_waitcnt lgkmcnt(7)
	v_mfma_f32_16x16x32_bf16 v[60:63], v[80:83], v[124:127], v[60:63]
	v_mfma_f32_16x16x32_bf16 v[48:51], v[88:91], v[124:127], v[48:51]
	s_waitcnt lgkmcnt(5)
	v_mfma_f32_16x16x32_bf16 v[40:43], v[80:83], v[140:143], v[40:43]
	v_mfma_f32_16x16x32_bf16 v[32:35], v[88:91], v[140:143], v[32:35]
	s_waitcnt lgkmcnt(3)
	v_mfma_f32_16x16x32_bf16 v[24:27], v[80:83], v[160:163], v[24:27]
	v_mfma_f32_16x16x32_bf16 v[16:19], v[88:91], v[160:163], v[16:19]
	s_waitcnt lgkmcnt(1)
	v_mfma_f32_16x16x32_bf16 v[12:15], v[80:83], v[198:201], v[12:15]
	v_mfma_f32_16x16x32_bf16 v[8:11], v[88:91], v[198:201], v[8:11]
	v_mfma_f32_16x16x32_bf16 v[60:63], v[84:87], v[132:135], v[60:63]
	v_mfma_f32_16x16x32_bf16 v[48:51], v[92:95], v[132:135], v[48:51]
	v_mfma_f32_16x16x32_bf16 v[40:43], v[84:87], v[152:155], v[40:43]
	v_mfma_f32_16x16x32_bf16 v[32:35], v[92:95], v[152:155], v[32:35]
	v_mfma_f32_16x16x32_bf16 v[24:27], v[84:87], v[164:167], v[24:27]
	v_mfma_f32_16x16x32_bf16 v[16:19], v[92:95], v[164:167], v[16:19]
	s_waitcnt lgkmcnt(0)
	v_mfma_f32_16x16x32_bf16 v[12:15], v[84:87], v[202:205], v[12:15]
	v_mfma_f32_16x16x32_bf16 v[8:11], v[92:95], v[202:205], v[8:11]
	s_setprio 0
	s_barrier
; #define PG8_STAGE(bufoff, gbase, voff) do { _Pragma("unroll") for (int _i = 0; _i < 2; ++_i) \
;         __builtin_amdgcn_global_load_lds((const unsigned*)((const char*)(gbase) + (voff)[_i]), (LAS unsigned*)(lds + (bufoff) + ldsw + _i * 8192), 16, 0, 0); } while (0)
; #define PG8_LDA(dst, b, h) do { _Pragma("unroll") for (int m = 0; m < 4; ++m) _Pragma("unroll") for (int k = 0; k < 2; ++k) dst[m][k] = *(const LAS bf16x8*)(lds + PG8_SA(b, h) + aoff + m * 2048 + k * 1024); } while (0)
; #define PG8_LDB(dst, b, h) do { _Pragma("unroll") for (int n = 0; n < 2; ++n) _Pragma("unroll") for (int k = 0; k < 2; ++k) dst[n][k] = *(const LAS bf16x8*)(lds + PG8_SB(b, h) + boff + n * 2048 + k * 1024); } while (0)
; #define PG8_MMA(ai, bj, At, Bt) do { __builtin_amdgcn_s_setprio(1); _Pragma("unroll") for (int m = 0; m < 4; ++m) _Pragma("unroll") for (int n = 0; n < 2; ++n) _Pragma("unroll") for (int k = 0; k < 2; ++k) \
;         acc[ai][bj][m][n] = __builtin_amdgcn_mfma_f32_16x16x32_bf16(Bt[n][k], At[m][k], acc[ai][bj][m][n], 0, 0, 0); __builtin_amdgcn_s_setprio(0); } while (0)
; #define PG8_WAIT_V(n) asm volatile("s_waitcnt vmcnt(" #n ")" ::: "memory")
; #define PG8_WAIT_L(n) asm volatile("s_waitcnt lgkmcnt(" #n ")" ::: "memory")
; #define PG8_BAR __builtin_amdgcn_s_barrier()
; #define PG8_SCHED __builtin_amdgcn_sched_barrier(0)
; template <class Map, class Epi>
; DI void gemm_phase(LAS unsigned char* lds, const Map& MP, const Epi& E, const int nM, const int nN, const int K, const int lda, const int ldb) {
;     ...
;             PG8_STAGE(PG8_SB(0, 1), b2 + hstepB, voffB);
;             PG8_WAIT_V(6); PG8_BAR; PG8_MMA(1, 1, At, B1); PG8_BAR;
;             PG8_LDB(B0, 1, 0); PG8_SCHED; PG8_LDA(At, 1, 0); PG8_STAGE(PG8_SA(0, 1), a2 + hstepA, voffA);
;             PG8_WAIT_L(8); PG8_BAR; PG8_WAIT_L(0); PG8_MMA(0, 0, At, B0); PG8_BAR; PG8_SCHED;
;             PG8_LDB(B1, 1, 1); PG8_STAGE(PG8_SB(1, 0), b3, voffB);
;             PG8_BAR; PG8_WAIT_L(0); PG8_MMA(0, 1, At, B1); PG8_BAR;
;             PG8_LDA(At, 1, 1); PG8_STAGE(PG8_SA(1, 0), a3, voffA);
	s_add_u32 s68, s28, 0x80000
	s_addc_u32 s69, s29, 0
	s_add_i32 s70, s2, s37
	s_mov_b32 m0, s70
	s_nop 0
	global_load_lds_dwordx4 v172, s[68:69]
	s_add_i32 m0, s70, 0x2000
	s_nop 0
	global_load_lds_dwordx4 v168, s[68:69]
	s_waitcnt vmcnt(6)
	s_barrier
	s_setprio 1
	v_mfma_f32_16x16x32_bf16 v[56:59], v[206:209], v[124:127], v[56:59]
	v_mfma_f32_16x16x32_bf16 v[52:55], v[214:217], v[124:127], v[52:55]
	v_mfma_f32_16x16x32_bf16 v[44:47], v[206:209], v[140:143], v[44:47]
	v_mfma_f32_16x16x32_bf16 v[36:39], v[214:217], v[140:143], v[36:39]
	v_mfma_f32_16x16x32_bf16 v[28:31], v[206:209], v[160:163], v[28:31]
	v_mfma_f32_16x16x32_bf16 v[20:23], v[214:217], v[160:163], v[20:23]
	v_mfma_f32_16x16x32_bf16 v[4:7], v[206:209], v[198:201], v[4:7]
	v_mfma_f32_16x16x32_bf16 v[0:3], v[214:217], v[198:201], v[0:3]
	v_mfma_f32_16x16x32_bf16 v[56:59], v[210:213], v[132:135], v[56:59]
	v_mfma_f32_16x16x32_bf16 v[52:55], v[218:221], v[132:135], v[52:55]
	v_mfma_f32_16x16x32_bf16 v[44:47], v[210:213], v[152:155], v[44:47]
	v_mfma_f32_16x16x32_bf16 v[36:39], v[218:221], v[152:155], v[36:39]
	v_mfma_f32_16x16x32_bf16 v[28:31], v[210:213], v[164:167], v[28:31]
	v_mfma_f32_16x16x32_bf16 v[20:23], v[218:221], v[164:167], v[20:23]
	v_mfma_f32_16x16x32_bf16 v[4:7], v[210:213], v[202:205], v[4:7]
	v_mfma_f32_16x16x32_bf16 v[0:3], v[218:221], v[202:205], v[0:3]
	s_setprio 0
	s_add_i32 s68, 0, 0x18000
	v_add_u32_e32 v92, s68, v188
	s_barrier
	ds_read_b128 v[80:83], v92
	ds_read_b128 v[84:87], v92 offset:1024
	ds_read_b128 v[88:91], v92 offset:2048
	ds_read_b128 v[92:95], v92 offset:3072
	s_add_u32 s46, s46, 0x80000
	s_addc_u32 s47, s47, 0
	s_mov_b32 m0, s56
	ds_read_b128 v[124:127], v190 offset:32768
	ds_read_b128 v[132:135], v190 offset:33792
	ds_read_b128 v[160:163], v190 offset:34816
	ds_read_b128 v[164:167], v190 offset:35840
	ds_read_b128 v[198:201], v190 offset:36864
	ds_read_b128 v[202:205], v190 offset:37888
	ds_read_b128 v[206:209], v190 offset:38912
	ds_read_b128 v[210:213], v190 offset:39936
	global_load_lds_dwordx4 v174, s[46:47]
	s_mov_b32 m0, s57
	s_nop 0
	global_load_lds_dwordx4 v170, s[46:47]
	s_waitcnt lgkmcnt(8)
	s_barrier
	s_setprio 1
	s_waitcnt lgkmcnt(7)
	v_mfma_f32_16x16x32_bf16 v[140:143], v[80:83], v[124:127], v[148:151]
	s_waitcnt lgkmcnt(6)
	v_mfma_f32_16x16x32_bf16 v[148:151], v[84:87], v[132:135], v[140:143]
	v_mfma_f32_16x16x32_bf16 v[140:143], v[88:91], v[124:127], v[144:147]
	s_waitcnt lgkmcnt(5)
	v_mfma_f32_16x16x32_bf16 v[136:139], v[80:83], v[160:163], v[136:139]
	v_mfma_f32_16x16x32_bf16 v[128:131], v[88:91], v[160:163], v[128:131]
	s_waitcnt lgkmcnt(3)
	v_mfma_f32_16x16x32_bf16 v[120:123], v[80:83], v[198:201], v[120:123]
	v_mfma_f32_16x16x32_bf16 v[104:107], v[88:91], v[198:201], v[104:107]
	s_waitcnt lgkmcnt(1)
	v_mfma_f32_16x16x32_bf16 v[76:79], v[80:83], v[206:209], v[76:79]
	v_mfma_f32_16x16x32_bf16 v[72:75], v[88:91], v[206:209], v[72:75]
	v_mfma_f32_16x16x32_bf16 v[144:147], v[92:95], v[132:135], v[140:143]
	v_mfma_f32_16x16x32_bf16 v[136:139], v[84:87], v[164:167], v[136:139]
	v_mfma_f32_16x16x32_bf16 v[128:131], v[92:95], v[164:167], v[128:131]
	v_mfma_f32_16x16x32_bf16 v[120:123], v[84:87], v[202:205], v[120:123]
	v_mfma_f32_16x16x32_bf16 v[104:107], v[92:95], v[202:205], v[104:107]
	s_waitcnt lgkmcnt(0)
	v_mfma_f32_16x16x32_bf16 v[76:79], v[84:87], v[210:213], v[76:79]
	v_mfma_f32_16x16x32_bf16 v[72:75], v[92:95], v[210:213], v[72:75]
	s_setprio 0
	s_barrier
	s_add_i32 s46, 0, 0x1c000
	v_add_u32_e32 v140, s46, v188
	s_add_i32 s47, s68, s37
	ds_read_b128 v[214:217], v140
	ds_read_b128 v[218:221], v140 offset:1024
	ds_read_b128 v[222:225], v140 offset:2048
	ds_read_b128 v[230:233], v140 offset:3072
	v_lshl_add_u64 v[140:141], v[184:185], 0, s[14:15]
	s_mov_b32 m0, s47
	s_nop 0
	global_load_lds_dwordx4 v[140:141], off
	v_lshl_add_u64 v[140:141], v[194:195], 0, s[14:15]
	s_add_i32 m0, s47, 0x2000
	s_nop 0
	global_load_lds_dwordx4 v[140:141], off
	s_barrier
	s_setprio 1
	s_waitcnt lgkmcnt(1)
	v_mfma_f32_16x16x32_bf16 v[96:99], v[222:225], v[124:127], v[96:99]
	v_mfma_f32_16x16x32_bf16 v[140:143], v[214:217], v[124:127], v[156:159]
	s_waitcnt lgkmcnt(0)
	v_mfma_f32_16x16x32_bf16 v[152:155], v[230:233], v[132:135], v[96:99]
	v_mfma_f32_16x16x32_bf16 v[96:99], v[214:217], v[160:163], v[100:103]
	v_mfma_f32_16x16x32_bf16 v[156:159], v[218:221], v[132:135], v[140:143]
	v_mfma_f32_16x16x32_bf16 v[140:143], v[218:221], v[164:167], v[96:99]
	v_mfma_f32_16x16x32_bf16 v[96:99], v[222:225], v[160:163], v[108:111]
	v_mfma_f32_16x16x32_bf16 v[132:135], v[230:233], v[164:167], v[96:99]
	v_mfma_f32_16x16x32_bf16 v[96:99], v[214:217], v[198:201], v[112:115]
	v_mfma_f32_16x16x32_bf16 v[124:127], v[218:221], v[202:205], v[96:99]
	v_mfma_f32_16x16x32_bf16 v[96:99], v[222:225], v[198:201], v[116:119]
	v_mfma_f32_16x16x32_bf16 v[68:71], v[214:217], v[206:209], v[68:71]
	v_mfma_f32_16x16x32_bf16 v[64:67], v[222:225], v[206:209], v[64:67]
	v_mfma_f32_16x16x32_bf16 v[116:119], v[230:233], v[202:205], v[96:99]
	v_mfma_f32_16x16x32_bf16 v[68:71], v[218:221], v[210:213], v[68:71]
	v_mfma_f32_16x16x32_bf16 v[64:67], v[230:233], v[210:213], v[64:67]
	s_setprio 0
	s_mov_b32 m0, s62
	v_lshl_add_u64 v[184:185], v[226:227], 0, s[14:15]
	s_barrier
	ds_read_b128 v[96:99], v190 offset:49152
	ds_read_b128 v[100:103], v190 offset:50176
	ds_read_b128 v[108:111], v190 offset:51200
	ds_read_b128 v[112:115], v190 offset:52224
	ds_read_b128 v[160:163], v190 offset:53248
	ds_read_b128 v[164:167], v190 offset:54272
	ds_read_b128 v[198:201], v190 offset:55296
	ds_read_b128 v[202:205], v190 offset:56320
	global_load_lds_dwordx4 v[184:185], off
	v_lshl_add_u64 v[184:185], v[234:235], 0, s[14:15]
	s_mov_b32 m0, s63
	s_nop 0
	global_load_lds_dwordx4 v[184:185], off
	s_barrier
; #define PG8_STAGE(bufoff, gbase, voff) do { _Pragma("unroll") for (int _i = 0; _i < 2; ++_i) \
;         __builtin_amdgcn_global_load_lds((const unsigned*)((const char*)(gbase) + (voff)[_i]), (LAS unsigned*)(lds + (bufoff) + ldsw + _i * 8192), 16, 0, 0); } while (0)
; #define PG8_MMA(ai, bj, At, Bt) do { __builtin_amdgcn_s_setprio(1); _Pragma("unroll") for (int m = 0; m < 4; ++m) _Pragma("unroll") for (int n = 0; n < 2; ++n) _Pragma("unroll") for (int k = 0; k < 2; ++k) \
;         acc[ai][bj][m][n] = __builtin_amdgcn_mfma_f32_16x16x32_bf16(Bt[n][k], At[m][k], acc[ai][bj][m][n], 0, 0, 0); __builtin_amdgcn_s_setprio(0); } while (0)
; #define PG8_WAIT_V(n) asm volatile("s_waitcnt vmcnt(" #n ")" ::: "memory")
; #define PG8_WAIT_L(n) asm volatile("s_waitcnt lgkmcnt(" #n ")" ::: "memory")
; #define PG8_BAR __builtin_amdgcn_s_barrier()
; #define PG8_SCHED __builtin_amdgcn_sched_barrier(0)
; template <class Map, class Epi>
; DI void gemm_phase(LAS unsigned char* lds, const Map& MP, const Epi& E, const int nM, const int nN, const int K, const int lda, const int ldb) {
;     ...
;             PG8_BAR; PG8_WAIT_L(0); PG8_MMA(1, 0, At, B0); PG8_BAR; PG8_SCHED;
;             PG8_STAGE(PG8_SB(1, 1), b3 + hstepB, voffB);
;             PG8_WAIT_V(6); PG8_BAR; PG8_MMA(1, 1, At, B1); PG8_BAR;
	s_setprio 1
	s_waitcnt lgkmcnt(7)
	v_mfma_f32_16x16x32_bf16 v[60:63], v[80:83], v[96:99], v[60:63]
	v_mfma_f32_16x16x32_bf16 v[48:51], v[88:91], v[96:99], v[48:51]
	s_waitcnt lgkmcnt(5)
	v_mfma_f32_16x16x32_bf16 v[40:43], v[80:83], v[108:111], v[40:43]
	v_mfma_f32_16x16x32_bf16 v[32:35], v[88:91], v[108:111], v[32:35]
	s_waitcnt lgkmcnt(3)
	v_mfma_f32_16x16x32_bf16 v[24:27], v[80:83], v[160:163], v[24:27]
	v_mfma_f32_16x16x32_bf16 v[16:19], v[88:91], v[160:163], v[16:19]
	s_waitcnt lgkmcnt(1)
	v_mfma_f32_16x16x32_bf16 v[12:15], v[80:83], v[198:201], v[12:15]
	v_mfma_f32_16x16x32_bf16 v[8:11], v[88:91], v[198:201], v[8:11]
	v_mfma_f32_16x16x32_bf16 v[60:63], v[84:87], v[100:103], v[60:63]
	v_mfma_f32_16x16x32_bf16 v[48:51], v[92:95], v[100:103], v[48:51]
	v_mfma_f32_16x16x32_bf16 v[40:43], v[84:87], v[112:115], v[40:43]
	v_mfma_f32_16x16x32_bf16 v[32:35], v[92:95], v[112:115], v[32:35]
	v_mfma_f32_16x16x32_bf16 v[24:27], v[84:87], v[164:167], v[24:27]
	v_mfma_f32_16x16x32_bf16 v[16:19], v[92:95], v[164:167], v[16:19]
	s_waitcnt lgkmcnt(0)
	v_mfma_f32_16x16x32_bf16 v[12:15], v[84:87], v[202:205], v[12:15]
	v_mfma_f32_16x16x32_bf16 v[8:11], v[92:95], v[202:205], v[8:11]
	s_setprio 0
	s_barrier
	s_add_u32 s28, s28, 0x80080
	s_addc_u32 s29, s29, 0
	s_add_i32 s46, s46, s37
	s_mov_b32 m0, s46
	s_nop 0
	global_load_lds_dwordx4 v172, s[28:29]
	s_add_i32 m0, s46, 0x2000
	s_nop 0
	global_load_lds_dwordx4 v168, s[28:29]
	s_waitcnt vmcnt(6)
	s_barrier
	s_setprio 1
	v_mfma_f32_16x16x32_bf16 v[56:59], v[214:217], v[96:99], v[56:59]
	v_mfma_f32_16x16x32_bf16 v[52:55], v[222:225], v[96:99], v[52:55]
	v_mfma_f32_16x16x32_bf16 v[44:47], v[214:217], v[108:111], v[44:47]
	v_mfma_f32_16x16x32_bf16 v[36:39], v[222:225], v[108:111], v[36:39]
	v_mfma_f32_16x16x32_bf16 v[28:31], v[214:217], v[160:163], v[28:31]
	v_mfma_f32_16x16x32_bf16 v[20:23], v[222:225], v[160:163], v[20:23]
	v_mfma_f32_16x16x32_bf16 v[4:7], v[214:217], v[198:201], v[4:7]
	v_mfma_f32_16x16x32_bf16 v[0:3], v[222:225], v[198:201], v[0:3]
	v_mfma_f32_16x16x32_bf16 v[56:59], v[218:221], v[100:103], v[56:59]
	v_mfma_f32_16x16x32_bf16 v[52:55], v[230:233], v[100:103], v[52:55]
	v_mfma_f32_16x16x32_bf16 v[44:47], v[218:221], v[112:115], v[44:47]
	v_mfma_f32_16x16x32_bf16 v[36:39], v[230:233], v[112:115], v[36:39]
	v_mfma_f32_16x16x32_bf16 v[28:31], v[218:221], v[164:167], v[28:31]
	v_mfma_f32_16x16x32_bf16 v[20:23], v[230:233], v[164:167], v[20:23]
	v_mfma_f32_16x16x32_bf16 v[4:7], v[218:221], v[202:205], v[4:7]
	v_mfma_f32_16x16x32_bf16 v[0:3], v[230:233], v[202:205], v[0:3]
	s_setprio 0
	s_add_i32 vcc_hi, vcc_hi, 2
	s_add_u32 s59, s59, 0x100
	s_addc_u32 vcc_lo, vcc_lo, 0
	s_add_u32 s44, s44, 0x100
	s_addc_u32 s45, s45, 0
	s_cmp_gt_u32 vcc_hi, 29
	s_barrier
	s_cbranch_scc0 .LBB1_380
; DI float silu_mul(float g, float v) { return g * v * __builtin_amdgcn_rcpf(1.0f + __builtin_amdgcn_exp2f(-LOG2E * g)); }
;     DI void operator()(const f32x4 (&acc)[2][2][4][2], const Unit& u, int wr, int wc, int fr, int fq) const {
;         const int row0 = u.pm * BM + wr * 64 + fr, ch0 = u.pn * 128 + wc * 32 + 8 * fq;
;         f32x4 w0[2], w1[2], w2[2], bb[2];
; #pragma unroll
;         for (int n = 0; n < 2; ++n) { w0[n] = *(const f32x4*)(cw + ch0 + 4 * n); w1[n] = *(const f32x4*)(cw + DFF + ch0 + 4 * n); w2[n] = *(const f32x4*)(cw + 2 * DFF + ch0 + 4 * n); bb[n] = *(const f32x4*)(cb + ch0 + 4 * n); }
; #pragma unroll
;         for (int ai = 0; ai < 2; ++ai)
; #pragma unroll
;             for (int m = 0; m < 4; ++m) {
;                 const bool efirst = (m == 0) && (fr == 0), elast = (m == 3) && (fr == 15);
;                 const int row = row0 + ai * HALF + m * 16;
;                 f32x4 gc[2];
; #pragma unroll
;                 for (int n = 0; n < 2; ++n) {
;                     const f32x4 g = acc[ai][0][m][n];
;                     const f32x4 gprev = acc[ai][0][m > 0 ? m - 1 : 0][n], gnext = acc[ai][0][m < 3 ? m + 1 : 3][n];
;                     f32x4 up, dn;
; #pragma unroll
;                     for (int e = 0; e < 4; ++e) {
;                         const float pu = (m > 0 && fr == 15) ? gprev[e] : g[e];
;                         const float pd = (m < 3 && fr == 0) ? gnext[e] : g[e];
;                         up[e] = dpp_ror1(pu); dn[e] = dpp_ror15(pd);
;                     }
;                     if (efirst) up = (f32x4){0.f, 0.f, 0.f, 0.f};
;                     if (elast) dn = (f32x4){0.f, 0.f, 0.f, 0.f};
;                     gc[n] = w0[n] * up + w1[n] * g + w2[n] * dn + bb[n];
;                 }
;                 if (efirst || elast) {
;                     const size_t eo = (size_t)((row >> 6) * 2 + (elast ? 1 : 0)) * DFF + ch0;
; #pragma unroll
;                     for (int n = 0; n < 2; ++n) { *(f32x4*)(EP + eo + 4 * n) = gc[n]; *(f32x4*)(ER + eo + 4 * n) = acc[ai][0][m][n]; *(f32x4*)(EV + eo + 4 * n) = acc[ai][1][m][n]; }
;                 } else {
;                     const f32x4 v0 = acc[ai][1][m][0], v1 = acc[ai][1][m][1];
;                     u32x4 o;
;                     o[0] = pack2(silu_mul(gc[0][0], v0[0]), silu_mul(gc[0][1], v0[1])); o[1] = pack2(silu_mul(gc[0][2], v0[2]), silu_mul(gc[0][3], v0[3]));
	s_lshl_b32 s23, s43, 7
	v_mov_b32_e32 v194, v186
	v_mov_b32_e32 v80, v187
	s_or_b32 s23, s23, s67
	v_mov_b32_e32 v160, 0
	v_lshl_add_u32 v184, v80, 3, s23
	v_ashrrev_i32_e32 v185, 31, v184
	v_lshlrev_b64 v[80:81], 2, v[184:185]
	v_lshl_add_u64 v[84:85], s[52:53], 0, v[80:81]
	v_lshl_add_u64 v[88:89], s[16:17], 0, v[80:81]
	v_lshl_add_u64 v[92:93], s[18:19], 0, v[80:81]
	v_lshl_add_u64 v[112:113], s[54:55], 0, v[80:81]
	global_load_dwordx4 v[80:83], v[84:85], off offset:16
	global_load_dwordx4 v[96:99], v[84:85], off
	s_nop 0
	global_load_dwordx4 v[84:87], v[88:89], off offset:16
	global_load_dwordx4 v[100:103], v[88:89], off
	s_nop 0
	global_load_dwordx4 v[88:91], v[92:93], off offset:16
	global_load_dwordx4 v[108:111], v[92:93], off
	s_nop 0
	global_load_dwordx4 v[92:95], v[112:113], off offset:16
	s_nop 0
	global_load_dwordx4 v[112:115], v[112:113], off
	v_cmp_eq_u32_e32 vcc, 0, v194
	v_mov_b32_e32 v164, 0
	v_mov_b32_e32 v195, 0
	v_cndmask_b32_e32 v161, v148, v136, vcc
	v_cndmask_b32_e32 v162, v149, v137, vcc
	v_cndmask_b32_e32 v163, v150, v138, vcc
	v_mov_b32_dpp v160, v161 row_ror:15 row_mask:0xf bank_mask:0xf
	v_mov_b32_e32 v161, 0
	v_mov_b32_e32 v166, 0
	v_mov_b32_e32 v167, 0
	v_mov_b32_dpp v161, v162 row_ror:15 row_mask:0xf bank_mask:0xf
	v_mov_b32_e32 v162, 0
	v_mov_b32_dpp v164, v150 row_ror:1 row_mask:0xf bank_mask:0xf
	v_cndmask_b32_e32 v165, v151, v139, vcc
	v_mov_b32_dpp v162, v163 row_ror:15 row_mask:0xf bank_mask:0xf
	v_mov_b32_dpp v195, v151 row_ror:1 row_mask:0xf bank_mask:0xf
	v_mov_b32_e32 v163, 0
	v_mov_b32_dpp v166, v148 row_ror:1 row_mask:0xf bank_mask:0xf
	v_mov_b32_dpp v167, v149 row_ror:1 row_mask:0xf bank_mask:0xf
	v_mov_b32_dpp v163, v165 row_ror:15 row_mask:0xf bank_mask:0xf
	v_cndmask_b32_e64 v165, v195, 0, vcc
	v_cndmask_b32_e64 v164, v164, 0, vcc
	v_cndmask_b32_e64 v167, v167, 0, vcc
	v_cndmask_b32_e64 v166, v166, 0, vcc
	v_mov_b32_e32 v195, 0
	v_mov_b32_e32 v196, 0
	v_mov_b32_e32 v198, 0
	v_mov_b32_e32 v200, 0
	v_mov_b32_dpp v195, v144 row_ror:1 row_mask:0xf bank_mask:0xf
	v_mov_b32_dpp v196, v145 row_ror:1 row_mask:0xf bank_mask:0xf
	v_mov_b32_dpp v198, v146 row_ror:1 row_mask:0xf bank_mask:0xf
	v_cndmask_b32_e32 v199, v147, v131, vcc
	v_mov_b32_dpp v200, v147 row_ror:1 row_mask:0xf bank_mask:0xf
	v_cndmask_b32_e64 v198, v198, 0, vcc
	v_cndmask_b32_e64 v201, v196, 0, vcc
	s_lshl_b32 s21, s42, 8
	s_add_i32 s21, s21, s49
	v_add_u32_e32 v193, s21, v194
	v_cmp_ne_u32_e64 s[46:47], 0, v194
	s_waitcnt vmcnt(0)
	v_pk_mul_f32 v[164:165], v[98:99], v[164:165]
	v_pk_mul_f32 v[166:167], v[96:97], v[166:167]
	v_pk_fma_f32 v[164:165], v[150:151], v[102:103], v[164:165]
	v_pk_fma_f32 v[166:167], v[148:149], v[100:101], v[166:167]
	v_pk_fma_f32 v[162:163], v[110:111], v[162:163], v[164:165]
	v_cndmask_b32_e32 v165, v144, v128, vcc
	v_mov_b32_e32 v164, 0
	v_pk_fma_f32 v[160:161], v[108:109], v[160:161], v[166:167]
	v_cndmask_b32_e32 v166, v145, v129, vcc
	v_mov_b32_dpp v164, v165 row_ror:15 row_mask:0xf bank_mask:0xf
	v_mov_b32_e32 v165, 0
	v_cndmask_b32_e32 v167, v146, v130, vcc
	v_pk_add_f32 v[162:163], v[114:115], v[162:163]
	v_mov_b32_dpp v165, v166 row_ror:15 row_mask:0xf bank_mask:0xf
	v_mov_b32_e32 v166, 0
	v_pk_add_f32 v[160:161], v[112:113], v[160:161]
	s_nop 0
	v_mov_b32_dpp v166, v167 row_ror:15 row_mask:0xf bank_mask:0xf
	v_mov_b32_e32 v167, 0
	s_nop 1
	v_mov_b32_dpp v167, v199 row_ror:15 row_mask:0xf bank_mask:0xf
	v_cndmask_b32_e64 v199, v200, 0, vcc
	v_cndmask_b32_e64 v200, v195, 0, vcc
	v_pk_mul_f32 v[200:201], v[80:81], v[200:201]
	v_pk_mul_f32 v[198:199], v[82:83], v[198:199]
	v_pk_fma_f32 v[200:201], v[144:145], v[84:85], v[200:201]
	v_pk_fma_f32 v[198:199], v[146:147], v[86:87], v[198:199]
	v_pk_fma_f32 v[164:165], v[88:89], v[164:165], v[200:201]
	v_pk_fma_f32 v[166:167], v[90:91], v[166:167], v[198:199]
	v_pk_add_f32 v[164:165], v[92:93], v[164:165]
	v_pk_add_f32 v[166:167], v[94:95], v[166:167]
	s_and_saveexec_b64 s[28:29], s[46:47]
	s_xor_b64 s[28:29], exec, s[28:29]
	s_cbranch_execz .LBB1_383
	v_mul_f32_e32 v195, 0xbfb8aa3b, v160
	v_exp_f32_e32 v195, v195
	v_mul_f32_e32 v196, 0xbfb8aa3b, v161
	v_exp_f32_e32 v196, v196
	v_pk_mul_f32 v[160:161], v[156:157], v[160:161]
	v_add_f32_e32 v195, 1.0, v195
	v_rcp_f32_e32 v198, v195
	v_add_f32_e32 v196, 1.0, v196
	v_mul_f32_e32 v195, 0xbfb8aa3b, v162
	v_rcp_f32_e32 v199, v196
	v_exp_f32_e32 v195, v195
	v_mul_f32_e32 v196, 0xbfb8aa3b, v163
	v_exp_f32_e32 v196, v196
	v_pk_mul_f32 v[160:161], v[160:161], v[198:199]
	v_add_f32_e32 v195, 1.0, v195
	v_rcp_f32_e32 v200, v195
	v_add_f32_e32 v195, 1.0, v196
	v_rcp_f32_e32 v201, v195
	v_cvt_pk_bf16_f32 v160, v160, v161
	v_mul_f32_e32 v161, 0xbfb8aa3b, v164
	v_exp_f32_e32 v195, v161
	v_mul_f32_e32 v161, 0xbfb8aa3b, v165
	v_exp_f32_e32 v196, v161
	v_pk_mul_f32 v[162:163], v[158:159], v[162:163]
	v_pk_mul_f32 v[164:165], v[152:153], v[164:165]
	v_pk_mul_f32 v[162:163], v[162:163], v[200:201]
	s_nop 0
	v_cvt_pk_bf16_f32 v161, v162, v163
	v_add_f32_e32 v162, 1.0, v195
	v_mul_f32_e32 v195, 0xbfb8aa3b, v166
	v_add_f32_e32 v163, 1.0, v196
	v_exp_f32_e32 v195, v195
	v_mul_f32_e32 v196, 0xbfb8aa3b, v167
	v_exp_f32_e32 v196, v196
	v_rcp_f32_e32 v162, v162
	v_add_f32_e32 v195, 1.0, v195
	v_rcp_f32_e32 v198, v195
	v_add_f32_e32 v195, 1.0, v196
	v_rcp_f32_e32 v163, v163
	v_rcp_f32_e32 v199, v195
	v_pk_mul_f32 v[166:167], v[154:155], v[166:167]
	v_pk_mul_f32 v[162:163], v[164:165], v[162:163]
	v_pk_mul_f32 v[164:165], v[166:167], v[198:199]
	v_cvt_pk_bf16_f32 v162, v162, v163
	v_cvt_pk_bf16_f32 v163, v164, v165
	v_mov_b64_e32 v[164:165], s[6:7]
	v_mad_i64_i32 v[164:165], s[42:43], v193, s30, v[164:165]
	v_lshl_add_u64 v[164:165], v[184:185], 1, v[164:165]
	global_store_dwordx4 v[164:165], v[160:163], off

; #define PG8_STAGE(bufoff, gbase, voff) do { _Pragma("unroll") for (int _i = 0; _i < 2; ++_i) \
;         __builtin_amdgcn_global_load_lds((const unsigned*)((const char*)(gbase) + (voff)[_i]), (LAS unsigned*)(lds + (bufoff) + ldsw + _i * 8192), 16, 0, 0); } while (0)
; #define PG8_LDA(dst, b, h) do { _Pragma("unroll") for (int m = 0; m < 4; ++m) _Pragma("unroll") for (int k = 0; k < 2; ++k) dst[m][k] = *(const LAS bf16x8*)(lds + PG8_SA(b, h) + aoff + m * 2048 + k * 1024); } while (0)
; #define PG8_LDB(dst, b, h) do { _Pragma("unroll") for (int n = 0; n < 2; ++n) _Pragma("unroll") for (int k = 0; k < 2; ++k) dst[n][k] = *(const LAS bf16x8*)(lds + PG8_SB(b, h) + boff + n * 2048 + k * 1024); } while (0)
; #define PG8_MMA(ai, bj, At, Bt) do { __builtin_amdgcn_s_setprio(1); _Pragma("unroll") for (int m = 0; m < 4; ++m) _Pragma("unroll") for (int n = 0; n < 2; ++n) _Pragma("unroll") for (int k = 0; k < 2; ++k) \
;         acc[ai][bj][m][n] = __builtin_amdgcn_mfma_f32_16x16x32_bf16(Bt[n][k], At[m][k], acc[ai][bj][m][n], 0, 0, 0); __builtin_amdgcn_s_setprio(0); } while (0)
; #define PG8_WAIT_V(n) asm volatile("s_waitcnt vmcnt(" #n ")" ::: "memory")
; #define PG8_WAIT_L(n) asm volatile("s_waitcnt lgkmcnt(" #n ")" ::: "memory")
; #define PG8_BAR __builtin_amdgcn_s_barrier()
; #define PG8_SCHED __builtin_amdgcn_sched_barrier(0)
; template <class Map, class Epi>
; DI void gemm_phase(LAS unsigned char* lds, const Map& MP, const Epi& E, const int nM, const int nN, const int K, const int lda, const int ldb) {
;     ...
;             PG8_LDB(B0, 0, 0); PG8_SCHED; PG8_LDA(At, 0, 0); PG8_STAGE(PG8_SA(1, 1), a1 + hstepA, voffA);
;             PG8_WAIT_L(8); PG8_BAR; PG8_WAIT_L(0); PG8_MMA(0, 0, At, B0); PG8_BAR; PG8_SCHED;
;             PG8_LDB(B1, 0, 1); PG8_STAGE(PG8_SB(0, 0), b2, voffB);
;             PG8_BAR; PG8_WAIT_L(0); PG8_MMA(0, 1, At, B1); PG8_BAR;
;             PG8_LDA(At, 0, 1); PG8_STAGE(PG8_SA(0, 0), a2, voffA);
;             PG8_BAR; PG8_WAIT_L(0); PG8_MMA(1, 0, At, B0); PG8_BAR; PG8_SCHED;
;             PG8_STAGE(PG8_SB(0, 1), b2 + hstepB, voffB);
;             PG8_WAIT_V(6); PG8_BAR; PG8_MMA(1, 1, At, B1); PG8_BAR;
.LBB1_550:
	ds_read_b128 v[152:155], v149
	ds_read_b128 v[156:159], v149 offset:1024
	ds_read_b128 v[160:163], v149 offset:2048
	ds_read_b128 v[164:167], v149 offset:3072
	s_add_u32 s10, s8, 0x100
	s_addc_u32 s11, s9, 0
	s_cmpk_eq_i32 s3, 0x54
	s_cselect_b32 s15, s43, s11
	s_cselect_b32 s14, s42, s10
	s_cselect_b32 s13, s7, s38
	s_cselect_b32 s12, s6, s5
	s_add_i32 m0, s24, 0xc000
	ds_read_b128 v[168:171], v150
	ds_read_b128 v[172:175], v150 offset:1024
	ds_read_b128 v[176:179], v150 offset:2048
	ds_read_b128 v[180:183], v150 offset:3072
	ds_read_b128 v[184:187], v150 offset:4096
	ds_read_b128 v[188:191], v150 offset:5120
	ds_read_b128 v[192:195], v150 offset:6144
	ds_read_b128 v[198:201], v150 offset:7168
	global_load_lds_dwordx4 v138, s[8:9]
	s_add_i32 m0, s24, 0xe000
	s_nop 0
	global_load_lds_dwordx4 v136, s[8:9]
	s_waitcnt lgkmcnt(8)
	s_barrier
	s_setprio 1
	s_waitcnt lgkmcnt(7)
	v_mfma_f32_16x16x32_bf16 v[124:127], v[152:155], v[168:171], v[124:127]
	v_mfma_f32_16x16x32_bf16 v[120:123], v[160:163], v[168:171], v[120:123]
	s_waitcnt lgkmcnt(5)
	v_mfma_f32_16x16x32_bf16 v[108:111], v[152:155], v[176:179], v[108:111]
	v_mfma_f32_16x16x32_bf16 v[104:107], v[160:163], v[176:179], v[104:107]
	s_waitcnt lgkmcnt(3)
	v_mfma_f32_16x16x32_bf16 v[92:95], v[152:155], v[184:187], v[92:95]
	v_mfma_f32_16x16x32_bf16 v[88:91], v[160:163], v[184:187], v[88:91]
	s_waitcnt lgkmcnt(1)
	v_mfma_f32_16x16x32_bf16 v[76:79], v[152:155], v[192:195], v[76:79]
	v_mfma_f32_16x16x32_bf16 v[72:75], v[160:163], v[192:195], v[72:75]
	v_mfma_f32_16x16x32_bf16 v[124:127], v[156:159], v[172:175], v[124:127]
	v_mfma_f32_16x16x32_bf16 v[120:123], v[164:167], v[172:175], v[120:123]
	v_mfma_f32_16x16x32_bf16 v[108:111], v[156:159], v[180:183], v[108:111]
	v_mfma_f32_16x16x32_bf16 v[104:107], v[164:167], v[180:183], v[104:107]
	v_mfma_f32_16x16x32_bf16 v[92:95], v[156:159], v[188:191], v[92:95]
	v_mfma_f32_16x16x32_bf16 v[88:91], v[164:167], v[188:191], v[88:91]
	s_waitcnt lgkmcnt(0)
	v_mfma_f32_16x16x32_bf16 v[76:79], v[156:159], v[198:201], v[76:79]
	v_mfma_f32_16x16x32_bf16 v[72:75], v[164:167], v[198:201], v[72:75]
	s_setprio 0
	s_barrier
	s_add_i32 s8, s35, s22
	v_lshl_add_u64 v[144:145], s[12:13], 0, v[132:133]
	s_mov_b32 m0, s8
	ds_read_b128 v[202:205], v151
	ds_read_b128 v[206:209], v151 offset:1024
	ds_read_b128 v[210:213], v151 offset:2048
	ds_read_b128 v[214:217], v151 offset:3072
	global_load_lds_dwordx4 v[144:145], off
	v_lshl_add_u64 v[218:219], s[12:13], 0, v[128:129]
	s_add_i32 m0, s8, 0x2000
	s_nop 0
	global_load_lds_dwordx4 v[218:219], off
	s_barrier
	s_setprio 1
	s_waitcnt lgkmcnt(3)
	v_mfma_f32_16x16x32_bf16 v[116:119], v[202:205], v[168:171], v[116:119]
	s_waitcnt lgkmcnt(1)
	v_mfma_f32_16x16x32_bf16 v[112:115], v[210:213], v[168:171], v[112:115]
	v_mfma_f32_16x16x32_bf16 v[100:103], v[202:205], v[176:179], v[100:103]
	v_mfma_f32_16x16x32_bf16 v[96:99], v[210:213], v[176:179], v[96:99]
	v_mfma_f32_16x16x32_bf16 v[84:87], v[202:205], v[184:187], v[84:87]
	v_mfma_f32_16x16x32_bf16 v[80:83], v[210:213], v[184:187], v[80:83]
	v_mfma_f32_16x16x32_bf16 v[68:71], v[202:205], v[192:195], v[68:71]
	v_mfma_f32_16x16x32_bf16 v[64:67], v[210:213], v[192:195], v[64:67]
	v_mfma_f32_16x16x32_bf16 v[116:119], v[206:209], v[172:175], v[116:119]
	s_waitcnt lgkmcnt(0)
	v_mfma_f32_16x16x32_bf16 v[112:115], v[214:217], v[172:175], v[112:115]
	v_mfma_f32_16x16x32_bf16 v[100:103], v[206:209], v[180:183], v[100:103]
	v_mfma_f32_16x16x32_bf16 v[96:99], v[214:217], v[180:183], v[96:99]
	v_mfma_f32_16x16x32_bf16 v[84:87], v[206:209], v[188:191], v[84:87]
	v_mfma_f32_16x16x32_bf16 v[80:83], v[214:217], v[188:191], v[80:83]
	v_mfma_f32_16x16x32_bf16 v[68:71], v[206:209], v[198:201], v[68:71]
	v_mfma_f32_16x16x32_bf16 v[64:67], v[214:217], v[198:201], v[64:67]
	s_setprio 0
	s_mov_b32 m0, s24
	v_lshl_add_u64 v[220:221], s[14:15], 0, v[134:135]
	s_barrier
	ds_read_b128 v[168:171], v150 offset:16384
	ds_read_b128 v[172:175], v150 offset:17408
	ds_read_b128 v[176:179], v150 offset:18432
	ds_read_b128 v[180:183], v150 offset:19456
	ds_read_b128 v[184:187], v150 offset:20480
	ds_read_b128 v[188:191], v150 offset:21504
	ds_read_b128 v[192:195], v150 offset:22528
	ds_read_b128 v[198:201], v150 offset:23552
	global_load_lds_dwordx4 v[220:221], off
	v_lshl_add_u64 v[222:223], s[14:15], 0, v[130:131]
	s_mov_b32 m0, s25
	s_nop 0
	global_load_lds_dwordx4 v[222:223], off
	s_barrier
	s_setprio 1
	s_waitcnt lgkmcnt(7)
	v_mfma_f32_16x16x32_bf16 v[60:63], v[152:155], v[168:171], v[60:63]
	v_mfma_f32_16x16x32_bf16 v[56:59], v[160:163], v[168:171], v[56:59]
	s_waitcnt lgkmcnt(5)
	v_mfma_f32_16x16x32_bf16 v[44:47], v[152:155], v[176:179], v[44:47]
	v_mfma_f32_16x16x32_bf16 v[40:43], v[160:163], v[176:179], v[40:43]
	s_waitcnt lgkmcnt(3)
	v_mfma_f32_16x16x32_bf16 v[28:31], v[152:155], v[184:187], v[28:31]
	v_mfma_f32_16x16x32_bf16 v[24:27], v[160:163], v[184:187], v[24:27]
	s_waitcnt lgkmcnt(1)
	v_mfma_f32_16x16x32_bf16 v[12:15], v[152:155], v[192:195], v[12:15]
	v_mfma_f32_16x16x32_bf16 v[8:11], v[160:163], v[192:195], v[8:11]
	v_mfma_f32_16x16x32_bf16 v[60:63], v[156:159], v[172:175], v[60:63]
	v_mfma_f32_16x16x32_bf16 v[56:59], v[164:167], v[172:175], v[56:59]
	v_mfma_f32_16x16x32_bf16 v[44:47], v[156:159], v[180:183], v[44:47]
	v_mfma_f32_16x16x32_bf16 v[40:43], v[164:167], v[180:183], v[40:43]
	v_mfma_f32_16x16x32_bf16 v[28:31], v[156:159], v[188:191], v[28:31]
	v_mfma_f32_16x16x32_bf16 v[24:27], v[164:167], v[188:191], v[24:27]
	s_waitcnt lgkmcnt(0)
	v_mfma_f32_16x16x32_bf16 v[12:15], v[156:159], v[198:201], v[12:15]
	v_mfma_f32_16x16x32_bf16 v[8:11], v[164:167], v[198:201], v[8:11]
	s_setprio 0
	s_barrier
; #define PG8_STAGE(bufoff, gbase, voff) do { _Pragma("unroll") for (int _i = 0; _i < 2; ++_i) \
;         __builtin_amdgcn_global_load_lds((const unsigned*)((const char*)(gbase) + (voff)[_i]), (LAS unsigned*)(lds + (bufoff) + ldsw + _i * 8192), 16, 0, 0); } while (0)
; #define PG8_LDA(dst, b, h) do { _Pragma("unroll") for (int m = 0; m < 4; ++m) _Pragma("unroll") for (int k = 0; k < 2; ++k) dst[m][k] = *(const LAS bf16x8*)(lds + PG8_SA(b, h) + aoff + m * 2048 + k * 1024); } while (0)
; #define PG8_LDB(dst, b, h) do { _Pragma("unroll") for (int n = 0; n < 2; ++n) _Pragma("unroll") for (int k = 0; k < 2; ++k) dst[n][k] = *(const LAS bf16x8*)(lds + PG8_SB(b, h) + boff + n * 2048 + k * 1024); } while (0)
; #define PG8_MMA(ai, bj, At, Bt) do { __builtin_amdgcn_s_setprio(1); _Pragma("unroll") for (int m = 0; m < 4; ++m) _Pragma("unroll") for (int n = 0; n < 2; ++n) _Pragma("unroll") for (int k = 0; k < 2; ++k) \
;         acc[ai][bj][m][n] = __builtin_amdgcn_mfma_f32_16x16x32_bf16(Bt[n][k], At[m][k], acc[ai][bj][m][n], 0, 0, 0); __builtin_amdgcn_s_setprio(0); } while (0)
; #define PG8_WAIT_V(n) asm volatile("s_waitcnt vmcnt(" #n ")" ::: "memory")
; #define PG8_WAIT_L(n) asm volatile("s_waitcnt lgkmcnt(" #n ")" ::: "memory")
; #define PG8_BAR __builtin_amdgcn_s_barrier()
; #define PG8_SCHED __builtin_amdgcn_sched_barrier(0)
; template <class Map, class Epi>
; DI void gemm_phase(LAS unsigned char* lds, const Map& MP, const Epi& E, const int nM, const int nN, const int K, const int lda, const int ldb) {
;     ...
;             PG8_STAGE(PG8_SB(0, 1), b2 + hstepB, voffB);
;             PG8_WAIT_V(6); PG8_BAR; PG8_MMA(1, 1, At, B1); PG8_BAR;
;             PG8_LDB(B0, 1, 0); PG8_SCHED; PG8_LDA(At, 1, 0); PG8_STAGE(PG8_SA(0, 1), a2 + hstepA, voffA);
;             PG8_WAIT_L(8); PG8_BAR; PG8_WAIT_L(0); PG8_MMA(0, 0, At, B0); PG8_BAR; PG8_SCHED;
;             PG8_LDB(B1, 1, 1); PG8_STAGE(PG8_SB(1, 0), b3, voffB);
;             PG8_BAR; PG8_WAIT_L(0); PG8_MMA(0, 1, At, B1); PG8_BAR;
;             PG8_LDA(At, 1, 1); PG8_STAGE(PG8_SA(1, 0), a3, voffA);
	s_add_u32 s8, s12, 0x160000
	s_addc_u32 s9, s13, 0
	s_add_i32 s39, s36, s22
	s_mov_b32 m0, s39
	s_nop 0
	global_load_lds_dwordx4 v132, s[8:9]
	s_add_i32 m0, s39, 0x2000
	s_nop 0
	global_load_lds_dwordx4 v128, s[8:9]
	s_waitcnt vmcnt(6)
	s_barrier
	s_setprio 1
	v_mfma_f32_16x16x32_bf16 v[52:55], v[202:205], v[168:171], v[52:55]
	v_mfma_f32_16x16x32_bf16 v[48:51], v[210:213], v[168:171], v[48:51]
	v_mfma_f32_16x16x32_bf16 v[36:39], v[202:205], v[176:179], v[36:39]
	v_mfma_f32_16x16x32_bf16 v[32:35], v[210:213], v[176:179], v[32:35]
	v_mfma_f32_16x16x32_bf16 v[20:23], v[202:205], v[184:187], v[20:23]
	v_mfma_f32_16x16x32_bf16 v[16:19], v[210:213], v[184:187], v[16:19]
	v_mfma_f32_16x16x32_bf16 v[4:7], v[202:205], v[192:195], v[4:7]
	v_mfma_f32_16x16x32_bf16 v[0:3], v[210:213], v[192:195], v[0:3]
	v_mfma_f32_16x16x32_bf16 v[52:55], v[206:209], v[172:175], v[52:55]
	v_mfma_f32_16x16x32_bf16 v[48:51], v[214:217], v[172:175], v[48:51]
	v_mfma_f32_16x16x32_bf16 v[36:39], v[206:209], v[180:183], v[36:39]
	v_mfma_f32_16x16x32_bf16 v[32:35], v[214:217], v[180:183], v[32:35]
	v_mfma_f32_16x16x32_bf16 v[20:23], v[206:209], v[188:191], v[20:23]
	v_mfma_f32_16x16x32_bf16 v[16:19], v[214:217], v[188:191], v[16:19]
	v_mfma_f32_16x16x32_bf16 v[4:7], v[206:209], v[198:201], v[4:7]
	v_mfma_f32_16x16x32_bf16 v[0:3], v[214:217], v[198:201], v[0:3]
	s_setprio 0
	s_add_i32 s39, 0, 0x18000
	v_add_u32_e32 v164, s39, v148
	s_barrier
	ds_read_b128 v[152:155], v164
	ds_read_b128 v[156:159], v164 offset:1024
	ds_read_b128 v[160:163], v164 offset:2048
	ds_read_b128 v[164:167], v164 offset:3072
	s_add_u32 s8, s14, 0x160000
	s_addc_u32 s9, s15, 0
	s_mov_b32 m0, s26
	ds_read_b128 v[168:171], v150 offset:32768
	ds_read_b128 v[172:175], v150 offset:33792
	ds_read_b128 v[176:179], v150 offset:34816
	ds_read_b128 v[180:183], v150 offset:35840
	ds_read_b128 v[184:187], v150 offset:36864
	ds_read_b128 v[188:191], v150 offset:37888
	ds_read_b128 v[192:195], v150 offset:38912
	ds_read_b128 v[198:201], v150 offset:39936
	global_load_lds_dwordx4 v134, s[8:9]
	s_mov_b32 m0, s27
	s_nop 0
	global_load_lds_dwordx4 v130, s[8:9]
	s_waitcnt lgkmcnt(8)
	s_barrier
	s_setprio 1
	s_waitcnt lgkmcnt(7)
	v_mfma_f32_16x16x32_bf16 v[124:127], v[152:155], v[168:171], v[124:127]
	v_mfma_f32_16x16x32_bf16 v[120:123], v[160:163], v[168:171], v[120:123]
	s_waitcnt lgkmcnt(5)
	v_mfma_f32_16x16x32_bf16 v[108:111], v[152:155], v[176:179], v[108:111]
	v_mfma_f32_16x16x32_bf16 v[104:107], v[160:163], v[176:179], v[104:107]
	s_waitcnt lgkmcnt(3)
	v_mfma_f32_16x16x32_bf16 v[92:95], v[152:155], v[184:187], v[92:95]
	v_mfma_f32_16x16x32_bf16 v[88:91], v[160:163], v[184:187], v[88:91]
	s_waitcnt lgkmcnt(1)
	v_mfma_f32_16x16x32_bf16 v[76:79], v[152:155], v[192:195], v[76:79]
	v_mfma_f32_16x16x32_bf16 v[72:75], v[160:163], v[192:195], v[72:75]
	v_mfma_f32_16x16x32_bf16 v[124:127], v[156:159], v[172:175], v[124:127]
	v_mfma_f32_16x16x32_bf16 v[120:123], v[164:167], v[172:175], v[120:123]
	v_mfma_f32_16x16x32_bf16 v[108:111], v[156:159], v[180:183], v[108:111]
	v_mfma_f32_16x16x32_bf16 v[104:107], v[164:167], v[180:183], v[104:107]
	v_mfma_f32_16x16x32_bf16 v[92:95], v[156:159], v[188:191], v[92:95]
	v_mfma_f32_16x16x32_bf16 v[88:91], v[164:167], v[188:191], v[88:91]
	s_waitcnt lgkmcnt(0)
	v_mfma_f32_16x16x32_bf16 v[76:79], v[156:159], v[198:201], v[76:79]
	v_mfma_f32_16x16x32_bf16 v[72:75], v[164:167], v[198:201], v[72:75]
	s_setprio 0
	s_barrier
	s_add_i32 s14, 0, 0x1c000
	s_add_i32 s8, s39, s22
	v_add_u32_e32 v196, s14, v148
	v_lshl_add_u64 v[144:145], v[144:145], 0, s[52:53]
	s_mov_b32 m0, s8
	ds_read_b128 v[202:205], v196
	ds_read_b128 v[206:209], v196 offset:1024
	ds_read_b128 v[210:213], v196 offset:2048
	ds_read_b128 v[214:217], v196 offset:3072
	global_load_lds_dwordx4 v[144:145], off
	v_lshl_add_u64 v[144:145], v[218:219], 0, s[52:53]
	s_add_i32 m0, s8, 0x2000
	s_nop 0
	global_load_lds_dwordx4 v[144:145], off
	s_barrier
	s_setprio 1
	s_waitcnt lgkmcnt(3)
	v_mfma_f32_16x16x32_bf16 v[116:119], v[202:205], v[168:171], v[116:119]
	s_waitcnt lgkmcnt(1)
	v_mfma_f32_16x16x32_bf16 v[112:115], v[210:213], v[168:171], v[112:115]
	v_mfma_f32_16x16x32_bf16 v[100:103], v[202:205], v[176:179], v[100:103]
	v_mfma_f32_16x16x32_bf16 v[96:99], v[210:213], v[176:179], v[96:99]
	v_mfma_f32_16x16x32_bf16 v[84:87], v[202:205], v[184:187], v[84:87]
	v_mfma_f32_16x16x32_bf16 v[80:83], v[210:213], v[184:187], v[80:83]
	v_mfma_f32_16x16x32_bf16 v[68:71], v[202:205], v[192:195], v[68:71]
	v_mfma_f32_16x16x32_bf16 v[64:67], v[210:213], v[192:195], v[64:67]
	v_mfma_f32_16x16x32_bf16 v[116:119], v[206:209], v[172:175], v[116:119]
	s_waitcnt lgkmcnt(0)
	v_mfma_f32_16x16x32_bf16 v[112:115], v[214:217], v[172:175], v[112:115]
	v_mfma_f32_16x16x32_bf16 v[100:103], v[206:209], v[180:183], v[100:103]
	v_mfma_f32_16x16x32_bf16 v[96:99], v[214:217], v[180:183], v[96:99]
	v_mfma_f32_16x16x32_bf16 v[84:87], v[206:209], v[188:191], v[84:87]
	v_mfma_f32_16x16x32_bf16 v[80:83], v[214:217], v[188:191], v[80:83]
	v_mfma_f32_16x16x32_bf16 v[68:71], v[206:209], v[198:201], v[68:71]
	v_mfma_f32_16x16x32_bf16 v[64:67], v[214:217], v[198:201], v[64:67]
	s_setprio 0
	s_mov_b32 m0, s30
	v_lshl_add_u64 v[144:145], v[220:221], 0, s[52:53]
	s_barrier
	ds_read_b128 v[168:171], v150 offset:49152
	ds_read_b128 v[172:175], v150 offset:50176
	ds_read_b128 v[176:179], v150 offset:51200
	ds_read_b128 v[180:183], v150 offset:52224
	ds_read_b128 v[184:187], v150 offset:53248
	ds_read_b128 v[188:191], v150 offset:54272
	ds_read_b128 v[192:195], v150 offset:55296
	ds_read_b128 v[198:201], v150 offset:56320
	global_load_lds_dwordx4 v[144:145], off
	v_lshl_add_u64 v[144:145], v[222:223], 0, s[52:53]
	s_mov_b32 m0, s31
	s_nop 0
	global_load_lds_dwordx4 v[144:145], off
	s_barrier
; DI unsigned pack2(float a, float b) { f32x2 v = {a, b}; hwbf16x2 r = __builtin_convertvector(v, hwbf16x2); return __builtin_bit_cast(unsigned, r); }
; DI float bflo(unsigned w) { return __uint_as_float(w << 16); }
; DI float bfhi(unsigned w) { return __uint_as_float(w & 0xffff0000u); }
; #define PG8_STAGE(bufoff, gbase, voff) do { _Pragma("unroll") for (int _i = 0; _i < 2; ++_i) \
;         __builtin_amdgcn_global_load_lds((const unsigned*)((const char*)(gbase) + (voff)[_i]), (LAS unsigned*)(lds + (bufoff) + ldsw + _i * 8192), 16, 0, 0); } while (0)
; #define PG8_WAIT_V(n) asm volatile("s_waitcnt vmcnt(" #n ")" ::: "memory")
; #define PG8_WAIT_L(n) asm volatile("s_waitcnt lgkmcnt(" #n ")" ::: "memory")
;     DI void operator()(const f32x4 (&acc)[2][2][4][2], const Unit& u, int wr, int wc, int fr, int fq) const {
;     ...
;         for (int ai = 0; ai < 2; ++ai)
; #pragma unroll
;             for (int m = 0; m < 4; ++m) { const size_t ro = (size_t)(row0 + ai * HALF + m * 16) * D + col0;
; #pragma unroll
;                 for (int bj = 0; bj < 2; ++bj) {
;                     f32x4 x0, x1;
;                     if constexpr (IB) { const u32x4 w = *(const u32x4*)((const bf16_t*)Xin + ro + bj * HALF);
;                         x0 = (f32x4){bflo(w[0]), bfhi(w[0]), bflo(w[1]), bfhi(w[1])}; x1 = (f32x4){bflo(w[2]), bfhi(w[2]), bflo(w[3]), bfhi(w[3])}; }
;                     else { x0 = *(const f32x4*)((const float*)Xin + ro + bj * HALF); x1 = *(const f32x4*)((const float*)Xin + ro + bj * HALF + 4); }
;                     x0 += acc[ai][bj][m][0] * sc[bj][0]; x1 += acc[ai][bj][m][1] * sc[bj][1];
;                     if constexpr (OB) { u32x4 o; o[0] = pack2(x0[0], x0[1]); o[1] = pack2(x0[2], x0[3]); o[2] = pack2(x1[0], x1[1]); o[3] = pack2(x1[2], x1[3]);
;                         *(u32x4*)((bf16_t*)Xout + ro + bj * HALF) = o; }
;                     else { *(f32x4*)((float*)Xout + ro + bj * HALF) = x0; *(f32x4*)((float*)Xout + ro + bj * HALF + 4) = x1; } } }
; template <class Map, class Epi>
; DI void gemm_phase(LAS unsigned char* lds, const Map& MP, const Epi& E, const int nM, const int nN, const int K, const int lda, const int ldb) {
;     ...
;             PG8_BAR; PG8_WAIT_L(0); PG8_MMA(1, 0, At, B0); PG8_BAR; PG8_SCHED;
;             PG8_STAGE(PG8_SB(1, 1), b3 + hstepB, voffB);
;             PG8_WAIT_V(6); PG8_BAR; PG8_MMA(1, 1, At, B1); PG8_BAR;
	s_setprio 1
	s_waitcnt lgkmcnt(7)
	v_mfma_f32_16x16x32_bf16 v[60:63], v[152:155], v[168:171], v[60:63]
	v_mfma_f32_16x16x32_bf16 v[56:59], v[160:163], v[168:171], v[56:59]
	s_waitcnt lgkmcnt(5)
	v_mfma_f32_16x16x32_bf16 v[44:47], v[152:155], v[176:179], v[44:47]
	v_mfma_f32_16x16x32_bf16 v[40:43], v[160:163], v[176:179], v[40:43]
	s_waitcnt lgkmcnt(3)
	v_mfma_f32_16x16x32_bf16 v[28:31], v[152:155], v[184:187], v[28:31]
	v_mfma_f32_16x16x32_bf16 v[24:27], v[160:163], v[184:187], v[24:27]
	s_waitcnt lgkmcnt(1)
	v_mfma_f32_16x16x32_bf16 v[12:15], v[152:155], v[192:195], v[12:15]
	v_mfma_f32_16x16x32_bf16 v[8:11], v[160:163], v[192:195], v[8:11]
	v_mfma_f32_16x16x32_bf16 v[60:63], v[156:159], v[172:175], v[60:63]
	v_mfma_f32_16x16x32_bf16 v[56:59], v[164:167], v[172:175], v[56:59]
	v_mfma_f32_16x16x32_bf16 v[44:47], v[156:159], v[180:183], v[44:47]
	v_mfma_f32_16x16x32_bf16 v[40:43], v[164:167], v[180:183], v[40:43]
	v_mfma_f32_16x16x32_bf16 v[28:31], v[156:159], v[188:191], v[28:31]
	v_mfma_f32_16x16x32_bf16 v[24:27], v[164:167], v[188:191], v[24:27]
	s_waitcnt lgkmcnt(0)
	v_mfma_f32_16x16x32_bf16 v[12:15], v[156:159], v[198:201], v[12:15]
	v_mfma_f32_16x16x32_bf16 v[8:11], v[164:167], v[198:201], v[8:11]
	s_setprio 0
	s_barrier
	s_add_u32 s8, s12, 0x160080
	s_addc_u32 s9, s13, 0
	s_add_i32 s12, s14, s22
	s_mov_b32 m0, s12
	s_nop 0
	global_load_lds_dwordx4 v132, s[8:9]
	s_add_i32 m0, s12, 0x2000
	s_nop 0
	global_load_lds_dwordx4 v128, s[8:9]
	s_waitcnt vmcnt(6)
	s_barrier
	s_setprio 1
	v_mfma_f32_16x16x32_bf16 v[52:55], v[202:205], v[168:171], v[52:55]
	v_mfma_f32_16x16x32_bf16 v[48:51], v[210:213], v[168:171], v[48:51]
	v_mfma_f32_16x16x32_bf16 v[36:39], v[202:205], v[176:179], v[36:39]
	v_mfma_f32_16x16x32_bf16 v[32:35], v[210:213], v[176:179], v[32:35]
	v_mfma_f32_16x16x32_bf16 v[20:23], v[202:205], v[184:187], v[20:23]
	v_mfma_f32_16x16x32_bf16 v[16:19], v[210:213], v[184:187], v[16:19]
	v_mfma_f32_16x16x32_bf16 v[4:7], v[202:205], v[192:195], v[4:7]
	v_mfma_f32_16x16x32_bf16 v[0:3], v[210:213], v[192:195], v[0:3]
	v_mfma_f32_16x16x32_bf16 v[52:55], v[206:209], v[172:175], v[52:55]
	v_mfma_f32_16x16x32_bf16 v[48:51], v[214:217], v[172:175], v[48:51]
	v_mfma_f32_16x16x32_bf16 v[36:39], v[206:209], v[180:183], v[36:39]
	v_mfma_f32_16x16x32_bf16 v[32:35], v[214:217], v[180:183], v[32:35]
	v_mfma_f32_16x16x32_bf16 v[20:23], v[206:209], v[188:191], v[20:23]
	v_mfma_f32_16x16x32_bf16 v[16:19], v[214:217], v[188:191], v[16:19]
	v_mfma_f32_16x16x32_bf16 v[4:7], v[206:209], v[198:201], v[4:7]
	v_mfma_f32_16x16x32_bf16 v[0:3], v[214:217], v[198:201], v[0:3]
	s_setprio 0
	s_add_i32 s3, s3, 2
	s_add_u32 s5, s5, 0x100
	s_addc_u32 s38, s38, 0
	s_cmpk_gt_u32 s3, 0x55
	s_mov_b64 s[8:9], s[10:11]
	s_barrier
	s_cbranch_scc0 .LBB1_550
	v_mov_b32_e32 v144, v146
	v_mov_b32_e32 v152, v147
	s_lshl_b32 s2, s2, 8
	s_add_i32 s2, s2, s29
	s_lshl_b32 s3, s4, 8
	v_add_u32_e32 v152, s2, v152
	s_or_b32 s3, s3, s54
	v_ashrrev_i32_e32 v153, 31, v152
	v_lshl_add_u32 v144, v144, 3, s3
	v_lshlrev_b64 v[152:153], 12, v[152:153]
	v_ashrrev_i32_e32 v145, 31, v144
	v_lshl_add_u64 v[152:153], s[46:47], 0, v[152:153]
	v_lshl_add_u64 v[144:145], v[144:145], 1, v[152:153]
	global_load_dwordx4 v[160:163], v[144:145], off
	global_load_dwordx4 v[164:167], v[144:145], off offset:256
	s_mov_b64 s[98:99], 0x10000
	v_lshl_add_u64 v[154:155], v[144:145], 0, s[98:99]
	global_load_dwordx4 v[168:171], v[154:155], off
	global_load_dwordx4 v[172:175], v[154:155], off offset:256
	s_mov_b64 s[98:99], 0x20000
	v_lshl_add_u64 v[154:155], v[144:145], 0, s[98:99]
	global_load_dwordx4 v[176:179], v[154:155], off
	global_load_dwordx4 v[180:183], v[154:155], off offset:256
	s_mov_b64 s[98:99], 0x30000
	v_lshl_add_u64 v[154:155], v[144:145], 0, s[98:99]
	global_load_dwordx4 v[184:187], v[154:155], off
	global_load_dwordx4 v[188:191], v[154:155], off offset:256
	s_mov_b64 s[98:99], 0x80000
	v_lshl_add_u64 v[154:155], v[144:145], 0, s[98:99]
	global_load_dwordx4 v[192:195], v[154:155], off
	global_load_dwordx4 v[198:201], v[154:155], off offset:256
	s_mov_b64 s[98:99], 0x90000
	v_lshl_add_u64 v[154:155], v[144:145], 0, s[98:99]
	global_load_dwordx4 v[202:205], v[154:155], off
	global_load_dwordx4 v[206:209], v[154:155], off offset:256
	s_mov_b64 s[98:99], 0xa0000
	v_lshl_add_u64 v[154:155], v[144:145], 0, s[98:99]
	global_load_dwordx4 v[210:213], v[154:155], off
	global_load_dwordx4 v[214:217], v[154:155], off offset:256
	s_mov_b64 s[98:99], 0xb0000
	v_lshl_add_u64 v[154:155], v[144:145], 0, s[98:99]
	global_load_dwordx4 v[248:251], v[154:155], off
	global_load_dwordx4 v[252:255], v[154:155], off offset:256
	s_waitcnt vmcnt(15)
	s_nop 1
	v_mov_b32_e32 v152, v160
	v_mov_b32_e32 v153, v161
	v_mov_b32_e32 v154, v162
	v_mov_b32_e32 v155, v163
	s_mov_b64 s[2:3], 0x10000
	s_mov_b32 s4, s37
	s_mov_b64 s[10:11], s[6:7]
	s_mov_b64 s[8:9], s[42:43]
	s_waitcnt lgkmcnt(0)
	v_lshlrev_b32_e32 v156, 16, v152
	v_and_b32_e32 v157, 0xffff0000, v152
	v_lshlrev_b32_e32 v152, 16, v153
	v_and_b32_e32 v153, 0xffff0000, v153
	v_lshlrev_b32_e32 v158, 16, v154
	v_and_b32_e32 v159, 0xffff0000, v154
	v_lshlrev_b32_e32 v154, 16, v155
	v_and_b32_e32 v155, 0xffff0000, v155
	v_pk_add_f32 v[126:127], v[126:127], v[152:153]
	v_pk_add_f32 v[124:125], v[124:125], v[156:157]
	v_pk_add_f32 v[152:153], v[122:123], v[154:155]
	v_pk_add_f32 v[122:123], v[120:121], v[158:159]
	v_cvt_pk_bf16_f32 v120, v124, v125
	v_cvt_pk_bf16_f32 v121, v126, v127
	v_cvt_pk_bf16_f32 v122, v122, v123
	v_cvt_pk_bf16_f32 v123, v152, v153
	global_store_dwordx4 v[144:145], v[120:123], off
	s_waitcnt vmcnt(15)
; DI unsigned pack2(float a, float b) { f32x2 v = {a, b}; hwbf16x2 r = __builtin_convertvector(v, hwbf16x2); return __builtin_bit_cast(unsigned, r); }
; DI float bflo(unsigned w) { return __uint_as_float(w << 16); }
; DI float bfhi(unsigned w) { return __uint_as_float(w & 0xffff0000u); }
;     DI void operator()(const f32x4 (&acc)[2][2][4][2], const Unit& u, int wr, int wc, int fr, int fq) const {
;     ...
;         for (int ai = 0; ai < 2; ++ai)
; #pragma unroll
;             for (int m = 0; m < 4; ++m) { const size_t ro = (size_t)(row0 + ai * HALF + m * 16) * D + col0;
; #pragma unroll
;                 for (int bj = 0; bj < 2; ++bj) {
;                     f32x4 x0, x1;
;                     if constexpr (IB) { const u32x4 w = *(const u32x4*)((const bf16_t*)Xin + ro + bj * HALF);
;                         x0 = (f32x4){bflo(w[0]), bfhi(w[0]), bflo(w[1]), bfhi(w[1])}; x1 = (f32x4){bflo(w[2]), bfhi(w[2]), bflo(w[3]), bfhi(w[3])}; }
;                     else { x0 = *(const f32x4*)((const float*)Xin + ro + bj * HALF); x1 = *(const f32x4*)((const float*)Xin + ro + bj * HALF + 4); }
;                     x0 += acc[ai][bj][m][0] * sc[bj][0]; x1 += acc[ai][bj][m][1] * sc[bj][1];
;                     if constexpr (OB) { u32x4 o; o[0] = pack2(x0[0], x0[1]); o[1] = pack2(x0[2], x0[3]); o[2] = pack2(x1[0], x1[1]); o[3] = pack2(x1[2], x1[3]);
;                         *(u32x4*)((bf16_t*)Xout + ro + bj * HALF) = o; }
;                     else { *(f32x4*)((float*)Xout + ro + bj * HALF) = x0; *(f32x4*)((float*)Xout + ro + bj * HALF + 4) = x1; } } }
	s_nop 1
	v_mov_b32_e32 v120, v164
	v_mov_b32_e32 v121, v165
	v_mov_b32_e32 v122, v166
	v_mov_b32_e32 v123, v167
	s_waitcnt lgkmcnt(0)
	v_lshlrev_b32_e32 v124, 16, v120
	v_and_b32_e32 v125, 0xffff0000, v120
	v_lshlrev_b32_e32 v120, 16, v121
	v_and_b32_e32 v121, 0xffff0000, v121
	v_lshlrev_b32_e32 v126, 16, v122
	v_and_b32_e32 v127, 0xffff0000, v122
	v_lshlrev_b32_e32 v122, 16, v123
	v_and_b32_e32 v123, 0xffff0000, v123
	v_pk_add_f32 v[116:117], v[116:117], v[124:125]
	v_pk_add_f32 v[118:119], v[118:119], v[120:121]
	v_pk_add_f32 v[120:121], v[114:115], v[122:123]
	v_pk_add_f32 v[114:115], v[112:113], v[126:127]
	v_cvt_pk_bf16_f32 v112, v116, v117
	v_lshl_add_u64 v[116:117], v[144:145], 0, s[2:3]
	s_mov_b32 s2, 0x10000
	v_cvt_pk_bf16_f32 v113, v118, v119
	v_add_co_u32_e32 v118, vcc, s2, v144
	v_cvt_pk_bf16_f32 v114, v114, v115
	v_cvt_pk_bf16_f32 v115, v120, v121
	v_addc_co_u32_e32 v119, vcc, 0, v145, vcc
	global_store_dwordx4 v[144:145], v[112:115], off offset:256
	s_waitcnt vmcnt(15)
	s_nop 1
	v_mov_b32_e32 v112, v168
	v_mov_b32_e32 v113, v169
	v_mov_b32_e32 v114, v170
	v_mov_b32_e32 v115, v171
	s_mov_b64 s[2:3], 0x20000
	s_waitcnt lgkmcnt(0)
	v_lshlrev_b32_e32 v120, 16, v112
	v_and_b32_e32 v121, 0xffff0000, v112
	v_lshlrev_b32_e32 v112, 16, v113
	v_and_b32_e32 v113, 0xffff0000, v113
	v_lshlrev_b32_e32 v122, 16, v114
	v_and_b32_e32 v123, 0xffff0000, v114
	v_lshlrev_b32_e32 v114, 16, v115
	v_and_b32_e32 v115, 0xffff0000, v115
	v_pk_add_f32 v[110:111], v[110:111], v[112:113]
	v_pk_add_f32 v[108:109], v[108:109], v[120:121]
	v_pk_add_f32 v[112:113], v[106:107], v[114:115]
	v_pk_add_f32 v[106:107], v[104:105], v[122:123]
	v_cvt_pk_bf16_f32 v104, v108, v109
	v_cvt_pk_bf16_f32 v105, v110, v111
	v_cvt_pk_bf16_f32 v106, v106, v107
	v_cvt_pk_bf16_f32 v107, v112, v113
	global_store_dwordx4 v[118:119], v[104:107], off
	s_waitcnt vmcnt(15)
	s_nop 1
	v_mov_b32_e32 v104, v172
	v_mov_b32_e32 v105, v173
	v_mov_b32_e32 v106, v174
	v_mov_b32_e32 v107, v175
	s_waitcnt lgkmcnt(0)
	v_lshlrev_b32_e32 v108, 16, v104
	v_and_b32_e32 v109, 0xffff0000, v104
	v_lshlrev_b32_e32 v104, 16, v105
	v_and_b32_e32 v105, 0xffff0000, v105
	v_lshlrev_b32_e32 v110, 16, v106
	v_and_b32_e32 v111, 0xffff0000, v106
	v_lshlrev_b32_e32 v106, 16, v107
	v_and_b32_e32 v107, 0xffff0000, v107
	v_pk_add_f32 v[100:101], v[100:101], v[108:109]
	v_pk_add_f32 v[102:103], v[102:103], v[104:105]
	v_pk_add_f32 v[104:105], v[98:99], v[106:107]
	v_pk_add_f32 v[98:99], v[96:97], v[110:111]
	v_cvt_pk_bf16_f32 v96, v100, v101
	v_lshl_add_u64 v[100:101], v[144:145], 0, s[2:3]
	s_mov_b32 s2, 0x20000
	v_cvt_pk_bf16_f32 v97, v102, v103
	v_add_co_u32_e32 v102, vcc, s2, v144
	v_cvt_pk_bf16_f32 v98, v98, v99
	v_cvt_pk_bf16_f32 v99, v104, v105
	v_addc_co_u32_e32 v103, vcc, 0, v145, vcc
	global_store_dwordx4 v[116:117], v[96:99], off offset:256
	s_waitcnt vmcnt(15)
	s_nop 1
	v_mov_b32_e32 v96, v176
	v_mov_b32_e32 v97, v177
	v_mov_b32_e32 v98, v178
	v_mov_b32_e32 v99, v179
	s_mov_b64 s[2:3], 0x30000
	s_waitcnt lgkmcnt(0)
	v_lshlrev_b32_e32 v104, 16, v96
	v_and_b32_e32 v105, 0xffff0000, v96
	v_lshlrev_b32_e32 v96, 16, v97
	v_and_b32_e32 v97, 0xffff0000, v97
	v_lshlrev_b32_e32 v106, 16, v98
	v_and_b32_e32 v107, 0xffff0000, v98
	v_lshlrev_b32_e32 v98, 16, v99
	v_and_b32_e32 v99, 0xffff0000, v99
	v_pk_add_f32 v[94:95], v[94:95], v[96:97]
	v_pk_add_f32 v[92:93], v[92:93], v[104:105]
	v_pk_add_f32 v[96:97], v[90:91], v[98:99]
	v_pk_add_f32 v[90:91], v[88:89], v[106:107]
	v_cvt_pk_bf16_f32 v88, v92, v93
	v_cvt_pk_bf16_f32 v89, v94, v95
	v_cvt_pk_bf16_f32 v90, v90, v91
	v_cvt_pk_bf16_f32 v91, v96, v97
	global_store_dwordx4 v[102:103], v[88:91], off
	s_waitcnt vmcnt(15)
	s_nop 1
	v_mov_b32_e32 v88, v180
	v_mov_b32_e32 v89, v181
	v_mov_b32_e32 v90, v182
	v_mov_b32_e32 v91, v183
	s_waitcnt lgkmcnt(0)
	v_lshlrev_b32_e32 v92, 16, v88
	v_and_b32_e32 v93, 0xffff0000, v88
	v_lshlrev_b32_e32 v88, 16, v89
	v_and_b32_e32 v89, 0xffff0000, v89
	v_lshlrev_b32_e32 v94, 16, v90
	v_and_b32_e32 v95, 0xffff0000, v90
	v_lshlrev_b32_e32 v90, 16, v91
	v_and_b32_e32 v91, 0xffff0000, v91
	v_pk_add_f32 v[86:87], v[86:87], v[88:89]
	v_pk_add_f32 v[84:85], v[84:85], v[92:93]
	v_pk_add_f32 v[88:89], v[82:83], v[90:91]
	v_pk_add_f32 v[82:83], v[80:81], v[94:95]
	v_cvt_pk_bf16_f32 v80, v84, v85
	v_cvt_pk_bf16_f32 v81, v86, v87
	v_cvt_pk_bf16_f32 v82, v82, v83
	v_cvt_pk_bf16_f32 v83, v88, v89
	global_store_dwordx4 v[100:101], v[80:83], off offset:256
	s_nop 1
	v_lshl_add_u64 v[80:81], v[144:145], 0, s[2:3]
	s_mov_b32 s2, 0x30000
	v_add_co_u32_e32 v86, vcc, s2, v144
	s_mov_b64 s[2:3], 0x80000
	s_nop 0
	v_addc_co_u32_e32 v87, vcc, 0, v145, vcc
	s_waitcnt vmcnt(15)
	s_nop 1
	v_mov_b32_e32 v82, v184
	v_mov_b32_e32 v83, v185
	v_mov_b32_e32 v84, v186
	v_mov_b32_e32 v85, v187
	s_waitcnt lgkmcnt(0)
	v_lshlrev_b32_e32 v88, 16, v82
	v_and_b32_e32 v89, 0xffff0000, v82
	v_lshlrev_b32_e32 v82, 16, v83
	v_and_b32_e32 v83, 0xffff0000, v83
	v_lshlrev_b32_e32 v90, 16, v84
	v_and_b32_e32 v91, 0xffff0000, v84
	v_lshlrev_b32_e32 v84, 16, v85
	v_and_b32_e32 v85, 0xffff0000, v85
	v_pk_add_f32 v[78:79], v[78:79], v[82:83]
	v_pk_add_f32 v[76:77], v[76:77], v[88:89]
	v_pk_add_f32 v[82:83], v[74:75], v[84:85]
	v_pk_add_f32 v[74:75], v[72:73], v[90:91]
	v_cvt_pk_bf16_f32 v72, v76, v77
	v_cvt_pk_bf16_f32 v73, v78, v79
	v_cvt_pk_bf16_f32 v74, v74, v75
	v_cvt_pk_bf16_f32 v75, v82, v83
	global_store_dwordx4 v[86:87], v[72:75], off
	s_waitcnt vmcnt(15)
	s_nop 1
	v_mov_b32_e32 v72, v188
	v_mov_b32_e32 v73, v189
	v_mov_b32_e32 v74, v190
	v_mov_b32_e32 v75, v191
	s_waitcnt lgkmcnt(0)
; DI unsigned pack2(float a, float b) { f32x2 v = {a, b}; hwbf16x2 r = __builtin_convertvector(v, hwbf16x2); return __builtin_bit_cast(unsigned, r); }
; DI float bflo(unsigned w) { return __uint_as_float(w << 16); }
; DI float bfhi(unsigned w) { return __uint_as_float(w & 0xffff0000u); }
;     DI void operator()(const f32x4 (&acc)[2][2][4][2], const Unit& u, int wr, int wc, int fr, int fq) const {
;     ...
;         for (int ai = 0; ai < 2; ++ai)
; #pragma unroll
;             for (int m = 0; m < 4; ++m) { const size_t ro = (size_t)(row0 + ai * HALF + m * 16) * D + col0;
; #pragma unroll
;                 for (int bj = 0; bj < 2; ++bj) {
;                     f32x4 x0, x1;
;                     if constexpr (IB) { const u32x4 w = *(const u32x4*)((const bf16_t*)Xin + ro + bj * HALF);
;                         x0 = (f32x4){bflo(w[0]), bfhi(w[0]), bflo(w[1]), bfhi(w[1])}; x1 = (f32x4){bflo(w[2]), bfhi(w[2]), bflo(w[3]), bfhi(w[3])}; }
;                     else { x0 = *(const f32x4*)((const float*)Xin + ro + bj * HALF); x1 = *(const f32x4*)((const float*)Xin + ro + bj * HALF + 4); }
;                     x0 += acc[ai][bj][m][0] * sc[bj][0]; x1 += acc[ai][bj][m][1] * sc[bj][1];
;                     if constexpr (OB) { u32x4 o; o[0] = pack2(x0[0], x0[1]); o[1] = pack2(x0[2], x0[3]); o[2] = pack2(x1[0], x1[1]); o[3] = pack2(x1[2], x1[3]);
;                         *(u32x4*)((bf16_t*)Xout + ro + bj * HALF) = o; }
;                     else { *(f32x4*)((float*)Xout + ro + bj * HALF) = x0; *(f32x4*)((float*)Xout + ro + bj * HALF + 4) = x1; } } }
	v_lshlrev_b32_e32 v76, 16, v72
	v_and_b32_e32 v77, 0xffff0000, v72
	v_lshlrev_b32_e32 v72, 16, v73
	v_and_b32_e32 v73, 0xffff0000, v73
	v_lshlrev_b32_e32 v78, 16, v74
	v_and_b32_e32 v79, 0xffff0000, v74
	v_lshlrev_b32_e32 v74, 16, v75
	v_and_b32_e32 v75, 0xffff0000, v75
	v_pk_add_f32 v[70:71], v[70:71], v[72:73]
	v_pk_add_f32 v[68:69], v[68:69], v[76:77]
	v_pk_add_f32 v[72:73], v[66:67], v[74:75]
	v_pk_add_f32 v[66:67], v[64:65], v[78:79]
	v_cvt_pk_bf16_f32 v64, v68, v69
	v_cvt_pk_bf16_f32 v65, v70, v71
	v_cvt_pk_bf16_f32 v66, v66, v67
	v_cvt_pk_bf16_f32 v67, v72, v73
	global_store_dwordx4 v[80:81], v[64:67], off offset:256
	s_nop 1
	v_lshl_add_u64 v[64:65], v[144:145], 0, s[2:3]
	s_mov_b32 s2, 0x80000
	v_add_co_u32_e32 v70, vcc, s2, v144
	s_mov_b64 s[2:3], 0x90000
	s_nop 0
	v_addc_co_u32_e32 v71, vcc, 0, v145, vcc
	s_waitcnt vmcnt(15)
	s_nop 1
	v_mov_b32_e32 v66, v192
	v_mov_b32_e32 v67, v193
	v_mov_b32_e32 v68, v194
	v_mov_b32_e32 v69, v195
	s_waitcnt lgkmcnt(0)
	v_lshlrev_b32_e32 v72, 16, v66
	v_and_b32_e32 v73, 0xffff0000, v66
	v_lshlrev_b32_e32 v66, 16, v67
	v_and_b32_e32 v67, 0xffff0000, v67
	v_lshlrev_b32_e32 v74, 16, v68
	v_and_b32_e32 v75, 0xffff0000, v68
	v_lshlrev_b32_e32 v68, 16, v69
	v_and_b32_e32 v69, 0xffff0000, v69
	v_pk_add_f32 v[62:63], v[62:63], v[66:67]
	v_pk_add_f32 v[60:61], v[60:61], v[72:73]
	v_pk_add_f32 v[66:67], v[58:59], v[68:69]
	v_pk_add_f32 v[58:59], v[56:57], v[74:75]
	v_cvt_pk_bf16_f32 v56, v60, v61
	v_cvt_pk_bf16_f32 v57, v62, v63
	v_cvt_pk_bf16_f32 v58, v58, v59
	v_cvt_pk_bf16_f32 v59, v66, v67
	global_store_dwordx4 v[70:71], v[56:59], off
	s_waitcnt vmcnt(15)
	s_nop 1
	v_mov_b32_e32 v56, v198
	v_mov_b32_e32 v57, v199
	v_mov_b32_e32 v58, v200
	v_mov_b32_e32 v59, v201
	s_waitcnt lgkmcnt(0)
	v_lshlrev_b32_e32 v60, 16, v56
	v_and_b32_e32 v61, 0xffff0000, v56
	v_lshlrev_b32_e32 v56, 16, v57
	v_and_b32_e32 v57, 0xffff0000, v57
	v_lshlrev_b32_e32 v62, 16, v58
	v_and_b32_e32 v63, 0xffff0000, v58
	v_lshlrev_b32_e32 v58, 16, v59
	v_and_b32_e32 v59, 0xffff0000, v59
	v_pk_add_f32 v[54:55], v[54:55], v[56:57]
	v_pk_add_f32 v[52:53], v[52:53], v[60:61]
	v_pk_add_f32 v[56:57], v[50:51], v[58:59]
	v_pk_add_f32 v[50:51], v[48:49], v[62:63]
	v_cvt_pk_bf16_f32 v48, v52, v53
	v_cvt_pk_bf16_f32 v49, v54, v55
	v_cvt_pk_bf16_f32 v50, v50, v51
	v_cvt_pk_bf16_f32 v51, v56, v57
	global_store_dwordx4 v[64:65], v[48:51], off offset:256
	s_nop 1
	v_lshl_add_u64 v[48:49], v[144:145], 0, s[2:3]
	s_mov_b32 s2, 0x90000
	v_add_co_u32_e32 v54, vcc, s2, v144
	s_mov_b64 s[2:3], 0xa0000
	s_nop 0
	v_addc_co_u32_e32 v55, vcc, 0, v145, vcc
	s_waitcnt vmcnt(15)
	s_nop 1
	v_mov_b32_e32 v50, v202
	v_mov_b32_e32 v51, v203
	v_mov_b32_e32 v52, v204
	v_mov_b32_e32 v53, v205
	s_waitcnt lgkmcnt(0)
	v_lshlrev_b32_e32 v56, 16, v50
	v_and_b32_e32 v57, 0xffff0000, v50
	v_lshlrev_b32_e32 v50, 16, v51
	v_and_b32_e32 v51, 0xffff0000, v51
	v_lshlrev_b32_e32 v58, 16, v52
	v_and_b32_e32 v59, 0xffff0000, v52
	v_lshlrev_b32_e32 v52, 16, v53
	v_and_b32_e32 v53, 0xffff0000, v53
	v_pk_add_f32 v[46:47], v[46:47], v[50:51]
	v_pk_add_f32 v[44:45], v[44:45], v[56:57]
	v_pk_add_f32 v[50:51], v[42:43], v[52:53]
	v_pk_add_f32 v[42:43], v[40:41], v[58:59]
	v_cvt_pk_bf16_f32 v40, v44, v45
	v_cvt_pk_bf16_f32 v41, v46, v47
	v_cvt_pk_bf16_f32 v42, v42, v43
	v_cvt_pk_bf16_f32 v43, v50, v51
	global_store_dwordx4 v[54:55], v[40:43], off
	s_waitcnt vmcnt(15)
	s_nop 1
	v_mov_b32_e32 v40, v206
	v_mov_b32_e32 v41, v207
	v_mov_b32_e32 v42, v208
	v_mov_b32_e32 v43, v209
	s_waitcnt lgkmcnt(0)
; DI unsigned pack2(float a, float b) { f32x2 v = {a, b}; hwbf16x2 r = __builtin_convertvector(v, hwbf16x2); return __builtin_bit_cast(unsigned, r); }
; DI float bflo(unsigned w) { return __uint_as_float(w << 16); }
; DI float bfhi(unsigned w) { return __uint_as_float(w & 0xffff0000u); }
;     DI void operator()(const f32x4 (&acc)[2][2][4][2], const Unit& u, int wr, int wc, int fr, int fq) const {
;     ...
;         for (int ai = 0; ai < 2; ++ai)
; #pragma unroll
;             for (int m = 0; m < 4; ++m) { const size_t ro = (size_t)(row0 + ai * HALF + m * 16) * D + col0;
; #pragma unroll
;                 for (int bj = 0; bj < 2; ++bj) {
;                     f32x4 x0, x1;
;                     if constexpr (IB) { const u32x4 w = *(const u32x4*)((const bf16_t*)Xin + ro + bj * HALF);
;                         x0 = (f32x4){bflo(w[0]), bfhi(w[0]), bflo(w[1]), bfhi(w[1])}; x1 = (f32x4){bflo(w[2]), bfhi(w[2]), bflo(w[3]), bfhi(w[3])}; }
;                     else { x0 = *(const f32x4*)((const float*)Xin + ro + bj * HALF); x1 = *(const f32x4*)((const float*)Xin + ro + bj * HALF + 4); }
;                     x0 += acc[ai][bj][m][0] * sc[bj][0]; x1 += acc[ai][bj][m][1] * sc[bj][1];
;                     if constexpr (OB) { u32x4 o; o[0] = pack2(x0[0], x0[1]); o[1] = pack2(x0[2], x0[3]); o[2] = pack2(x1[0], x1[1]); o[3] = pack2(x1[2], x1[3]);
;                         *(u32x4*)((bf16_t*)Xout + ro + bj * HALF) = o; }
;                     else { *(f32x4*)((float*)Xout + ro + bj * HALF) = x0; *(f32x4*)((float*)Xout + ro + bj * HALF + 4) = x1; } } }
	v_lshlrev_b32_e32 v44, 16, v40
	v_and_b32_e32 v45, 0xffff0000, v40
	v_lshlrev_b32_e32 v40, 16, v41
	v_and_b32_e32 v41, 0xffff0000, v41
	v_lshlrev_b32_e32 v46, 16, v42
	v_and_b32_e32 v47, 0xffff0000, v42
	v_lshlrev_b32_e32 v42, 16, v43
	v_and_b32_e32 v43, 0xffff0000, v43
	v_pk_add_f32 v[38:39], v[38:39], v[40:41]
	v_pk_add_f32 v[36:37], v[36:37], v[44:45]
	v_pk_add_f32 v[40:41], v[34:35], v[42:43]
	v_pk_add_f32 v[34:35], v[32:33], v[46:47]
	v_cvt_pk_bf16_f32 v32, v36, v37
	v_cvt_pk_bf16_f32 v33, v38, v39
	v_cvt_pk_bf16_f32 v34, v34, v35
	v_cvt_pk_bf16_f32 v35, v40, v41
	global_store_dwordx4 v[48:49], v[32:35], off offset:256
	s_nop 1
	v_lshl_add_u64 v[32:33], v[144:145], 0, s[2:3]
	s_mov_b32 s2, 0xa0000
	v_add_co_u32_e32 v38, vcc, s2, v144
	s_mov_b64 s[2:3], 0xb0000
	s_nop 0
	v_addc_co_u32_e32 v39, vcc, 0, v145, vcc
	s_waitcnt vmcnt(15)
	s_nop 1
	v_mov_b32_e32 v34, v210
	v_mov_b32_e32 v35, v211
	v_mov_b32_e32 v36, v212
	v_mov_b32_e32 v37, v213
	s_waitcnt lgkmcnt(0)
	v_lshlrev_b32_e32 v40, 16, v34
	v_and_b32_e32 v41, 0xffff0000, v34
	v_lshlrev_b32_e32 v34, 16, v35
	v_and_b32_e32 v35, 0xffff0000, v35
	v_lshlrev_b32_e32 v42, 16, v36
	v_and_b32_e32 v43, 0xffff0000, v36
	v_lshlrev_b32_e32 v36, 16, v37
	v_and_b32_e32 v37, 0xffff0000, v37
	v_pk_add_f32 v[30:31], v[30:31], v[34:35]
	v_pk_add_f32 v[28:29], v[28:29], v[40:41]
	v_pk_add_f32 v[34:35], v[26:27], v[36:37]
	v_pk_add_f32 v[26:27], v[24:25], v[42:43]
	v_cvt_pk_bf16_f32 v24, v28, v29
	v_cvt_pk_bf16_f32 v25, v30, v31
	v_cvt_pk_bf16_f32 v26, v26, v27
	v_cvt_pk_bf16_f32 v27, v34, v35
	global_store_dwordx4 v[38:39], v[24:27], off
	s_waitcnt vmcnt(15)
	s_nop 1
	v_mov_b32_e32 v24, v214
	v_mov_b32_e32 v25, v215
	v_mov_b32_e32 v26, v216
	v_mov_b32_e32 v27, v217
	s_waitcnt lgkmcnt(0)
	v_lshlrev_b32_e32 v28, 16, v24
	v_and_b32_e32 v29, 0xffff0000, v24
	v_lshlrev_b32_e32 v24, 16, v25
	v_and_b32_e32 v25, 0xffff0000, v25
	v_lshlrev_b32_e32 v30, 16, v26
	v_and_b32_e32 v31, 0xffff0000, v26
	v_lshlrev_b32_e32 v26, 16, v27
	v_and_b32_e32 v27, 0xffff0000, v27
	v_pk_add_f32 v[22:23], v[22:23], v[24:25]
	v_pk_add_f32 v[20:21], v[20:21], v[28:29]
	v_pk_add_f32 v[24:25], v[18:19], v[26:27]
	v_pk_add_f32 v[18:19], v[16:17], v[30:31]
	v_cvt_pk_bf16_f32 v16, v20, v21
	v_cvt_pk_bf16_f32 v17, v22, v23
	v_cvt_pk_bf16_f32 v18, v18, v19
	v_cvt_pk_bf16_f32 v19, v24, v25
	global_store_dwordx4 v[32:33], v[16:19], off offset:256
	s_nop 1
	v_lshl_add_u64 v[16:17], v[144:145], 0, s[2:3]
	s_mov_b32 s2, 0xb0000
	v_add_co_u32_e32 v22, vcc, s2, v144
	s_mov_b32 s2, s55
	s_nop 0
	v_addc_co_u32_e32 v23, vcc, 0, v145, vcc
	s_waitcnt vmcnt(15)
	s_nop 1
	v_mov_b32_e32 v18, v248
	v_mov_b32_e32 v19, v249
	v_mov_b32_e32 v20, v250
	v_mov_b32_e32 v21, v251
	s_and_b64 vcc, exec, s[40:41]
	s_waitcnt lgkmcnt(0)
	v_lshlrev_b32_e32 v24, 16, v18
	v_and_b32_e32 v25, 0xffff0000, v18
	v_lshlrev_b32_e32 v18, 16, v19
	v_and_b32_e32 v19, 0xffff0000, v19
	v_lshlrev_b32_e32 v26, 16, v20
	v_and_b32_e32 v27, 0xffff0000, v20
	v_lshlrev_b32_e32 v20, 16, v21
	v_and_b32_e32 v21, 0xffff0000, v21
	v_pk_add_f32 v[14:15], v[14:15], v[18:19]
	v_pk_add_f32 v[12:13], v[12:13], v[24:25]
	v_pk_add_f32 v[18:19], v[10:11], v[20:21]
	v_pk_add_f32 v[10:11], v[8:9], v[26:27]
	v_cvt_pk_bf16_f32 v8, v12, v13
	v_cvt_pk_bf16_f32 v9, v14, v15
	v_cvt_pk_bf16_f32 v10, v10, v11
	v_cvt_pk_bf16_f32 v11, v18, v19
	global_store_dwordx4 v[22:23], v[8:11], off
	s_waitcnt vmcnt(15)
	s_nop 1
	v_mov_b32_e32 v8, v252
	v_mov_b32_e32 v9, v253
	v_mov_b32_e32 v10, v254
	v_mov_b32_e32 v11, v255
	s_waitcnt lgkmcnt(0)
	v_lshlrev_b32_e32 v12, 16, v8
	v_and_b32_e32 v13, 0xffff0000, v8
	v_lshlrev_b32_e32 v8, 16, v9
	v_and_b32_e32 v9, 0xffff0000, v9
	v_lshlrev_b32_e32 v14, 16, v10
	v_and_b32_e32 v15, 0xffff0000, v10
	v_lshlrev_b32_e32 v10, 16, v11
	v_and_b32_e32 v11, 0xffff0000, v11
	v_pk_add_f32 v[6:7], v[6:7], v[8:9]
	v_pk_add_f32 v[4:5], v[4:5], v[12:13]
	v_pk_add_f32 v[8:9], v[2:3], v[10:11]
	v_pk_add_f32 v[2:3], v[0:1], v[14:15]
	v_cvt_pk_bf16_f32 v0, v4, v5
	v_cvt_pk_bf16_f32 v1, v6, v7
	v_cvt_pk_bf16_f32 v2, v2, v3
	v_cvt_pk_bf16_f32 v3, v8, v9
	global_store_dwordx4 v[16:17], v[0:3], off offset:256
	s_cbranch_vccz .LBB1_543
	s_waitcnt vmcnt(0)
	s_cmpk_gt_u32 s17, 0xff
	s_cbranch_scc1 .LBB1_554
	s_barrier

; #define PG8_STAGE(bufoff, gbase, voff) do { _Pragma("unroll") for (int _i = 0; _i < 2; ++_i) \
;         __builtin_amdgcn_global_load_lds((const unsigned*)((const char*)(gbase) + (voff)[_i]), (LAS unsigned*)(lds + (bufoff) + ldsw + _i * 8192), 16, 0, 0); } while (0)
; #define PG8_LDA(dst, b, h) do { _Pragma("unroll") for (int m = 0; m < 4; ++m) _Pragma("unroll") for (int k = 0; k < 2; ++k) dst[m][k] = *(const LAS bf16x8*)(lds + PG8_SA(b, h) + aoff + m * 2048 + k * 1024); } while (0)
; #define PG8_LDB(dst, b, h) do { _Pragma("unroll") for (int n = 0; n < 2; ++n) _Pragma("unroll") for (int k = 0; k < 2; ++k) dst[n][k] = *(const LAS bf16x8*)(lds + PG8_SB(b, h) + boff + n * 2048 + k * 1024); } while (0)
; #define PG8_MMA(ai, bj, At, Bt) do { __builtin_amdgcn_s_setprio(1); _Pragma("unroll") for (int m = 0; m < 4; ++m) _Pragma("unroll") for (int n = 0; n < 2; ++n) _Pragma("unroll") for (int k = 0; k < 2; ++k) \
;         acc[ai][bj][m][n] = __builtin_amdgcn_mfma_f32_16x16x32_bf16(Bt[n][k], At[m][k], acc[ai][bj][m][n], 0, 0, 0); __builtin_amdgcn_s_setprio(0); } while (0)
; #define PG8_WAIT_V(n) asm volatile("s_waitcnt vmcnt(" #n ")" ::: "memory")
; #define PG8_WAIT_L(n) asm volatile("s_waitcnt lgkmcnt(" #n ")" ::: "memory")
; #define PG8_BAR __builtin_amdgcn_s_barrier()
; #define PG8_SCHED __builtin_amdgcn_sched_barrier(0)
; template <class Map, class Epi>
; DI void gemm_phase(LAS unsigned char* lds, const Map& MP, const Epi& E, const int nM, const int nN, const int K, const int lda, const int ldb) {
;     ...
;             PG8_LDB(B0, 0, 0); PG8_SCHED; PG8_LDA(At, 0, 0); PG8_STAGE(PG8_SA(1, 1), a1 + hstepA, voffA);
;             PG8_WAIT_L(8); PG8_BAR; PG8_WAIT_L(0); PG8_MMA(0, 0, At, B0); PG8_BAR; PG8_SCHED;
;             PG8_LDB(B1, 0, 1); PG8_STAGE(PG8_SB(0, 0), b2, voffB);
;             PG8_BAR; PG8_WAIT_L(0); PG8_MMA(0, 1, At, B1); PG8_BAR;
;             PG8_LDA(At, 0, 1); PG8_STAGE(PG8_SA(0, 0), a2, voffA);
;             PG8_BAR; PG8_WAIT_L(0); PG8_MMA(1, 0, At, B0); PG8_BAR; PG8_SCHED;
;             PG8_STAGE(PG8_SB(0, 1), b2 + hstepB, voffB);
;             PG8_WAIT_V(6); PG8_BAR; PG8_MMA(1, 1, At, B1); PG8_BAR;
.LBB1_693:
	ds_read_b128 v[150:153], v147
	ds_read_b128 v[154:157], v147 offset:1024
	ds_read_b128 v[158:161], v147 offset:2048
	ds_read_b128 v[162:165], v147 offset:3072
	s_add_u32 s3, s20, 0xfff80080
	s_addc_u32 s22, s21, -1
	s_cmp_eq_u32 s54, 28
	s_cselect_b32 s25, s15, s22
	s_cselect_b32 s24, s48, s3
	s_cselect_b32 s23, s13, s53
	s_cselect_b32 s22, s49, s52
	s_add_i32 m0, s31, 0xc000
	ds_read_b128 v[166:169], v148
	ds_read_b128 v[170:173], v148 offset:1024
	ds_read_b128 v[174:177], v148 offset:2048
	ds_read_b128 v[178:181], v148 offset:3072
	ds_read_b128 v[182:185], v148 offset:4096
	ds_read_b128 v[186:189], v148 offset:5120
	ds_read_b128 v[190:193], v148 offset:6144
	ds_read_b128 v[198:201], v148 offset:7168
	global_load_lds_dwordx4 v138, s[20:21]
	s_add_i32 m0, s31, 0xe000
	s_nop 0
	global_load_lds_dwordx4 v136, s[20:21]
	s_waitcnt lgkmcnt(8)
	s_barrier
	s_setprio 1
	s_waitcnt lgkmcnt(7)
	v_mfma_f32_16x16x32_bf16 v[124:127], v[150:153], v[166:169], v[124:127]
	v_mfma_f32_16x16x32_bf16 v[120:123], v[158:161], v[166:169], v[120:123]
	s_waitcnt lgkmcnt(5)
	v_mfma_f32_16x16x32_bf16 v[116:119], v[150:153], v[174:177], v[116:119]
	v_mfma_f32_16x16x32_bf16 v[112:115], v[158:161], v[174:177], v[112:115]
	s_waitcnt lgkmcnt(3)
	v_mfma_f32_16x16x32_bf16 v[100:103], v[150:153], v[182:185], v[100:103]
	v_mfma_f32_16x16x32_bf16 v[96:99], v[158:161], v[182:185], v[96:99]
	s_waitcnt lgkmcnt(1)
	v_mfma_f32_16x16x32_bf16 v[84:87], v[150:153], v[190:193], v[84:87]
	v_mfma_f32_16x16x32_bf16 v[80:83], v[158:161], v[190:193], v[80:83]
	v_mfma_f32_16x16x32_bf16 v[124:127], v[154:157], v[170:173], v[124:127]
	v_mfma_f32_16x16x32_bf16 v[120:123], v[162:165], v[170:173], v[120:123]
	v_mfma_f32_16x16x32_bf16 v[116:119], v[154:157], v[178:181], v[116:119]
	v_mfma_f32_16x16x32_bf16 v[112:115], v[162:165], v[178:181], v[112:115]
	v_mfma_f32_16x16x32_bf16 v[100:103], v[154:157], v[186:189], v[100:103]
	v_mfma_f32_16x16x32_bf16 v[96:99], v[162:165], v[186:189], v[96:99]
	s_waitcnt lgkmcnt(0)
	v_mfma_f32_16x16x32_bf16 v[84:87], v[154:157], v[198:201], v[84:87]
	v_mfma_f32_16x16x32_bf16 v[80:83], v[162:165], v[198:201], v[80:83]
	s_setprio 0
	s_barrier
	s_add_i32 s3, s44, s29
	v_lshl_add_u64 v[194:195], s[22:23], 0, v[132:133]
	s_mov_b32 m0, s3
	ds_read_b128 v[202:205], v149
	ds_read_b128 v[206:209], v149 offset:1024
	ds_read_b128 v[210:213], v149 offset:2048
	ds_read_b128 v[214:217], v149 offset:3072
	global_load_lds_dwordx4 v[194:195], off
	v_lshl_add_u64 v[218:219], s[22:23], 0, v[128:129]
	s_add_i32 m0, s3, 0x2000
	s_nop 0
	global_load_lds_dwordx4 v[218:219], off
	s_barrier
	s_setprio 1
	s_waitcnt lgkmcnt(3)
	v_mfma_f32_16x16x32_bf16 v[108:111], v[202:205], v[166:169], v[108:111]
	s_waitcnt lgkmcnt(1)
	v_mfma_f32_16x16x32_bf16 v[104:107], v[210:213], v[166:169], v[104:107]
	v_mfma_f32_16x16x32_bf16 v[92:95], v[202:205], v[174:177], v[92:95]
	v_mfma_f32_16x16x32_bf16 v[88:91], v[210:213], v[174:177], v[88:91]
	v_mfma_f32_16x16x32_bf16 v[76:79], v[202:205], v[182:185], v[76:79]
	v_mfma_f32_16x16x32_bf16 v[72:75], v[210:213], v[182:185], v[72:75]
	v_mfma_f32_16x16x32_bf16 v[68:71], v[202:205], v[190:193], v[68:71]
	v_mfma_f32_16x16x32_bf16 v[64:67], v[210:213], v[190:193], v[64:67]
	v_mfma_f32_16x16x32_bf16 v[108:111], v[206:209], v[170:173], v[108:111]
	s_waitcnt lgkmcnt(0)
	v_mfma_f32_16x16x32_bf16 v[104:107], v[214:217], v[170:173], v[104:107]
	v_mfma_f32_16x16x32_bf16 v[92:95], v[206:209], v[178:181], v[92:95]
	v_mfma_f32_16x16x32_bf16 v[88:91], v[214:217], v[178:181], v[88:91]
	v_mfma_f32_16x16x32_bf16 v[76:79], v[206:209], v[186:189], v[76:79]
	v_mfma_f32_16x16x32_bf16 v[72:75], v[214:217], v[186:189], v[72:75]
	v_mfma_f32_16x16x32_bf16 v[68:71], v[206:209], v[198:201], v[68:71]
	v_mfma_f32_16x16x32_bf16 v[64:67], v[214:217], v[198:201], v[64:67]
	s_setprio 0
	s_mov_b32 m0, s31
	v_lshl_add_u64 v[220:221], s[24:25], 0, v[134:135]
	s_barrier
	ds_read_b128 v[166:169], v148 offset:16384
	ds_read_b128 v[170:173], v148 offset:17408
	ds_read_b128 v[174:177], v148 offset:18432
	ds_read_b128 v[178:181], v148 offset:19456
	ds_read_b128 v[182:185], v148 offset:20480
	ds_read_b128 v[186:189], v148 offset:21504
	ds_read_b128 v[190:193], v148 offset:22528
	ds_read_b128 v[198:201], v148 offset:23552
	global_load_lds_dwordx4 v[220:221], off
	v_lshl_add_u64 v[222:223], s[24:25], 0, v[130:131]
	s_mov_b32 m0, s11
	s_nop 0
	global_load_lds_dwordx4 v[222:223], off
	s_barrier
	s_setprio 1
	s_waitcnt lgkmcnt(7)
	v_mfma_f32_16x16x32_bf16 v[60:63], v[150:153], v[166:169], v[60:63]
	v_mfma_f32_16x16x32_bf16 v[56:59], v[158:161], v[166:169], v[56:59]
	s_waitcnt lgkmcnt(5)
	v_mfma_f32_16x16x32_bf16 v[52:55], v[150:153], v[174:177], v[52:55]
	v_mfma_f32_16x16x32_bf16 v[48:51], v[158:161], v[174:177], v[48:51]
	s_waitcnt lgkmcnt(3)
	v_mfma_f32_16x16x32_bf16 v[36:39], v[150:153], v[182:185], v[36:39]
	v_mfma_f32_16x16x32_bf16 v[32:35], v[158:161], v[182:185], v[32:35]
	s_waitcnt lgkmcnt(1)
	v_mfma_f32_16x16x32_bf16 v[20:23], v[150:153], v[190:193], v[20:23]
	v_mfma_f32_16x16x32_bf16 v[16:19], v[158:161], v[190:193], v[16:19]
	v_mfma_f32_16x16x32_bf16 v[60:63], v[154:157], v[170:173], v[60:63]
	v_mfma_f32_16x16x32_bf16 v[56:59], v[162:165], v[170:173], v[56:59]
	v_mfma_f32_16x16x32_bf16 v[52:55], v[154:157], v[178:181], v[52:55]
	v_mfma_f32_16x16x32_bf16 v[48:51], v[162:165], v[178:181], v[48:51]
	v_mfma_f32_16x16x32_bf16 v[36:39], v[154:157], v[186:189], v[36:39]
	v_mfma_f32_16x16x32_bf16 v[32:35], v[162:165], v[186:189], v[32:35]
	s_waitcnt lgkmcnt(0)
	v_mfma_f32_16x16x32_bf16 v[20:23], v[154:157], v[198:201], v[20:23]
	v_mfma_f32_16x16x32_bf16 v[16:19], v[162:165], v[198:201], v[16:19]
	s_setprio 0
	s_barrier
; #define PG8_STAGE(bufoff, gbase, voff) do { _Pragma("unroll") for (int _i = 0; _i < 2; ++_i) \
;         __builtin_amdgcn_global_load_lds((const unsigned*)((const char*)(gbase) + (voff)[_i]), (LAS unsigned*)(lds + (bufoff) + ldsw + _i * 8192), 16, 0, 0); } while (0)
; #define PG8_LDA(dst, b, h) do { _Pragma("unroll") for (int m = 0; m < 4; ++m) _Pragma("unroll") for (int k = 0; k < 2; ++k) dst[m][k] = *(const LAS bf16x8*)(lds + PG8_SA(b, h) + aoff + m * 2048 + k * 1024); } while (0)
; #define PG8_LDB(dst, b, h) do { _Pragma("unroll") for (int n = 0; n < 2; ++n) _Pragma("unroll") for (int k = 0; k < 2; ++k) dst[n][k] = *(const LAS bf16x8*)(lds + PG8_SB(b, h) + boff + n * 2048 + k * 1024); } while (0)
; #define PG8_MMA(ai, bj, At, Bt) do { __builtin_amdgcn_s_setprio(1); _Pragma("unroll") for (int m = 0; m < 4; ++m) _Pragma("unroll") for (int n = 0; n < 2; ++n) _Pragma("unroll") for (int k = 0; k < 2; ++k) \
;         acc[ai][bj][m][n] = __builtin_amdgcn_mfma_f32_16x16x32_bf16(Bt[n][k], At[m][k], acc[ai][bj][m][n], 0, 0, 0); __builtin_amdgcn_s_setprio(0); } while (0)
; #define PG8_WAIT_V(n) asm volatile("s_waitcnt vmcnt(" #n ")" ::: "memory")
; #define PG8_WAIT_L(n) asm volatile("s_waitcnt lgkmcnt(" #n ")" ::: "memory")
; #define PG8_BAR __builtin_amdgcn_s_barrier()
; #define PG8_SCHED __builtin_amdgcn_sched_barrier(0)
; template <class Map, class Epi>
; DI void gemm_phase(LAS unsigned char* lds, const Map& MP, const Epi& E, const int nM, const int nN, const int K, const int lda, const int ldb) {
;     ...
;             PG8_STAGE(PG8_SB(0, 1), b2 + hstepB, voffB);
;             PG8_WAIT_V(6); PG8_BAR; PG8_MMA(1, 1, At, B1); PG8_BAR;
;             PG8_LDB(B0, 1, 0); PG8_SCHED; PG8_LDA(At, 1, 0); PG8_STAGE(PG8_SA(0, 1), a2 + hstepA, voffA);
;             PG8_WAIT_L(8); PG8_BAR; PG8_WAIT_L(0); PG8_MMA(0, 0, At, B0); PG8_BAR; PG8_SCHED;
;             PG8_LDB(B1, 1, 1); PG8_STAGE(PG8_SB(1, 0), b3, voffB);
;             PG8_BAR; PG8_WAIT_L(0); PG8_MMA(0, 1, At, B1); PG8_BAR;
;             PG8_LDA(At, 1, 1); PG8_STAGE(PG8_SA(1, 0), a3, voffA);
	s_add_u32 s56, s22, 0x80000
	s_addc_u32 s57, s23, 0
	s_add_i32 s3, s45, s29
	s_mov_b32 m0, s3
	s_nop 0
	global_load_lds_dwordx4 v132, s[56:57]
	s_add_i32 m0, s3, 0x2000
	s_nop 0
	global_load_lds_dwordx4 v128, s[56:57]
	s_waitcnt vmcnt(6)
	s_barrier
	s_setprio 1
	v_mfma_f32_16x16x32_bf16 v[44:47], v[202:205], v[166:169], v[44:47]
	v_mfma_f32_16x16x32_bf16 v[40:43], v[210:213], v[166:169], v[40:43]
	v_mfma_f32_16x16x32_bf16 v[28:31], v[202:205], v[174:177], v[28:31]
	v_mfma_f32_16x16x32_bf16 v[24:27], v[210:213], v[174:177], v[24:27]
	v_mfma_f32_16x16x32_bf16 v[12:15], v[202:205], v[182:185], v[12:15]
	v_mfma_f32_16x16x32_bf16 v[8:11], v[210:213], v[182:185], v[8:11]
	v_mfma_f32_16x16x32_bf16 v[4:7], v[202:205], v[190:193], v[4:7]
	v_mfma_f32_16x16x32_bf16 v[0:3], v[210:213], v[190:193], v[0:3]
	v_mfma_f32_16x16x32_bf16 v[44:47], v[206:209], v[170:173], v[44:47]
	v_mfma_f32_16x16x32_bf16 v[40:43], v[214:217], v[170:173], v[40:43]
	v_mfma_f32_16x16x32_bf16 v[28:31], v[206:209], v[178:181], v[28:31]
	v_mfma_f32_16x16x32_bf16 v[24:27], v[214:217], v[178:181], v[24:27]
	v_mfma_f32_16x16x32_bf16 v[12:15], v[206:209], v[186:189], v[12:15]
	v_mfma_f32_16x16x32_bf16 v[8:11], v[214:217], v[186:189], v[8:11]
	v_mfma_f32_16x16x32_bf16 v[4:7], v[206:209], v[198:201], v[4:7]
	v_mfma_f32_16x16x32_bf16 v[0:3], v[214:217], v[198:201], v[0:3]
	s_setprio 0
	s_add_i32 s3, 0, 0x18000
	v_add_u32_e32 v162, s3, v146
	s_barrier
	ds_read_b128 v[150:153], v162
	ds_read_b128 v[154:157], v162 offset:1024
	ds_read_b128 v[158:161], v162 offset:2048
	ds_read_b128 v[162:165], v162 offset:3072
	s_add_u32 s24, s24, 0x80000
	s_addc_u32 s25, s25, 0
	s_mov_b32 m0, s34
	ds_read_b128 v[166:169], v148 offset:32768
	ds_read_b128 v[170:173], v148 offset:33792
	ds_read_b128 v[174:177], v148 offset:34816
	ds_read_b128 v[178:181], v148 offset:35840
	ds_read_b128 v[182:185], v148 offset:36864
	ds_read_b128 v[186:189], v148 offset:37888
	ds_read_b128 v[190:193], v148 offset:38912
	ds_read_b128 v[198:201], v148 offset:39936
	global_load_lds_dwordx4 v134, s[24:25]
	s_mov_b32 m0, s35
	s_nop 0
	global_load_lds_dwordx4 v130, s[24:25]
	s_waitcnt lgkmcnt(8)
	s_barrier
	s_setprio 1
	s_waitcnt lgkmcnt(7)
	v_mfma_f32_16x16x32_bf16 v[124:127], v[150:153], v[166:169], v[124:127]
	v_mfma_f32_16x16x32_bf16 v[120:123], v[158:161], v[166:169], v[120:123]
	s_waitcnt lgkmcnt(5)
	v_mfma_f32_16x16x32_bf16 v[116:119], v[150:153], v[174:177], v[116:119]
	v_mfma_f32_16x16x32_bf16 v[112:115], v[158:161], v[174:177], v[112:115]
	s_waitcnt lgkmcnt(3)
	v_mfma_f32_16x16x32_bf16 v[100:103], v[150:153], v[182:185], v[100:103]
	v_mfma_f32_16x16x32_bf16 v[96:99], v[158:161], v[182:185], v[96:99]
	s_waitcnt lgkmcnt(1)
	v_mfma_f32_16x16x32_bf16 v[84:87], v[150:153], v[190:193], v[84:87]
	v_mfma_f32_16x16x32_bf16 v[80:83], v[158:161], v[190:193], v[80:83]
	v_mfma_f32_16x16x32_bf16 v[124:127], v[154:157], v[170:173], v[124:127]
	v_mfma_f32_16x16x32_bf16 v[120:123], v[162:165], v[170:173], v[120:123]
	v_mfma_f32_16x16x32_bf16 v[116:119], v[154:157], v[178:181], v[116:119]
	v_mfma_f32_16x16x32_bf16 v[112:115], v[162:165], v[178:181], v[112:115]
	v_mfma_f32_16x16x32_bf16 v[100:103], v[154:157], v[186:189], v[100:103]
	v_mfma_f32_16x16x32_bf16 v[96:99], v[162:165], v[186:189], v[96:99]
	s_waitcnt lgkmcnt(0)
	v_mfma_f32_16x16x32_bf16 v[84:87], v[154:157], v[198:201], v[84:87]
	v_mfma_f32_16x16x32_bf16 v[80:83], v[162:165], v[198:201], v[80:83]
	s_setprio 0
	s_barrier
	s_add_i32 s24, 0, 0x1c000
	s_add_i32 s3, s3, s29
	v_add_u32_e32 v196, s24, v146
	v_lshl_add_u64 v[194:195], v[194:195], 0, s[8:9]
	s_mov_b32 m0, s3
	ds_read_b128 v[202:205], v196
	ds_read_b128 v[206:209], v196 offset:1024
	ds_read_b128 v[210:213], v196 offset:2048
	ds_read_b128 v[214:217], v196 offset:3072
	global_load_lds_dwordx4 v[194:195], off
	v_lshl_add_u64 v[194:195], v[218:219], 0, s[8:9]
	s_add_i32 m0, s3, 0x2000
	s_nop 0
	global_load_lds_dwordx4 v[194:195], off
	s_barrier
	s_setprio 1
	s_waitcnt lgkmcnt(3)
	v_mfma_f32_16x16x32_bf16 v[108:111], v[202:205], v[166:169], v[108:111]
	s_waitcnt lgkmcnt(1)
	v_mfma_f32_16x16x32_bf16 v[104:107], v[210:213], v[166:169], v[104:107]
	v_mfma_f32_16x16x32_bf16 v[92:95], v[202:205], v[174:177], v[92:95]
	v_mfma_f32_16x16x32_bf16 v[88:91], v[210:213], v[174:177], v[88:91]
	v_mfma_f32_16x16x32_bf16 v[76:79], v[202:205], v[182:185], v[76:79]
	v_mfma_f32_16x16x32_bf16 v[72:75], v[210:213], v[182:185], v[72:75]
	v_mfma_f32_16x16x32_bf16 v[68:71], v[202:205], v[190:193], v[68:71]
	v_mfma_f32_16x16x32_bf16 v[64:67], v[210:213], v[190:193], v[64:67]
	v_mfma_f32_16x16x32_bf16 v[108:111], v[206:209], v[170:173], v[108:111]
	s_waitcnt lgkmcnt(0)
	v_mfma_f32_16x16x32_bf16 v[104:107], v[214:217], v[170:173], v[104:107]
	v_mfma_f32_16x16x32_bf16 v[92:95], v[206:209], v[178:181], v[92:95]
	v_mfma_f32_16x16x32_bf16 v[88:91], v[214:217], v[178:181], v[88:91]
	v_mfma_f32_16x16x32_bf16 v[76:79], v[206:209], v[186:189], v[76:79]
	v_mfma_f32_16x16x32_bf16 v[72:75], v[214:217], v[186:189], v[72:75]
	v_mfma_f32_16x16x32_bf16 v[68:71], v[206:209], v[198:201], v[68:71]
	v_mfma_f32_16x16x32_bf16 v[64:67], v[214:217], v[198:201], v[64:67]
	s_setprio 0
	s_mov_b32 m0, s39
	v_lshl_add_u64 v[194:195], v[220:221], 0, s[8:9]
	s_barrier
	ds_read_b128 v[166:169], v148 offset:49152
	ds_read_b128 v[170:173], v148 offset:50176
	ds_read_b128 v[174:177], v148 offset:51200
	ds_read_b128 v[178:181], v148 offset:52224
	ds_read_b128 v[182:185], v148 offset:53248
	ds_read_b128 v[186:189], v148 offset:54272
	ds_read_b128 v[190:193], v148 offset:55296
	ds_read_b128 v[198:201], v148 offset:56320
	global_load_lds_dwordx4 v[194:195], off
	v_lshl_add_u64 v[194:195], v[222:223], 0, s[8:9]
	s_mov_b32 m0, s42
	s_nop 0
	global_load_lds_dwordx4 v[194:195], off
	s_barrier
; DI unsigned pack2(float a, float b) { f32x2 v = {a, b}; hwbf16x2 r = __builtin_convertvector(v, hwbf16x2); return __builtin_bit_cast(unsigned, r); }
; #define PG8_STAGE(bufoff, gbase, voff) do { _Pragma("unroll") for (int _i = 0; _i < 2; ++_i) \
;         __builtin_amdgcn_global_load_lds((const unsigned*)((const char*)(gbase) + (voff)[_i]), (LAS unsigned*)(lds + (bufoff) + ldsw + _i * 8192), 16, 0, 0); } while (0)
; #define PG8_MMA(ai, bj, At, Bt) do { __builtin_amdgcn_s_setprio(1); _Pragma("unroll") for (int m = 0; m < 4; ++m) _Pragma("unroll") for (int n = 0; n < 2; ++n) _Pragma("unroll") for (int k = 0; k < 2; ++k) \
;         acc[ai][bj][m][n] = __builtin_amdgcn_mfma_f32_16x16x32_bf16(Bt[n][k], At[m][k], acc[ai][bj][m][n], 0, 0, 0); __builtin_amdgcn_s_setprio(0); } while (0)
; #define PG8_WAIT_V(n) asm volatile("s_waitcnt vmcnt(" #n ")" ::: "memory")
; #define PG8_WAIT_L(n) asm volatile("s_waitcnt lgkmcnt(" #n ")" ::: "memory")
; #define PG8_BAR __builtin_amdgcn_s_barrier()
; #define PG8_SCHED __builtin_amdgcn_sched_barrier(0)
;     DI void operator()(const f32x4 (&acc)[2][2][4][2], const Unit& u, int wr, int wc, int fr, int fq) const {
;         bf16_t* O = O1; int ldc = ldc1, pn = u.pn; if (pn >= split) { O = O2; ldc = ldc2; pn -= split; }
;         const int row0 = u.pm * BM + wr * 64 + fr, col0 = pn * BM + wc * 32 + 8 * fq;
; #pragma unroll
;         for (int ai = 0; ai < 2; ++ai)
; #pragma unroll
;             for (int m = 0; m < 4; ++m) { bf16_t* rowp = O + (size_t)(row0 + ai * HALF + m * 16) * ldc + col0;
; #pragma unroll
;                 for (int bj = 0; bj < 2; ++bj) { const f32x4 v0 = acc[ai][bj][m][0], v1 = acc[ai][bj][m][1];
;                     u32x4 o; o[0] = pack2(v0[0], v0[1]); o[1] = pack2(v0[2], v0[3]); o[2] = pack2(v1[0], v1[1]); o[3] = pack2(v1[2], v1[3]);
;                     *(u32x4*)(rowp + bj * HALF) = o; } }
;     }
; template <class Map, class Epi>
; DI void gemm_phase(LAS unsigned char* lds, const Map& MP, const Epi& E, const int nM, const int nN, const int K, const int lda, const int ldb) {
;     ...
;             PG8_BAR; PG8_WAIT_L(0); PG8_MMA(1, 0, At, B0); PG8_BAR; PG8_SCHED;
;             PG8_STAGE(PG8_SB(1, 1), b3 + hstepB, voffB);
;             PG8_WAIT_V(6); PG8_BAR; PG8_MMA(1, 1, At, B1); PG8_BAR;
;         }
;         { int frr = fr, fqq = fq; asm volatile("" : "+v"(frr), "+v"(fqq)); E(acc, cur, wr, wc, frr, fqq); }
	s_setprio 1
	s_waitcnt lgkmcnt(7)
	v_mfma_f32_16x16x32_bf16 v[60:63], v[150:153], v[166:169], v[60:63]
	v_mfma_f32_16x16x32_bf16 v[56:59], v[158:161], v[166:169], v[56:59]
	s_waitcnt lgkmcnt(5)
	v_mfma_f32_16x16x32_bf16 v[52:55], v[150:153], v[174:177], v[52:55]
	v_mfma_f32_16x16x32_bf16 v[48:51], v[158:161], v[174:177], v[48:51]
	s_waitcnt lgkmcnt(3)
	v_mfma_f32_16x16x32_bf16 v[36:39], v[150:153], v[182:185], v[36:39]
	v_mfma_f32_16x16x32_bf16 v[32:35], v[158:161], v[182:185], v[32:35]
	s_waitcnt lgkmcnt(1)
	v_mfma_f32_16x16x32_bf16 v[20:23], v[150:153], v[190:193], v[20:23]
	v_mfma_f32_16x16x32_bf16 v[16:19], v[158:161], v[190:193], v[16:19]
	v_mfma_f32_16x16x32_bf16 v[60:63], v[154:157], v[170:173], v[60:63]
	v_mfma_f32_16x16x32_bf16 v[56:59], v[162:165], v[170:173], v[56:59]
	v_mfma_f32_16x16x32_bf16 v[52:55], v[154:157], v[178:181], v[52:55]
	v_mfma_f32_16x16x32_bf16 v[48:51], v[162:165], v[178:181], v[48:51]
	v_mfma_f32_16x16x32_bf16 v[36:39], v[154:157], v[186:189], v[36:39]
	v_mfma_f32_16x16x32_bf16 v[32:35], v[162:165], v[186:189], v[32:35]
	s_waitcnt lgkmcnt(0)
	v_mfma_f32_16x16x32_bf16 v[20:23], v[154:157], v[198:201], v[20:23]
	v_mfma_f32_16x16x32_bf16 v[16:19], v[162:165], v[198:201], v[16:19]
	s_setprio 0
	s_barrier
	s_add_u32 s22, s22, 0x80080
	s_addc_u32 s23, s23, 0
	s_add_i32 s3, s24, s29
	s_mov_b32 m0, s3
	s_nop 0
	global_load_lds_dwordx4 v132, s[22:23]
	s_add_i32 m0, s3, 0x2000
	s_nop 0
	global_load_lds_dwordx4 v128, s[22:23]
	s_waitcnt vmcnt(6)
	s_barrier
	s_setprio 1
	v_mfma_f32_16x16x32_bf16 v[44:47], v[202:205], v[166:169], v[44:47]
	v_mfma_f32_16x16x32_bf16 v[40:43], v[210:213], v[166:169], v[40:43]
	v_mfma_f32_16x16x32_bf16 v[28:31], v[202:205], v[174:177], v[28:31]
	v_mfma_f32_16x16x32_bf16 v[24:27], v[210:213], v[174:177], v[24:27]
	v_mfma_f32_16x16x32_bf16 v[12:15], v[202:205], v[182:185], v[12:15]
	v_mfma_f32_16x16x32_bf16 v[8:11], v[210:213], v[182:185], v[8:11]
	v_mfma_f32_16x16x32_bf16 v[4:7], v[202:205], v[190:193], v[4:7]
	v_mfma_f32_16x16x32_bf16 v[0:3], v[210:213], v[190:193], v[0:3]
	v_mfma_f32_16x16x32_bf16 v[44:47], v[206:209], v[170:173], v[44:47]
	v_mfma_f32_16x16x32_bf16 v[40:43], v[214:217], v[170:173], v[40:43]
	v_mfma_f32_16x16x32_bf16 v[28:31], v[206:209], v[178:181], v[28:31]
	v_mfma_f32_16x16x32_bf16 v[24:27], v[214:217], v[178:181], v[24:27]
	v_mfma_f32_16x16x32_bf16 v[12:15], v[206:209], v[186:189], v[12:15]
	v_mfma_f32_16x16x32_bf16 v[8:11], v[214:217], v[186:189], v[8:11]
	v_mfma_f32_16x16x32_bf16 v[4:7], v[206:209], v[198:201], v[4:7]
	v_mfma_f32_16x16x32_bf16 v[0:3], v[214:217], v[198:201], v[0:3]
	s_setprio 0
	s_add_i32 s54, s54, 2
	s_add_u32 s52, s52, 0x100
	s_addc_u32 s53, s53, 0
	s_add_u32 s20, s20, 0x100
	s_addc_u32 s21, s21, 0
	s_cmp_gt_u32 s54, 29
	s_barrier
	s_cbranch_scc0 .LBB1_693
	s_lshl_b32 s3, s10, 8
	v_mov_b32_e32 v150, v144
	v_mov_b32_e32 v151, v145
	s_add_i32 s3, s3, s37
	v_cvt_pk_bf16_f32 v68, v68, v69
	v_add_u32_e32 v154, s3, v150
	s_lshl_b32 s3, s47, 8
	s_or_b32 s3, s3, s38
	v_lshl_add_u32 v150, v151, 3, s3
	v_ashrrev_i32_e32 v151, 31, v150
	v_lshl_add_u64 v[150:151], v[150:151], 1, s[6:7]
	v_cvt_pk_bf16_f32 v69, v70, v71
	v_cvt_pk_bf16_f32 v70, v64, v65
	v_add_u32_e32 v64, 0x80, v154
	v_mad_i64_i32 v[152:153], s[20:21], v154, s46, v[150:151]
	v_cvt_pk_bf16_f32 v108, v108, v109
	v_cvt_pk_bf16_f32 v109, v110, v111
	v_cvt_pk_bf16_f32 v110, v104, v105
	v_cvt_pk_bf16_f32 v111, v106, v107
	v_add_u32_e32 v104, 16, v154
	v_mad_i64_i32 v[64:65], s[20:21], v64, s46, v[150:151]
	v_cvt_pk_bf16_f32 v44, v44, v45
	v_cvt_pk_bf16_f32 v45, v46, v47
	v_cvt_pk_bf16_f32 v46, v40, v41
	v_cvt_pk_bf16_f32 v47, v42, v43
	v_add_u32_e32 v40, 0x90, v154
	global_store_dwordx4 v[152:153], v[108:111], off offset:256
	v_cvt_pk_bf16_f32 v92, v92, v93
	v_cvt_pk_bf16_f32 v93, v94, v95
	v_mad_i64_i32 v[108:109], s[20:21], v104, s46, v[150:151]
	v_cvt_pk_bf16_f32 v94, v88, v89
	v_cvt_pk_bf16_f32 v95, v90, v91
	v_add_u32_e32 v88, 32, v154
	global_store_dwordx4 v[64:65], v[44:47], off offset:256
	v_cvt_pk_bf16_f32 v28, v28, v29
	v_cvt_pk_bf16_f32 v29, v30, v31
	v_mad_i64_i32 v[44:45], s[20:21], v40, s46, v[150:151]
	v_cvt_pk_bf16_f32 v30, v24, v25
	v_cvt_pk_bf16_f32 v31, v26, v27
	v_add_u32_e32 v24, 0xa0, v154
	global_store_dwordx4 v[108:109], v[92:95], off offset:256
	v_cvt_pk_bf16_f32 v76, v76, v77
	v_cvt_pk_bf16_f32 v77, v78, v79
	v_mad_i64_i32 v[92:93], s[20:21], v88, s46, v[150:151]
	v_cvt_pk_bf16_f32 v78, v72, v73
	v_cvt_pk_bf16_f32 v79, v74, v75
	v_add_u32_e32 v72, 48, v154
	global_store_dwordx4 v[44:45], v[28:31], off offset:256
	v_cvt_pk_bf16_f32 v12, v12, v13
	v_cvt_pk_bf16_f32 v13, v14, v15
	v_mad_i64_i32 v[28:29], s[20:21], v24, s46, v[150:151]
	v_cvt_pk_bf16_f32 v14, v8, v9
	v_cvt_pk_bf16_f32 v15, v10, v11
	v_add_u32_e32 v8, 0xb0, v154
	global_store_dwordx4 v[92:93], v[76:79], off offset:256
	global_store_dwordx4 v[28:29], v[12:15], off offset:256
	v_cvt_pk_bf16_f32 v124, v124, v125
	v_mad_i64_i32 v[76:77], s[20:21], v72, s46, v[150:151]
	v_mad_i64_i32 v[12:13], s[20:21], v8, s46, v[150:151]
	v_cvt_pk_bf16_f32 v125, v126, v127
	v_cvt_pk_bf16_f32 v126, v120, v121
	v_cvt_pk_bf16_f32 v127, v122, v123
	v_cvt_pk_bf16_f32 v104, v116, v117
	v_cvt_pk_bf16_f32 v105, v118, v119
	v_cvt_pk_bf16_f32 v106, v112, v113
	v_cvt_pk_bf16_f32 v107, v114, v115
	v_cvt_pk_bf16_f32 v88, v100, v101
	v_cvt_pk_bf16_f32 v89, v102, v103
	v_cvt_pk_bf16_f32 v90, v96, v97
	v_cvt_pk_bf16_f32 v91, v98, v99
	v_cvt_pk_bf16_f32 v72, v84, v85
	v_cvt_pk_bf16_f32 v73, v86, v87
	v_cvt_pk_bf16_f32 v74, v80, v81
	v_cvt_pk_bf16_f32 v75, v82, v83
	v_cvt_pk_bf16_f32 v71, v66, v67
	v_cvt_pk_bf16_f32 v60, v60, v61
	v_cvt_pk_bf16_f32 v61, v62, v63
	v_cvt_pk_bf16_f32 v62, v56, v57
	v_cvt_pk_bf16_f32 v63, v58, v59
	v_cvt_pk_bf16_f32 v40, v52, v53
	v_cvt_pk_bf16_f32 v41, v54, v55
	v_cvt_pk_bf16_f32 v42, v48, v49
	v_cvt_pk_bf16_f32 v43, v50, v51
	v_cvt_pk_bf16_f32 v24, v36, v37
	v_cvt_pk_bf16_f32 v25, v38, v39
	v_cvt_pk_bf16_f32 v26, v32, v33
	v_cvt_pk_bf16_f32 v27, v34, v35
	v_cvt_pk_bf16_f32 v8, v20, v21
	v_cvt_pk_bf16_f32 v9, v22, v23
	v_cvt_pk_bf16_f32 v10, v16, v17
	v_cvt_pk_bf16_f32 v11, v18, v19
	v_cvt_pk_bf16_f32 v4, v4, v5
	v_cvt_pk_bf16_f32 v5, v6, v7
	v_cvt_pk_bf16_f32 v6, v0, v1
	v_cvt_pk_bf16_f32 v7, v2, v3
	s_and_b64 vcc, exec, s[40:41]
	s_mov_b32 s47, s12
	s_mov_b32 s10, s14
	s_mov_b64 s[20:21], s[18:19]
	s_mov_b64 s[22:23], s[16:17]
	global_store_dwordx4 v[152:153], v[124:127], off
	global_store_dwordx4 v[108:109], v[104:107], off
	global_store_dwordx4 v[92:93], v[88:91], off
	global_store_dwordx4 v[76:77], v[72:75], off
	global_store_dwordx4 v[76:77], v[68:71], off offset:256
	global_store_dwordx4 v[64:65], v[60:63], off
	global_store_dwordx4 v[44:45], v[40:43], off
	global_store_dwordx4 v[28:29], v[24:27], off
	global_store_dwordx4 v[12:13], v[8:11], off
	global_store_dwordx4 v[12:13], v[4:7], off offset:256
	s_cbranch_vccz .LBB1_690
	s_waitcnt vmcnt(0)
	s_cmpk_gt_u32 s4, 0xff
	s_cbranch_scc1 .LBB1_697
	s_barrier

; #define PG8_STAGE(bufoff, gbase, voff) do { _Pragma("unroll") for (int _i = 0; _i < 2; ++_i) \
;         __builtin_amdgcn_global_load_lds((const unsigned*)((const char*)(gbase) + (voff)[_i]), (LAS unsigned*)(lds + (bufoff) + ldsw + _i * 8192), 16, 0, 0); } while (0)
; #define PG8_LDA(dst, b, h) do { _Pragma("unroll") for (int m = 0; m < 4; ++m) _Pragma("unroll") for (int k = 0; k < 2; ++k) dst[m][k] = *(const LAS bf16x8*)(lds + PG8_SA(b, h) + aoff + m * 2048 + k * 1024); } while (0)
; #define PG8_LDB(dst, b, h) do { _Pragma("unroll") for (int n = 0; n < 2; ++n) _Pragma("unroll") for (int k = 0; k < 2; ++k) dst[n][k] = *(const LAS bf16x8*)(lds + PG8_SB(b, h) + boff + n * 2048 + k * 1024); } while (0)
; #define PG8_MMA(ai, bj, At, Bt) do { __builtin_amdgcn_s_setprio(1); _Pragma("unroll") for (int m = 0; m < 4; ++m) _Pragma("unroll") for (int n = 0; n < 2; ++n) _Pragma("unroll") for (int k = 0; k < 2; ++k) \
;         acc[ai][bj][m][n] = __builtin_amdgcn_mfma_f32_16x16x32_bf16(Bt[n][k], At[m][k], acc[ai][bj][m][n], 0, 0, 0); __builtin_amdgcn_s_setprio(0); } while (0)
; #define PG8_WAIT_V(n) asm volatile("s_waitcnt vmcnt(" #n ")" ::: "memory")
; #define PG8_WAIT_L(n) asm volatile("s_waitcnt lgkmcnt(" #n ")" ::: "memory")
; #define PG8_BAR __builtin_amdgcn_s_barrier()
; #define PG8_SCHED __builtin_amdgcn_sched_barrier(0)
; template <class Map, class Epi>
; DI void gemm_phase(LAS unsigned char* lds, const Map& MP, const Epi& E, const int nM, const int nN, const int K, const int lda, const int ldb) {
;     ...
;             PG8_LDB(B0, 0, 0); PG8_SCHED; PG8_LDA(At, 0, 0); PG8_STAGE(PG8_SA(1, 1), a1 + hstepA, voffA);
;             PG8_WAIT_L(8); PG8_BAR; PG8_WAIT_L(0); PG8_MMA(0, 0, At, B0); PG8_BAR; PG8_SCHED;
;             PG8_LDB(B1, 0, 1); PG8_STAGE(PG8_SB(0, 0), b2, voffB);
;             PG8_BAR; PG8_WAIT_L(0); PG8_MMA(0, 1, At, B1); PG8_BAR;
;             PG8_LDA(At, 0, 1); PG8_STAGE(PG8_SA(0, 0), a2, voffA);
;             PG8_BAR; PG8_WAIT_L(0); PG8_MMA(1, 0, At, B0); PG8_BAR; PG8_SCHED;
;             PG8_STAGE(PG8_SB(0, 1), b2 + hstepB, voffB);
;             PG8_WAIT_V(6); PG8_BAR; PG8_MMA(1, 1, At, B1); PG8_BAR;
.LBB1_925:
	ds_read_b128 v[152:155], v149
	ds_read_b128 v[156:159], v149 offset:1024
	ds_read_b128 v[160:163], v149 offset:2048
	ds_read_b128 v[164:167], v149 offset:3072
	s_add_u32 s3, s10, 0xfff80080
	s_addc_u32 s12, s11, -1
	s_cmp_eq_u32 s48, 28
	s_cselect_b32 s15, s4, s12
	s_cselect_b32 s14, s5, s3
	s_cselect_b32 s13, s37, s47
	s_cselect_b32 s12, s38, s39
	s_add_i32 m0, s24, 0xc000
	ds_read_b128 v[168:171], v150
	ds_read_b128 v[172:175], v150 offset:1024
	ds_read_b128 v[176:179], v150 offset:2048
	ds_read_b128 v[180:183], v150 offset:3072
	ds_read_b128 v[184:187], v150 offset:4096
	ds_read_b128 v[188:191], v150 offset:5120
	ds_read_b128 v[192:195], v150 offset:6144
	ds_read_b128 v[198:201], v150 offset:7168
	global_load_lds_dwordx4 v138, s[10:11]
	s_add_i32 m0, s24, 0xe000
	s_nop 0
	global_load_lds_dwordx4 v136, s[10:11]
	s_waitcnt lgkmcnt(8)
	s_barrier
	s_setprio 1
	s_waitcnt lgkmcnt(7)
	v_mfma_f32_16x16x32_bf16 v[124:127], v[152:155], v[168:171], v[124:127]
	v_mfma_f32_16x16x32_bf16 v[120:123], v[160:163], v[168:171], v[120:123]
	s_waitcnt lgkmcnt(5)
	v_mfma_f32_16x16x32_bf16 v[108:111], v[152:155], v[176:179], v[108:111]
	v_mfma_f32_16x16x32_bf16 v[104:107], v[160:163], v[176:179], v[104:107]
	s_waitcnt lgkmcnt(3)
	v_mfma_f32_16x16x32_bf16 v[92:95], v[152:155], v[184:187], v[92:95]
	v_mfma_f32_16x16x32_bf16 v[88:91], v[160:163], v[184:187], v[88:91]
	s_waitcnt lgkmcnt(1)
	v_mfma_f32_16x16x32_bf16 v[76:79], v[152:155], v[192:195], v[76:79]
	v_mfma_f32_16x16x32_bf16 v[72:75], v[160:163], v[192:195], v[72:75]
	v_mfma_f32_16x16x32_bf16 v[124:127], v[156:159], v[172:175], v[124:127]
	v_mfma_f32_16x16x32_bf16 v[120:123], v[164:167], v[172:175], v[120:123]
	v_mfma_f32_16x16x32_bf16 v[108:111], v[156:159], v[180:183], v[108:111]
	v_mfma_f32_16x16x32_bf16 v[104:107], v[164:167], v[180:183], v[104:107]
	v_mfma_f32_16x16x32_bf16 v[92:95], v[156:159], v[188:191], v[92:95]
	v_mfma_f32_16x16x32_bf16 v[88:91], v[164:167], v[188:191], v[88:91]
	s_waitcnt lgkmcnt(0)
	v_mfma_f32_16x16x32_bf16 v[76:79], v[156:159], v[198:201], v[76:79]
	v_mfma_f32_16x16x32_bf16 v[72:75], v[164:167], v[198:201], v[72:75]
	s_setprio 0
	s_barrier
	s_add_i32 s3, s35, s22
	v_lshl_add_u64 v[144:145], s[12:13], 0, v[132:133]
	s_mov_b32 m0, s3
	ds_read_b128 v[202:205], v151
	ds_read_b128 v[206:209], v151 offset:1024
	ds_read_b128 v[210:213], v151 offset:2048
	ds_read_b128 v[214:217], v151 offset:3072
	global_load_lds_dwordx4 v[144:145], off
	v_lshl_add_u64 v[218:219], s[12:13], 0, v[128:129]
	s_add_i32 m0, s3, 0x2000
	s_nop 0
	global_load_lds_dwordx4 v[218:219], off
	s_barrier
	s_setprio 1
	s_waitcnt lgkmcnt(3)
	v_mfma_f32_16x16x32_bf16 v[116:119], v[202:205], v[168:171], v[116:119]
	s_waitcnt lgkmcnt(1)
	v_mfma_f32_16x16x32_bf16 v[112:115], v[210:213], v[168:171], v[112:115]
	v_mfma_f32_16x16x32_bf16 v[100:103], v[202:205], v[176:179], v[100:103]
	v_mfma_f32_16x16x32_bf16 v[96:99], v[210:213], v[176:179], v[96:99]
	v_mfma_f32_16x16x32_bf16 v[84:87], v[202:205], v[184:187], v[84:87]
	v_mfma_f32_16x16x32_bf16 v[80:83], v[210:213], v[184:187], v[80:83]
	v_mfma_f32_16x16x32_bf16 v[68:71], v[202:205], v[192:195], v[68:71]
	v_mfma_f32_16x16x32_bf16 v[64:67], v[210:213], v[192:195], v[64:67]
	v_mfma_f32_16x16x32_bf16 v[116:119], v[206:209], v[172:175], v[116:119]
	s_waitcnt lgkmcnt(0)
	v_mfma_f32_16x16x32_bf16 v[112:115], v[214:217], v[172:175], v[112:115]
	v_mfma_f32_16x16x32_bf16 v[100:103], v[206:209], v[180:183], v[100:103]
	v_mfma_f32_16x16x32_bf16 v[96:99], v[214:217], v[180:183], v[96:99]
	v_mfma_f32_16x16x32_bf16 v[84:87], v[206:209], v[188:191], v[84:87]
	v_mfma_f32_16x16x32_bf16 v[80:83], v[214:217], v[188:191], v[80:83]
	v_mfma_f32_16x16x32_bf16 v[68:71], v[206:209], v[198:201], v[68:71]
	v_mfma_f32_16x16x32_bf16 v[64:67], v[214:217], v[198:201], v[64:67]
	s_setprio 0
	s_mov_b32 m0, s24
	v_lshl_add_u64 v[220:221], s[14:15], 0, v[134:135]
	s_barrier
	ds_read_b128 v[168:171], v150 offset:16384
	ds_read_b128 v[172:175], v150 offset:17408
	ds_read_b128 v[176:179], v150 offset:18432
	ds_read_b128 v[180:183], v150 offset:19456
	ds_read_b128 v[184:187], v150 offset:20480
	ds_read_b128 v[188:191], v150 offset:21504
	ds_read_b128 v[192:195], v150 offset:22528
	ds_read_b128 v[198:201], v150 offset:23552
	global_load_lds_dwordx4 v[220:221], off
	v_lshl_add_u64 v[222:223], s[14:15], 0, v[130:131]
	s_mov_b32 m0, s9
	s_nop 0
	global_load_lds_dwordx4 v[222:223], off
	s_barrier
	s_setprio 1
	s_waitcnt lgkmcnt(7)
	v_mfma_f32_16x16x32_bf16 v[60:63], v[152:155], v[168:171], v[60:63]
	v_mfma_f32_16x16x32_bf16 v[56:59], v[160:163], v[168:171], v[56:59]
	s_waitcnt lgkmcnt(5)
	v_mfma_f32_16x16x32_bf16 v[44:47], v[152:155], v[176:179], v[44:47]
	v_mfma_f32_16x16x32_bf16 v[40:43], v[160:163], v[176:179], v[40:43]
	s_waitcnt lgkmcnt(3)
	v_mfma_f32_16x16x32_bf16 v[28:31], v[152:155], v[184:187], v[28:31]
	v_mfma_f32_16x16x32_bf16 v[24:27], v[160:163], v[184:187], v[24:27]
	s_waitcnt lgkmcnt(1)
	v_mfma_f32_16x16x32_bf16 v[12:15], v[152:155], v[192:195], v[12:15]
	v_mfma_f32_16x16x32_bf16 v[8:11], v[160:163], v[192:195], v[8:11]
	v_mfma_f32_16x16x32_bf16 v[60:63], v[156:159], v[172:175], v[60:63]
	v_mfma_f32_16x16x32_bf16 v[56:59], v[164:167], v[172:175], v[56:59]
	v_mfma_f32_16x16x32_bf16 v[44:47], v[156:159], v[180:183], v[44:47]
	v_mfma_f32_16x16x32_bf16 v[40:43], v[164:167], v[180:183], v[40:43]
	v_mfma_f32_16x16x32_bf16 v[28:31], v[156:159], v[188:191], v[28:31]
	v_mfma_f32_16x16x32_bf16 v[24:27], v[164:167], v[188:191], v[24:27]
	s_waitcnt lgkmcnt(0)
	v_mfma_f32_16x16x32_bf16 v[12:15], v[156:159], v[198:201], v[12:15]
	v_mfma_f32_16x16x32_bf16 v[8:11], v[164:167], v[198:201], v[8:11]
	s_setprio 0
	s_barrier
; #define PG8_STAGE(bufoff, gbase, voff) do { _Pragma("unroll") for (int _i = 0; _i < 2; ++_i) \
;         __builtin_amdgcn_global_load_lds((const unsigned*)((const char*)(gbase) + (voff)[_i]), (LAS unsigned*)(lds + (bufoff) + ldsw + _i * 8192), 16, 0, 0); } while (0)
; #define PG8_LDA(dst, b, h) do { _Pragma("unroll") for (int m = 0; m < 4; ++m) _Pragma("unroll") for (int k = 0; k < 2; ++k) dst[m][k] = *(const LAS bf16x8*)(lds + PG8_SA(b, h) + aoff + m * 2048 + k * 1024); } while (0)
; #define PG8_LDB(dst, b, h) do { _Pragma("unroll") for (int n = 0; n < 2; ++n) _Pragma("unroll") for (int k = 0; k < 2; ++k) dst[n][k] = *(const LAS bf16x8*)(lds + PG8_SB(b, h) + boff + n * 2048 + k * 1024); } while (0)
; #define PG8_MMA(ai, bj, At, Bt) do { __builtin_amdgcn_s_setprio(1); _Pragma("unroll") for (int m = 0; m < 4; ++m) _Pragma("unroll") for (int n = 0; n < 2; ++n) _Pragma("unroll") for (int k = 0; k < 2; ++k) \
;         acc[ai][bj][m][n] = __builtin_amdgcn_mfma_f32_16x16x32_bf16(Bt[n][k], At[m][k], acc[ai][bj][m][n], 0, 0, 0); __builtin_amdgcn_s_setprio(0); } while (0)
; #define PG8_WAIT_V(n) asm volatile("s_waitcnt vmcnt(" #n ")" ::: "memory")
; #define PG8_WAIT_L(n) asm volatile("s_waitcnt lgkmcnt(" #n ")" ::: "memory")
; #define PG8_BAR __builtin_amdgcn_s_barrier()
; #define PG8_SCHED __builtin_amdgcn_sched_barrier(0)
; template <class Map, class Epi>
; DI void gemm_phase(LAS unsigned char* lds, const Map& MP, const Epi& E, const int nM, const int nN, const int K, const int lda, const int ldb) {
;     ...
;             PG8_STAGE(PG8_SB(0, 1), b2 + hstepB, voffB);
;             PG8_WAIT_V(6); PG8_BAR; PG8_MMA(1, 1, At, B1); PG8_BAR;
;             PG8_LDB(B0, 1, 0); PG8_SCHED; PG8_LDA(At, 1, 0); PG8_STAGE(PG8_SA(0, 1), a2 + hstepA, voffA);
;             PG8_WAIT_L(8); PG8_BAR; PG8_WAIT_L(0); PG8_MMA(0, 0, At, B0); PG8_BAR; PG8_SCHED;
;             PG8_LDB(B1, 1, 1); PG8_STAGE(PG8_SB(1, 0), b3, voffB);
;             PG8_BAR; PG8_WAIT_L(0); PG8_MMA(0, 1, At, B1); PG8_BAR;
;             PG8_LDA(At, 1, 1); PG8_STAGE(PG8_SA(1, 0), a3, voffA);
	s_add_u32 s56, s12, 0x80000
	s_addc_u32 s57, s13, 0
	s_add_i32 s3, s36, s22
	s_mov_b32 m0, s3
	s_nop 0
	global_load_lds_dwordx4 v132, s[56:57]
	s_add_i32 m0, s3, 0x2000
	s_nop 0
	global_load_lds_dwordx4 v128, s[56:57]
	s_waitcnt vmcnt(6)
	s_barrier
	s_setprio 1
	v_mfma_f32_16x16x32_bf16 v[52:55], v[202:205], v[168:171], v[52:55]
	v_mfma_f32_16x16x32_bf16 v[48:51], v[210:213], v[168:171], v[48:51]
	v_mfma_f32_16x16x32_bf16 v[36:39], v[202:205], v[176:179], v[36:39]
	v_mfma_f32_16x16x32_bf16 v[32:35], v[210:213], v[176:179], v[32:35]
	v_mfma_f32_16x16x32_bf16 v[20:23], v[202:205], v[184:187], v[20:23]
	v_mfma_f32_16x16x32_bf16 v[16:19], v[210:213], v[184:187], v[16:19]
	v_mfma_f32_16x16x32_bf16 v[4:7], v[202:205], v[192:195], v[4:7]
	v_mfma_f32_16x16x32_bf16 v[0:3], v[210:213], v[192:195], v[0:3]
	v_mfma_f32_16x16x32_bf16 v[52:55], v[206:209], v[172:175], v[52:55]
	v_mfma_f32_16x16x32_bf16 v[48:51], v[214:217], v[172:175], v[48:51]
	v_mfma_f32_16x16x32_bf16 v[36:39], v[206:209], v[180:183], v[36:39]
	v_mfma_f32_16x16x32_bf16 v[32:35], v[214:217], v[180:183], v[32:35]
	v_mfma_f32_16x16x32_bf16 v[20:23], v[206:209], v[188:191], v[20:23]
	v_mfma_f32_16x16x32_bf16 v[16:19], v[214:217], v[188:191], v[16:19]
	v_mfma_f32_16x16x32_bf16 v[4:7], v[206:209], v[198:201], v[4:7]
	v_mfma_f32_16x16x32_bf16 v[0:3], v[214:217], v[198:201], v[0:3]
	s_setprio 0
	s_add_i32 s3, 0, 0x18000
	v_add_u32_e32 v164, s3, v148
	s_barrier
	ds_read_b128 v[152:155], v164
	ds_read_b128 v[156:159], v164 offset:1024
	ds_read_b128 v[160:163], v164 offset:2048
	ds_read_b128 v[164:167], v164 offset:3072
	s_add_u32 s14, s14, 0x80000
	s_addc_u32 s15, s15, 0
	s_mov_b32 m0, s25
	ds_read_b128 v[168:171], v150 offset:32768
	ds_read_b128 v[172:175], v150 offset:33792
	ds_read_b128 v[176:179], v150 offset:34816
	ds_read_b128 v[180:183], v150 offset:35840
	ds_read_b128 v[184:187], v150 offset:36864
	ds_read_b128 v[188:191], v150 offset:37888
	ds_read_b128 v[192:195], v150 offset:38912
	ds_read_b128 v[198:201], v150 offset:39936
	global_load_lds_dwordx4 v134, s[14:15]
	s_mov_b32 m0, s26
	s_nop 0
	global_load_lds_dwordx4 v130, s[14:15]
	s_waitcnt lgkmcnt(8)
	s_barrier
	s_setprio 1
	s_waitcnt lgkmcnt(7)
	v_mfma_f32_16x16x32_bf16 v[124:127], v[152:155], v[168:171], v[124:127]
	v_mfma_f32_16x16x32_bf16 v[120:123], v[160:163], v[168:171], v[120:123]
	s_waitcnt lgkmcnt(5)
	v_mfma_f32_16x16x32_bf16 v[108:111], v[152:155], v[176:179], v[108:111]
	v_mfma_f32_16x16x32_bf16 v[104:107], v[160:163], v[176:179], v[104:107]
	s_waitcnt lgkmcnt(3)
	v_mfma_f32_16x16x32_bf16 v[92:95], v[152:155], v[184:187], v[92:95]
	v_mfma_f32_16x16x32_bf16 v[88:91], v[160:163], v[184:187], v[88:91]
	s_waitcnt lgkmcnt(1)
	v_mfma_f32_16x16x32_bf16 v[76:79], v[152:155], v[192:195], v[76:79]
	v_mfma_f32_16x16x32_bf16 v[72:75], v[160:163], v[192:195], v[72:75]
	v_mfma_f32_16x16x32_bf16 v[124:127], v[156:159], v[172:175], v[124:127]
	v_mfma_f32_16x16x32_bf16 v[120:123], v[164:167], v[172:175], v[120:123]
	v_mfma_f32_16x16x32_bf16 v[108:111], v[156:159], v[180:183], v[108:111]
	v_mfma_f32_16x16x32_bf16 v[104:107], v[164:167], v[180:183], v[104:107]
	v_mfma_f32_16x16x32_bf16 v[92:95], v[156:159], v[188:191], v[92:95]
	v_mfma_f32_16x16x32_bf16 v[88:91], v[164:167], v[188:191], v[88:91]
	s_waitcnt lgkmcnt(0)
	v_mfma_f32_16x16x32_bf16 v[76:79], v[156:159], v[198:201], v[76:79]
	v_mfma_f32_16x16x32_bf16 v[72:75], v[164:167], v[198:201], v[72:75]
	s_setprio 0
	s_barrier
	s_add_i32 s14, 0, 0x1c000
	s_add_i32 s3, s3, s22
	v_add_u32_e32 v196, s14, v148
	v_lshl_add_u64 v[144:145], v[144:145], 0, s[44:45]
	s_mov_b32 m0, s3
	ds_read_b128 v[202:205], v196
	ds_read_b128 v[206:209], v196 offset:1024
	ds_read_b128 v[210:213], v196 offset:2048
	ds_read_b128 v[214:217], v196 offset:3072
	global_load_lds_dwordx4 v[144:145], off
	v_lshl_add_u64 v[144:145], v[218:219], 0, s[44:45]
	s_add_i32 m0, s3, 0x2000
	s_nop 0
	global_load_lds_dwordx4 v[144:145], off
	s_barrier
	s_setprio 1
	s_waitcnt lgkmcnt(3)
	v_mfma_f32_16x16x32_bf16 v[116:119], v[202:205], v[168:171], v[116:119]
	s_waitcnt lgkmcnt(1)
	v_mfma_f32_16x16x32_bf16 v[112:115], v[210:213], v[168:171], v[112:115]
	v_mfma_f32_16x16x32_bf16 v[100:103], v[202:205], v[176:179], v[100:103]
	v_mfma_f32_16x16x32_bf16 v[96:99], v[210:213], v[176:179], v[96:99]
	v_mfma_f32_16x16x32_bf16 v[84:87], v[202:205], v[184:187], v[84:87]
	v_mfma_f32_16x16x32_bf16 v[80:83], v[210:213], v[184:187], v[80:83]
	v_mfma_f32_16x16x32_bf16 v[68:71], v[202:205], v[192:195], v[68:71]
	v_mfma_f32_16x16x32_bf16 v[64:67], v[210:213], v[192:195], v[64:67]
	v_mfma_f32_16x16x32_bf16 v[116:119], v[206:209], v[172:175], v[116:119]
	s_waitcnt lgkmcnt(0)
	v_mfma_f32_16x16x32_bf16 v[112:115], v[214:217], v[172:175], v[112:115]
	v_mfma_f32_16x16x32_bf16 v[100:103], v[206:209], v[180:183], v[100:103]
	v_mfma_f32_16x16x32_bf16 v[96:99], v[214:217], v[180:183], v[96:99]
	v_mfma_f32_16x16x32_bf16 v[84:87], v[206:209], v[188:191], v[84:87]
	v_mfma_f32_16x16x32_bf16 v[80:83], v[214:217], v[188:191], v[80:83]
	v_mfma_f32_16x16x32_bf16 v[68:71], v[206:209], v[198:201], v[68:71]
	v_mfma_f32_16x16x32_bf16 v[64:67], v[214:217], v[198:201], v[64:67]
	s_setprio 0
	s_mov_b32 m0, s30
	v_lshl_add_u64 v[144:145], v[220:221], 0, s[44:45]
	s_barrier
	ds_read_b128 v[168:171], v150 offset:49152
	ds_read_b128 v[172:175], v150 offset:50176
	ds_read_b128 v[176:179], v150 offset:51200
	ds_read_b128 v[180:183], v150 offset:52224
	ds_read_b128 v[184:187], v150 offset:53248
	ds_read_b128 v[188:191], v150 offset:54272
	ds_read_b128 v[192:195], v150 offset:55296
	ds_read_b128 v[198:201], v150 offset:56320
	global_load_lds_dwordx4 v[144:145], off
	v_lshl_add_u64 v[144:145], v[222:223], 0, s[44:45]
	s_mov_b32 m0, s31
	s_nop 0
	global_load_lds_dwordx4 v[144:145], off
	s_barrier
; DI unsigned pack2(float a, float b) { f32x2 v = {a, b}; hwbf16x2 r = __builtin_convertvector(v, hwbf16x2); return __builtin_bit_cast(unsigned, r); }
; DI float bflo(unsigned w) { return __uint_as_float(w << 16); }
; DI float bfhi(unsigned w) { return __uint_as_float(w & 0xffff0000u); }
; #define PG8_STAGE(bufoff, gbase, voff) do { _Pragma("unroll") for (int _i = 0; _i < 2; ++_i) \
;         __builtin_amdgcn_global_load_lds((const unsigned*)((const char*)(gbase) + (voff)[_i]), (LAS unsigned*)(lds + (bufoff) + ldsw + _i * 8192), 16, 0, 0); } while (0)
; #define PG8_WAIT_V(n) asm volatile("s_waitcnt vmcnt(" #n ")" ::: "memory")
; #define PG8_WAIT_L(n) asm volatile("s_waitcnt lgkmcnt(" #n ")" ::: "memory")
;     DI void operator()(const f32x4 (&acc)[2][2][4][2], const Unit& u, int wr, int wc, int fr, int fq) const {
;     ...
;         for (int ai = 0; ai < 2; ++ai)
; #pragma unroll
;             for (int m = 0; m < 4; ++m) { const size_t ro = (size_t)(row0 + ai * HALF + m * 16) * D + col0;
; #pragma unroll
;                 for (int bj = 0; bj < 2; ++bj) {
;                     f32x4 x0, x1;
;                     if constexpr (IB) { const u32x4 w = *(const u32x4*)((const bf16_t*)Xin + ro + bj * HALF);
;                         x0 = (f32x4){bflo(w[0]), bfhi(w[0]), bflo(w[1]), bfhi(w[1])}; x1 = (f32x4){bflo(w[2]), bfhi(w[2]), bflo(w[3]), bfhi(w[3])}; }
;                     else { x0 = *(const f32x4*)((const float*)Xin + ro + bj * HALF); x1 = *(const f32x4*)((const float*)Xin + ro + bj * HALF + 4); }
;                     x0 += acc[ai][bj][m][0] * sc[bj][0]; x1 += acc[ai][bj][m][1] * sc[bj][1];
;                     if constexpr (OB) { u32x4 o; o[0] = pack2(x0[0], x0[1]); o[1] = pack2(x0[2], x0[3]); o[2] = pack2(x1[0], x1[1]); o[3] = pack2(x1[2], x1[3]);
;                         *(u32x4*)((bf16_t*)Xout + ro + bj * HALF) = o; }
;                     else { *(f32x4*)((float*)Xout + ro + bj * HALF) = x0; *(f32x4*)((float*)Xout + ro + bj * HALF + 4) = x1; } } }
; template <class Map, class Epi>
; DI void gemm_phase(LAS unsigned char* lds, const Map& MP, const Epi& E, const int nM, const int nN, const int K, const int lda, const int ldb) {
;     ...
;             PG8_BAR; PG8_WAIT_L(0); PG8_MMA(1, 0, At, B0); PG8_BAR; PG8_SCHED;
;             PG8_STAGE(PG8_SB(1, 1), b3 + hstepB, voffB);
;             PG8_WAIT_V(6); PG8_BAR; PG8_MMA(1, 1, At, B1); PG8_BAR;
	s_setprio 1
	s_waitcnt lgkmcnt(7)
	v_mfma_f32_16x16x32_bf16 v[60:63], v[152:155], v[168:171], v[60:63]
	v_mfma_f32_16x16x32_bf16 v[56:59], v[160:163], v[168:171], v[56:59]
	s_waitcnt lgkmcnt(5)
	v_mfma_f32_16x16x32_bf16 v[44:47], v[152:155], v[176:179], v[44:47]
	v_mfma_f32_16x16x32_bf16 v[40:43], v[160:163], v[176:179], v[40:43]
	s_waitcnt lgkmcnt(3)
	v_mfma_f32_16x16x32_bf16 v[28:31], v[152:155], v[184:187], v[28:31]
	v_mfma_f32_16x16x32_bf16 v[24:27], v[160:163], v[184:187], v[24:27]
	s_waitcnt lgkmcnt(1)
	v_mfma_f32_16x16x32_bf16 v[12:15], v[152:155], v[192:195], v[12:15]
	v_mfma_f32_16x16x32_bf16 v[8:11], v[160:163], v[192:195], v[8:11]
	v_mfma_f32_16x16x32_bf16 v[60:63], v[156:159], v[172:175], v[60:63]
	v_mfma_f32_16x16x32_bf16 v[56:59], v[164:167], v[172:175], v[56:59]
	v_mfma_f32_16x16x32_bf16 v[44:47], v[156:159], v[180:183], v[44:47]
	v_mfma_f32_16x16x32_bf16 v[40:43], v[164:167], v[180:183], v[40:43]
	v_mfma_f32_16x16x32_bf16 v[28:31], v[156:159], v[188:191], v[28:31]
	v_mfma_f32_16x16x32_bf16 v[24:27], v[164:167], v[188:191], v[24:27]
	s_waitcnt lgkmcnt(0)
	v_mfma_f32_16x16x32_bf16 v[12:15], v[156:159], v[198:201], v[12:15]
	v_mfma_f32_16x16x32_bf16 v[8:11], v[164:167], v[198:201], v[8:11]
	s_setprio 0
	s_barrier
	s_add_u32 s12, s12, 0x80080
	s_addc_u32 s13, s13, 0
	s_add_i32 s3, s14, s22
	s_mov_b32 m0, s3
	s_nop 0
	global_load_lds_dwordx4 v132, s[12:13]
	s_add_i32 m0, s3, 0x2000
	s_nop 0
	global_load_lds_dwordx4 v128, s[12:13]
	s_waitcnt vmcnt(6)
	s_barrier
	s_setprio 1
	v_mfma_f32_16x16x32_bf16 v[52:55], v[202:205], v[168:171], v[52:55]
	v_mfma_f32_16x16x32_bf16 v[48:51], v[210:213], v[168:171], v[48:51]
	v_mfma_f32_16x16x32_bf16 v[36:39], v[202:205], v[176:179], v[36:39]
	v_mfma_f32_16x16x32_bf16 v[32:35], v[210:213], v[176:179], v[32:35]
	v_mfma_f32_16x16x32_bf16 v[20:23], v[202:205], v[184:187], v[20:23]
	v_mfma_f32_16x16x32_bf16 v[16:19], v[210:213], v[184:187], v[16:19]
	v_mfma_f32_16x16x32_bf16 v[4:7], v[202:205], v[192:195], v[4:7]
	v_mfma_f32_16x16x32_bf16 v[0:3], v[210:213], v[192:195], v[0:3]
	v_mfma_f32_16x16x32_bf16 v[52:55], v[206:209], v[172:175], v[52:55]
	v_mfma_f32_16x16x32_bf16 v[48:51], v[214:217], v[172:175], v[48:51]
	v_mfma_f32_16x16x32_bf16 v[36:39], v[206:209], v[180:183], v[36:39]
	v_mfma_f32_16x16x32_bf16 v[32:35], v[214:217], v[180:183], v[32:35]
	v_mfma_f32_16x16x32_bf16 v[20:23], v[206:209], v[188:191], v[20:23]
	v_mfma_f32_16x16x32_bf16 v[16:19], v[214:217], v[188:191], v[16:19]
	v_mfma_f32_16x16x32_bf16 v[4:7], v[206:209], v[198:201], v[4:7]
	v_mfma_f32_16x16x32_bf16 v[0:3], v[214:217], v[198:201], v[0:3]
	s_setprio 0
	s_add_i32 s48, s48, 2
	s_add_u32 s39, s39, 0x100
	s_addc_u32 s47, s47, 0
	s_add_u32 s10, s10, 0x100
	s_addc_u32 s11, s11, 0
	s_cmp_gt_u32 s48, 29
	s_barrier
	s_cbranch_scc0 .LBB1_925
	v_mov_b32_e32 v152, v147
	v_mov_b32_e32 v144, v146
	s_lshl_b32 s2, s2, 8
	s_or_b32 s2, s2, s29
	v_lshl_add_u32 v144, v144, 3, s2
	s_lshl_b32 s2, s8, 8
	s_add_i32 s2, s2, s28
	v_add_u32_e32 v152, s2, v152
	v_ashrrev_i32_e32 v153, 31, v152
	v_lshlrev_b64 v[152:153], 12, v[152:153]
	v_ashrrev_i32_e32 v145, 31, v144
	v_lshl_add_u64 v[152:153], s[42:43], 0, v[152:153]
	v_lshl_add_u64 v[144:145], v[144:145], 1, v[152:153]
	global_load_dwordx4 v[160:163], v[144:145], off
	global_load_dwordx4 v[164:167], v[144:145], off offset:256
	s_mov_b64 s[98:99], 0x10000
	v_lshl_add_u64 v[154:155], v[144:145], 0, s[98:99]
	global_load_dwordx4 v[168:171], v[154:155], off
	global_load_dwordx4 v[172:175], v[154:155], off offset:256
	s_mov_b64 s[98:99], 0x20000
	v_lshl_add_u64 v[154:155], v[144:145], 0, s[98:99]
	global_load_dwordx4 v[176:179], v[154:155], off
	global_load_dwordx4 v[180:183], v[154:155], off offset:256
	s_mov_b64 s[98:99], 0x30000
	v_lshl_add_u64 v[154:155], v[144:145], 0, s[98:99]
	global_load_dwordx4 v[184:187], v[154:155], off
	global_load_dwordx4 v[188:191], v[154:155], off offset:256
	s_mov_b64 s[98:99], 0x80000
	v_lshl_add_u64 v[154:155], v[144:145], 0, s[98:99]
	global_load_dwordx4 v[192:195], v[154:155], off
	global_load_dwordx4 v[198:201], v[154:155], off offset:256
	s_mov_b64 s[98:99], 0x90000
	v_lshl_add_u64 v[154:155], v[144:145], 0, s[98:99]
	global_load_dwordx4 v[202:205], v[154:155], off
	global_load_dwordx4 v[206:209], v[154:155], off offset:256
	s_mov_b64 s[98:99], 0xa0000
	v_lshl_add_u64 v[154:155], v[144:145], 0, s[98:99]
	global_load_dwordx4 v[210:213], v[154:155], off
	global_load_dwordx4 v[214:217], v[154:155], off offset:256
	s_mov_b64 s[98:99], 0xb0000
	v_lshl_add_u64 v[154:155], v[144:145], 0, s[98:99]
	global_load_dwordx4 v[248:251], v[154:155], off
	global_load_dwordx4 v[252:255], v[154:155], off offset:256
	s_waitcnt vmcnt(15)
	s_nop 1
	v_mov_b32_e32 v152, v160
	v_mov_b32_e32 v153, v161
	v_mov_b32_e32 v154, v162
	v_mov_b32_e32 v155, v163
	s_mov_b64 s[2:3], 0x10000
	s_mov_b32 s8, s52
	s_mov_b64 s[10:11], s[6:7]
	s_mov_b64 s[12:13], s[54:55]
	s_waitcnt lgkmcnt(0)
	v_lshlrev_b32_e32 v156, 16, v152
	v_and_b32_e32 v157, 0xffff0000, v152
	v_lshlrev_b32_e32 v152, 16, v153
	v_and_b32_e32 v153, 0xffff0000, v153
	v_lshlrev_b32_e32 v158, 16, v154
	v_and_b32_e32 v159, 0xffff0000, v154
	v_lshlrev_b32_e32 v154, 16, v155
	v_and_b32_e32 v155, 0xffff0000, v155
	v_pk_add_f32 v[126:127], v[126:127], v[152:153]
	v_pk_add_f32 v[124:125], v[124:125], v[156:157]
	v_pk_add_f32 v[152:153], v[122:123], v[154:155]
	v_pk_add_f32 v[122:123], v[120:121], v[158:159]
	v_cvt_pk_bf16_f32 v120, v124, v125
	v_cvt_pk_bf16_f32 v121, v126, v127
	v_cvt_pk_bf16_f32 v122, v122, v123
	v_cvt_pk_bf16_f32 v123, v152, v153
	global_store_dwordx4 v[144:145], v[120:123], off
	s_waitcnt vmcnt(15)
; DI unsigned pack2(float a, float b) { f32x2 v = {a, b}; hwbf16x2 r = __builtin_convertvector(v, hwbf16x2); return __builtin_bit_cast(unsigned, r); }
; DI float bflo(unsigned w) { return __uint_as_float(w << 16); }
; DI float bfhi(unsigned w) { return __uint_as_float(w & 0xffff0000u); }
;     DI void operator()(const f32x4 (&acc)[2][2][4][2], const Unit& u, int wr, int wc, int fr, int fq) const {
;     ...
;         for (int ai = 0; ai < 2; ++ai)
; #pragma unroll
;             for (int m = 0; m < 4; ++m) { const size_t ro = (size_t)(row0 + ai * HALF + m * 16) * D + col0;
; #pragma unroll
;                 for (int bj = 0; bj < 2; ++bj) {
;                     f32x4 x0, x1;
;                     if constexpr (IB) { const u32x4 w = *(const u32x4*)((const bf16_t*)Xin + ro + bj * HALF);
;                         x0 = (f32x4){bflo(w[0]), bfhi(w[0]), bflo(w[1]), bfhi(w[1])}; x1 = (f32x4){bflo(w[2]), bfhi(w[2]), bflo(w[3]), bfhi(w[3])}; }
;                     else { x0 = *(const f32x4*)((const float*)Xin + ro + bj * HALF); x1 = *(const f32x4*)((const float*)Xin + ro + bj * HALF + 4); }
;                     x0 += acc[ai][bj][m][0] * sc[bj][0]; x1 += acc[ai][bj][m][1] * sc[bj][1];
;                     if constexpr (OB) { u32x4 o; o[0] = pack2(x0[0], x0[1]); o[1] = pack2(x0[2], x0[3]); o[2] = pack2(x1[0], x1[1]); o[3] = pack2(x1[2], x1[3]);
;                         *(u32x4*)((bf16_t*)Xout + ro + bj * HALF) = o; }
;                     else { *(f32x4*)((float*)Xout + ro + bj * HALF) = x0; *(f32x4*)((float*)Xout + ro + bj * HALF + 4) = x1; } } }
	s_nop 1
	v_mov_b32_e32 v120, v164
	v_mov_b32_e32 v121, v165
	v_mov_b32_e32 v122, v166
	v_mov_b32_e32 v123, v167
	s_waitcnt lgkmcnt(0)
	v_lshlrev_b32_e32 v124, 16, v120
	v_and_b32_e32 v125, 0xffff0000, v120
	v_lshlrev_b32_e32 v120, 16, v121
	v_and_b32_e32 v121, 0xffff0000, v121
	v_lshlrev_b32_e32 v126, 16, v122
	v_and_b32_e32 v127, 0xffff0000, v122
	v_lshlrev_b32_e32 v122, 16, v123
	v_and_b32_e32 v123, 0xffff0000, v123
	v_pk_add_f32 v[116:117], v[116:117], v[124:125]
	v_pk_add_f32 v[118:119], v[118:119], v[120:121]
	v_pk_add_f32 v[120:121], v[114:115], v[122:123]
	v_pk_add_f32 v[114:115], v[112:113], v[126:127]
	v_cvt_pk_bf16_f32 v112, v116, v117
	v_lshl_add_u64 v[116:117], v[144:145], 0, s[2:3]
	s_mov_b32 s2, 0x10000
	v_cvt_pk_bf16_f32 v113, v118, v119
	v_add_co_u32_e32 v118, vcc, s2, v144
	v_cvt_pk_bf16_f32 v114, v114, v115
	v_cvt_pk_bf16_f32 v115, v120, v121
	v_addc_co_u32_e32 v119, vcc, 0, v145, vcc
	global_store_dwordx4 v[144:145], v[112:115], off offset:256
	s_waitcnt vmcnt(15)
	s_nop 1
	v_mov_b32_e32 v112, v168
	v_mov_b32_e32 v113, v169
	v_mov_b32_e32 v114, v170
	v_mov_b32_e32 v115, v171
	s_mov_b64 s[2:3], 0x20000
	s_waitcnt lgkmcnt(0)
	v_lshlrev_b32_e32 v120, 16, v112
	v_and_b32_e32 v121, 0xffff0000, v112
	v_lshlrev_b32_e32 v112, 16, v113
	v_and_b32_e32 v113, 0xffff0000, v113
	v_lshlrev_b32_e32 v122, 16, v114
	v_and_b32_e32 v123, 0xffff0000, v114
	v_lshlrev_b32_e32 v114, 16, v115
	v_and_b32_e32 v115, 0xffff0000, v115
	v_pk_add_f32 v[110:111], v[110:111], v[112:113]
	v_pk_add_f32 v[108:109], v[108:109], v[120:121]
	v_pk_add_f32 v[112:113], v[106:107], v[114:115]
	v_pk_add_f32 v[106:107], v[104:105], v[122:123]
	v_cvt_pk_bf16_f32 v104, v108, v109
	v_cvt_pk_bf16_f32 v105, v110, v111
	v_cvt_pk_bf16_f32 v106, v106, v107
	v_cvt_pk_bf16_f32 v107, v112, v113
	global_store_dwordx4 v[118:119], v[104:107], off
	s_waitcnt vmcnt(15)
	s_nop 1
	v_mov_b32_e32 v104, v172
	v_mov_b32_e32 v105, v173
	v_mov_b32_e32 v106, v174
	v_mov_b32_e32 v107, v175
	s_waitcnt lgkmcnt(0)
	v_lshlrev_b32_e32 v108, 16, v104
	v_and_b32_e32 v109, 0xffff0000, v104
	v_lshlrev_b32_e32 v104, 16, v105
	v_and_b32_e32 v105, 0xffff0000, v105
	v_lshlrev_b32_e32 v110, 16, v106
	v_and_b32_e32 v111, 0xffff0000, v106
	v_lshlrev_b32_e32 v106, 16, v107
	v_and_b32_e32 v107, 0xffff0000, v107
	v_pk_add_f32 v[100:101], v[100:101], v[108:109]
	v_pk_add_f32 v[102:103], v[102:103], v[104:105]
	v_pk_add_f32 v[104:105], v[98:99], v[106:107]
	v_pk_add_f32 v[98:99], v[96:97], v[110:111]
	v_cvt_pk_bf16_f32 v96, v100, v101
	v_lshl_add_u64 v[100:101], v[144:145], 0, s[2:3]
	s_mov_b32 s2, 0x20000
	v_cvt_pk_bf16_f32 v97, v102, v103
	v_add_co_u32_e32 v102, vcc, s2, v144
	v_cvt_pk_bf16_f32 v98, v98, v99
	v_cvt_pk_bf16_f32 v99, v104, v105
	v_addc_co_u32_e32 v103, vcc, 0, v145, vcc
	global_store_dwordx4 v[116:117], v[96:99], off offset:256
	s_waitcnt vmcnt(15)
	s_nop 1
	v_mov_b32_e32 v96, v176
	v_mov_b32_e32 v97, v177
	v_mov_b32_e32 v98, v178
	v_mov_b32_e32 v99, v179
	s_mov_b64 s[2:3], 0x30000
	s_waitcnt lgkmcnt(0)
	v_lshlrev_b32_e32 v104, 16, v96
	v_and_b32_e32 v105, 0xffff0000, v96
	v_lshlrev_b32_e32 v96, 16, v97
	v_and_b32_e32 v97, 0xffff0000, v97
	v_lshlrev_b32_e32 v106, 16, v98
	v_and_b32_e32 v107, 0xffff0000, v98
	v_lshlrev_b32_e32 v98, 16, v99
	v_and_b32_e32 v99, 0xffff0000, v99
	v_pk_add_f32 v[94:95], v[94:95], v[96:97]
	v_pk_add_f32 v[92:93], v[92:93], v[104:105]
	v_pk_add_f32 v[96:97], v[90:91], v[98:99]
	v_pk_add_f32 v[90:91], v[88:89], v[106:107]
	v_cvt_pk_bf16_f32 v88, v92, v93
	v_cvt_pk_bf16_f32 v89, v94, v95
	v_cvt_pk_bf16_f32 v90, v90, v91
	v_cvt_pk_bf16_f32 v91, v96, v97
	global_store_dwordx4 v[102:103], v[88:91], off
	s_waitcnt vmcnt(15)
	s_nop 1
	v_mov_b32_e32 v88, v180
	v_mov_b32_e32 v89, v181
	v_mov_b32_e32 v90, v182
	v_mov_b32_e32 v91, v183
	s_waitcnt lgkmcnt(0)
	v_lshlrev_b32_e32 v92, 16, v88
	v_and_b32_e32 v93, 0xffff0000, v88
	v_lshlrev_b32_e32 v88, 16, v89
	v_and_b32_e32 v89, 0xffff0000, v89
	v_lshlrev_b32_e32 v94, 16, v90
	v_and_b32_e32 v95, 0xffff0000, v90
	v_lshlrev_b32_e32 v90, 16, v91
	v_and_b32_e32 v91, 0xffff0000, v91
	v_pk_add_f32 v[86:87], v[86:87], v[88:89]
	v_pk_add_f32 v[84:85], v[84:85], v[92:93]
	v_pk_add_f32 v[88:89], v[82:83], v[90:91]
	v_pk_add_f32 v[82:83], v[80:81], v[94:95]
	v_cvt_pk_bf16_f32 v80, v84, v85
	v_cvt_pk_bf16_f32 v81, v86, v87
	v_cvt_pk_bf16_f32 v82, v82, v83
	v_cvt_pk_bf16_f32 v83, v88, v89
	global_store_dwordx4 v[100:101], v[80:83], off offset:256
	s_nop 1
	v_lshl_add_u64 v[80:81], v[144:145], 0, s[2:3]
	s_mov_b32 s2, 0x30000
	v_add_co_u32_e32 v86, vcc, s2, v144
	s_mov_b64 s[2:3], 0x80000
	s_nop 0
	v_addc_co_u32_e32 v87, vcc, 0, v145, vcc
	s_waitcnt vmcnt(15)
	s_nop 1
	v_mov_b32_e32 v82, v184
	v_mov_b32_e32 v83, v185
	v_mov_b32_e32 v84, v186
	v_mov_b32_e32 v85, v187
	s_waitcnt lgkmcnt(0)
	v_lshlrev_b32_e32 v88, 16, v82
	v_and_b32_e32 v89, 0xffff0000, v82
	v_lshlrev_b32_e32 v82, 16, v83
	v_and_b32_e32 v83, 0xffff0000, v83
	v_lshlrev_b32_e32 v90, 16, v84
	v_and_b32_e32 v91, 0xffff0000, v84
	v_lshlrev_b32_e32 v84, 16, v85
	v_and_b32_e32 v85, 0xffff0000, v85
	v_pk_add_f32 v[78:79], v[78:79], v[82:83]
	v_pk_add_f32 v[76:77], v[76:77], v[88:89]
	v_pk_add_f32 v[82:83], v[74:75], v[84:85]
	v_pk_add_f32 v[74:75], v[72:73], v[90:91]
	v_cvt_pk_bf16_f32 v72, v76, v77
	v_cvt_pk_bf16_f32 v73, v78, v79
	v_cvt_pk_bf16_f32 v74, v74, v75
	v_cvt_pk_bf16_f32 v75, v82, v83
	global_store_dwordx4 v[86:87], v[72:75], off
	s_waitcnt vmcnt(15)
	s_nop 1
	v_mov_b32_e32 v72, v188
	v_mov_b32_e32 v73, v189
	v_mov_b32_e32 v74, v190
	v_mov_b32_e32 v75, v191
	s_waitcnt lgkmcnt(0)
; DI unsigned pack2(float a, float b) { f32x2 v = {a, b}; hwbf16x2 r = __builtin_convertvector(v, hwbf16x2); return __builtin_bit_cast(unsigned, r); }
; DI float bflo(unsigned w) { return __uint_as_float(w << 16); }
; DI float bfhi(unsigned w) { return __uint_as_float(w & 0xffff0000u); }
;     DI void operator()(const f32x4 (&acc)[2][2][4][2], const Unit& u, int wr, int wc, int fr, int fq) const {
;     ...
;         for (int ai = 0; ai < 2; ++ai)
; #pragma unroll
;             for (int m = 0; m < 4; ++m) { const size_t ro = (size_t)(row0 + ai * HALF + m * 16) * D + col0;
; #pragma unroll
;                 for (int bj = 0; bj < 2; ++bj) {
;                     f32x4 x0, x1;
;                     if constexpr (IB) { const u32x4 w = *(const u32x4*)((const bf16_t*)Xin + ro + bj * HALF);
;                         x0 = (f32x4){bflo(w[0]), bfhi(w[0]), bflo(w[1]), bfhi(w[1])}; x1 = (f32x4){bflo(w[2]), bfhi(w[2]), bflo(w[3]), bfhi(w[3])}; }
;                     else { x0 = *(const f32x4*)((const float*)Xin + ro + bj * HALF); x1 = *(const f32x4*)((const float*)Xin + ro + bj * HALF + 4); }
;                     x0 += acc[ai][bj][m][0] * sc[bj][0]; x1 += acc[ai][bj][m][1] * sc[bj][1];
;                     if constexpr (OB) { u32x4 o; o[0] = pack2(x0[0], x0[1]); o[1] = pack2(x0[2], x0[3]); o[2] = pack2(x1[0], x1[1]); o[3] = pack2(x1[2], x1[3]);
;                         *(u32x4*)((bf16_t*)Xout + ro + bj * HALF) = o; }
;                     else { *(f32x4*)((float*)Xout + ro + bj * HALF) = x0; *(f32x4*)((float*)Xout + ro + bj * HALF + 4) = x1; } } }
	v_lshlrev_b32_e32 v76, 16, v72
	v_and_b32_e32 v77, 0xffff0000, v72
	v_lshlrev_b32_e32 v72, 16, v73
	v_and_b32_e32 v73, 0xffff0000, v73
	v_lshlrev_b32_e32 v78, 16, v74
	v_and_b32_e32 v79, 0xffff0000, v74
	v_lshlrev_b32_e32 v74, 16, v75
	v_and_b32_e32 v75, 0xffff0000, v75
	v_pk_add_f32 v[70:71], v[70:71], v[72:73]
	v_pk_add_f32 v[68:69], v[68:69], v[76:77]
	v_pk_add_f32 v[72:73], v[66:67], v[74:75]
	v_pk_add_f32 v[66:67], v[64:65], v[78:79]
	v_cvt_pk_bf16_f32 v64, v68, v69
	v_cvt_pk_bf16_f32 v65, v70, v71
	v_cvt_pk_bf16_f32 v66, v66, v67
	v_cvt_pk_bf16_f32 v67, v72, v73
	global_store_dwordx4 v[80:81], v[64:67], off offset:256
	s_nop 1
	v_lshl_add_u64 v[64:65], v[144:145], 0, s[2:3]
	s_mov_b32 s2, 0x80000
	v_add_co_u32_e32 v70, vcc, s2, v144
	s_mov_b64 s[2:3], 0x90000
	s_nop 0
	v_addc_co_u32_e32 v71, vcc, 0, v145, vcc
	s_waitcnt vmcnt(15)
	s_nop 1
	v_mov_b32_e32 v66, v192
	v_mov_b32_e32 v67, v193
	v_mov_b32_e32 v68, v194
	v_mov_b32_e32 v69, v195
	s_waitcnt lgkmcnt(0)
	v_lshlrev_b32_e32 v72, 16, v66
	v_and_b32_e32 v73, 0xffff0000, v66
	v_lshlrev_b32_e32 v66, 16, v67
	v_and_b32_e32 v67, 0xffff0000, v67
	v_lshlrev_b32_e32 v74, 16, v68
	v_and_b32_e32 v75, 0xffff0000, v68
	v_lshlrev_b32_e32 v68, 16, v69
	v_and_b32_e32 v69, 0xffff0000, v69
	v_pk_add_f32 v[62:63], v[62:63], v[66:67]
	v_pk_add_f32 v[60:61], v[60:61], v[72:73]
	v_pk_add_f32 v[66:67], v[58:59], v[68:69]
	v_pk_add_f32 v[58:59], v[56:57], v[74:75]
	v_cvt_pk_bf16_f32 v56, v60, v61
	v_cvt_pk_bf16_f32 v57, v62, v63
	v_cvt_pk_bf16_f32 v58, v58, v59
	v_cvt_pk_bf16_f32 v59, v66, v67
	global_store_dwordx4 v[70:71], v[56:59], off
	s_waitcnt vmcnt(15)
	s_nop 1
	v_mov_b32_e32 v56, v198
	v_mov_b32_e32 v57, v199
	v_mov_b32_e32 v58, v200
	v_mov_b32_e32 v59, v201
	s_waitcnt lgkmcnt(0)
	v_lshlrev_b32_e32 v60, 16, v56
	v_and_b32_e32 v61, 0xffff0000, v56
	v_lshlrev_b32_e32 v56, 16, v57
	v_and_b32_e32 v57, 0xffff0000, v57
	v_lshlrev_b32_e32 v62, 16, v58
	v_and_b32_e32 v63, 0xffff0000, v58
	v_lshlrev_b32_e32 v58, 16, v59
	v_and_b32_e32 v59, 0xffff0000, v59
	v_pk_add_f32 v[54:55], v[54:55], v[56:57]
	v_pk_add_f32 v[52:53], v[52:53], v[60:61]
	v_pk_add_f32 v[56:57], v[50:51], v[58:59]
	v_pk_add_f32 v[50:51], v[48:49], v[62:63]
	v_cvt_pk_bf16_f32 v48, v52, v53
	v_cvt_pk_bf16_f32 v49, v54, v55
	v_cvt_pk_bf16_f32 v50, v50, v51
	v_cvt_pk_bf16_f32 v51, v56, v57
	global_store_dwordx4 v[64:65], v[48:51], off offset:256
	s_nop 1
	v_lshl_add_u64 v[48:49], v[144:145], 0, s[2:3]
	s_mov_b32 s2, 0x90000
	v_add_co_u32_e32 v54, vcc, s2, v144
	s_mov_b64 s[2:3], 0xa0000
	s_nop 0
	v_addc_co_u32_e32 v55, vcc, 0, v145, vcc
	s_waitcnt vmcnt(15)
	s_nop 1
	v_mov_b32_e32 v50, v202
	v_mov_b32_e32 v51, v203
	v_mov_b32_e32 v52, v204
	v_mov_b32_e32 v53, v205
	s_waitcnt lgkmcnt(0)
	v_lshlrev_b32_e32 v56, 16, v50
	v_and_b32_e32 v57, 0xffff0000, v50
	v_lshlrev_b32_e32 v50, 16, v51
	v_and_b32_e32 v51, 0xffff0000, v51
	v_lshlrev_b32_e32 v58, 16, v52
	v_and_b32_e32 v59, 0xffff0000, v52
	v_lshlrev_b32_e32 v52, 16, v53
	v_and_b32_e32 v53, 0xffff0000, v53
	v_pk_add_f32 v[46:47], v[46:47], v[50:51]
	v_pk_add_f32 v[44:45], v[44:45], v[56:57]
	v_pk_add_f32 v[50:51], v[42:43], v[52:53]
	v_pk_add_f32 v[42:43], v[40:41], v[58:59]
	v_cvt_pk_bf16_f32 v40, v44, v45
	v_cvt_pk_bf16_f32 v41, v46, v47
	v_cvt_pk_bf16_f32 v42, v42, v43
	v_cvt_pk_bf16_f32 v43, v50, v51
	global_store_dwordx4 v[54:55], v[40:43], off
	s_waitcnt vmcnt(15)
	s_nop 1
	v_mov_b32_e32 v40, v206
	v_mov_b32_e32 v41, v207
	v_mov_b32_e32 v42, v208
	v_mov_b32_e32 v43, v209
	s_waitcnt lgkmcnt(0)
; DI unsigned pack2(float a, float b) { f32x2 v = {a, b}; hwbf16x2 r = __builtin_convertvector(v, hwbf16x2); return __builtin_bit_cast(unsigned, r); }
; DI float bflo(unsigned w) { return __uint_as_float(w << 16); }
; DI float bfhi(unsigned w) { return __uint_as_float(w & 0xffff0000u); }
;     DI const char* a(const Unit& u) const { return (const char*)(A + (size_t)u.pm * BM * lda); }
;     DI const char* a(const Unit& u) const { return (const char*)(A + (size_t)u.pm * BM * 2048 + (u.pn >> 1) * 512); }
;     DI void operator()(const f32x4 (&acc)[2][2][4][2], const Unit& u, int wr, int wc, int fr, int fq) const {
;     ...
;         for (int ai = 0; ai < 2; ++ai)
; #pragma unroll
;             for (int m = 0; m < 4; ++m) { const size_t ro = (size_t)(row0 + ai * HALF + m * 16) * D + col0;
; #pragma unroll
;                 for (int bj = 0; bj < 2; ++bj) {
;                     f32x4 x0, x1;
;                     if constexpr (IB) { const u32x4 w = *(const u32x4*)((const bf16_t*)Xin + ro + bj * HALF);
;                         x0 = (f32x4){bflo(w[0]), bfhi(w[0]), bflo(w[1]), bfhi(w[1])}; x1 = (f32x4){bflo(w[2]), bfhi(w[2]), bflo(w[3]), bfhi(w[3])}; }
;                     else { x0 = *(const f32x4*)((const float*)Xin + ro + bj * HALF); x1 = *(const f32x4*)((const float*)Xin + ro + bj * HALF + 4); }
;                     x0 += acc[ai][bj][m][0] * sc[bj][0]; x1 += acc[ai][bj][m][1] * sc[bj][1];
;                     if constexpr (OB) { u32x4 o; o[0] = pack2(x0[0], x0[1]); o[1] = pack2(x0[2], x0[3]); o[2] = pack2(x1[0], x1[1]); o[3] = pack2(x1[2], x1[3]);
;                         *(u32x4*)((bf16_t*)Xout + ro + bj * HALF) = o; }
;                     else { *(f32x4*)((float*)Xout + ro + bj * HALF) = x0; *(f32x4*)((float*)Xout + ro + bj * HALF + 4) = x1; } } }
; template <class Map, class Epi>
; DI void gemm_phase(LAS unsigned char* lds, const Map& MP, const Epi& E, const int nM, const int nN, const int K, const int lda, const int ldb) {
;     ...
;         if (!has_next) break;
; #pragma unroll
;         for (int a = 0; a < 2; ++a)
; #pragma unroll
;             for (int b = 0; b < 2; ++b)
; #pragma unroll
;                 for (int m = 0; m < 4; ++m)
; #pragma unroll
;                     for (int n = 0; n < 2; ++n) acc[a][b][m][n] = (f32x4){0.f, 0.f, 0.f, 0.f};
;         cur = nxt; cA = nA; cB = nB; ++ui;
;     }
;     PG8_WAIT_V(0);
;     if (wr == 0) PG8_BAR;
;     PG8_BAR;
	v_lshlrev_b32_e32 v44, 16, v40
	v_and_b32_e32 v45, 0xffff0000, v40
	v_lshlrev_b32_e32 v40, 16, v41
	v_and_b32_e32 v41, 0xffff0000, v41
	v_lshlrev_b32_e32 v46, 16, v42
	v_and_b32_e32 v47, 0xffff0000, v42
	v_lshlrev_b32_e32 v42, 16, v43
	v_and_b32_e32 v43, 0xffff0000, v43
	v_pk_add_f32 v[38:39], v[38:39], v[40:41]
	v_pk_add_f32 v[36:37], v[36:37], v[44:45]
	v_pk_add_f32 v[40:41], v[34:35], v[42:43]
	v_pk_add_f32 v[34:35], v[32:33], v[46:47]
	v_cvt_pk_bf16_f32 v32, v36, v37
	v_cvt_pk_bf16_f32 v33, v38, v39
	v_cvt_pk_bf16_f32 v34, v34, v35
	v_cvt_pk_bf16_f32 v35, v40, v41
	global_store_dwordx4 v[48:49], v[32:35], off offset:256
	s_nop 1
	v_lshl_add_u64 v[32:33], v[144:145], 0, s[2:3]
	s_mov_b32 s2, 0xa0000
	v_add_co_u32_e32 v38, vcc, s2, v144
	s_mov_b64 s[2:3], 0xb0000
	s_nop 0
	v_addc_co_u32_e32 v39, vcc, 0, v145, vcc
	s_waitcnt vmcnt(15)
	s_nop 1
	v_mov_b32_e32 v34, v210
	v_mov_b32_e32 v35, v211
	v_mov_b32_e32 v36, v212
	v_mov_b32_e32 v37, v213
	s_waitcnt lgkmcnt(0)
	v_lshlrev_b32_e32 v40, 16, v34
	v_and_b32_e32 v41, 0xffff0000, v34
	v_lshlrev_b32_e32 v34, 16, v35
	v_and_b32_e32 v35, 0xffff0000, v35
	v_lshlrev_b32_e32 v42, 16, v36
	v_and_b32_e32 v43, 0xffff0000, v36
	v_lshlrev_b32_e32 v36, 16, v37
	v_and_b32_e32 v37, 0xffff0000, v37
	v_pk_add_f32 v[30:31], v[30:31], v[34:35]
	v_pk_add_f32 v[28:29], v[28:29], v[40:41]
	v_pk_add_f32 v[34:35], v[26:27], v[36:37]
	v_pk_add_f32 v[26:27], v[24:25], v[42:43]
	v_cvt_pk_bf16_f32 v24, v28, v29
	v_cvt_pk_bf16_f32 v25, v30, v31
	v_cvt_pk_bf16_f32 v26, v26, v27
	v_cvt_pk_bf16_f32 v27, v34, v35
	global_store_dwordx4 v[38:39], v[24:27], off
	s_waitcnt vmcnt(15)
	s_nop 1
	v_mov_b32_e32 v24, v214
	v_mov_b32_e32 v25, v215
	v_mov_b32_e32 v26, v216
	v_mov_b32_e32 v27, v217
	s_waitcnt lgkmcnt(0)
	v_lshlrev_b32_e32 v28, 16, v24
	v_and_b32_e32 v29, 0xffff0000, v24
	v_lshlrev_b32_e32 v24, 16, v25
	v_and_b32_e32 v25, 0xffff0000, v25
	v_lshlrev_b32_e32 v30, 16, v26
	v_and_b32_e32 v31, 0xffff0000, v26
	v_lshlrev_b32_e32 v26, 16, v27
	v_and_b32_e32 v27, 0xffff0000, v27
	v_pk_add_f32 v[22:23], v[22:23], v[24:25]
	v_pk_add_f32 v[20:21], v[20:21], v[28:29]
	v_pk_add_f32 v[24:25], v[18:19], v[26:27]
	v_pk_add_f32 v[18:19], v[16:17], v[30:31]
	v_cvt_pk_bf16_f32 v16, v20, v21
	v_cvt_pk_bf16_f32 v17, v22, v23
	v_cvt_pk_bf16_f32 v18, v18, v19
	v_cvt_pk_bf16_f32 v19, v24, v25
	global_store_dwordx4 v[32:33], v[16:19], off offset:256
	s_nop 1
	v_lshl_add_u64 v[16:17], v[144:145], 0, s[2:3]
	s_mov_b32 s2, 0xb0000
	v_add_co_u32_e32 v22, vcc, s2, v144
	s_mov_b32 s2, s46
	s_nop 0
	v_addc_co_u32_e32 v23, vcc, 0, v145, vcc
	s_waitcnt vmcnt(15)
	s_nop 1
	v_mov_b32_e32 v18, v248
	v_mov_b32_e32 v19, v249
	v_mov_b32_e32 v20, v250
	v_mov_b32_e32 v21, v251
	s_and_b64 vcc, exec, s[40:41]
	s_waitcnt lgkmcnt(0)
	v_lshlrev_b32_e32 v24, 16, v18
	v_and_b32_e32 v25, 0xffff0000, v18
	v_lshlrev_b32_e32 v18, 16, v19
	v_and_b32_e32 v19, 0xffff0000, v19
	v_lshlrev_b32_e32 v26, 16, v20
	v_and_b32_e32 v27, 0xffff0000, v20
	v_lshlrev_b32_e32 v20, 16, v21
	v_and_b32_e32 v21, 0xffff0000, v21
	v_pk_add_f32 v[14:15], v[14:15], v[18:19]
	v_pk_add_f32 v[12:13], v[12:13], v[24:25]
	v_pk_add_f32 v[18:19], v[10:11], v[20:21]
	v_pk_add_f32 v[10:11], v[8:9], v[26:27]
	v_cvt_pk_bf16_f32 v8, v12, v13
	v_cvt_pk_bf16_f32 v9, v14, v15
	v_cvt_pk_bf16_f32 v10, v10, v11
	v_cvt_pk_bf16_f32 v11, v18, v19
	global_store_dwordx4 v[22:23], v[8:11], off
	s_waitcnt vmcnt(15)
	s_nop 1
	v_mov_b32_e32 v8, v252
	v_mov_b32_e32 v9, v253
	v_mov_b32_e32 v10, v254
	v_mov_b32_e32 v11, v255
	s_waitcnt lgkmcnt(0)
	v_lshlrev_b32_e32 v12, 16, v8
	v_and_b32_e32 v13, 0xffff0000, v8
	v_lshlrev_b32_e32 v8, 16, v9
	v_and_b32_e32 v9, 0xffff0000, v9
	v_lshlrev_b32_e32 v14, 16, v10
	v_and_b32_e32 v15, 0xffff0000, v10
	v_lshlrev_b32_e32 v10, 16, v11
	v_and_b32_e32 v11, 0xffff0000, v11
	v_pk_add_f32 v[6:7], v[6:7], v[8:9]
	v_pk_add_f32 v[4:5], v[4:5], v[12:13]
	v_pk_add_f32 v[8:9], v[2:3], v[10:11]
	v_pk_add_f32 v[2:3], v[0:1], v[14:15]
	v_cvt_pk_bf16_f32 v0, v4, v5
	v_cvt_pk_bf16_f32 v1, v6, v7
	v_cvt_pk_bf16_f32 v2, v2, v3
	v_cvt_pk_bf16_f32 v3, v8, v9
	global_store_dwordx4 v[16:17], v[0:3], off offset:256
	s_cbranch_vccz .LBB1_922
	s_waitcnt vmcnt(0)
	s_cmpk_gt_u32 s17, 0xff
	s_cbranch_scc1 .LBB1_929
	s_barrier

; #define PG8_STAGE(bufoff, gbase, voff) do { _Pragma("unroll") for (int _i = 0; _i < 2; ++_i) \
;         __builtin_amdgcn_global_load_lds((const unsigned*)((const char*)(gbase) + (voff)[_i]), (LAS unsigned*)(lds + (bufoff) + ldsw + _i * 8192), 16, 0, 0); } while (0)
; #define PG8_LDA(dst, b, h) do { _Pragma("unroll") for (int m = 0; m < 4; ++m) _Pragma("unroll") for (int k = 0; k < 2; ++k) dst[m][k] = *(const LAS bf16x8*)(lds + PG8_SA(b, h) + aoff + m * 2048 + k * 1024); } while (0)
; #define PG8_LDB(dst, b, h) do { _Pragma("unroll") for (int n = 0; n < 2; ++n) _Pragma("unroll") for (int k = 0; k < 2; ++k) dst[n][k] = *(const LAS bf16x8*)(lds + PG8_SB(b, h) + boff + n * 2048 + k * 1024); } while (0)
; #define PG8_MMA(ai, bj, At, Bt) do { __builtin_amdgcn_s_setprio(1); _Pragma("unroll") for (int m = 0; m < 4; ++m) _Pragma("unroll") for (int n = 0; n < 2; ++n) _Pragma("unroll") for (int k = 0; k < 2; ++k) \
;         acc[ai][bj][m][n] = __builtin_amdgcn_mfma_f32_16x16x32_bf16(Bt[n][k], At[m][k], acc[ai][bj][m][n], 0, 0, 0); __builtin_amdgcn_s_setprio(0); } while (0)
; #define PG8_WAIT_L(n) asm volatile("s_waitcnt lgkmcnt(" #n ")" ::: "memory")
; #define PG8_BAR __builtin_amdgcn_s_barrier()
; #define PG8_SCHED __builtin_amdgcn_sched_barrier(0)
; template <class Map, class Epi>
; DI void gemm_phase(LAS unsigned char* lds, const Map& MP, const Epi& E, const int nM, const int nN, const int K, const int lda, const int ldb) {
;     ...
;             const bool last = (t == nt - 2);
;             const char* a1 = cA + (size_t)(t + 1) * kstep;
;             const char* a2 = last ? nA : cA + (size_t)(t + 2) * kstep; const char* b2 = last ? nB : cB + (size_t)(t + 2) * kstep;
;             const char* a3 = a2 + kstep; const char* b3 = b2 + kstep;
;             PG8_LDB(B0, 0, 0); PG8_SCHED; PG8_LDA(At, 0, 0); PG8_STAGE(PG8_SA(1, 1), a1 + hstepA, voffA);
;             PG8_WAIT_L(8); PG8_BAR; PG8_WAIT_L(0); PG8_MMA(0, 0, At, B0); PG8_BAR; PG8_SCHED;
;             PG8_LDB(B1, 0, 1); PG8_STAGE(PG8_SB(0, 0), b2, voffB);
;             PG8_BAR; PG8_WAIT_L(0); PG8_MMA(0, 1, At, B1); PG8_BAR;
;             PG8_LDA(At, 0, 1); PG8_STAGE(PG8_SA(0, 0), a2, voffA);
;             PG8_BAR; PG8_WAIT_L(0); PG8_MMA(1, 0, At, B0); PG8_BAR; PG8_SCHED;
.LBB1_1069:
	ds_read_b128 v[80:83], v189
	ds_read_b128 v[84:87], v189 offset:1024
	ds_read_b128 v[88:91], v189 offset:2048
	ds_read_b128 v[92:95], v189 offset:3072
	s_add_u32 s24, s42, 0xfff80080
	s_addc_u32 s25, s43, -1
	s_cmp_eq_u32 s3, 28
	s_cselect_b32 s47, s23, s25
	s_cselect_b32 s46, s58, s24
	s_cselect_b32 s25, s21, vcc_hi
	s_cselect_b32 s24, s59, vcc_lo
	s_add_i32 m0, s38, 0xc000
	ds_read_b128 v[96:99], v190
	ds_read_b128 v[100:103], v190 offset:1024
	ds_read_b128 v[108:111], v190 offset:2048
	ds_read_b128 v[112:115], v190 offset:3072
	ds_read_b128 v[160:163], v190 offset:4096
	ds_read_b128 v[164:167], v190 offset:5120
	ds_read_b128 v[198:201], v190 offset:6144
	ds_read_b128 v[202:205], v190 offset:7168
	global_load_lds_dwordx4 v178, s[42:43]
	s_add_i32 m0, s38, 0xe000
	s_nop 0
	global_load_lds_dwordx4 v176, s[42:43]
	s_waitcnt lgkmcnt(8)
	s_barrier
	s_setprio 1
	s_waitcnt lgkmcnt(7)
	v_mfma_f32_16x16x32_bf16 v[148:151], v[80:83], v[96:99], v[148:151]
	v_mfma_f32_16x16x32_bf16 v[144:147], v[88:91], v[96:99], v[144:147]
	s_waitcnt lgkmcnt(5)
	v_mfma_f32_16x16x32_bf16 v[136:139], v[80:83], v[108:111], v[136:139]
	v_mfma_f32_16x16x32_bf16 v[128:131], v[88:91], v[108:111], v[128:131]
	s_waitcnt lgkmcnt(3)
	v_mfma_f32_16x16x32_bf16 v[120:123], v[80:83], v[160:163], v[120:123]
	v_mfma_f32_16x16x32_bf16 v[104:107], v[88:91], v[160:163], v[104:107]
	s_waitcnt lgkmcnt(1)
	v_mfma_f32_16x16x32_bf16 v[76:79], v[80:83], v[198:201], v[76:79]
	v_mfma_f32_16x16x32_bf16 v[72:75], v[88:91], v[198:201], v[72:75]
	v_mfma_f32_16x16x32_bf16 v[148:151], v[84:87], v[100:103], v[148:151]
	v_mfma_f32_16x16x32_bf16 v[144:147], v[92:95], v[100:103], v[144:147]
	v_mfma_f32_16x16x32_bf16 v[136:139], v[84:87], v[112:115], v[136:139]
	v_mfma_f32_16x16x32_bf16 v[128:131], v[92:95], v[112:115], v[128:131]
	v_mfma_f32_16x16x32_bf16 v[120:123], v[84:87], v[164:167], v[120:123]
	v_mfma_f32_16x16x32_bf16 v[104:107], v[92:95], v[164:167], v[104:107]
	s_waitcnt lgkmcnt(0)
	v_mfma_f32_16x16x32_bf16 v[76:79], v[84:87], v[202:205], v[76:79]
	v_mfma_f32_16x16x32_bf16 v[72:75], v[92:95], v[202:205], v[72:75]
	s_setprio 0
	s_barrier
	s_add_i32 s68, s31, s66
	v_lshl_add_u64 v[184:185], s[24:25], 0, v[172:173]
	s_mov_b32 m0, s68
	ds_read_b128 v[206:209], v191
	ds_read_b128 v[210:213], v191 offset:1024
	ds_read_b128 v[214:217], v191 offset:2048
	ds_read_b128 v[218:221], v191 offset:3072
	global_load_lds_dwordx4 v[184:185], off
	v_lshl_add_u64 v[194:195], s[24:25], 0, v[168:169]
	s_add_i32 m0, s68, 0x2000
	s_nop 0
	global_load_lds_dwordx4 v[194:195], off
	s_barrier
	s_setprio 1
	s_waitcnt lgkmcnt(3)
	v_mfma_f32_16x16x32_bf16 v[156:159], v[206:209], v[96:99], v[156:159]
	s_waitcnt lgkmcnt(1)
	v_mfma_f32_16x16x32_bf16 v[96:99], v[214:217], v[96:99], v[152:155]
	v_mfma_f32_16x16x32_bf16 v[156:159], v[210:213], v[100:103], v[156:159]
	s_waitcnt lgkmcnt(0)
	v_mfma_f32_16x16x32_bf16 v[96:99], v[218:221], v[100:103], v[96:99]
	v_mfma_f32_16x16x32_bf16 v[100:103], v[206:209], v[108:111], v[140:143]
	v_mfma_f32_16x16x32_bf16 v[108:111], v[214:217], v[108:111], v[132:135]
	v_mfma_f32_16x16x32_bf16 v[116:119], v[214:217], v[160:163], v[116:119]
	v_mfma_f32_16x16x32_bf16 v[68:71], v[206:209], v[198:201], v[68:71]
	v_mfma_f32_16x16x32_bf16 v[64:67], v[214:217], v[198:201], v[64:67]
	v_mfma_f32_16x16x32_bf16 v[100:103], v[210:213], v[112:115], v[100:103]
	v_mfma_f32_16x16x32_bf16 v[108:111], v[218:221], v[112:115], v[108:111]
	v_mfma_f32_16x16x32_bf16 v[112:115], v[206:209], v[160:163], v[124:127]
	v_mfma_f32_16x16x32_bf16 v[116:119], v[218:221], v[164:167], v[116:119]
	v_mfma_f32_16x16x32_bf16 v[68:71], v[210:213], v[202:205], v[68:71]
	v_mfma_f32_16x16x32_bf16 v[64:67], v[218:221], v[202:205], v[64:67]
	v_mfma_f32_16x16x32_bf16 v[112:115], v[210:213], v[164:167], v[112:115]
	s_setprio 0
	s_mov_b32 m0, s38
	v_lshl_add_u64 v[226:227], s[46:47], 0, v[174:175]
	s_barrier
	ds_read_b128 v[124:127], v190 offset:16384
	ds_read_b128 v[132:135], v190 offset:17408
	ds_read_b128 v[140:143], v190 offset:18432
	ds_read_b128 v[152:155], v190 offset:19456
	ds_read_b128 v[160:163], v190 offset:20480
	ds_read_b128 v[164:167], v190 offset:21504
	ds_read_b128 v[198:201], v190 offset:22528
	ds_read_b128 v[202:205], v190 offset:23552
	global_load_lds_dwordx4 v[226:227], off
	v_lshl_add_u64 v[234:235], s[46:47], 0, v[170:171]
	s_mov_b32 m0, s39
	s_nop 0
	global_load_lds_dwordx4 v[234:235], off
	s_barrier
	s_setprio 1
	s_waitcnt lgkmcnt(7)
	v_mfma_f32_16x16x32_bf16 v[60:63], v[80:83], v[124:127], v[60:63]
	v_mfma_f32_16x16x32_bf16 v[48:51], v[88:91], v[124:127], v[48:51]
	s_waitcnt lgkmcnt(5)
	v_mfma_f32_16x16x32_bf16 v[40:43], v[80:83], v[140:143], v[40:43]
	v_mfma_f32_16x16x32_bf16 v[32:35], v[88:91], v[140:143], v[32:35]
	s_waitcnt lgkmcnt(3)
	v_mfma_f32_16x16x32_bf16 v[24:27], v[80:83], v[160:163], v[24:27]
	v_mfma_f32_16x16x32_bf16 v[16:19], v[88:91], v[160:163], v[16:19]
	s_waitcnt lgkmcnt(1)
	v_mfma_f32_16x16x32_bf16 v[12:15], v[80:83], v[198:201], v[12:15]
	v_mfma_f32_16x16x32_bf16 v[8:11], v[88:91], v[198:201], v[8:11]
	v_mfma_f32_16x16x32_bf16 v[60:63], v[84:87], v[132:135], v[60:63]
	v_mfma_f32_16x16x32_bf16 v[48:51], v[92:95], v[132:135], v[48:51]
	v_mfma_f32_16x16x32_bf16 v[40:43], v[84:87], v[152:155], v[40:43]
	v_mfma_f32_16x16x32_bf16 v[32:35], v[92:95], v[152:155], v[32:35]
	v_mfma_f32_16x16x32_bf16 v[24:27], v[84:87], v[164:167], v[24:27]
	v_mfma_f32_16x16x32_bf16 v[16:19], v[92:95], v[164:167], v[16:19]
	s_waitcnt lgkmcnt(0)
	v_mfma_f32_16x16x32_bf16 v[12:15], v[84:87], v[202:205], v[12:15]
	v_mfma_f32_16x16x32_bf16 v[8:11], v[92:95], v[202:205], v[8:11]
	s_setprio 0
	s_barrier
; #define PG8_STAGE(bufoff, gbase, voff) do { _Pragma("unroll") for (int _i = 0; _i < 2; ++_i) \
;         __builtin_amdgcn_global_load_lds((const unsigned*)((const char*)(gbase) + (voff)[_i]), (LAS unsigned*)(lds + (bufoff) + ldsw + _i * 8192), 16, 0, 0); } while (0)
; #define PG8_LDA(dst, b, h) do { _Pragma("unroll") for (int m = 0; m < 4; ++m) _Pragma("unroll") for (int k = 0; k < 2; ++k) dst[m][k] = *(const LAS bf16x8*)(lds + PG8_SA(b, h) + aoff + m * 2048 + k * 1024); } while (0)
; #define PG8_LDB(dst, b, h) do { _Pragma("unroll") for (int n = 0; n < 2; ++n) _Pragma("unroll") for (int k = 0; k < 2; ++k) dst[n][k] = *(const LAS bf16x8*)(lds + PG8_SB(b, h) + boff + n * 2048 + k * 1024); } while (0)
; #define PG8_MMA(ai, bj, At, Bt) do { __builtin_amdgcn_s_setprio(1); _Pragma("unroll") for (int m = 0; m < 4; ++m) _Pragma("unroll") for (int n = 0; n < 2; ++n) _Pragma("unroll") for (int k = 0; k < 2; ++k) \
;         acc[ai][bj][m][n] = __builtin_amdgcn_mfma_f32_16x16x32_bf16(Bt[n][k], At[m][k], acc[ai][bj][m][n], 0, 0, 0); __builtin_amdgcn_s_setprio(0); } while (0)
; #define PG8_WAIT_V(n) asm volatile("s_waitcnt vmcnt(" #n ")" ::: "memory")
; #define PG8_WAIT_L(n) asm volatile("s_waitcnt lgkmcnt(" #n ")" ::: "memory")
; #define PG8_BAR __builtin_amdgcn_s_barrier()
; #define PG8_SCHED __builtin_amdgcn_sched_barrier(0)
; template <class Map, class Epi>
; DI void gemm_phase(LAS unsigned char* lds, const Map& MP, const Epi& E, const int nM, const int nN, const int K, const int lda, const int ldb) {
;     ...
;             PG8_STAGE(PG8_SB(0, 1), b2 + hstepB, voffB);
;             PG8_WAIT_V(6); PG8_BAR; PG8_MMA(1, 1, At, B1); PG8_BAR;
;             PG8_LDB(B0, 1, 0); PG8_SCHED; PG8_LDA(At, 1, 0); PG8_STAGE(PG8_SA(0, 1), a2 + hstepA, voffA);
;             PG8_WAIT_L(8); PG8_BAR; PG8_WAIT_L(0); PG8_MMA(0, 0, At, B0); PG8_BAR; PG8_SCHED;
;             PG8_LDB(B1, 1, 1); PG8_STAGE(PG8_SB(1, 0), b3, voffB);
;             PG8_BAR; PG8_WAIT_L(0); PG8_MMA(0, 1, At, B1); PG8_BAR;
;             PG8_LDA(At, 1, 1); PG8_STAGE(PG8_SA(1, 0), a3, voffA);
;             PG8_BAR; PG8_WAIT_L(0); PG8_MMA(1, 0, At, B0); PG8_BAR; PG8_SCHED;
	s_add_u32 s68, s24, 0x80000
	s_addc_u32 s69, s25, 0
	s_add_i32 s70, s2, s66
	s_mov_b32 m0, s70
	s_nop 0
	global_load_lds_dwordx4 v172, s[68:69]
	s_add_i32 m0, s70, 0x2000
	s_nop 0
	global_load_lds_dwordx4 v168, s[68:69]
	s_waitcnt vmcnt(6)
	s_barrier
	s_setprio 1
	v_mfma_f32_16x16x32_bf16 v[56:59], v[206:209], v[124:127], v[56:59]
	v_mfma_f32_16x16x32_bf16 v[52:55], v[214:217], v[124:127], v[52:55]
	v_mfma_f32_16x16x32_bf16 v[44:47], v[206:209], v[140:143], v[44:47]
	v_mfma_f32_16x16x32_bf16 v[36:39], v[214:217], v[140:143], v[36:39]
	v_mfma_f32_16x16x32_bf16 v[28:31], v[206:209], v[160:163], v[28:31]
	v_mfma_f32_16x16x32_bf16 v[20:23], v[214:217], v[160:163], v[20:23]
	v_mfma_f32_16x16x32_bf16 v[4:7], v[206:209], v[198:201], v[4:7]
	v_mfma_f32_16x16x32_bf16 v[0:3], v[214:217], v[198:201], v[0:3]
	v_mfma_f32_16x16x32_bf16 v[56:59], v[210:213], v[132:135], v[56:59]
	v_mfma_f32_16x16x32_bf16 v[52:55], v[218:221], v[132:135], v[52:55]
	v_mfma_f32_16x16x32_bf16 v[44:47], v[210:213], v[152:155], v[44:47]
	v_mfma_f32_16x16x32_bf16 v[36:39], v[218:221], v[152:155], v[36:39]
	v_mfma_f32_16x16x32_bf16 v[28:31], v[210:213], v[164:167], v[28:31]
	v_mfma_f32_16x16x32_bf16 v[20:23], v[218:221], v[164:167], v[20:23]
	v_mfma_f32_16x16x32_bf16 v[4:7], v[210:213], v[202:205], v[4:7]
	v_mfma_f32_16x16x32_bf16 v[0:3], v[218:221], v[202:205], v[0:3]
	s_setprio 0
	s_add_i32 s68, 0, 0x18000
	v_add_u32_e32 v92, s68, v188
	s_barrier
	ds_read_b128 v[80:83], v92
	ds_read_b128 v[84:87], v92 offset:1024
	ds_read_b128 v[88:91], v92 offset:2048
	ds_read_b128 v[92:95], v92 offset:3072
	s_add_u32 s46, s46, 0x80000
	s_addc_u32 s47, s47, 0
	s_mov_b32 m0, s56
	ds_read_b128 v[124:127], v190 offset:32768
	ds_read_b128 v[132:135], v190 offset:33792
	ds_read_b128 v[160:163], v190 offset:34816
	ds_read_b128 v[164:167], v190 offset:35840
	ds_read_b128 v[198:201], v190 offset:36864
	ds_read_b128 v[202:205], v190 offset:37888
	ds_read_b128 v[206:209], v190 offset:38912
	ds_read_b128 v[210:213], v190 offset:39936
	global_load_lds_dwordx4 v174, s[46:47]
	s_mov_b32 m0, s57
	s_nop 0
	global_load_lds_dwordx4 v170, s[46:47]
	s_waitcnt lgkmcnt(8)
	s_barrier
	s_setprio 1
	s_waitcnt lgkmcnt(7)
	v_mfma_f32_16x16x32_bf16 v[140:143], v[80:83], v[124:127], v[148:151]
	s_waitcnt lgkmcnt(6)
	v_mfma_f32_16x16x32_bf16 v[148:151], v[84:87], v[132:135], v[140:143]
	v_mfma_f32_16x16x32_bf16 v[140:143], v[88:91], v[124:127], v[144:147]
	s_waitcnt lgkmcnt(5)
	v_mfma_f32_16x16x32_bf16 v[136:139], v[80:83], v[160:163], v[136:139]
	v_mfma_f32_16x16x32_bf16 v[128:131], v[88:91], v[160:163], v[128:131]
	s_waitcnt lgkmcnt(3)
	v_mfma_f32_16x16x32_bf16 v[120:123], v[80:83], v[198:201], v[120:123]
	v_mfma_f32_16x16x32_bf16 v[104:107], v[88:91], v[198:201], v[104:107]
	s_waitcnt lgkmcnt(1)
	v_mfma_f32_16x16x32_bf16 v[76:79], v[80:83], v[206:209], v[76:79]
	v_mfma_f32_16x16x32_bf16 v[72:75], v[88:91], v[206:209], v[72:75]
	v_mfma_f32_16x16x32_bf16 v[144:147], v[92:95], v[132:135], v[140:143]
	v_mfma_f32_16x16x32_bf16 v[136:139], v[84:87], v[164:167], v[136:139]
	v_mfma_f32_16x16x32_bf16 v[128:131], v[92:95], v[164:167], v[128:131]
	v_mfma_f32_16x16x32_bf16 v[120:123], v[84:87], v[202:205], v[120:123]
	v_mfma_f32_16x16x32_bf16 v[104:107], v[92:95], v[202:205], v[104:107]
	s_waitcnt lgkmcnt(0)
	v_mfma_f32_16x16x32_bf16 v[76:79], v[84:87], v[210:213], v[76:79]
	v_mfma_f32_16x16x32_bf16 v[72:75], v[92:95], v[210:213], v[72:75]
	s_setprio 0
	s_barrier
	s_add_i32 s46, 0, 0x1c000
	v_add_u32_e32 v140, s46, v188
	s_add_i32 s47, s68, s66
	ds_read_b128 v[214:217], v140
	ds_read_b128 v[218:221], v140 offset:1024
	ds_read_b128 v[222:225], v140 offset:2048
	ds_read_b128 v[230:233], v140 offset:3072
	v_lshl_add_u64 v[140:141], v[184:185], 0, s[14:15]
	s_mov_b32 m0, s47
	s_nop 0
	global_load_lds_dwordx4 v[140:141], off
	v_lshl_add_u64 v[140:141], v[194:195], 0, s[14:15]
	s_add_i32 m0, s47, 0x2000
	s_nop 0
	global_load_lds_dwordx4 v[140:141], off
	s_barrier
	s_setprio 1
	s_waitcnt lgkmcnt(1)
	v_mfma_f32_16x16x32_bf16 v[96:99], v[222:225], v[124:127], v[96:99]
	v_mfma_f32_16x16x32_bf16 v[140:143], v[214:217], v[124:127], v[156:159]
	s_waitcnt lgkmcnt(0)
	v_mfma_f32_16x16x32_bf16 v[152:155], v[230:233], v[132:135], v[96:99]
	v_mfma_f32_16x16x32_bf16 v[96:99], v[214:217], v[160:163], v[100:103]
	v_mfma_f32_16x16x32_bf16 v[156:159], v[218:221], v[132:135], v[140:143]
	v_mfma_f32_16x16x32_bf16 v[140:143], v[218:221], v[164:167], v[96:99]
	v_mfma_f32_16x16x32_bf16 v[96:99], v[222:225], v[160:163], v[108:111]
	v_mfma_f32_16x16x32_bf16 v[132:135], v[230:233], v[164:167], v[96:99]
	v_mfma_f32_16x16x32_bf16 v[96:99], v[214:217], v[198:201], v[112:115]
	v_mfma_f32_16x16x32_bf16 v[124:127], v[218:221], v[202:205], v[96:99]
	v_mfma_f32_16x16x32_bf16 v[96:99], v[222:225], v[198:201], v[116:119]
	v_mfma_f32_16x16x32_bf16 v[68:71], v[214:217], v[206:209], v[68:71]
	v_mfma_f32_16x16x32_bf16 v[64:67], v[222:225], v[206:209], v[64:67]
	v_mfma_f32_16x16x32_bf16 v[116:119], v[230:233], v[202:205], v[96:99]
	v_mfma_f32_16x16x32_bf16 v[68:71], v[218:221], v[210:213], v[68:71]
	v_mfma_f32_16x16x32_bf16 v[64:67], v[230:233], v[210:213], v[64:67]
	s_setprio 0
	s_mov_b32 m0, s63
	v_lshl_add_u64 v[184:185], v[226:227], 0, s[14:15]
	s_barrier
	ds_read_b128 v[96:99], v190 offset:49152
	ds_read_b128 v[100:103], v190 offset:50176
	ds_read_b128 v[108:111], v190 offset:51200
	ds_read_b128 v[112:115], v190 offset:52224
	ds_read_b128 v[160:163], v190 offset:53248
	ds_read_b128 v[164:167], v190 offset:54272
	ds_read_b128 v[198:201], v190 offset:55296
	ds_read_b128 v[202:205], v190 offset:56320
	global_load_lds_dwordx4 v[184:185], off
	v_lshl_add_u64 v[184:185], v[234:235], 0, s[14:15]
	s_mov_b32 m0, s4
	s_nop 0
	global_load_lds_dwordx4 v[184:185], off
	s_barrier
; #define PG8_STAGE(bufoff, gbase, voff) do { _Pragma("unroll") for (int _i = 0; _i < 2; ++_i) \
;         __builtin_amdgcn_global_load_lds((const unsigned*)((const char*)(gbase) + (voff)[_i]), (LAS unsigned*)(lds + (bufoff) + ldsw + _i * 8192), 16, 0, 0); } while (0)
; #define PG8_MMA(ai, bj, At, Bt) do { __builtin_amdgcn_s_setprio(1); _Pragma("unroll") for (int m = 0; m < 4; ++m) _Pragma("unroll") for (int n = 0; n < 2; ++n) _Pragma("unroll") for (int k = 0; k < 2; ++k) \
;         acc[ai][bj][m][n] = __builtin_amdgcn_mfma_f32_16x16x32_bf16(Bt[n][k], At[m][k], acc[ai][bj][m][n], 0, 0, 0); __builtin_amdgcn_s_setprio(0); } while (0)
; #define PG8_WAIT_V(n) asm volatile("s_waitcnt vmcnt(" #n ")" ::: "memory")
; #define PG8_WAIT_L(n) asm volatile("s_waitcnt lgkmcnt(" #n ")" ::: "memory")
; #define PG8_BAR __builtin_amdgcn_s_barrier()
; #define PG8_SCHED __builtin_amdgcn_sched_barrier(0)
; template <class Map, class Epi>
; DI void gemm_phase(LAS unsigned char* lds, const Map& MP, const Epi& E, const int nM, const int nN, const int K, const int lda, const int ldb) {
;     ...
;             PG8_BAR; PG8_WAIT_L(0); PG8_MMA(1, 0, At, B0); PG8_BAR; PG8_SCHED;
;             PG8_STAGE(PG8_SB(1, 1), b3 + hstepB, voffB);
;             PG8_WAIT_V(6); PG8_BAR; PG8_MMA(1, 1, At, B1); PG8_BAR;
	s_setprio 1
	s_waitcnt lgkmcnt(7)
	v_mfma_f32_16x16x32_bf16 v[60:63], v[80:83], v[96:99], v[60:63]
	v_mfma_f32_16x16x32_bf16 v[48:51], v[88:91], v[96:99], v[48:51]
	s_waitcnt lgkmcnt(5)
	v_mfma_f32_16x16x32_bf16 v[40:43], v[80:83], v[108:111], v[40:43]
	v_mfma_f32_16x16x32_bf16 v[32:35], v[88:91], v[108:111], v[32:35]
	s_waitcnt lgkmcnt(3)
	v_mfma_f32_16x16x32_bf16 v[24:27], v[80:83], v[160:163], v[24:27]
	v_mfma_f32_16x16x32_bf16 v[16:19], v[88:91], v[160:163], v[16:19]
	s_waitcnt lgkmcnt(1)
	v_mfma_f32_16x16x32_bf16 v[12:15], v[80:83], v[198:201], v[12:15]
	v_mfma_f32_16x16x32_bf16 v[8:11], v[88:91], v[198:201], v[8:11]
	v_mfma_f32_16x16x32_bf16 v[60:63], v[84:87], v[100:103], v[60:63]
	v_mfma_f32_16x16x32_bf16 v[48:51], v[92:95], v[100:103], v[48:51]
	v_mfma_f32_16x16x32_bf16 v[40:43], v[84:87], v[112:115], v[40:43]
	v_mfma_f32_16x16x32_bf16 v[32:35], v[92:95], v[112:115], v[32:35]
	v_mfma_f32_16x16x32_bf16 v[24:27], v[84:87], v[164:167], v[24:27]
	v_mfma_f32_16x16x32_bf16 v[16:19], v[92:95], v[164:167], v[16:19]
	s_waitcnt lgkmcnt(0)
	v_mfma_f32_16x16x32_bf16 v[12:15], v[84:87], v[202:205], v[12:15]
	v_mfma_f32_16x16x32_bf16 v[8:11], v[92:95], v[202:205], v[8:11]
	s_setprio 0
	s_barrier
	s_add_u32 s24, s24, 0x80080
	s_addc_u32 s25, s25, 0
	s_add_i32 s46, s46, s66
	s_mov_b32 m0, s46
	s_nop 0
	global_load_lds_dwordx4 v172, s[24:25]
	s_add_i32 m0, s46, 0x2000
	s_nop 0
	global_load_lds_dwordx4 v168, s[24:25]
	s_waitcnt vmcnt(6)
	s_barrier
	s_setprio 1
	v_mfma_f32_16x16x32_bf16 v[56:59], v[214:217], v[96:99], v[56:59]
	v_mfma_f32_16x16x32_bf16 v[52:55], v[222:225], v[96:99], v[52:55]
	v_mfma_f32_16x16x32_bf16 v[44:47], v[214:217], v[108:111], v[44:47]
	v_mfma_f32_16x16x32_bf16 v[36:39], v[222:225], v[108:111], v[36:39]
	v_mfma_f32_16x16x32_bf16 v[28:31], v[214:217], v[160:163], v[28:31]
	v_mfma_f32_16x16x32_bf16 v[20:23], v[222:225], v[160:163], v[20:23]
	v_mfma_f32_16x16x32_bf16 v[4:7], v[214:217], v[198:201], v[4:7]
	v_mfma_f32_16x16x32_bf16 v[0:3], v[222:225], v[198:201], v[0:3]
	v_mfma_f32_16x16x32_bf16 v[56:59], v[218:221], v[100:103], v[56:59]
	v_mfma_f32_16x16x32_bf16 v[52:55], v[230:233], v[100:103], v[52:55]
	v_mfma_f32_16x16x32_bf16 v[44:47], v[218:221], v[112:115], v[44:47]
	v_mfma_f32_16x16x32_bf16 v[36:39], v[230:233], v[112:115], v[36:39]
	v_mfma_f32_16x16x32_bf16 v[28:31], v[218:221], v[164:167], v[28:31]
	v_mfma_f32_16x16x32_bf16 v[20:23], v[230:233], v[164:167], v[20:23]
	v_mfma_f32_16x16x32_bf16 v[4:7], v[218:221], v[202:205], v[4:7]
	v_mfma_f32_16x16x32_bf16 v[0:3], v[230:233], v[202:205], v[0:3]
	s_setprio 0
	s_add_i32 s3, s3, 2
	s_add_u32 vcc_lo, vcc_lo, 0x100
	s_addc_u32 vcc_hi, vcc_hi, 0
	s_add_u32 s42, s42, 0x100
	s_addc_u32 s43, s43, 0
	s_cmp_gt_u32 s3, 29
	s_barrier
	s_cbranch_scc0 .LBB1_1069
; DI float silu_mul(float g, float v) { return g * v * __builtin_amdgcn_rcpf(1.0f + __builtin_amdgcn_exp2f(-LOG2E * g)); }
;     DI void operator()(const f32x4 (&acc)[2][2][4][2], const Unit& u, int wr, int wc, int fr, int fq) const {
;         const int row0 = u.pm * BM + wr * 64 + fr, ch0 = u.pn * 128 + wc * 32 + 8 * fq;
;         f32x4 w0[2], w1[2], w2[2], bb[2];
; #pragma unroll
;         for (int n = 0; n < 2; ++n) { w0[n] = *(const f32x4*)(cw + ch0 + 4 * n); w1[n] = *(const f32x4*)(cw + DFF + ch0 + 4 * n); w2[n] = *(const f32x4*)(cw + 2 * DFF + ch0 + 4 * n); bb[n] = *(const f32x4*)(cb + ch0 + 4 * n); }
; #pragma unroll
;         for (int ai = 0; ai < 2; ++ai)
; #pragma unroll
;             for (int m = 0; m < 4; ++m) {
;                 const bool efirst = (m == 0) && (fr == 0), elast = (m == 3) && (fr == 15);
;                 const int row = row0 + ai * HALF + m * 16;
;                 f32x4 gc[2];
; #pragma unroll
;                 for (int n = 0; n < 2; ++n) {
;                     const f32x4 g = acc[ai][0][m][n];
;                     const f32x4 gprev = acc[ai][0][m > 0 ? m - 1 : 0][n], gnext = acc[ai][0][m < 3 ? m + 1 : 3][n];
;                     f32x4 up, dn;
; #pragma unroll
;                     for (int e = 0; e < 4; ++e) {
;                         const float pu = (m > 0 && fr == 15) ? gprev[e] : g[e];
;                         const float pd = (m < 3 && fr == 0) ? gnext[e] : g[e];
;                         up[e] = dpp_ror1(pu); dn[e] = dpp_ror15(pd);
;                     }
;                     if (efirst) up = (f32x4){0.f, 0.f, 0.f, 0.f};
;                     if (elast) dn = (f32x4){0.f, 0.f, 0.f, 0.f};
;                     gc[n] = w0[n] * up + w1[n] * g + w2[n] * dn + bb[n];
;                 }
;                 if (efirst || elast) {
;                     const size_t eo = (size_t)((row >> 6) * 2 + (elast ? 1 : 0)) * DFF + ch0;
; #pragma unroll
;                     for (int n = 0; n < 2; ++n) { *(f32x4*)(EP + eo + 4 * n) = gc[n]; *(f32x4*)(ER + eo + 4 * n) = acc[ai][0][m][n]; *(f32x4*)(EV + eo + 4 * n) = acc[ai][1][m][n]; }
;                 } else {
;                     const f32x4 v0 = acc[ai][1][m][0], v1 = acc[ai][1][m][1];
;                     u32x4 o;
;                     o[0] = pack2(silu_mul(gc[0][0], v0[0]), silu_mul(gc[0][1], v0[1])); o[1] = pack2(silu_mul(gc[0][2], v0[2]), silu_mul(gc[0][3], v0[3]));
	s_lshl_b32 s21, s45, 7
	v_mov_b32_e32 v194, v186
	v_mov_b32_e32 v80, v187
	s_or_b32 s21, s21, s62
	v_mov_b32_e32 v160, 0
	v_lshl_add_u32 v184, v80, 3, s21
	v_ashrrev_i32_e32 v185, 31, v184
	v_lshlrev_b64 v[80:81], 2, v[184:185]
	v_lshl_add_u64 v[84:85], s[6:7], 0, v[80:81]
	v_lshl_add_u64 v[88:89], s[16:17], 0, v[80:81]
	v_lshl_add_u64 v[92:93], s[18:19], 0, v[80:81]
	v_lshl_add_u64 v[112:113], s[52:53], 0, v[80:81]
	global_load_dwordx4 v[80:83], v[84:85], off offset:16
	global_load_dwordx4 v[96:99], v[84:85], off
	s_nop 0
	global_load_dwordx4 v[84:87], v[88:89], off offset:16
	global_load_dwordx4 v[100:103], v[88:89], off
	s_nop 0
	global_load_dwordx4 v[88:91], v[92:93], off offset:16
	global_load_dwordx4 v[108:111], v[92:93], off
	s_nop 0
	global_load_dwordx4 v[92:95], v[112:113], off offset:16
	s_nop 0
	global_load_dwordx4 v[112:115], v[112:113], off
	v_cmp_eq_u32_e32 vcc, 0, v194
	v_mov_b32_e32 v164, 0
	v_mov_b32_e32 v195, 0
	v_cndmask_b32_e32 v161, v148, v136, vcc
	v_cndmask_b32_e32 v162, v149, v137, vcc
	v_cndmask_b32_e32 v163, v150, v138, vcc
	v_mov_b32_dpp v160, v161 row_ror:15 row_mask:0xf bank_mask:0xf
	v_mov_b32_e32 v161, 0
	v_mov_b32_e32 v166, 0
	v_mov_b32_e32 v167, 0
	v_mov_b32_dpp v161, v162 row_ror:15 row_mask:0xf bank_mask:0xf
	v_mov_b32_e32 v162, 0
	v_mov_b32_dpp v164, v150 row_ror:1 row_mask:0xf bank_mask:0xf
	v_cndmask_b32_e32 v165, v151, v139, vcc
	v_mov_b32_dpp v162, v163 row_ror:15 row_mask:0xf bank_mask:0xf
	v_mov_b32_dpp v195, v151 row_ror:1 row_mask:0xf bank_mask:0xf
	v_mov_b32_e32 v163, 0
	v_mov_b32_dpp v166, v148 row_ror:1 row_mask:0xf bank_mask:0xf
	v_mov_b32_dpp v167, v149 row_ror:1 row_mask:0xf bank_mask:0xf
	v_mov_b32_dpp v163, v165 row_ror:15 row_mask:0xf bank_mask:0xf
	v_cndmask_b32_e64 v165, v195, 0, vcc
	v_cndmask_b32_e64 v164, v164, 0, vcc
	v_cndmask_b32_e64 v167, v167, 0, vcc
	v_cndmask_b32_e64 v166, v166, 0, vcc
	v_mov_b32_e32 v195, 0
	v_mov_b32_e32 v196, 0
	v_mov_b32_e32 v198, 0
	v_mov_b32_e32 v200, 0
	v_mov_b32_dpp v195, v144 row_ror:1 row_mask:0xf bank_mask:0xf
	v_mov_b32_dpp v196, v145 row_ror:1 row_mask:0xf bank_mask:0xf
	v_mov_b32_dpp v198, v146 row_ror:1 row_mask:0xf bank_mask:0xf
	v_cndmask_b32_e32 v199, v147, v131, vcc
	v_mov_b32_dpp v200, v147 row_ror:1 row_mask:0xf bank_mask:0xf
	v_cndmask_b32_e64 v198, v198, 0, vcc
	v_cndmask_b32_e64 v201, v196, 0, vcc
	s_lshl_b32 s3, s44, 8
	s_add_i32 s3, s3, s49
	v_add_u32_e32 v193, s3, v194
	v_cmp_ne_u32_e64 s[46:47], 0, v194
	s_waitcnt vmcnt(0)
	v_pk_mul_f32 v[164:165], v[98:99], v[164:165]
	v_pk_mul_f32 v[166:167], v[96:97], v[166:167]
	v_pk_fma_f32 v[164:165], v[150:151], v[102:103], v[164:165]
	v_pk_fma_f32 v[166:167], v[148:149], v[100:101], v[166:167]
	v_pk_fma_f32 v[162:163], v[110:111], v[162:163], v[164:165]
	v_cndmask_b32_e32 v165, v144, v128, vcc
	v_mov_b32_e32 v164, 0
	v_pk_fma_f32 v[160:161], v[108:109], v[160:161], v[166:167]
	v_cndmask_b32_e32 v166, v145, v129, vcc
	v_mov_b32_dpp v164, v165 row_ror:15 row_mask:0xf bank_mask:0xf
	v_mov_b32_e32 v165, 0
	v_cndmask_b32_e32 v167, v146, v130, vcc
	v_pk_add_f32 v[162:163], v[114:115], v[162:163]
	v_mov_b32_dpp v165, v166 row_ror:15 row_mask:0xf bank_mask:0xf
	v_mov_b32_e32 v166, 0
	v_pk_add_f32 v[160:161], v[112:113], v[160:161]
	s_nop 0
	v_mov_b32_dpp v166, v167 row_ror:15 row_mask:0xf bank_mask:0xf
	v_mov_b32_e32 v167, 0
	s_nop 1
	v_mov_b32_dpp v167, v199 row_ror:15 row_mask:0xf bank_mask:0xf
	v_cndmask_b32_e64 v199, v200, 0, vcc
	v_cndmask_b32_e64 v200, v195, 0, vcc
	v_pk_mul_f32 v[200:201], v[80:81], v[200:201]
	v_pk_mul_f32 v[198:199], v[82:83], v[198:199]
	v_pk_fma_f32 v[200:201], v[144:145], v[84:85], v[200:201]
	v_pk_fma_f32 v[198:199], v[146:147], v[86:87], v[198:199]
	v_pk_fma_f32 v[164:165], v[88:89], v[164:165], v[200:201]
	v_pk_fma_f32 v[166:167], v[90:91], v[166:167], v[198:199]
	v_pk_add_f32 v[164:165], v[92:93], v[164:165]
	v_pk_add_f32 v[166:167], v[94:95], v[166:167]
	s_and_saveexec_b64 s[24:25], s[46:47]
	s_xor_b64 s[24:25], exec, s[24:25]
	s_cbranch_execz .LBB1_1072
	v_mul_f32_e32 v195, 0xbfb8aa3b, v160
	v_exp_f32_e32 v195, v195
	v_mul_f32_e32 v196, 0xbfb8aa3b, v161
	v_exp_f32_e32 v196, v196
	v_pk_mul_f32 v[160:161], v[156:157], v[160:161]
	v_add_f32_e32 v195, 1.0, v195
	v_rcp_f32_e32 v198, v195
	v_add_f32_e32 v196, 1.0, v196
	v_mul_f32_e32 v195, 0xbfb8aa3b, v162
	v_rcp_f32_e32 v199, v196
	v_exp_f32_e32 v195, v195
	v_mul_f32_e32 v196, 0xbfb8aa3b, v163
	v_exp_f32_e32 v196, v196
	v_pk_mul_f32 v[160:161], v[160:161], v[198:199]
	v_add_f32_e32 v195, 1.0, v195
	v_rcp_f32_e32 v200, v195
	v_add_f32_e32 v195, 1.0, v196
	v_rcp_f32_e32 v201, v195
	v_cvt_pk_bf16_f32 v160, v160, v161
	v_mul_f32_e32 v161, 0xbfb8aa3b, v164
	v_exp_f32_e32 v195, v161
	v_mul_f32_e32 v161, 0xbfb8aa3b, v165
	v_exp_f32_e32 v196, v161
	v_pk_mul_f32 v[162:163], v[158:159], v[162:163]
	v_pk_mul_f32 v[164:165], v[152:153], v[164:165]
	v_pk_mul_f32 v[162:163], v[162:163], v[200:201]
	s_nop 0
	v_cvt_pk_bf16_f32 v161, v162, v163
	v_add_f32_e32 v162, 1.0, v195
	v_mul_f32_e32 v195, 0xbfb8aa3b, v166
	v_add_f32_e32 v163, 1.0, v196
	v_exp_f32_e32 v195, v195
	v_mul_f32_e32 v196, 0xbfb8aa3b, v167
	v_exp_f32_e32 v196, v196
	v_rcp_f32_e32 v162, v162
	v_add_f32_e32 v195, 1.0, v195
	v_rcp_f32_e32 v198, v195
	v_add_f32_e32 v195, 1.0, v196
	v_rcp_f32_e32 v163, v163
	v_rcp_f32_e32 v199, v195
	v_pk_mul_f32 v[166:167], v[154:155], v[166:167]
	v_pk_mul_f32 v[162:163], v[164:165], v[162:163]
	v_pk_mul_f32 v[164:165], v[166:167], v[198:199]
	v_cvt_pk_bf16_f32 v162, v162, v163
	v_cvt_pk_bf16_f32 v163, v164, v165
	v_mov_b64_e32 v[164:165], s[54:55]
	v_mad_i64_i32 v[164:165], s[42:43], v193, s60, v[164:165]
	v_lshl_add_u64 v[164:165], v[184:185], 1, v[164:165]
	global_store_dwordx4 v[164:165], v[160:163], off

; #define PG8_STAGE(bufoff, gbase, voff) do { _Pragma("unroll") for (int _i = 0; _i < 2; ++_i) \
;         __builtin_amdgcn_global_load_lds((const unsigned*)((const char*)(gbase) + (voff)[_i]), (LAS unsigned*)(lds + (bufoff) + ldsw + _i * 8192), 16, 0, 0); } while (0)
; #define PG8_LDA(dst, b, h) do { _Pragma("unroll") for (int m = 0; m < 4; ++m) _Pragma("unroll") for (int k = 0; k < 2; ++k) dst[m][k] = *(const LAS bf16x8*)(lds + PG8_SA(b, h) + aoff + m * 2048 + k * 1024); } while (0)
; #define PG8_LDB(dst, b, h) do { _Pragma("unroll") for (int n = 0; n < 2; ++n) _Pragma("unroll") for (int k = 0; k < 2; ++k) dst[n][k] = *(const LAS bf16x8*)(lds + PG8_SB(b, h) + boff + n * 2048 + k * 1024); } while (0)
; #define PG8_MMA(ai, bj, At, Bt) do { __builtin_amdgcn_s_setprio(1); _Pragma("unroll") for (int m = 0; m < 4; ++m) _Pragma("unroll") for (int n = 0; n < 2; ++n) _Pragma("unroll") for (int k = 0; k < 2; ++k) \
;         acc[ai][bj][m][n] = __builtin_amdgcn_mfma_f32_16x16x32_bf16(Bt[n][k], At[m][k], acc[ai][bj][m][n], 0, 0, 0); __builtin_amdgcn_s_setprio(0); } while (0)
; #define PG8_WAIT_L(n) asm volatile("s_waitcnt lgkmcnt(" #n ")" ::: "memory")
; #define PG8_BAR __builtin_amdgcn_s_barrier()
; #define PG8_SCHED __builtin_amdgcn_sched_barrier(0)
; template <class Map, class Epi>
; DI void gemm_phase(LAS unsigned char* lds, const Map& MP, const Epi& E, const int nM, const int nN, const int K, const int lda, const int ldb) {
;     ...
;             const bool last = (t == nt - 2);
;             const char* a1 = cA + (size_t)(t + 1) * kstep;
;             const char* a2 = last ? nA : cA + (size_t)(t + 2) * kstep; const char* b2 = last ? nB : cB + (size_t)(t + 2) * kstep;
;             const char* a3 = a2 + kstep; const char* b3 = b2 + kstep;
;             PG8_LDB(B0, 0, 0); PG8_SCHED; PG8_LDA(At, 0, 0); PG8_STAGE(PG8_SA(1, 1), a1 + hstepA, voffA);
;             PG8_WAIT_L(8); PG8_BAR; PG8_WAIT_L(0); PG8_MMA(0, 0, At, B0); PG8_BAR; PG8_SCHED;
;             PG8_LDB(B1, 0, 1); PG8_STAGE(PG8_SB(0, 0), b2, voffB);
;             PG8_BAR; PG8_WAIT_L(0); PG8_MMA(0, 1, At, B1); PG8_BAR;
;             PG8_LDA(At, 0, 1); PG8_STAGE(PG8_SA(0, 0), a2, voffA);
;             PG8_BAR; PG8_WAIT_L(0); PG8_MMA(1, 0, At, B0); PG8_BAR; PG8_SCHED;
.LBB1_1239:
	ds_read_b128 v[152:155], v149
	ds_read_b128 v[156:159], v149 offset:1024
	ds_read_b128 v[160:163], v149 offset:2048
	ds_read_b128 v[164:167], v149 offset:3072
	s_add_u32 s10, s8, 0x100
	s_addc_u32 s11, s9, 0
	s_cmpk_eq_i32 s3, 0x54
	s_cselect_b32 s15, s43, s11
	s_cselect_b32 s14, s42, s10
	s_cselect_b32 s13, s7, s38
	s_cselect_b32 s12, s6, s5
	s_add_i32 m0, s24, 0xc000
	ds_read_b128 v[168:171], v150
	ds_read_b128 v[172:175], v150 offset:1024
	ds_read_b128 v[176:179], v150 offset:2048
	ds_read_b128 v[180:183], v150 offset:3072
	ds_read_b128 v[184:187], v150 offset:4096
	ds_read_b128 v[188:191], v150 offset:5120
	ds_read_b128 v[192:195], v150 offset:6144
	ds_read_b128 v[198:201], v150 offset:7168
	global_load_lds_dwordx4 v138, s[8:9]
	s_add_i32 m0, s24, 0xe000
	s_nop 0
	global_load_lds_dwordx4 v136, s[8:9]
	s_waitcnt lgkmcnt(8)
	s_barrier
	s_setprio 1
	s_waitcnt lgkmcnt(7)
	v_mfma_f32_16x16x32_bf16 v[124:127], v[152:155], v[168:171], v[124:127]
	v_mfma_f32_16x16x32_bf16 v[120:123], v[160:163], v[168:171], v[120:123]
	s_waitcnt lgkmcnt(5)
	v_mfma_f32_16x16x32_bf16 v[108:111], v[152:155], v[176:179], v[108:111]
	v_mfma_f32_16x16x32_bf16 v[104:107], v[160:163], v[176:179], v[104:107]
	s_waitcnt lgkmcnt(3)
	v_mfma_f32_16x16x32_bf16 v[92:95], v[152:155], v[184:187], v[92:95]
	v_mfma_f32_16x16x32_bf16 v[88:91], v[160:163], v[184:187], v[88:91]
	s_waitcnt lgkmcnt(1)
	v_mfma_f32_16x16x32_bf16 v[76:79], v[152:155], v[192:195], v[76:79]
	v_mfma_f32_16x16x32_bf16 v[72:75], v[160:163], v[192:195], v[72:75]
	v_mfma_f32_16x16x32_bf16 v[124:127], v[156:159], v[172:175], v[124:127]
	v_mfma_f32_16x16x32_bf16 v[120:123], v[164:167], v[172:175], v[120:123]
	v_mfma_f32_16x16x32_bf16 v[108:111], v[156:159], v[180:183], v[108:111]
	v_mfma_f32_16x16x32_bf16 v[104:107], v[164:167], v[180:183], v[104:107]
	v_mfma_f32_16x16x32_bf16 v[92:95], v[156:159], v[188:191], v[92:95]
	v_mfma_f32_16x16x32_bf16 v[88:91], v[164:167], v[188:191], v[88:91]
	s_waitcnt lgkmcnt(0)
	v_mfma_f32_16x16x32_bf16 v[76:79], v[156:159], v[198:201], v[76:79]
	v_mfma_f32_16x16x32_bf16 v[72:75], v[164:167], v[198:201], v[72:75]
	s_setprio 0
	s_barrier
	s_add_i32 s8, s35, s22
	v_lshl_add_u64 v[144:145], s[12:13], 0, v[132:133]
	s_mov_b32 m0, s8
	ds_read_b128 v[202:205], v151
	ds_read_b128 v[206:209], v151 offset:1024
	ds_read_b128 v[210:213], v151 offset:2048
	ds_read_b128 v[214:217], v151 offset:3072
	global_load_lds_dwordx4 v[144:145], off
	v_lshl_add_u64 v[218:219], s[12:13], 0, v[128:129]
	s_add_i32 m0, s8, 0x2000
	s_nop 0
	global_load_lds_dwordx4 v[218:219], off
	s_barrier
	s_setprio 1
	s_waitcnt lgkmcnt(3)
	v_mfma_f32_16x16x32_bf16 v[116:119], v[202:205], v[168:171], v[116:119]
	s_waitcnt lgkmcnt(1)
	v_mfma_f32_16x16x32_bf16 v[112:115], v[210:213], v[168:171], v[112:115]
	v_mfma_f32_16x16x32_bf16 v[100:103], v[202:205], v[176:179], v[100:103]
	v_mfma_f32_16x16x32_bf16 v[96:99], v[210:213], v[176:179], v[96:99]
	v_mfma_f32_16x16x32_bf16 v[84:87], v[202:205], v[184:187], v[84:87]
	v_mfma_f32_16x16x32_bf16 v[80:83], v[210:213], v[184:187], v[80:83]
	v_mfma_f32_16x16x32_bf16 v[68:71], v[202:205], v[192:195], v[68:71]
	v_mfma_f32_16x16x32_bf16 v[64:67], v[210:213], v[192:195], v[64:67]
	v_mfma_f32_16x16x32_bf16 v[116:119], v[206:209], v[172:175], v[116:119]
	s_waitcnt lgkmcnt(0)
	v_mfma_f32_16x16x32_bf16 v[112:115], v[214:217], v[172:175], v[112:115]
	v_mfma_f32_16x16x32_bf16 v[100:103], v[206:209], v[180:183], v[100:103]
	v_mfma_f32_16x16x32_bf16 v[96:99], v[214:217], v[180:183], v[96:99]
	v_mfma_f32_16x16x32_bf16 v[84:87], v[206:209], v[188:191], v[84:87]
	v_mfma_f32_16x16x32_bf16 v[80:83], v[214:217], v[188:191], v[80:83]
	v_mfma_f32_16x16x32_bf16 v[68:71], v[206:209], v[198:201], v[68:71]
	v_mfma_f32_16x16x32_bf16 v[64:67], v[214:217], v[198:201], v[64:67]
	s_setprio 0
	s_mov_b32 m0, s24
	v_lshl_add_u64 v[220:221], s[14:15], 0, v[134:135]
	s_barrier
	ds_read_b128 v[168:171], v150 offset:16384
	ds_read_b128 v[172:175], v150 offset:17408
	ds_read_b128 v[176:179], v150 offset:18432
	ds_read_b128 v[180:183], v150 offset:19456
	ds_read_b128 v[184:187], v150 offset:20480
	ds_read_b128 v[188:191], v150 offset:21504
	ds_read_b128 v[192:195], v150 offset:22528
	ds_read_b128 v[198:201], v150 offset:23552
	global_load_lds_dwordx4 v[220:221], off
	v_lshl_add_u64 v[222:223], s[14:15], 0, v[130:131]
	s_mov_b32 m0, s25
	s_nop 0
	global_load_lds_dwordx4 v[222:223], off
	s_barrier
	s_setprio 1
	s_waitcnt lgkmcnt(7)
	v_mfma_f32_16x16x32_bf16 v[60:63], v[152:155], v[168:171], v[60:63]
	v_mfma_f32_16x16x32_bf16 v[56:59], v[160:163], v[168:171], v[56:59]
	s_waitcnt lgkmcnt(5)
	v_mfma_f32_16x16x32_bf16 v[44:47], v[152:155], v[176:179], v[44:47]
	v_mfma_f32_16x16x32_bf16 v[40:43], v[160:163], v[176:179], v[40:43]
	s_waitcnt lgkmcnt(3)
	v_mfma_f32_16x16x32_bf16 v[28:31], v[152:155], v[184:187], v[28:31]
	v_mfma_f32_16x16x32_bf16 v[24:27], v[160:163], v[184:187], v[24:27]
	s_waitcnt lgkmcnt(1)
	v_mfma_f32_16x16x32_bf16 v[12:15], v[152:155], v[192:195], v[12:15]
	v_mfma_f32_16x16x32_bf16 v[8:11], v[160:163], v[192:195], v[8:11]
	v_mfma_f32_16x16x32_bf16 v[60:63], v[156:159], v[172:175], v[60:63]
	v_mfma_f32_16x16x32_bf16 v[56:59], v[164:167], v[172:175], v[56:59]
	v_mfma_f32_16x16x32_bf16 v[44:47], v[156:159], v[180:183], v[44:47]
	v_mfma_f32_16x16x32_bf16 v[40:43], v[164:167], v[180:183], v[40:43]
	v_mfma_f32_16x16x32_bf16 v[28:31], v[156:159], v[188:191], v[28:31]
	v_mfma_f32_16x16x32_bf16 v[24:27], v[164:167], v[188:191], v[24:27]
	s_waitcnt lgkmcnt(0)
	v_mfma_f32_16x16x32_bf16 v[12:15], v[156:159], v[198:201], v[12:15]
	v_mfma_f32_16x16x32_bf16 v[8:11], v[164:167], v[198:201], v[8:11]
	s_setprio 0
	s_barrier
; #define PG8_STAGE(bufoff, gbase, voff) do { _Pragma("unroll") for (int _i = 0; _i < 2; ++_i) \
;         __builtin_amdgcn_global_load_lds((const unsigned*)((const char*)(gbase) + (voff)[_i]), (LAS unsigned*)(lds + (bufoff) + ldsw + _i * 8192), 16, 0, 0); } while (0)
; #define PG8_LDA(dst, b, h) do { _Pragma("unroll") for (int m = 0; m < 4; ++m) _Pragma("unroll") for (int k = 0; k < 2; ++k) dst[m][k] = *(const LAS bf16x8*)(lds + PG8_SA(b, h) + aoff + m * 2048 + k * 1024); } while (0)
; #define PG8_LDB(dst, b, h) do { _Pragma("unroll") for (int n = 0; n < 2; ++n) _Pragma("unroll") for (int k = 0; k < 2; ++k) dst[n][k] = *(const LAS bf16x8*)(lds + PG8_SB(b, h) + boff + n * 2048 + k * 1024); } while (0)
; #define PG8_MMA(ai, bj, At, Bt) do { __builtin_amdgcn_s_setprio(1); _Pragma("unroll") for (int m = 0; m < 4; ++m) _Pragma("unroll") for (int n = 0; n < 2; ++n) _Pragma("unroll") for (int k = 0; k < 2; ++k) \
;         acc[ai][bj][m][n] = __builtin_amdgcn_mfma_f32_16x16x32_bf16(Bt[n][k], At[m][k], acc[ai][bj][m][n], 0, 0, 0); __builtin_amdgcn_s_setprio(0); } while (0)
; #define PG8_WAIT_V(n) asm volatile("s_waitcnt vmcnt(" #n ")" ::: "memory")
; #define PG8_WAIT_L(n) asm volatile("s_waitcnt lgkmcnt(" #n ")" ::: "memory")
; #define PG8_BAR __builtin_amdgcn_s_barrier()
; #define PG8_SCHED __builtin_amdgcn_sched_barrier(0)
; template <class Map, class Epi>
; DI void gemm_phase(LAS unsigned char* lds, const Map& MP, const Epi& E, const int nM, const int nN, const int K, const int lda, const int ldb) {
;     ...
;             PG8_STAGE(PG8_SB(0, 1), b2 + hstepB, voffB);
;             PG8_WAIT_V(6); PG8_BAR; PG8_MMA(1, 1, At, B1); PG8_BAR;
;             PG8_LDB(B0, 1, 0); PG8_SCHED; PG8_LDA(At, 1, 0); PG8_STAGE(PG8_SA(0, 1), a2 + hstepA, voffA);
;             PG8_WAIT_L(8); PG8_BAR; PG8_WAIT_L(0); PG8_MMA(0, 0, At, B0); PG8_BAR; PG8_SCHED;
;             PG8_LDB(B1, 1, 1); PG8_STAGE(PG8_SB(1, 0), b3, voffB);
;             PG8_BAR; PG8_WAIT_L(0); PG8_MMA(0, 1, At, B1); PG8_BAR;
;             PG8_LDA(At, 1, 1); PG8_STAGE(PG8_SA(1, 0), a3, voffA);
;             PG8_BAR; PG8_WAIT_L(0); PG8_MMA(1, 0, At, B0); PG8_BAR; PG8_SCHED;
	s_add_u32 s8, s12, 0x160000
	s_addc_u32 s9, s13, 0
	s_add_i32 s39, s36, s22
	s_mov_b32 m0, s39
	s_nop 0
	global_load_lds_dwordx4 v132, s[8:9]
	s_add_i32 m0, s39, 0x2000
	s_nop 0
	global_load_lds_dwordx4 v128, s[8:9]
	s_waitcnt vmcnt(6)
	s_barrier
	s_setprio 1
	v_mfma_f32_16x16x32_bf16 v[52:55], v[202:205], v[168:171], v[52:55]
	v_mfma_f32_16x16x32_bf16 v[48:51], v[210:213], v[168:171], v[48:51]
	v_mfma_f32_16x16x32_bf16 v[36:39], v[202:205], v[176:179], v[36:39]
	v_mfma_f32_16x16x32_bf16 v[32:35], v[210:213], v[176:179], v[32:35]
	v_mfma_f32_16x16x32_bf16 v[20:23], v[202:205], v[184:187], v[20:23]
	v_mfma_f32_16x16x32_bf16 v[16:19], v[210:213], v[184:187], v[16:19]
	v_mfma_f32_16x16x32_bf16 v[4:7], v[202:205], v[192:195], v[4:7]
	v_mfma_f32_16x16x32_bf16 v[0:3], v[210:213], v[192:195], v[0:3]
	v_mfma_f32_16x16x32_bf16 v[52:55], v[206:209], v[172:175], v[52:55]
	v_mfma_f32_16x16x32_bf16 v[48:51], v[214:217], v[172:175], v[48:51]
	v_mfma_f32_16x16x32_bf16 v[36:39], v[206:209], v[180:183], v[36:39]
	v_mfma_f32_16x16x32_bf16 v[32:35], v[214:217], v[180:183], v[32:35]
	v_mfma_f32_16x16x32_bf16 v[20:23], v[206:209], v[188:191], v[20:23]
	v_mfma_f32_16x16x32_bf16 v[16:19], v[214:217], v[188:191], v[16:19]
	v_mfma_f32_16x16x32_bf16 v[4:7], v[206:209], v[198:201], v[4:7]
	v_mfma_f32_16x16x32_bf16 v[0:3], v[214:217], v[198:201], v[0:3]
	s_setprio 0
	s_add_i32 s39, 0, 0x18000
	v_add_u32_e32 v164, s39, v148
	s_barrier
	ds_read_b128 v[152:155], v164
	ds_read_b128 v[156:159], v164 offset:1024
	ds_read_b128 v[160:163], v164 offset:2048
	ds_read_b128 v[164:167], v164 offset:3072
	s_add_u32 s8, s14, 0x160000
	s_addc_u32 s9, s15, 0
	s_mov_b32 m0, s26
	ds_read_b128 v[168:171], v150 offset:32768
	ds_read_b128 v[172:175], v150 offset:33792
	ds_read_b128 v[176:179], v150 offset:34816
	ds_read_b128 v[180:183], v150 offset:35840
	ds_read_b128 v[184:187], v150 offset:36864
	ds_read_b128 v[188:191], v150 offset:37888
	ds_read_b128 v[192:195], v150 offset:38912
	ds_read_b128 v[198:201], v150 offset:39936
	global_load_lds_dwordx4 v134, s[8:9]
	s_mov_b32 m0, s27
	s_nop 0
	global_load_lds_dwordx4 v130, s[8:9]
	s_waitcnt lgkmcnt(8)
	s_barrier
	s_setprio 1
	s_waitcnt lgkmcnt(7)
	v_mfma_f32_16x16x32_bf16 v[124:127], v[152:155], v[168:171], v[124:127]
	v_mfma_f32_16x16x32_bf16 v[120:123], v[160:163], v[168:171], v[120:123]
	s_waitcnt lgkmcnt(5)
	v_mfma_f32_16x16x32_bf16 v[108:111], v[152:155], v[176:179], v[108:111]
	v_mfma_f32_16x16x32_bf16 v[104:107], v[160:163], v[176:179], v[104:107]
	s_waitcnt lgkmcnt(3)
	v_mfma_f32_16x16x32_bf16 v[92:95], v[152:155], v[184:187], v[92:95]
	v_mfma_f32_16x16x32_bf16 v[88:91], v[160:163], v[184:187], v[88:91]
	s_waitcnt lgkmcnt(1)
	v_mfma_f32_16x16x32_bf16 v[76:79], v[152:155], v[192:195], v[76:79]
	v_mfma_f32_16x16x32_bf16 v[72:75], v[160:163], v[192:195], v[72:75]
	v_mfma_f32_16x16x32_bf16 v[124:127], v[156:159], v[172:175], v[124:127]
	v_mfma_f32_16x16x32_bf16 v[120:123], v[164:167], v[172:175], v[120:123]
	v_mfma_f32_16x16x32_bf16 v[108:111], v[156:159], v[180:183], v[108:111]
	v_mfma_f32_16x16x32_bf16 v[104:107], v[164:167], v[180:183], v[104:107]
	v_mfma_f32_16x16x32_bf16 v[92:95], v[156:159], v[188:191], v[92:95]
	v_mfma_f32_16x16x32_bf16 v[88:91], v[164:167], v[188:191], v[88:91]
	s_waitcnt lgkmcnt(0)
	v_mfma_f32_16x16x32_bf16 v[76:79], v[156:159], v[198:201], v[76:79]
	v_mfma_f32_16x16x32_bf16 v[72:75], v[164:167], v[198:201], v[72:75]
	s_setprio 0
	s_barrier
	s_add_i32 s14, 0, 0x1c000
	s_add_i32 s8, s39, s22
	v_add_u32_e32 v196, s14, v148
	v_lshl_add_u64 v[144:145], v[144:145], 0, s[52:53]
	s_mov_b32 m0, s8
	ds_read_b128 v[202:205], v196
	ds_read_b128 v[206:209], v196 offset:1024
	ds_read_b128 v[210:213], v196 offset:2048
	ds_read_b128 v[214:217], v196 offset:3072
	global_load_lds_dwordx4 v[144:145], off
	v_lshl_add_u64 v[144:145], v[218:219], 0, s[52:53]
	s_add_i32 m0, s8, 0x2000
	s_nop 0
	global_load_lds_dwordx4 v[144:145], off
	s_barrier
	s_setprio 1
	s_waitcnt lgkmcnt(3)
	v_mfma_f32_16x16x32_bf16 v[116:119], v[202:205], v[168:171], v[116:119]
	s_waitcnt lgkmcnt(1)
	v_mfma_f32_16x16x32_bf16 v[112:115], v[210:213], v[168:171], v[112:115]
	v_mfma_f32_16x16x32_bf16 v[100:103], v[202:205], v[176:179], v[100:103]
	v_mfma_f32_16x16x32_bf16 v[96:99], v[210:213], v[176:179], v[96:99]
	v_mfma_f32_16x16x32_bf16 v[84:87], v[202:205], v[184:187], v[84:87]
	v_mfma_f32_16x16x32_bf16 v[80:83], v[210:213], v[184:187], v[80:83]
	v_mfma_f32_16x16x32_bf16 v[68:71], v[202:205], v[192:195], v[68:71]
	v_mfma_f32_16x16x32_bf16 v[64:67], v[210:213], v[192:195], v[64:67]
	v_mfma_f32_16x16x32_bf16 v[116:119], v[206:209], v[172:175], v[116:119]
	s_waitcnt lgkmcnt(0)
	v_mfma_f32_16x16x32_bf16 v[112:115], v[214:217], v[172:175], v[112:115]
	v_mfma_f32_16x16x32_bf16 v[100:103], v[206:209], v[180:183], v[100:103]
	v_mfma_f32_16x16x32_bf16 v[96:99], v[214:217], v[180:183], v[96:99]
	v_mfma_f32_16x16x32_bf16 v[84:87], v[206:209], v[188:191], v[84:87]
	v_mfma_f32_16x16x32_bf16 v[80:83], v[214:217], v[188:191], v[80:83]
	v_mfma_f32_16x16x32_bf16 v[68:71], v[206:209], v[198:201], v[68:71]
	v_mfma_f32_16x16x32_bf16 v[64:67], v[214:217], v[198:201], v[64:67]
	s_setprio 0
	s_mov_b32 m0, s30
	v_lshl_add_u64 v[144:145], v[220:221], 0, s[52:53]
	s_barrier
	ds_read_b128 v[168:171], v150 offset:49152
	ds_read_b128 v[172:175], v150 offset:50176
	ds_read_b128 v[176:179], v150 offset:51200
	ds_read_b128 v[180:183], v150 offset:52224
	ds_read_b128 v[184:187], v150 offset:53248
	ds_read_b128 v[188:191], v150 offset:54272
	ds_read_b128 v[192:195], v150 offset:55296
	ds_read_b128 v[198:201], v150 offset:56320
	global_load_lds_dwordx4 v[144:145], off
	v_lshl_add_u64 v[144:145], v[222:223], 0, s[52:53]
	s_mov_b32 m0, s31
	s_nop 0
	global_load_lds_dwordx4 v[144:145], off
	s_barrier
; DI unsigned pack2(float a, float b) { f32x2 v = {a, b}; hwbf16x2 r = __builtin_convertvector(v, hwbf16x2); return __builtin_bit_cast(unsigned, r); }
; DI float bflo(unsigned w) { return __uint_as_float(w << 16); }
; DI float bfhi(unsigned w) { return __uint_as_float(w & 0xffff0000u); }
; #define PG8_STAGE(bufoff, gbase, voff) do { _Pragma("unroll") for (int _i = 0; _i < 2; ++_i) \
;         __builtin_amdgcn_global_load_lds((const unsigned*)((const char*)(gbase) + (voff)[_i]), (LAS unsigned*)(lds + (bufoff) + ldsw + _i * 8192), 16, 0, 0); } while (0)
; #define PG8_WAIT_V(n) asm volatile("s_waitcnt vmcnt(" #n ")" ::: "memory")
; #define PG8_WAIT_L(n) asm volatile("s_waitcnt lgkmcnt(" #n ")" ::: "memory")
;     DI void operator()(const f32x4 (&acc)[2][2][4][2], const Unit& u, int wr, int wc, int fr, int fq) const {
;     ...
;         for (int ai = 0; ai < 2; ++ai)
; #pragma unroll
;             for (int m = 0; m < 4; ++m) { const size_t ro = (size_t)(row0 + ai * HALF + m * 16) * D + col0;
; #pragma unroll
;                 for (int bj = 0; bj < 2; ++bj) {
;                     f32x4 x0, x1;
;                     if constexpr (IB) { const u32x4 w = *(const u32x4*)((const bf16_t*)Xin + ro + bj * HALF);
;                         x0 = (f32x4){bflo(w[0]), bfhi(w[0]), bflo(w[1]), bfhi(w[1])}; x1 = (f32x4){bflo(w[2]), bfhi(w[2]), bflo(w[3]), bfhi(w[3])}; }
;                     else { x0 = *(const f32x4*)((const float*)Xin + ro + bj * HALF); x1 = *(const f32x4*)((const float*)Xin + ro + bj * HALF + 4); }
;                     x0 += acc[ai][bj][m][0] * sc[bj][0]; x1 += acc[ai][bj][m][1] * sc[bj][1];
;                     if constexpr (OB) { u32x4 o; o[0] = pack2(x0[0], x0[1]); o[1] = pack2(x0[2], x0[3]); o[2] = pack2(x1[0], x1[1]); o[3] = pack2(x1[2], x1[3]);
;                         *(u32x4*)((bf16_t*)Xout + ro + bj * HALF) = o; }
;                     else { *(f32x4*)((float*)Xout + ro + bj * HALF) = x0; *(f32x4*)((float*)Xout + ro + bj * HALF + 4) = x1; } } }
; template <class Map, class Epi>
; DI void gemm_phase(LAS unsigned char* lds, const Map& MP, const Epi& E, const int nM, const int nN, const int K, const int lda, const int ldb) {
;     ...
;             PG8_BAR; PG8_WAIT_L(0); PG8_MMA(1, 0, At, B0); PG8_BAR; PG8_SCHED;
;             PG8_STAGE(PG8_SB(1, 1), b3 + hstepB, voffB);
;             PG8_WAIT_V(6); PG8_BAR; PG8_MMA(1, 1, At, B1); PG8_BAR;
	s_setprio 1
	s_waitcnt lgkmcnt(7)
	v_mfma_f32_16x16x32_bf16 v[60:63], v[152:155], v[168:171], v[60:63]
	v_mfma_f32_16x16x32_bf16 v[56:59], v[160:163], v[168:171], v[56:59]
	s_waitcnt lgkmcnt(5)
	v_mfma_f32_16x16x32_bf16 v[44:47], v[152:155], v[176:179], v[44:47]
	v_mfma_f32_16x16x32_bf16 v[40:43], v[160:163], v[176:179], v[40:43]
	s_waitcnt lgkmcnt(3)
	v_mfma_f32_16x16x32_bf16 v[28:31], v[152:155], v[184:187], v[28:31]
	v_mfma_f32_16x16x32_bf16 v[24:27], v[160:163], v[184:187], v[24:27]
	s_waitcnt lgkmcnt(1)
	v_mfma_f32_16x16x32_bf16 v[12:15], v[152:155], v[192:195], v[12:15]
	v_mfma_f32_16x16x32_bf16 v[8:11], v[160:163], v[192:195], v[8:11]
	v_mfma_f32_16x16x32_bf16 v[60:63], v[156:159], v[172:175], v[60:63]
	v_mfma_f32_16x16x32_bf16 v[56:59], v[164:167], v[172:175], v[56:59]
	v_mfma_f32_16x16x32_bf16 v[44:47], v[156:159], v[180:183], v[44:47]
	v_mfma_f32_16x16x32_bf16 v[40:43], v[164:167], v[180:183], v[40:43]
	v_mfma_f32_16x16x32_bf16 v[28:31], v[156:159], v[188:191], v[28:31]
	v_mfma_f32_16x16x32_bf16 v[24:27], v[164:167], v[188:191], v[24:27]
	s_waitcnt lgkmcnt(0)
	v_mfma_f32_16x16x32_bf16 v[12:15], v[156:159], v[198:201], v[12:15]
	v_mfma_f32_16x16x32_bf16 v[8:11], v[164:167], v[198:201], v[8:11]
	s_setprio 0
	s_barrier
	s_add_u32 s8, s12, 0x160080
	s_addc_u32 s9, s13, 0
	s_add_i32 s12, s14, s22
	s_mov_b32 m0, s12
	s_nop 0
	global_load_lds_dwordx4 v132, s[8:9]
	s_add_i32 m0, s12, 0x2000
	s_nop 0
	global_load_lds_dwordx4 v128, s[8:9]
	s_waitcnt vmcnt(6)
	s_barrier
	s_setprio 1
	v_mfma_f32_16x16x32_bf16 v[52:55], v[202:205], v[168:171], v[52:55]
	v_mfma_f32_16x16x32_bf16 v[48:51], v[210:213], v[168:171], v[48:51]
	v_mfma_f32_16x16x32_bf16 v[36:39], v[202:205], v[176:179], v[36:39]
	v_mfma_f32_16x16x32_bf16 v[32:35], v[210:213], v[176:179], v[32:35]
	v_mfma_f32_16x16x32_bf16 v[20:23], v[202:205], v[184:187], v[20:23]
	v_mfma_f32_16x16x32_bf16 v[16:19], v[210:213], v[184:187], v[16:19]
	v_mfma_f32_16x16x32_bf16 v[4:7], v[202:205], v[192:195], v[4:7]
	v_mfma_f32_16x16x32_bf16 v[0:3], v[210:213], v[192:195], v[0:3]
	v_mfma_f32_16x16x32_bf16 v[52:55], v[206:209], v[172:175], v[52:55]
	v_mfma_f32_16x16x32_bf16 v[48:51], v[214:217], v[172:175], v[48:51]
	v_mfma_f32_16x16x32_bf16 v[36:39], v[206:209], v[180:183], v[36:39]
	v_mfma_f32_16x16x32_bf16 v[32:35], v[214:217], v[180:183], v[32:35]
	v_mfma_f32_16x16x32_bf16 v[20:23], v[206:209], v[188:191], v[20:23]
	v_mfma_f32_16x16x32_bf16 v[16:19], v[214:217], v[188:191], v[16:19]
	v_mfma_f32_16x16x32_bf16 v[4:7], v[206:209], v[198:201], v[4:7]
	v_mfma_f32_16x16x32_bf16 v[0:3], v[214:217], v[198:201], v[0:3]
	s_setprio 0
	s_add_i32 s3, s3, 2
	s_add_u32 s5, s5, 0x100
	s_addc_u32 s38, s38, 0
	s_cmpk_gt_u32 s3, 0x55
	s_mov_b64 s[8:9], s[10:11]
	s_barrier
	s_cbranch_scc0 .LBB1_1239
	v_mov_b32_e32 v152, v147
	v_mov_b32_e32 v144, v146
	s_lshl_b32 s2, s2, 8
	s_add_i32 s2, s2, s29
	s_lshl_b32 s3, s4, 8
	v_add_u32_e32 v152, s2, v152
	s_or_b32 s3, s3, s54
	v_ashrrev_i32_e32 v153, 31, v152
	v_lshl_add_u32 v144, v144, 3, s3
	v_lshlrev_b64 v[152:153], 12, v[152:153]
	v_ashrrev_i32_e32 v145, 31, v144
	v_lshl_add_u64 v[152:153], s[46:47], 0, v[152:153]
	v_lshl_add_u64 v[144:145], v[144:145], 1, v[152:153]
	global_load_dwordx4 v[160:163], v[144:145], off
	global_load_dwordx4 v[164:167], v[144:145], off offset:256
	s_mov_b64 s[98:99], 0x10000
	v_lshl_add_u64 v[154:155], v[144:145], 0, s[98:99]
	global_load_dwordx4 v[168:171], v[154:155], off
	global_load_dwordx4 v[172:175], v[154:155], off offset:256
	s_mov_b64 s[98:99], 0x20000
	v_lshl_add_u64 v[154:155], v[144:145], 0, s[98:99]
	global_load_dwordx4 v[176:179], v[154:155], off
	global_load_dwordx4 v[180:183], v[154:155], off offset:256
	s_mov_b64 s[98:99], 0x30000
	v_lshl_add_u64 v[154:155], v[144:145], 0, s[98:99]
	global_load_dwordx4 v[184:187], v[154:155], off
	global_load_dwordx4 v[188:191], v[154:155], off offset:256
	s_mov_b64 s[98:99], 0x80000
	v_lshl_add_u64 v[154:155], v[144:145], 0, s[98:99]
	global_load_dwordx4 v[192:195], v[154:155], off
	global_load_dwordx4 v[198:201], v[154:155], off offset:256
	s_mov_b64 s[98:99], 0x90000
	v_lshl_add_u64 v[154:155], v[144:145], 0, s[98:99]
	global_load_dwordx4 v[202:205], v[154:155], off
	global_load_dwordx4 v[206:209], v[154:155], off offset:256
	s_mov_b64 s[98:99], 0xa0000
	v_lshl_add_u64 v[154:155], v[144:145], 0, s[98:99]
	global_load_dwordx4 v[210:213], v[154:155], off
	global_load_dwordx4 v[214:217], v[154:155], off offset:256
	s_mov_b64 s[98:99], 0xb0000
	v_lshl_add_u64 v[154:155], v[144:145], 0, s[98:99]
	global_load_dwordx4 v[248:251], v[154:155], off
	global_load_dwordx4 v[252:255], v[154:155], off offset:256
	s_waitcnt vmcnt(15)
	s_nop 1
	v_mov_b32_e32 v152, v160
	v_mov_b32_e32 v153, v161
	v_mov_b32_e32 v154, v162
	v_mov_b32_e32 v155, v163
	s_mov_b64 s[2:3], 0x10000
	s_mov_b32 s4, s37
	s_mov_b64 s[10:11], s[6:7]
	s_mov_b64 s[8:9], s[42:43]
	s_waitcnt lgkmcnt(0)
	v_lshlrev_b32_e32 v156, 16, v152
	v_and_b32_e32 v157, 0xffff0000, v152
	v_lshlrev_b32_e32 v152, 16, v153
	v_and_b32_e32 v153, 0xffff0000, v153
	v_lshlrev_b32_e32 v158, 16, v154
	v_and_b32_e32 v159, 0xffff0000, v154
	v_lshlrev_b32_e32 v154, 16, v155
	v_and_b32_e32 v155, 0xffff0000, v155
	v_pk_add_f32 v[126:127], v[126:127], v[152:153]
	v_pk_add_f32 v[124:125], v[124:125], v[156:157]
	v_pk_add_f32 v[152:153], v[122:123], v[154:155]
	v_pk_add_f32 v[122:123], v[120:121], v[158:159]
	v_cvt_pk_bf16_f32 v120, v124, v125
	v_cvt_pk_bf16_f32 v121, v126, v127
	v_cvt_pk_bf16_f32 v122, v122, v123
	v_cvt_pk_bf16_f32 v123, v152, v153
	global_store_dwordx4 v[144:145], v[120:123], off
	s_waitcnt vmcnt(15)
; DI unsigned pack2(float a, float b) { f32x2 v = {a, b}; hwbf16x2 r = __builtin_convertvector(v, hwbf16x2); return __builtin_bit_cast(unsigned, r); }
; DI float bflo(unsigned w) { return __uint_as_float(w << 16); }
; DI float bfhi(unsigned w) { return __uint_as_float(w & 0xffff0000u); }
;     DI void operator()(const f32x4 (&acc)[2][2][4][2], const Unit& u, int wr, int wc, int fr, int fq) const {
;     ...
;         for (int ai = 0; ai < 2; ++ai)
; #pragma unroll
;             for (int m = 0; m < 4; ++m) { const size_t ro = (size_t)(row0 + ai * HALF + m * 16) * D + col0;
; #pragma unroll
;                 for (int bj = 0; bj < 2; ++bj) {
;                     f32x4 x0, x1;
;                     if constexpr (IB) { const u32x4 w = *(const u32x4*)((const bf16_t*)Xin + ro + bj * HALF);
;                         x0 = (f32x4){bflo(w[0]), bfhi(w[0]), bflo(w[1]), bfhi(w[1])}; x1 = (f32x4){bflo(w[2]), bfhi(w[2]), bflo(w[3]), bfhi(w[3])}; }
;                     else { x0 = *(const f32x4*)((const float*)Xin + ro + bj * HALF); x1 = *(const f32x4*)((const float*)Xin + ro + bj * HALF + 4); }
;                     x0 += acc[ai][bj][m][0] * sc[bj][0]; x1 += acc[ai][bj][m][1] * sc[bj][1];
;                     if constexpr (OB) { u32x4 o; o[0] = pack2(x0[0], x0[1]); o[1] = pack2(x0[2], x0[3]); o[2] = pack2(x1[0], x1[1]); o[3] = pack2(x1[2], x1[3]);
;                         *(u32x4*)((bf16_t*)Xout + ro + bj * HALF) = o; }
;                     else { *(f32x4*)((float*)Xout + ro + bj * HALF) = x0; *(f32x4*)((float*)Xout + ro + bj * HALF + 4) = x1; } } }
	s_nop 1
	v_mov_b32_e32 v120, v164
	v_mov_b32_e32 v121, v165
	v_mov_b32_e32 v122, v166
	v_mov_b32_e32 v123, v167
	s_waitcnt lgkmcnt(0)
	v_lshlrev_b32_e32 v124, 16, v120
	v_and_b32_e32 v125, 0xffff0000, v120
	v_lshlrev_b32_e32 v120, 16, v121
	v_and_b32_e32 v121, 0xffff0000, v121
	v_lshlrev_b32_e32 v126, 16, v122
	v_and_b32_e32 v127, 0xffff0000, v122
	v_lshlrev_b32_e32 v122, 16, v123
	v_and_b32_e32 v123, 0xffff0000, v123
	v_pk_add_f32 v[116:117], v[116:117], v[124:125]
	v_pk_add_f32 v[118:119], v[118:119], v[120:121]
	v_pk_add_f32 v[120:121], v[114:115], v[122:123]
	v_pk_add_f32 v[114:115], v[112:113], v[126:127]
	v_cvt_pk_bf16_f32 v112, v116, v117
	v_lshl_add_u64 v[116:117], v[144:145], 0, s[2:3]
	s_mov_b32 s2, 0x10000
	v_cvt_pk_bf16_f32 v113, v118, v119
	v_add_co_u32_e32 v118, vcc, s2, v144
	v_cvt_pk_bf16_f32 v114, v114, v115
	v_cvt_pk_bf16_f32 v115, v120, v121
	v_addc_co_u32_e32 v119, vcc, 0, v145, vcc
	global_store_dwordx4 v[144:145], v[112:115], off offset:256
	s_waitcnt vmcnt(15)
	s_nop 1
	v_mov_b32_e32 v112, v168
	v_mov_b32_e32 v113, v169
	v_mov_b32_e32 v114, v170
	v_mov_b32_e32 v115, v171
	s_mov_b64 s[2:3], 0x20000
	s_waitcnt lgkmcnt(0)
	v_lshlrev_b32_e32 v120, 16, v112
	v_and_b32_e32 v121, 0xffff0000, v112
	v_lshlrev_b32_e32 v112, 16, v113
	v_and_b32_e32 v113, 0xffff0000, v113
	v_lshlrev_b32_e32 v122, 16, v114
	v_and_b32_e32 v123, 0xffff0000, v114
	v_lshlrev_b32_e32 v114, 16, v115
	v_and_b32_e32 v115, 0xffff0000, v115
	v_pk_add_f32 v[110:111], v[110:111], v[112:113]
	v_pk_add_f32 v[108:109], v[108:109], v[120:121]
	v_pk_add_f32 v[112:113], v[106:107], v[114:115]
	v_pk_add_f32 v[106:107], v[104:105], v[122:123]
	v_cvt_pk_bf16_f32 v104, v108, v109
	v_cvt_pk_bf16_f32 v105, v110, v111
	v_cvt_pk_bf16_f32 v106, v106, v107
	v_cvt_pk_bf16_f32 v107, v112, v113
	global_store_dwordx4 v[118:119], v[104:107], off
	s_waitcnt vmcnt(15)
	s_nop 1
	v_mov_b32_e32 v104, v172
	v_mov_b32_e32 v105, v173
	v_mov_b32_e32 v106, v174
	v_mov_b32_e32 v107, v175
	s_waitcnt lgkmcnt(0)
	v_lshlrev_b32_e32 v108, 16, v104
	v_and_b32_e32 v109, 0xffff0000, v104
	v_lshlrev_b32_e32 v104, 16, v105
	v_and_b32_e32 v105, 0xffff0000, v105
	v_lshlrev_b32_e32 v110, 16, v106
	v_and_b32_e32 v111, 0xffff0000, v106
	v_lshlrev_b32_e32 v106, 16, v107
	v_and_b32_e32 v107, 0xffff0000, v107
	v_pk_add_f32 v[100:101], v[100:101], v[108:109]
	v_pk_add_f32 v[102:103], v[102:103], v[104:105]
	v_pk_add_f32 v[104:105], v[98:99], v[106:107]
	v_pk_add_f32 v[98:99], v[96:97], v[110:111]
	v_cvt_pk_bf16_f32 v96, v100, v101
	v_lshl_add_u64 v[100:101], v[144:145], 0, s[2:3]
	s_mov_b32 s2, 0x20000
	v_cvt_pk_bf16_f32 v97, v102, v103
	v_add_co_u32_e32 v102, vcc, s2, v144
	v_cvt_pk_bf16_f32 v98, v98, v99
	v_cvt_pk_bf16_f32 v99, v104, v105
	v_addc_co_u32_e32 v103, vcc, 0, v145, vcc
	global_store_dwordx4 v[116:117], v[96:99], off offset:256
	s_waitcnt vmcnt(15)
	s_nop 1
	v_mov_b32_e32 v96, v176
	v_mov_b32_e32 v97, v177
	v_mov_b32_e32 v98, v178
	v_mov_b32_e32 v99, v179
	s_mov_b64 s[2:3], 0x30000
	s_waitcnt lgkmcnt(0)
	v_lshlrev_b32_e32 v104, 16, v96
	v_and_b32_e32 v105, 0xffff0000, v96
	v_lshlrev_b32_e32 v96, 16, v97
	v_and_b32_e32 v97, 0xffff0000, v97
	v_lshlrev_b32_e32 v106, 16, v98
	v_and_b32_e32 v107, 0xffff0000, v98
	v_lshlrev_b32_e32 v98, 16, v99
	v_and_b32_e32 v99, 0xffff0000, v99
	v_pk_add_f32 v[94:95], v[94:95], v[96:97]
	v_pk_add_f32 v[92:93], v[92:93], v[104:105]
	v_pk_add_f32 v[96:97], v[90:91], v[98:99]
	v_pk_add_f32 v[90:91], v[88:89], v[106:107]
	v_cvt_pk_bf16_f32 v88, v92, v93
	v_cvt_pk_bf16_f32 v89, v94, v95
	v_cvt_pk_bf16_f32 v90, v90, v91
	v_cvt_pk_bf16_f32 v91, v96, v97
	global_store_dwordx4 v[102:103], v[88:91], off
	s_waitcnt vmcnt(15)
	s_nop 1
	v_mov_b32_e32 v88, v180
	v_mov_b32_e32 v89, v181
	v_mov_b32_e32 v90, v182
	v_mov_b32_e32 v91, v183
	s_waitcnt lgkmcnt(0)
	v_lshlrev_b32_e32 v92, 16, v88
	v_and_b32_e32 v93, 0xffff0000, v88
	v_lshlrev_b32_e32 v88, 16, v89
	v_and_b32_e32 v89, 0xffff0000, v89
	v_lshlrev_b32_e32 v94, 16, v90
	v_and_b32_e32 v95, 0xffff0000, v90
	v_lshlrev_b32_e32 v90, 16, v91
	v_and_b32_e32 v91, 0xffff0000, v91
	v_pk_add_f32 v[86:87], v[86:87], v[88:89]
	v_pk_add_f32 v[84:85], v[84:85], v[92:93]
	v_pk_add_f32 v[88:89], v[82:83], v[90:91]
	v_pk_add_f32 v[82:83], v[80:81], v[94:95]
	v_cvt_pk_bf16_f32 v80, v84, v85
	v_cvt_pk_bf16_f32 v81, v86, v87
	v_cvt_pk_bf16_f32 v82, v82, v83
	v_cvt_pk_bf16_f32 v83, v88, v89
	global_store_dwordx4 v[100:101], v[80:83], off offset:256
	s_nop 1
	v_lshl_add_u64 v[80:81], v[144:145], 0, s[2:3]
	s_mov_b32 s2, 0x30000
	v_add_co_u32_e32 v86, vcc, s2, v144
	s_mov_b64 s[2:3], 0x80000
	s_nop 0
	v_addc_co_u32_e32 v87, vcc, 0, v145, vcc
	s_waitcnt vmcnt(15)
	s_nop 1
	v_mov_b32_e32 v82, v184
	v_mov_b32_e32 v83, v185
	v_mov_b32_e32 v84, v186
	v_mov_b32_e32 v85, v187
	s_waitcnt lgkmcnt(0)
	v_lshlrev_b32_e32 v88, 16, v82
	v_and_b32_e32 v89, 0xffff0000, v82
	v_lshlrev_b32_e32 v82, 16, v83
	v_and_b32_e32 v83, 0xffff0000, v83
	v_lshlrev_b32_e32 v90, 16, v84
	v_and_b32_e32 v91, 0xffff0000, v84
	v_lshlrev_b32_e32 v84, 16, v85
	v_and_b32_e32 v85, 0xffff0000, v85
	v_pk_add_f32 v[78:79], v[78:79], v[82:83]
	v_pk_add_f32 v[76:77], v[76:77], v[88:89]
	v_pk_add_f32 v[82:83], v[74:75], v[84:85]
	v_pk_add_f32 v[74:75], v[72:73], v[90:91]
	v_cvt_pk_bf16_f32 v72, v76, v77
	v_cvt_pk_bf16_f32 v73, v78, v79
	v_cvt_pk_bf16_f32 v74, v74, v75
	v_cvt_pk_bf16_f32 v75, v82, v83
	global_store_dwordx4 v[86:87], v[72:75], off
	s_waitcnt vmcnt(15)
	s_nop 1
	v_mov_b32_e32 v72, v188
	v_mov_b32_e32 v73, v189
	v_mov_b32_e32 v74, v190
	v_mov_b32_e32 v75, v191
	s_waitcnt lgkmcnt(0)
; DI unsigned pack2(float a, float b) { f32x2 v = {a, b}; hwbf16x2 r = __builtin_convertvector(v, hwbf16x2); return __builtin_bit_cast(unsigned, r); }
; DI float bflo(unsigned w) { return __uint_as_float(w << 16); }
; DI float bfhi(unsigned w) { return __uint_as_float(w & 0xffff0000u); }
;     DI void operator()(const f32x4 (&acc)[2][2][4][2], const Unit& u, int wr, int wc, int fr, int fq) const {
;     ...
;         for (int ai = 0; ai < 2; ++ai)
; #pragma unroll
;             for (int m = 0; m < 4; ++m) { const size_t ro = (size_t)(row0 + ai * HALF + m * 16) * D + col0;
; #pragma unroll
;                 for (int bj = 0; bj < 2; ++bj) {
;                     f32x4 x0, x1;
;                     if constexpr (IB) { const u32x4 w = *(const u32x4*)((const bf16_t*)Xin + ro + bj * HALF);
;                         x0 = (f32x4){bflo(w[0]), bfhi(w[0]), bflo(w[1]), bfhi(w[1])}; x1 = (f32x4){bflo(w[2]), bfhi(w[2]), bflo(w[3]), bfhi(w[3])}; }
;                     else { x0 = *(const f32x4*)((const float*)Xin + ro + bj * HALF); x1 = *(const f32x4*)((const float*)Xin + ro + bj * HALF + 4); }
;                     x0 += acc[ai][bj][m][0] * sc[bj][0]; x1 += acc[ai][bj][m][1] * sc[bj][1];
;                     if constexpr (OB) { u32x4 o; o[0] = pack2(x0[0], x0[1]); o[1] = pack2(x0[2], x0[3]); o[2] = pack2(x1[0], x1[1]); o[3] = pack2(x1[2], x1[3]);
;                         *(u32x4*)((bf16_t*)Xout + ro + bj * HALF) = o; }
;                     else { *(f32x4*)((float*)Xout + ro + bj * HALF) = x0; *(f32x4*)((float*)Xout + ro + bj * HALF + 4) = x1; } } }
	v_lshlrev_b32_e32 v76, 16, v72
	v_and_b32_e32 v77, 0xffff0000, v72
	v_lshlrev_b32_e32 v72, 16, v73
	v_and_b32_e32 v73, 0xffff0000, v73
	v_lshlrev_b32_e32 v78, 16, v74
	v_and_b32_e32 v79, 0xffff0000, v74
	v_lshlrev_b32_e32 v74, 16, v75
	v_and_b32_e32 v75, 0xffff0000, v75
	v_pk_add_f32 v[70:71], v[70:71], v[72:73]
	v_pk_add_f32 v[68:69], v[68:69], v[76:77]
	v_pk_add_f32 v[72:73], v[66:67], v[74:75]
	v_pk_add_f32 v[66:67], v[64:65], v[78:79]
	v_cvt_pk_bf16_f32 v64, v68, v69
	v_cvt_pk_bf16_f32 v65, v70, v71
	v_cvt_pk_bf16_f32 v66, v66, v67
	v_cvt_pk_bf16_f32 v67, v72, v73
	global_store_dwordx4 v[80:81], v[64:67], off offset:256
	s_nop 1
	v_lshl_add_u64 v[64:65], v[144:145], 0, s[2:3]
	s_mov_b32 s2, 0x80000
	v_add_co_u32_e32 v70, vcc, s2, v144
	s_mov_b64 s[2:3], 0x90000
	s_nop 0
	v_addc_co_u32_e32 v71, vcc, 0, v145, vcc
	s_waitcnt vmcnt(15)
	s_nop 1
	v_mov_b32_e32 v66, v192
	v_mov_b32_e32 v67, v193
	v_mov_b32_e32 v68, v194
	v_mov_b32_e32 v69, v195
	s_waitcnt lgkmcnt(0)
	v_lshlrev_b32_e32 v72, 16, v66
	v_and_b32_e32 v73, 0xffff0000, v66
	v_lshlrev_b32_e32 v66, 16, v67
	v_and_b32_e32 v67, 0xffff0000, v67
	v_lshlrev_b32_e32 v74, 16, v68
	v_and_b32_e32 v75, 0xffff0000, v68
	v_lshlrev_b32_e32 v68, 16, v69
	v_and_b32_e32 v69, 0xffff0000, v69
	v_pk_add_f32 v[62:63], v[62:63], v[66:67]
	v_pk_add_f32 v[60:61], v[60:61], v[72:73]
	v_pk_add_f32 v[66:67], v[58:59], v[68:69]
	v_pk_add_f32 v[58:59], v[56:57], v[74:75]
	v_cvt_pk_bf16_f32 v56, v60, v61
	v_cvt_pk_bf16_f32 v57, v62, v63
	v_cvt_pk_bf16_f32 v58, v58, v59
	v_cvt_pk_bf16_f32 v59, v66, v67
	global_store_dwordx4 v[70:71], v[56:59], off
	s_waitcnt vmcnt(15)
	s_nop 1
	v_mov_b32_e32 v56, v198
	v_mov_b32_e32 v57, v199
	v_mov_b32_e32 v58, v200
	v_mov_b32_e32 v59, v201
	s_waitcnt lgkmcnt(0)
	v_lshlrev_b32_e32 v60, 16, v56
	v_and_b32_e32 v61, 0xffff0000, v56
	v_lshlrev_b32_e32 v56, 16, v57
	v_and_b32_e32 v57, 0xffff0000, v57
	v_lshlrev_b32_e32 v62, 16, v58
	v_and_b32_e32 v63, 0xffff0000, v58
	v_lshlrev_b32_e32 v58, 16, v59
	v_and_b32_e32 v59, 0xffff0000, v59
	v_pk_add_f32 v[54:55], v[54:55], v[56:57]
	v_pk_add_f32 v[52:53], v[52:53], v[60:61]
	v_pk_add_f32 v[56:57], v[50:51], v[58:59]
	v_pk_add_f32 v[50:51], v[48:49], v[62:63]
	v_cvt_pk_bf16_f32 v48, v52, v53
	v_cvt_pk_bf16_f32 v49, v54, v55
	v_cvt_pk_bf16_f32 v50, v50, v51
	v_cvt_pk_bf16_f32 v51, v56, v57
	global_store_dwordx4 v[64:65], v[48:51], off offset:256
	s_nop 1
	v_lshl_add_u64 v[48:49], v[144:145], 0, s[2:3]
	s_mov_b32 s2, 0x90000
	v_add_co_u32_e32 v54, vcc, s2, v144
	s_mov_b64 s[2:3], 0xa0000
	s_nop 0
	v_addc_co_u32_e32 v55, vcc, 0, v145, vcc
	s_waitcnt vmcnt(15)
	s_nop 1
	v_mov_b32_e32 v50, v202
	v_mov_b32_e32 v51, v203
	v_mov_b32_e32 v52, v204
	v_mov_b32_e32 v53, v205
	s_waitcnt lgkmcnt(0)
	v_lshlrev_b32_e32 v56, 16, v50
	v_and_b32_e32 v57, 0xffff0000, v50
	v_lshlrev_b32_e32 v50, 16, v51
	v_and_b32_e32 v51, 0xffff0000, v51
	v_lshlrev_b32_e32 v58, 16, v52
	v_and_b32_e32 v59, 0xffff0000, v52
	v_lshlrev_b32_e32 v52, 16, v53
	v_and_b32_e32 v53, 0xffff0000, v53
	v_pk_add_f32 v[46:47], v[46:47], v[50:51]
	v_pk_add_f32 v[44:45], v[44:45], v[56:57]
	v_pk_add_f32 v[50:51], v[42:43], v[52:53]
	v_pk_add_f32 v[42:43], v[40:41], v[58:59]
	v_cvt_pk_bf16_f32 v40, v44, v45
	v_cvt_pk_bf16_f32 v41, v46, v47
	v_cvt_pk_bf16_f32 v42, v42, v43
	v_cvt_pk_bf16_f32 v43, v50, v51
	global_store_dwordx4 v[54:55], v[40:43], off
	s_waitcnt vmcnt(15)
	s_nop 1
	v_mov_b32_e32 v40, v206
	v_mov_b32_e32 v41, v207
	v_mov_b32_e32 v42, v208
	v_mov_b32_e32 v43, v209
	s_waitcnt lgkmcnt(0)
; DI unsigned pack2(float a, float b) { f32x2 v = {a, b}; hwbf16x2 r = __builtin_convertvector(v, hwbf16x2); return __builtin_bit_cast(unsigned, r); }
; DI float bflo(unsigned w) { return __uint_as_float(w << 16); }
; DI float bfhi(unsigned w) { return __uint_as_float(w & 0xffff0000u); }
;     DI const char* a(const Unit& u) const { return (const char*)(A + (size_t)u.pm * BM * lda); }
;     DI const char* a(const Unit& u) const { return (const char*)(A + (size_t)u.pm * BM * 2048 + (u.pn >> 1) * 512); }
;     DI void operator()(const f32x4 (&acc)[2][2][4][2], const Unit& u, int wr, int wc, int fr, int fq) const {
;     ...
;         for (int ai = 0; ai < 2; ++ai)
; #pragma unroll
;             for (int m = 0; m < 4; ++m) { const size_t ro = (size_t)(row0 + ai * HALF + m * 16) * D + col0;
; #pragma unroll
;                 for (int bj = 0; bj < 2; ++bj) {
;                     f32x4 x0, x1;
;                     if constexpr (IB) { const u32x4 w = *(const u32x4*)((const bf16_t*)Xin + ro + bj * HALF);
;                         x0 = (f32x4){bflo(w[0]), bfhi(w[0]), bflo(w[1]), bfhi(w[1])}; x1 = (f32x4){bflo(w[2]), bfhi(w[2]), bflo(w[3]), bfhi(w[3])}; }
;                     else { x0 = *(const f32x4*)((const float*)Xin + ro + bj * HALF); x1 = *(const f32x4*)((const float*)Xin + ro + bj * HALF + 4); }
;                     x0 += acc[ai][bj][m][0] * sc[bj][0]; x1 += acc[ai][bj][m][1] * sc[bj][1];
;                     if constexpr (OB) { u32x4 o; o[0] = pack2(x0[0], x0[1]); o[1] = pack2(x0[2], x0[3]); o[2] = pack2(x1[0], x1[1]); o[3] = pack2(x1[2], x1[3]);
;                         *(u32x4*)((bf16_t*)Xout + ro + bj * HALF) = o; }
;                     else { *(f32x4*)((float*)Xout + ro + bj * HALF) = x0; *(f32x4*)((float*)Xout + ro + bj * HALF + 4) = x1; } } }
; template <class Map, class Epi>
; DI void gemm_phase(LAS unsigned char* lds, const Map& MP, const Epi& E, const int nM, const int nN, const int K, const int lda, const int ldb) {
;     ...
;         if (!has_next) break;
; #pragma unroll
;         for (int a = 0; a < 2; ++a)
; #pragma unroll
;             for (int b = 0; b < 2; ++b)
; #pragma unroll
;                 for (int m = 0; m < 4; ++m)
; #pragma unroll
;                     for (int n = 0; n < 2; ++n) acc[a][b][m][n] = (f32x4){0.f, 0.f, 0.f, 0.f};
;         cur = nxt; cA = nA; cB = nB; ++ui;
;     }
;     PG8_WAIT_V(0);
;     if (wr == 0) PG8_BAR;
;     PG8_BAR;
	v_lshlrev_b32_e32 v44, 16, v40
	v_and_b32_e32 v45, 0xffff0000, v40
	v_lshlrev_b32_e32 v40, 16, v41
	v_and_b32_e32 v41, 0xffff0000, v41
	v_lshlrev_b32_e32 v46, 16, v42
	v_and_b32_e32 v47, 0xffff0000, v42
	v_lshlrev_b32_e32 v42, 16, v43
	v_and_b32_e32 v43, 0xffff0000, v43
	v_pk_add_f32 v[38:39], v[38:39], v[40:41]
	v_pk_add_f32 v[36:37], v[36:37], v[44:45]
	v_pk_add_f32 v[40:41], v[34:35], v[42:43]
	v_pk_add_f32 v[34:35], v[32:33], v[46:47]
	v_cvt_pk_bf16_f32 v32, v36, v37
	v_cvt_pk_bf16_f32 v33, v38, v39
	v_cvt_pk_bf16_f32 v34, v34, v35
	v_cvt_pk_bf16_f32 v35, v40, v41
	global_store_dwordx4 v[48:49], v[32:35], off offset:256
	s_nop 1
	v_lshl_add_u64 v[32:33], v[144:145], 0, s[2:3]
	s_mov_b32 s2, 0xa0000
	v_add_co_u32_e32 v38, vcc, s2, v144
	s_mov_b64 s[2:3], 0xb0000
	s_nop 0
	v_addc_co_u32_e32 v39, vcc, 0, v145, vcc
	s_waitcnt vmcnt(15)
	s_nop 1
	v_mov_b32_e32 v34, v210
	v_mov_b32_e32 v35, v211
	v_mov_b32_e32 v36, v212
	v_mov_b32_e32 v37, v213
	s_waitcnt lgkmcnt(0)
	v_lshlrev_b32_e32 v40, 16, v34
	v_and_b32_e32 v41, 0xffff0000, v34
	v_lshlrev_b32_e32 v34, 16, v35
	v_and_b32_e32 v35, 0xffff0000, v35
	v_lshlrev_b32_e32 v42, 16, v36
	v_and_b32_e32 v43, 0xffff0000, v36
	v_lshlrev_b32_e32 v36, 16, v37
	v_and_b32_e32 v37, 0xffff0000, v37
	v_pk_add_f32 v[30:31], v[30:31], v[34:35]
	v_pk_add_f32 v[28:29], v[28:29], v[40:41]
	v_pk_add_f32 v[34:35], v[26:27], v[36:37]
	v_pk_add_f32 v[26:27], v[24:25], v[42:43]
	v_cvt_pk_bf16_f32 v24, v28, v29
	v_cvt_pk_bf16_f32 v25, v30, v31
	v_cvt_pk_bf16_f32 v26, v26, v27
	v_cvt_pk_bf16_f32 v27, v34, v35
	global_store_dwordx4 v[38:39], v[24:27], off
	s_waitcnt vmcnt(15)
	s_nop 1
	v_mov_b32_e32 v24, v214
	v_mov_b32_e32 v25, v215
	v_mov_b32_e32 v26, v216
	v_mov_b32_e32 v27, v217
	s_waitcnt lgkmcnt(0)
	v_lshlrev_b32_e32 v28, 16, v24
	v_and_b32_e32 v29, 0xffff0000, v24
	v_lshlrev_b32_e32 v24, 16, v25
	v_and_b32_e32 v25, 0xffff0000, v25
	v_lshlrev_b32_e32 v30, 16, v26
	v_and_b32_e32 v31, 0xffff0000, v26
	v_lshlrev_b32_e32 v26, 16, v27
	v_and_b32_e32 v27, 0xffff0000, v27
	v_pk_add_f32 v[22:23], v[22:23], v[24:25]
	v_pk_add_f32 v[20:21], v[20:21], v[28:29]
	v_pk_add_f32 v[24:25], v[18:19], v[26:27]
	v_pk_add_f32 v[18:19], v[16:17], v[30:31]
	v_cvt_pk_bf16_f32 v16, v20, v21
	v_cvt_pk_bf16_f32 v17, v22, v23
	v_cvt_pk_bf16_f32 v18, v18, v19
	v_cvt_pk_bf16_f32 v19, v24, v25
	global_store_dwordx4 v[32:33], v[16:19], off offset:256
	s_nop 1
	v_lshl_add_u64 v[16:17], v[144:145], 0, s[2:3]
	s_mov_b32 s2, 0xb0000
	v_add_co_u32_e32 v22, vcc, s2, v144
	s_mov_b32 s2, s55
	s_nop 0
	v_addc_co_u32_e32 v23, vcc, 0, v145, vcc
	s_waitcnt vmcnt(15)
	s_nop 1
	v_mov_b32_e32 v18, v248
	v_mov_b32_e32 v19, v249
	v_mov_b32_e32 v20, v250
	v_mov_b32_e32 v21, v251
	s_and_b64 vcc, exec, s[40:41]
	s_waitcnt lgkmcnt(0)
	v_lshlrev_b32_e32 v24, 16, v18
	v_and_b32_e32 v25, 0xffff0000, v18
	v_lshlrev_b32_e32 v18, 16, v19
	v_and_b32_e32 v19, 0xffff0000, v19
	v_lshlrev_b32_e32 v26, 16, v20
	v_and_b32_e32 v27, 0xffff0000, v20
	v_lshlrev_b32_e32 v20, 16, v21
	v_and_b32_e32 v21, 0xffff0000, v21
	v_pk_add_f32 v[14:15], v[14:15], v[18:19]
	v_pk_add_f32 v[12:13], v[12:13], v[24:25]
	v_pk_add_f32 v[18:19], v[10:11], v[20:21]
	v_pk_add_f32 v[10:11], v[8:9], v[26:27]
	v_cvt_pk_bf16_f32 v8, v12, v13
	v_cvt_pk_bf16_f32 v9, v14, v15
	v_cvt_pk_bf16_f32 v10, v10, v11
	v_cvt_pk_bf16_f32 v11, v18, v19
	global_store_dwordx4 v[22:23], v[8:11], off
	s_waitcnt vmcnt(15)
	s_nop 1
	v_mov_b32_e32 v8, v252
	v_mov_b32_e32 v9, v253
	v_mov_b32_e32 v10, v254
	v_mov_b32_e32 v11, v255
	s_waitcnt lgkmcnt(0)
	v_lshlrev_b32_e32 v12, 16, v8
	v_and_b32_e32 v13, 0xffff0000, v8
	v_lshlrev_b32_e32 v8, 16, v9
	v_and_b32_e32 v9, 0xffff0000, v9
	v_lshlrev_b32_e32 v14, 16, v10
	v_and_b32_e32 v15, 0xffff0000, v10
	v_lshlrev_b32_e32 v10, 16, v11
	v_and_b32_e32 v11, 0xffff0000, v11
	v_pk_add_f32 v[6:7], v[6:7], v[8:9]
	v_pk_add_f32 v[4:5], v[4:5], v[12:13]
	v_pk_add_f32 v[8:9], v[2:3], v[10:11]
	v_pk_add_f32 v[2:3], v[0:1], v[14:15]
	v_cvt_pk_bf16_f32 v0, v4, v5
	v_cvt_pk_bf16_f32 v1, v6, v7
	v_cvt_pk_bf16_f32 v2, v2, v3
	v_cvt_pk_bf16_f32 v3, v8, v9
	global_store_dwordx4 v[16:17], v[0:3], off offset:256
	s_cbranch_vccz .LBB1_1232
	s_waitcnt vmcnt(0)
	s_cmpk_gt_u32 s17, 0xff
	s_cbranch_scc1 .LBB1_1243
	s_barrier

; #define PG8_STAGE(bufoff, gbase, voff) do { _Pragma("unroll") for (int _i = 0; _i < 2; ++_i) \
;         __builtin_amdgcn_global_load_lds((const unsigned*)((const char*)(gbase) + (voff)[_i]), (LAS unsigned*)(lds + (bufoff) + ldsw + _i * 8192), 16, 0, 0); } while (0)
; #define PG8_LDA(dst, b, h) do { _Pragma("unroll") for (int m = 0; m < 4; ++m) _Pragma("unroll") for (int k = 0; k < 2; ++k) dst[m][k] = *(const LAS bf16x8*)(lds + PG8_SA(b, h) + aoff + m * 2048 + k * 1024); } while (0)
; #define PG8_LDB(dst, b, h) do { _Pragma("unroll") for (int n = 0; n < 2; ++n) _Pragma("unroll") for (int k = 0; k < 2; ++k) dst[n][k] = *(const LAS bf16x8*)(lds + PG8_SB(b, h) + boff + n * 2048 + k * 1024); } while (0)
; #define PG8_MMA(ai, bj, At, Bt) do { __builtin_amdgcn_s_setprio(1); _Pragma("unroll") for (int m = 0; m < 4; ++m) _Pragma("unroll") for (int n = 0; n < 2; ++n) _Pragma("unroll") for (int k = 0; k < 2; ++k) \
;         acc[ai][bj][m][n] = __builtin_amdgcn_mfma_f32_16x16x32_bf16(Bt[n][k], At[m][k], acc[ai][bj][m][n], 0, 0, 0); __builtin_amdgcn_s_setprio(0); } while (0)
; #define PG8_WAIT_L(n) asm volatile("s_waitcnt lgkmcnt(" #n ")" ::: "memory")
; #define PG8_BAR __builtin_amdgcn_s_barrier()
; #define PG8_SCHED __builtin_amdgcn_sched_barrier(0)
; template <class Map, class Epi>
; DI void gemm_phase(LAS unsigned char* lds, const Map& MP, const Epi& E, const int nM, const int nN, const int K, const int lda, const int ldb) {
;     ...
;             const bool last = (t == nt - 2);
;             const char* a1 = cA + (size_t)(t + 1) * kstep;
;             const char* a2 = last ? nA : cA + (size_t)(t + 2) * kstep; const char* b2 = last ? nB : cB + (size_t)(t + 2) * kstep;
;             const char* a3 = a2 + kstep; const char* b3 = b2 + kstep;
;             PG8_LDB(B0, 0, 0); PG8_SCHED; PG8_LDA(At, 0, 0); PG8_STAGE(PG8_SA(1, 1), a1 + hstepA, voffA);
;             PG8_WAIT_L(8); PG8_BAR; PG8_WAIT_L(0); PG8_MMA(0, 0, At, B0); PG8_BAR; PG8_SCHED;
;             PG8_LDB(B1, 0, 1); PG8_STAGE(PG8_SB(0, 0), b2, voffB);
;             PG8_BAR; PG8_WAIT_L(0); PG8_MMA(0, 1, At, B1); PG8_BAR;
;             PG8_LDA(At, 0, 1); PG8_STAGE(PG8_SA(0, 0), a2, voffA);
;             PG8_BAR; PG8_WAIT_L(0); PG8_MMA(1, 0, At, B0); PG8_BAR; PG8_SCHED;
.LBB1_1382:
	ds_read_b128 v[150:153], v147
	ds_read_b128 v[154:157], v147 offset:1024
	ds_read_b128 v[158:161], v147 offset:2048
	ds_read_b128 v[162:165], v147 offset:3072
	s_add_u32 s22, s20, 0xfff80080
	s_addc_u32 s23, s21, -1
	s_cmp_eq_u32 s3, 28
	s_cselect_b32 s25, s15, s23
	s_cselect_b32 s24, s48, s22
	s_cselect_b32 s23, s13, s53
	s_cselect_b32 s22, s49, s52
	s_add_i32 m0, s31, 0xc000
	ds_read_b128 v[166:169], v148
	ds_read_b128 v[170:173], v148 offset:1024
	ds_read_b128 v[174:177], v148 offset:2048
	ds_read_b128 v[178:181], v148 offset:3072
	ds_read_b128 v[182:185], v148 offset:4096
	ds_read_b128 v[186:189], v148 offset:5120
	ds_read_b128 v[190:193], v148 offset:6144
	ds_read_b128 v[198:201], v148 offset:7168
	global_load_lds_dwordx4 v138, s[20:21]
	s_add_i32 m0, s31, 0xe000
	s_nop 0
	global_load_lds_dwordx4 v136, s[20:21]
	s_waitcnt lgkmcnt(8)
	s_barrier
	s_setprio 1
	s_waitcnt lgkmcnt(7)
	v_mfma_f32_16x16x32_bf16 v[124:127], v[150:153], v[166:169], v[124:127]
	v_mfma_f32_16x16x32_bf16 v[120:123], v[158:161], v[166:169], v[120:123]
	s_waitcnt lgkmcnt(5)
	v_mfma_f32_16x16x32_bf16 v[116:119], v[150:153], v[174:177], v[116:119]
	v_mfma_f32_16x16x32_bf16 v[112:115], v[158:161], v[174:177], v[112:115]
	s_waitcnt lgkmcnt(3)
	v_mfma_f32_16x16x32_bf16 v[100:103], v[150:153], v[182:185], v[100:103]
	v_mfma_f32_16x16x32_bf16 v[96:99], v[158:161], v[182:185], v[96:99]
	s_waitcnt lgkmcnt(1)
	v_mfma_f32_16x16x32_bf16 v[84:87], v[150:153], v[190:193], v[84:87]
	v_mfma_f32_16x16x32_bf16 v[80:83], v[158:161], v[190:193], v[80:83]
	v_mfma_f32_16x16x32_bf16 v[124:127], v[154:157], v[170:173], v[124:127]
	v_mfma_f32_16x16x32_bf16 v[120:123], v[162:165], v[170:173], v[120:123]
	v_mfma_f32_16x16x32_bf16 v[116:119], v[154:157], v[178:181], v[116:119]
	v_mfma_f32_16x16x32_bf16 v[112:115], v[162:165], v[178:181], v[112:115]
	v_mfma_f32_16x16x32_bf16 v[100:103], v[154:157], v[186:189], v[100:103]
	v_mfma_f32_16x16x32_bf16 v[96:99], v[162:165], v[186:189], v[96:99]
	s_waitcnt lgkmcnt(0)
	v_mfma_f32_16x16x32_bf16 v[84:87], v[154:157], v[198:201], v[84:87]
	v_mfma_f32_16x16x32_bf16 v[80:83], v[162:165], v[198:201], v[80:83]
	s_setprio 0
	s_barrier
	s_add_i32 s54, s44, s29
	v_lshl_add_u64 v[194:195], s[22:23], 0, v[132:133]
	s_mov_b32 m0, s54
	ds_read_b128 v[202:205], v149
	ds_read_b128 v[206:209], v149 offset:1024
	ds_read_b128 v[210:213], v149 offset:2048
	ds_read_b128 v[214:217], v149 offset:3072
	global_load_lds_dwordx4 v[194:195], off
	v_lshl_add_u64 v[218:219], s[22:23], 0, v[128:129]
	s_add_i32 m0, s54, 0x2000
	s_nop 0
	global_load_lds_dwordx4 v[218:219], off
	s_barrier
	s_setprio 1
	s_waitcnt lgkmcnt(3)
	v_mfma_f32_16x16x32_bf16 v[108:111], v[202:205], v[166:169], v[108:111]
	s_waitcnt lgkmcnt(1)
	v_mfma_f32_16x16x32_bf16 v[104:107], v[210:213], v[166:169], v[104:107]
	v_mfma_f32_16x16x32_bf16 v[92:95], v[202:205], v[174:177], v[92:95]
	v_mfma_f32_16x16x32_bf16 v[88:91], v[210:213], v[174:177], v[88:91]
	v_mfma_f32_16x16x32_bf16 v[76:79], v[202:205], v[182:185], v[76:79]
	v_mfma_f32_16x16x32_bf16 v[72:75], v[210:213], v[182:185], v[72:75]
	v_mfma_f32_16x16x32_bf16 v[68:71], v[202:205], v[190:193], v[68:71]
	v_mfma_f32_16x16x32_bf16 v[64:67], v[210:213], v[190:193], v[64:67]
	v_mfma_f32_16x16x32_bf16 v[108:111], v[206:209], v[170:173], v[108:111]
	s_waitcnt lgkmcnt(0)
	v_mfma_f32_16x16x32_bf16 v[104:107], v[214:217], v[170:173], v[104:107]
	v_mfma_f32_16x16x32_bf16 v[92:95], v[206:209], v[178:181], v[92:95]
	v_mfma_f32_16x16x32_bf16 v[88:91], v[214:217], v[178:181], v[88:91]
	v_mfma_f32_16x16x32_bf16 v[76:79], v[206:209], v[186:189], v[76:79]
	v_mfma_f32_16x16x32_bf16 v[72:75], v[214:217], v[186:189], v[72:75]
	v_mfma_f32_16x16x32_bf16 v[68:71], v[206:209], v[198:201], v[68:71]
	v_mfma_f32_16x16x32_bf16 v[64:67], v[214:217], v[198:201], v[64:67]
	s_setprio 0
	s_mov_b32 m0, s31
	v_lshl_add_u64 v[220:221], s[24:25], 0, v[134:135]
	s_barrier
	ds_read_b128 v[166:169], v148 offset:16384
	ds_read_b128 v[170:173], v148 offset:17408
	ds_read_b128 v[174:177], v148 offset:18432
	ds_read_b128 v[178:181], v148 offset:19456
	ds_read_b128 v[182:185], v148 offset:20480
	ds_read_b128 v[186:189], v148 offset:21504
	ds_read_b128 v[190:193], v148 offset:22528
	ds_read_b128 v[198:201], v148 offset:23552
	global_load_lds_dwordx4 v[220:221], off
	v_lshl_add_u64 v[222:223], s[24:25], 0, v[130:131]
	s_mov_b32 m0, s11
	s_nop 0
	global_load_lds_dwordx4 v[222:223], off
	s_barrier
	s_setprio 1
	s_waitcnt lgkmcnt(7)
	v_mfma_f32_16x16x32_bf16 v[60:63], v[150:153], v[166:169], v[60:63]
	v_mfma_f32_16x16x32_bf16 v[56:59], v[158:161], v[166:169], v[56:59]
	s_waitcnt lgkmcnt(5)
	v_mfma_f32_16x16x32_bf16 v[52:55], v[150:153], v[174:177], v[52:55]
	v_mfma_f32_16x16x32_bf16 v[48:51], v[158:161], v[174:177], v[48:51]
	s_waitcnt lgkmcnt(3)
	v_mfma_f32_16x16x32_bf16 v[36:39], v[150:153], v[182:185], v[36:39]
	v_mfma_f32_16x16x32_bf16 v[32:35], v[158:161], v[182:185], v[32:35]
	s_waitcnt lgkmcnt(1)
	v_mfma_f32_16x16x32_bf16 v[20:23], v[150:153], v[190:193], v[20:23]
	v_mfma_f32_16x16x32_bf16 v[16:19], v[158:161], v[190:193], v[16:19]
	v_mfma_f32_16x16x32_bf16 v[60:63], v[154:157], v[170:173], v[60:63]
	v_mfma_f32_16x16x32_bf16 v[56:59], v[162:165], v[170:173], v[56:59]
	v_mfma_f32_16x16x32_bf16 v[52:55], v[154:157], v[178:181], v[52:55]
	v_mfma_f32_16x16x32_bf16 v[48:51], v[162:165], v[178:181], v[48:51]
	v_mfma_f32_16x16x32_bf16 v[36:39], v[154:157], v[186:189], v[36:39]
	v_mfma_f32_16x16x32_bf16 v[32:35], v[162:165], v[186:189], v[32:35]
	s_waitcnt lgkmcnt(0)
	v_mfma_f32_16x16x32_bf16 v[20:23], v[154:157], v[198:201], v[20:23]
	v_mfma_f32_16x16x32_bf16 v[16:19], v[162:165], v[198:201], v[16:19]
	s_setprio 0
	s_barrier
; #define PG8_STAGE(bufoff, gbase, voff) do { _Pragma("unroll") for (int _i = 0; _i < 2; ++_i) \
;         __builtin_amdgcn_global_load_lds((const unsigned*)((const char*)(gbase) + (voff)[_i]), (LAS unsigned*)(lds + (bufoff) + ldsw + _i * 8192), 16, 0, 0); } while (0)
; #define PG8_LDA(dst, b, h) do { _Pragma("unroll") for (int m = 0; m < 4; ++m) _Pragma("unroll") for (int k = 0; k < 2; ++k) dst[m][k] = *(const LAS bf16x8*)(lds + PG8_SA(b, h) + aoff + m * 2048 + k * 1024); } while (0)
; #define PG8_LDB(dst, b, h) do { _Pragma("unroll") for (int n = 0; n < 2; ++n) _Pragma("unroll") for (int k = 0; k < 2; ++k) dst[n][k] = *(const LAS bf16x8*)(lds + PG8_SB(b, h) + boff + n * 2048 + k * 1024); } while (0)
; #define PG8_MMA(ai, bj, At, Bt) do { __builtin_amdgcn_s_setprio(1); _Pragma("unroll") for (int m = 0; m < 4; ++m) _Pragma("unroll") for (int n = 0; n < 2; ++n) _Pragma("unroll") for (int k = 0; k < 2; ++k) \
;         acc[ai][bj][m][n] = __builtin_amdgcn_mfma_f32_16x16x32_bf16(Bt[n][k], At[m][k], acc[ai][bj][m][n], 0, 0, 0); __builtin_amdgcn_s_setprio(0); } while (0)
; #define PG8_WAIT_V(n) asm volatile("s_waitcnt vmcnt(" #n ")" ::: "memory")
; #define PG8_WAIT_L(n) asm volatile("s_waitcnt lgkmcnt(" #n ")" ::: "memory")
; #define PG8_BAR __builtin_amdgcn_s_barrier()
; #define PG8_SCHED __builtin_amdgcn_sched_barrier(0)
; template <class Map, class Epi>
; DI void gemm_phase(LAS unsigned char* lds, const Map& MP, const Epi& E, const int nM, const int nN, const int K, const int lda, const int ldb) {
;     ...
;             PG8_STAGE(PG8_SB(0, 1), b2 + hstepB, voffB);
;             PG8_WAIT_V(6); PG8_BAR; PG8_MMA(1, 1, At, B1); PG8_BAR;
;             PG8_LDB(B0, 1, 0); PG8_SCHED; PG8_LDA(At, 1, 0); PG8_STAGE(PG8_SA(0, 1), a2 + hstepA, voffA);
;             PG8_WAIT_L(8); PG8_BAR; PG8_WAIT_L(0); PG8_MMA(0, 0, At, B0); PG8_BAR; PG8_SCHED;
;             PG8_LDB(B1, 1, 1); PG8_STAGE(PG8_SB(1, 0), b3, voffB);
;             PG8_BAR; PG8_WAIT_L(0); PG8_MMA(0, 1, At, B1); PG8_BAR;
;             PG8_LDA(At, 1, 1); PG8_STAGE(PG8_SA(1, 0), a3, voffA);
;             PG8_BAR; PG8_WAIT_L(0); PG8_MMA(1, 0, At, B0); PG8_BAR; PG8_SCHED;
	s_add_u32 s54, s22, 0x80000
	s_addc_u32 s55, s23, 0
	s_add_i32 s56, s45, s29
	s_mov_b32 m0, s56
	s_nop 0
	global_load_lds_dwordx4 v132, s[54:55]
	s_add_i32 m0, s56, 0x2000
	s_nop 0
	global_load_lds_dwordx4 v128, s[54:55]
	s_waitcnt vmcnt(6)
	s_barrier
	s_setprio 1
	v_mfma_f32_16x16x32_bf16 v[44:47], v[202:205], v[166:169], v[44:47]
	v_mfma_f32_16x16x32_bf16 v[40:43], v[210:213], v[166:169], v[40:43]
	v_mfma_f32_16x16x32_bf16 v[28:31], v[202:205], v[174:177], v[28:31]
	v_mfma_f32_16x16x32_bf16 v[24:27], v[210:213], v[174:177], v[24:27]
	v_mfma_f32_16x16x32_bf16 v[12:15], v[202:205], v[182:185], v[12:15]
	v_mfma_f32_16x16x32_bf16 v[8:11], v[210:213], v[182:185], v[8:11]
	v_mfma_f32_16x16x32_bf16 v[4:7], v[202:205], v[190:193], v[4:7]
	v_mfma_f32_16x16x32_bf16 v[0:3], v[210:213], v[190:193], v[0:3]
	v_mfma_f32_16x16x32_bf16 v[44:47], v[206:209], v[170:173], v[44:47]
	v_mfma_f32_16x16x32_bf16 v[40:43], v[214:217], v[170:173], v[40:43]
	v_mfma_f32_16x16x32_bf16 v[28:31], v[206:209], v[178:181], v[28:31]
	v_mfma_f32_16x16x32_bf16 v[24:27], v[214:217], v[178:181], v[24:27]
	v_mfma_f32_16x16x32_bf16 v[12:15], v[206:209], v[186:189], v[12:15]
	v_mfma_f32_16x16x32_bf16 v[8:11], v[214:217], v[186:189], v[8:11]
	v_mfma_f32_16x16x32_bf16 v[4:7], v[206:209], v[198:201], v[4:7]
	v_mfma_f32_16x16x32_bf16 v[0:3], v[214:217], v[198:201], v[0:3]
	s_setprio 0
	s_add_i32 s54, 0, 0x18000
	v_add_u32_e32 v162, s54, v146
	s_barrier
	ds_read_b128 v[150:153], v162
	ds_read_b128 v[154:157], v162 offset:1024
	ds_read_b128 v[158:161], v162 offset:2048
	ds_read_b128 v[162:165], v162 offset:3072
	s_add_u32 s24, s24, 0x80000
	s_addc_u32 s25, s25, 0
	s_mov_b32 m0, s34
	ds_read_b128 v[166:169], v148 offset:32768
	ds_read_b128 v[170:173], v148 offset:33792
	ds_read_b128 v[174:177], v148 offset:34816
	ds_read_b128 v[178:181], v148 offset:35840
	ds_read_b128 v[182:185], v148 offset:36864
	ds_read_b128 v[186:189], v148 offset:37888
	ds_read_b128 v[190:193], v148 offset:38912
	ds_read_b128 v[198:201], v148 offset:39936
	global_load_lds_dwordx4 v134, s[24:25]
	s_mov_b32 m0, s35
	s_nop 0
	global_load_lds_dwordx4 v130, s[24:25]
	s_waitcnt lgkmcnt(8)
	s_barrier
	s_setprio 1
	s_waitcnt lgkmcnt(7)
	v_mfma_f32_16x16x32_bf16 v[124:127], v[150:153], v[166:169], v[124:127]
	v_mfma_f32_16x16x32_bf16 v[120:123], v[158:161], v[166:169], v[120:123]
	s_waitcnt lgkmcnt(5)
	v_mfma_f32_16x16x32_bf16 v[116:119], v[150:153], v[174:177], v[116:119]
	v_mfma_f32_16x16x32_bf16 v[112:115], v[158:161], v[174:177], v[112:115]
	s_waitcnt lgkmcnt(3)
	v_mfma_f32_16x16x32_bf16 v[100:103], v[150:153], v[182:185], v[100:103]
	v_mfma_f32_16x16x32_bf16 v[96:99], v[158:161], v[182:185], v[96:99]
	s_waitcnt lgkmcnt(1)
	v_mfma_f32_16x16x32_bf16 v[84:87], v[150:153], v[190:193], v[84:87]
	v_mfma_f32_16x16x32_bf16 v[80:83], v[158:161], v[190:193], v[80:83]
	v_mfma_f32_16x16x32_bf16 v[124:127], v[154:157], v[170:173], v[124:127]
	v_mfma_f32_16x16x32_bf16 v[120:123], v[162:165], v[170:173], v[120:123]
	v_mfma_f32_16x16x32_bf16 v[116:119], v[154:157], v[178:181], v[116:119]
	v_mfma_f32_16x16x32_bf16 v[112:115], v[162:165], v[178:181], v[112:115]
	v_mfma_f32_16x16x32_bf16 v[100:103], v[154:157], v[186:189], v[100:103]
	v_mfma_f32_16x16x32_bf16 v[96:99], v[162:165], v[186:189], v[96:99]
	s_waitcnt lgkmcnt(0)
	v_mfma_f32_16x16x32_bf16 v[84:87], v[154:157], v[198:201], v[84:87]
	v_mfma_f32_16x16x32_bf16 v[80:83], v[162:165], v[198:201], v[80:83]
	s_setprio 0
	s_barrier
	s_add_i32 s24, 0, 0x1c000
	s_add_i32 s25, s54, s29
	v_add_u32_e32 v196, s24, v146
	v_lshl_add_u64 v[194:195], v[194:195], 0, s[8:9]
	s_mov_b32 m0, s25
	ds_read_b128 v[202:205], v196
	ds_read_b128 v[206:209], v196 offset:1024
	ds_read_b128 v[210:213], v196 offset:2048
	ds_read_b128 v[214:217], v196 offset:3072
	global_load_lds_dwordx4 v[194:195], off
	v_lshl_add_u64 v[194:195], v[218:219], 0, s[8:9]
	s_add_i32 m0, s25, 0x2000
	s_nop 0
	global_load_lds_dwordx4 v[194:195], off
	s_barrier
	s_setprio 1
	s_waitcnt lgkmcnt(3)
	v_mfma_f32_16x16x32_bf16 v[108:111], v[202:205], v[166:169], v[108:111]
	s_waitcnt lgkmcnt(1)
	v_mfma_f32_16x16x32_bf16 v[104:107], v[210:213], v[166:169], v[104:107]
	v_mfma_f32_16x16x32_bf16 v[92:95], v[202:205], v[174:177], v[92:95]
	v_mfma_f32_16x16x32_bf16 v[88:91], v[210:213], v[174:177], v[88:91]
	v_mfma_f32_16x16x32_bf16 v[76:79], v[202:205], v[182:185], v[76:79]
	v_mfma_f32_16x16x32_bf16 v[72:75], v[210:213], v[182:185], v[72:75]
	v_mfma_f32_16x16x32_bf16 v[68:71], v[202:205], v[190:193], v[68:71]
	v_mfma_f32_16x16x32_bf16 v[64:67], v[210:213], v[190:193], v[64:67]
	v_mfma_f32_16x16x32_bf16 v[108:111], v[206:209], v[170:173], v[108:111]
	s_waitcnt lgkmcnt(0)
	v_mfma_f32_16x16x32_bf16 v[104:107], v[214:217], v[170:173], v[104:107]
	v_mfma_f32_16x16x32_bf16 v[92:95], v[206:209], v[178:181], v[92:95]
	v_mfma_f32_16x16x32_bf16 v[88:91], v[214:217], v[178:181], v[88:91]
	v_mfma_f32_16x16x32_bf16 v[76:79], v[206:209], v[186:189], v[76:79]
	v_mfma_f32_16x16x32_bf16 v[72:75], v[214:217], v[186:189], v[72:75]
	v_mfma_f32_16x16x32_bf16 v[68:71], v[206:209], v[198:201], v[68:71]
	v_mfma_f32_16x16x32_bf16 v[64:67], v[214:217], v[198:201], v[64:67]
	s_setprio 0
	s_mov_b32 m0, s39
	v_lshl_add_u64 v[194:195], v[220:221], 0, s[8:9]
	s_barrier
	ds_read_b128 v[166:169], v148 offset:49152
	ds_read_b128 v[170:173], v148 offset:50176
	ds_read_b128 v[174:177], v148 offset:51200
	ds_read_b128 v[178:181], v148 offset:52224
	ds_read_b128 v[182:185], v148 offset:53248
	ds_read_b128 v[186:189], v148 offset:54272
	ds_read_b128 v[190:193], v148 offset:55296
	ds_read_b128 v[198:201], v148 offset:56320
	global_load_lds_dwordx4 v[194:195], off
	v_lshl_add_u64 v[194:195], v[222:223], 0, s[8:9]
	s_mov_b32 m0, s42
	s_nop 0
	global_load_lds_dwordx4 v[194:195], off
	s_barrier
; DI unsigned pack2(float a, float b) { f32x2 v = {a, b}; hwbf16x2 r = __builtin_convertvector(v, hwbf16x2); return __builtin_bit_cast(unsigned, r); }
; #define PG8_STAGE(bufoff, gbase, voff) do { _Pragma("unroll") for (int _i = 0; _i < 2; ++_i) \
;         __builtin_amdgcn_global_load_lds((const unsigned*)((const char*)(gbase) + (voff)[_i]), (LAS unsigned*)(lds + (bufoff) + ldsw + _i * 8192), 16, 0, 0); } while (0)
; #define PG8_LDA(dst, b, h) do { _Pragma("unroll") for (int m = 0; m < 4; ++m) _Pragma("unroll") for (int k = 0; k < 2; ++k) dst[m][k] = *(const LAS bf16x8*)(lds + PG8_SA(b, h) + aoff + m * 2048 + k * 1024); } while (0)
; #define PG8_MMA(ai, bj, At, Bt) do { __builtin_amdgcn_s_setprio(1); _Pragma("unroll") for (int m = 0; m < 4; ++m) _Pragma("unroll") for (int n = 0; n < 2; ++n) _Pragma("unroll") for (int k = 0; k < 2; ++k) \
;         acc[ai][bj][m][n] = __builtin_amdgcn_mfma_f32_16x16x32_bf16(Bt[n][k], At[m][k], acc[ai][bj][m][n], 0, 0, 0); __builtin_amdgcn_s_setprio(0); } while (0)
;     DI void operator()(const f32x4 (&acc)[2][2][4][2], const Unit& u, int wr, int wc, int fr, int fq) const {
;         bf16_t* O = O1; int ldc = ldc1, pn = u.pn; if (pn >= split) { O = O2; ldc = ldc2; pn -= split; }
;         const int row0 = u.pm * BM + wr * 64 + fr, col0 = pn * BM + wc * 32 + 8 * fq;
; #pragma unroll
;         for (int ai = 0; ai < 2; ++ai)
; #pragma unroll
;             for (int m = 0; m < 4; ++m) { bf16_t* rowp = O + (size_t)(row0 + ai * HALF + m * 16) * ldc + col0;
; #pragma unroll
;                 for (int bj = 0; bj < 2; ++bj) { const f32x4 v0 = acc[ai][bj][m][0], v1 = acc[ai][bj][m][1];
;                     u32x4 o; o[0] = pack2(v0[0], v0[1]); o[1] = pack2(v0[2], v0[3]); o[2] = pack2(v1[0], v1[1]); o[3] = pack2(v1[2], v1[3]);
;                     *(u32x4*)(rowp + bj * HALF) = o; } }
; template <class Map, class Epi>
; DI void gemm_phase(LAS unsigned char* lds, const Map& MP, const Epi& E, const int nM, const int nN, const int K, const int lda, const int ldb) {
;     ...
;             PG8_BAR; PG8_WAIT_L(0); PG8_MMA(0, 1, At, B1); PG8_BAR;
;             PG8_LDA(At, 1, 1); PG8_STAGE(PG8_SA(1, 0), a3, voffA);
;             PG8_BAR; PG8_WAIT_L(0); PG8_MMA(1, 0, At, B0); PG8_BAR; PG8_SCHED;
;             PG8_STAGE(PG8_SB(1, 1), b3 + hstepB, voffB);
;             PG8_WAIT_V(6); PG8_BAR; PG8_MMA(1, 1, At, B1); PG8_BAR;
	s_setprio 1
	s_waitcnt lgkmcnt(7)
	v_mfma_f32_16x16x32_bf16 v[60:63], v[150:153], v[166:169], v[60:63]
	v_mfma_f32_16x16x32_bf16 v[56:59], v[158:161], v[166:169], v[56:59]
	s_waitcnt lgkmcnt(5)
	v_mfma_f32_16x16x32_bf16 v[52:55], v[150:153], v[174:177], v[52:55]
	v_mfma_f32_16x16x32_bf16 v[48:51], v[158:161], v[174:177], v[48:51]
	s_waitcnt lgkmcnt(3)
	v_mfma_f32_16x16x32_bf16 v[36:39], v[150:153], v[182:185], v[36:39]
	v_mfma_f32_16x16x32_bf16 v[32:35], v[158:161], v[182:185], v[32:35]
	s_waitcnt lgkmcnt(1)
	v_mfma_f32_16x16x32_bf16 v[20:23], v[150:153], v[190:193], v[20:23]
	v_mfma_f32_16x16x32_bf16 v[16:19], v[158:161], v[190:193], v[16:19]
	v_mfma_f32_16x16x32_bf16 v[60:63], v[154:157], v[170:173], v[60:63]
	v_mfma_f32_16x16x32_bf16 v[56:59], v[162:165], v[170:173], v[56:59]
	v_mfma_f32_16x16x32_bf16 v[52:55], v[154:157], v[178:181], v[52:55]
	v_mfma_f32_16x16x32_bf16 v[48:51], v[162:165], v[178:181], v[48:51]
	v_mfma_f32_16x16x32_bf16 v[36:39], v[154:157], v[186:189], v[36:39]
	v_mfma_f32_16x16x32_bf16 v[32:35], v[162:165], v[186:189], v[32:35]
	s_waitcnt lgkmcnt(0)
	v_mfma_f32_16x16x32_bf16 v[20:23], v[154:157], v[198:201], v[20:23]
	v_mfma_f32_16x16x32_bf16 v[16:19], v[162:165], v[198:201], v[16:19]
	s_setprio 0
	s_barrier
	s_add_u32 s22, s22, 0x80080
	s_addc_u32 s23, s23, 0
	s_add_i32 s24, s24, s29
	s_mov_b32 m0, s24
	s_nop 0
	global_load_lds_dwordx4 v132, s[22:23]
	s_add_i32 m0, s24, 0x2000
	s_nop 0
	global_load_lds_dwordx4 v128, s[22:23]
	s_waitcnt vmcnt(6)
	s_barrier
	s_setprio 1
	v_mfma_f32_16x16x32_bf16 v[44:47], v[202:205], v[166:169], v[44:47]
	v_mfma_f32_16x16x32_bf16 v[40:43], v[210:213], v[166:169], v[40:43]
	v_mfma_f32_16x16x32_bf16 v[28:31], v[202:205], v[174:177], v[28:31]
	v_mfma_f32_16x16x32_bf16 v[24:27], v[210:213], v[174:177], v[24:27]
	v_mfma_f32_16x16x32_bf16 v[12:15], v[202:205], v[182:185], v[12:15]
	v_mfma_f32_16x16x32_bf16 v[8:11], v[210:213], v[182:185], v[8:11]
	v_mfma_f32_16x16x32_bf16 v[4:7], v[202:205], v[190:193], v[4:7]
	v_mfma_f32_16x16x32_bf16 v[0:3], v[210:213], v[190:193], v[0:3]
	v_mfma_f32_16x16x32_bf16 v[44:47], v[206:209], v[170:173], v[44:47]
	v_mfma_f32_16x16x32_bf16 v[40:43], v[214:217], v[170:173], v[40:43]
	v_mfma_f32_16x16x32_bf16 v[28:31], v[206:209], v[178:181], v[28:31]
	v_mfma_f32_16x16x32_bf16 v[24:27], v[214:217], v[178:181], v[24:27]
	v_mfma_f32_16x16x32_bf16 v[12:15], v[206:209], v[186:189], v[12:15]
	v_mfma_f32_16x16x32_bf16 v[8:11], v[214:217], v[186:189], v[8:11]
	v_mfma_f32_16x16x32_bf16 v[4:7], v[206:209], v[198:201], v[4:7]
	v_mfma_f32_16x16x32_bf16 v[0:3], v[214:217], v[198:201], v[0:3]
	s_setprio 0
	s_add_i32 s3, s3, 2
	s_add_u32 s52, s52, 0x100
	s_addc_u32 s53, s53, 0
	s_add_u32 s20, s20, 0x100
	s_addc_u32 s21, s21, 0
	s_cmp_gt_u32 s3, 29
	s_barrier
	s_cbranch_scc0 .LBB1_1382
	s_lshl_b32 s3, s10, 8
	v_mov_b32_e32 v150, v144
	v_mov_b32_e32 v151, v145
	s_add_i32 s3, s3, s37
	v_cvt_pk_bf16_f32 v68, v68, v69
	v_add_u32_e32 v154, s3, v150
	s_lshl_b32 s3, s47, 8
	s_or_b32 s3, s3, s38
	v_lshl_add_u32 v150, v151, 3, s3
	v_ashrrev_i32_e32 v151, 31, v150
	v_lshl_add_u64 v[150:151], v[150:151], 1, s[6:7]
	v_cvt_pk_bf16_f32 v69, v70, v71
	v_cvt_pk_bf16_f32 v70, v64, v65
	v_add_u32_e32 v64, 0x80, v154
	v_mad_i64_i32 v[152:153], s[20:21], v154, s46, v[150:151]
	v_cvt_pk_bf16_f32 v108, v108, v109
	v_cvt_pk_bf16_f32 v109, v110, v111
	v_cvt_pk_bf16_f32 v110, v104, v105
	v_cvt_pk_bf16_f32 v111, v106, v107
	v_add_u32_e32 v104, 16, v154
	v_mad_i64_i32 v[64:65], s[20:21], v64, s46, v[150:151]
	v_cvt_pk_bf16_f32 v44, v44, v45
	v_cvt_pk_bf16_f32 v45, v46, v47
	v_cvt_pk_bf16_f32 v46, v40, v41
	v_cvt_pk_bf16_f32 v47, v42, v43
	v_add_u32_e32 v40, 0x90, v154
	global_store_dwordx4 v[152:153], v[108:111], off offset:256
	v_cvt_pk_bf16_f32 v92, v92, v93
	v_cvt_pk_bf16_f32 v93, v94, v95
	v_mad_i64_i32 v[108:109], s[20:21], v104, s46, v[150:151]
	v_cvt_pk_bf16_f32 v94, v88, v89
	v_cvt_pk_bf16_f32 v95, v90, v91
	v_add_u32_e32 v88, 32, v154
	global_store_dwordx4 v[64:65], v[44:47], off offset:256
	v_cvt_pk_bf16_f32 v28, v28, v29
	v_cvt_pk_bf16_f32 v29, v30, v31
	v_mad_i64_i32 v[44:45], s[20:21], v40, s46, v[150:151]
	v_cvt_pk_bf16_f32 v30, v24, v25
	v_cvt_pk_bf16_f32 v31, v26, v27
	v_add_u32_e32 v24, 0xa0, v154
	global_store_dwordx4 v[108:109], v[92:95], off offset:256
	v_cvt_pk_bf16_f32 v76, v76, v77
	v_cvt_pk_bf16_f32 v77, v78, v79
	v_mad_i64_i32 v[92:93], s[20:21], v88, s46, v[150:151]
	v_cvt_pk_bf16_f32 v78, v72, v73
	v_cvt_pk_bf16_f32 v79, v74, v75
	v_add_u32_e32 v72, 48, v154
	global_store_dwordx4 v[44:45], v[28:31], off offset:256
	v_cvt_pk_bf16_f32 v12, v12, v13
	v_cvt_pk_bf16_f32 v13, v14, v15
	v_mad_i64_i32 v[28:29], s[20:21], v24, s46, v[150:151]
	v_cvt_pk_bf16_f32 v14, v8, v9
	v_cvt_pk_bf16_f32 v15, v10, v11
	v_add_u32_e32 v8, 0xb0, v154
	global_store_dwordx4 v[92:93], v[76:79], off offset:256
	global_store_dwordx4 v[28:29], v[12:15], off offset:256
	v_cvt_pk_bf16_f32 v124, v124, v125
	v_mad_i64_i32 v[76:77], s[20:21], v72, s46, v[150:151]
	v_mad_i64_i32 v[12:13], s[20:21], v8, s46, v[150:151]
	v_cvt_pk_bf16_f32 v125, v126, v127
	v_cvt_pk_bf16_f32 v126, v120, v121
	v_cvt_pk_bf16_f32 v127, v122, v123
	v_cvt_pk_bf16_f32 v104, v116, v117
	v_cvt_pk_bf16_f32 v105, v118, v119
	v_cvt_pk_bf16_f32 v106, v112, v113
	v_cvt_pk_bf16_f32 v107, v114, v115
	v_cvt_pk_bf16_f32 v88, v100, v101
	v_cvt_pk_bf16_f32 v89, v102, v103
	v_cvt_pk_bf16_f32 v90, v96, v97
	v_cvt_pk_bf16_f32 v91, v98, v99
	v_cvt_pk_bf16_f32 v72, v84, v85
	v_cvt_pk_bf16_f32 v73, v86, v87
	v_cvt_pk_bf16_f32 v74, v80, v81
	v_cvt_pk_bf16_f32 v75, v82, v83
	v_cvt_pk_bf16_f32 v71, v66, v67
	v_cvt_pk_bf16_f32 v60, v60, v61
	v_cvt_pk_bf16_f32 v61, v62, v63
	v_cvt_pk_bf16_f32 v62, v56, v57
	v_cvt_pk_bf16_f32 v63, v58, v59
	v_cvt_pk_bf16_f32 v40, v52, v53
	v_cvt_pk_bf16_f32 v41, v54, v55
	v_cvt_pk_bf16_f32 v42, v48, v49
	v_cvt_pk_bf16_f32 v43, v50, v51
	v_cvt_pk_bf16_f32 v24, v36, v37
	v_cvt_pk_bf16_f32 v25, v38, v39
	v_cvt_pk_bf16_f32 v26, v32, v33
	v_cvt_pk_bf16_f32 v27, v34, v35
	v_cvt_pk_bf16_f32 v8, v20, v21
	v_cvt_pk_bf16_f32 v9, v22, v23
	v_cvt_pk_bf16_f32 v10, v16, v17
	v_cvt_pk_bf16_f32 v11, v18, v19
	v_cvt_pk_bf16_f32 v4, v4, v5
	v_cvt_pk_bf16_f32 v5, v6, v7
	v_cvt_pk_bf16_f32 v6, v0, v1
	v_cvt_pk_bf16_f32 v7, v2, v3
	s_and_b64 vcc, exec, s[40:41]
	s_mov_b32 s47, s12
	s_mov_b32 s10, s14
	s_mov_b64 s[20:21], s[18:19]
	s_mov_b64 s[22:23], s[16:17]
	global_store_dwordx4 v[152:153], v[124:127], off
	global_store_dwordx4 v[108:109], v[104:107], off
	global_store_dwordx4 v[92:93], v[88:91], off
	global_store_dwordx4 v[76:77], v[72:75], off
	global_store_dwordx4 v[76:77], v[68:71], off offset:256
	global_store_dwordx4 v[64:65], v[60:63], off
	global_store_dwordx4 v[44:45], v[40:43], off
	global_store_dwordx4 v[28:29], v[24:27], off
	global_store_dwordx4 v[12:13], v[8:11], off
	global_store_dwordx4 v[12:13], v[4:7], off offset:256
	s_cbranch_vccz .LBB1_1379
	s_waitcnt vmcnt(0)
	s_cmpk_gt_u32 s4, 0xff
	s_cbranch_scc1 .LBB1_1386
	s_barrier

; #define PG8_STAGE(bufoff, gbase, voff) do { _Pragma("unroll") for (int _i = 0; _i < 2; ++_i) \
;         __builtin_amdgcn_global_load_lds((const unsigned*)((const char*)(gbase) + (voff)[_i]), (LAS unsigned*)(lds + (bufoff) + ldsw + _i * 8192), 16, 0, 0); } while (0)
; #define PG8_LDA(dst, b, h) do { _Pragma("unroll") for (int m = 0; m < 4; ++m) _Pragma("unroll") for (int k = 0; k < 2; ++k) dst[m][k] = *(const LAS bf16x8*)(lds + PG8_SA(b, h) + aoff + m * 2048 + k * 1024); } while (0)
; #define PG8_LDB(dst, b, h) do { _Pragma("unroll") for (int n = 0; n < 2; ++n) _Pragma("unroll") for (int k = 0; k < 2; ++k) dst[n][k] = *(const LAS bf16x8*)(lds + PG8_SB(b, h) + boff + n * 2048 + k * 1024); } while (0)
; #define PG8_MMA(ai, bj, At, Bt) do { __builtin_amdgcn_s_setprio(1); _Pragma("unroll") for (int m = 0; m < 4; ++m) _Pragma("unroll") for (int n = 0; n < 2; ++n) _Pragma("unroll") for (int k = 0; k < 2; ++k) \
;         acc[ai][bj][m][n] = __builtin_amdgcn_mfma_f32_16x16x32_bf16(Bt[n][k], At[m][k], acc[ai][bj][m][n], 0, 0, 0); __builtin_amdgcn_s_setprio(0); } while (0)
; #define PG8_WAIT_L(n) asm volatile("s_waitcnt lgkmcnt(" #n ")" ::: "memory")
; #define PG8_BAR __builtin_amdgcn_s_barrier()
; #define PG8_SCHED __builtin_amdgcn_sched_barrier(0)
; template <class Map, class Epi>
; DI void gemm_phase(LAS unsigned char* lds, const Map& MP, const Epi& E, const int nM, const int nN, const int K, const int lda, const int ldb) {
;     ...
;             const bool last = (t == nt - 2);
;             const char* a1 = cA + (size_t)(t + 1) * kstep;
;             const char* a2 = last ? nA : cA + (size_t)(t + 2) * kstep; const char* b2 = last ? nB : cB + (size_t)(t + 2) * kstep;
;             const char* a3 = a2 + kstep; const char* b3 = b2 + kstep;
;             PG8_LDB(B0, 0, 0); PG8_SCHED; PG8_LDA(At, 0, 0); PG8_STAGE(PG8_SA(1, 1), a1 + hstepA, voffA);
;             PG8_WAIT_L(8); PG8_BAR; PG8_WAIT_L(0); PG8_MMA(0, 0, At, B0); PG8_BAR; PG8_SCHED;
;             PG8_LDB(B1, 0, 1); PG8_STAGE(PG8_SB(0, 0), b2, voffB);
;             PG8_BAR; PG8_WAIT_L(0); PG8_MMA(0, 1, At, B1); PG8_BAR;
;             PG8_LDA(At, 0, 1); PG8_STAGE(PG8_SA(0, 0), a2, voffA);
;             PG8_BAR; PG8_WAIT_L(0); PG8_MMA(1, 0, At, B0); PG8_BAR; PG8_SCHED;
.LBB1_1529:
	ds_read_b128 v[150:153], v147
	ds_read_b128 v[154:157], v147 offset:1024
	ds_read_b128 v[158:161], v147 offset:2048
	ds_read_b128 v[162:165], v147 offset:3072
	s_add_u32 s20, s18, 0xfffe0080
	s_addc_u32 s21, s19, -1
	s_cmp_eq_u32 s3, 4
	s_cselect_b32 s23, s13, s21
	s_cselect_b32 s22, s52, s20
	s_cselect_b32 s21, s53, s56
	s_cselect_b32 s20, s54, s55
	s_add_i32 m0, s11, 0xc000
	ds_read_b128 v[166:169], v148
	ds_read_b128 v[170:173], v148 offset:1024
	ds_read_b128 v[174:177], v148 offset:2048
	ds_read_b128 v[178:181], v148 offset:3072
	ds_read_b128 v[182:185], v148 offset:4096
	ds_read_b128 v[186:189], v148 offset:5120
	ds_read_b128 v[190:193], v148 offset:6144
	ds_read_b128 v[198:201], v148 offset:7168
	global_load_lds_dwordx4 v138, s[18:19]
	s_add_i32 m0, s11, 0xe000
	s_nop 0
	global_load_lds_dwordx4 v136, s[18:19]
	s_waitcnt lgkmcnt(8)
	s_barrier
	s_setprio 1
	s_waitcnt lgkmcnt(7)
	v_mfma_f32_16x16x32_bf16 v[124:127], v[150:153], v[166:169], v[124:127]
	v_mfma_f32_16x16x32_bf16 v[120:123], v[158:161], v[166:169], v[120:123]
	s_waitcnt lgkmcnt(5)
	v_mfma_f32_16x16x32_bf16 v[116:119], v[150:153], v[174:177], v[116:119]
	v_mfma_f32_16x16x32_bf16 v[112:115], v[158:161], v[174:177], v[112:115]
	s_waitcnt lgkmcnt(3)
	v_mfma_f32_16x16x32_bf16 v[100:103], v[150:153], v[182:185], v[100:103]
	v_mfma_f32_16x16x32_bf16 v[96:99], v[158:161], v[182:185], v[96:99]
	s_waitcnt lgkmcnt(1)
	v_mfma_f32_16x16x32_bf16 v[84:87], v[150:153], v[190:193], v[84:87]
	v_mfma_f32_16x16x32_bf16 v[80:83], v[158:161], v[190:193], v[80:83]
	v_mfma_f32_16x16x32_bf16 v[124:127], v[154:157], v[170:173], v[124:127]
	v_mfma_f32_16x16x32_bf16 v[120:123], v[162:165], v[170:173], v[120:123]
	v_mfma_f32_16x16x32_bf16 v[116:119], v[154:157], v[178:181], v[116:119]
	v_mfma_f32_16x16x32_bf16 v[112:115], v[162:165], v[178:181], v[112:115]
	v_mfma_f32_16x16x32_bf16 v[100:103], v[154:157], v[186:189], v[100:103]
	v_mfma_f32_16x16x32_bf16 v[96:99], v[162:165], v[186:189], v[96:99]
	s_waitcnt lgkmcnt(0)
	v_mfma_f32_16x16x32_bf16 v[84:87], v[154:157], v[198:201], v[84:87]
	v_mfma_f32_16x16x32_bf16 v[80:83], v[162:165], v[198:201], v[80:83]
	s_setprio 0
	s_barrier
	s_add_i32 s57, s47, s31
	v_lshl_add_u64 v[194:195], s[20:21], 0, v[132:133]
	s_mov_b32 m0, s57
	ds_read_b128 v[202:205], v149
	ds_read_b128 v[206:209], v149 offset:1024
	ds_read_b128 v[210:213], v149 offset:2048
	ds_read_b128 v[214:217], v149 offset:3072
	global_load_lds_dwordx4 v[194:195], off
	v_lshl_add_u64 v[218:219], s[20:21], 0, v[128:129]
	s_add_i32 m0, s57, 0x2000
	s_nop 0
	global_load_lds_dwordx4 v[218:219], off
	s_barrier
	s_setprio 1
	s_waitcnt lgkmcnt(3)
	v_mfma_f32_16x16x32_bf16 v[108:111], v[202:205], v[166:169], v[108:111]
	s_waitcnt lgkmcnt(1)
	v_mfma_f32_16x16x32_bf16 v[104:107], v[210:213], v[166:169], v[104:107]
	v_mfma_f32_16x16x32_bf16 v[92:95], v[202:205], v[174:177], v[92:95]
	v_mfma_f32_16x16x32_bf16 v[88:91], v[210:213], v[174:177], v[88:91]
	v_mfma_f32_16x16x32_bf16 v[76:79], v[202:205], v[182:185], v[76:79]
	v_mfma_f32_16x16x32_bf16 v[72:75], v[210:213], v[182:185], v[72:75]
	v_mfma_f32_16x16x32_bf16 v[68:71], v[202:205], v[190:193], v[68:71]
	v_mfma_f32_16x16x32_bf16 v[64:67], v[210:213], v[190:193], v[64:67]
	v_mfma_f32_16x16x32_bf16 v[108:111], v[206:209], v[170:173], v[108:111]
	s_waitcnt lgkmcnt(0)
	v_mfma_f32_16x16x32_bf16 v[104:107], v[214:217], v[170:173], v[104:107]
	v_mfma_f32_16x16x32_bf16 v[92:95], v[206:209], v[178:181], v[92:95]
	v_mfma_f32_16x16x32_bf16 v[88:91], v[214:217], v[178:181], v[88:91]
	v_mfma_f32_16x16x32_bf16 v[76:79], v[206:209], v[186:189], v[76:79]
	v_mfma_f32_16x16x32_bf16 v[72:75], v[214:217], v[186:189], v[72:75]
	v_mfma_f32_16x16x32_bf16 v[68:71], v[206:209], v[198:201], v[68:71]
	v_mfma_f32_16x16x32_bf16 v[64:67], v[214:217], v[198:201], v[64:67]
	s_setprio 0
	s_mov_b32 m0, s11
	v_lshl_add_u64 v[220:221], s[22:23], 0, v[134:135]
	s_barrier
	ds_read_b128 v[166:169], v148 offset:16384
	ds_read_b128 v[170:173], v148 offset:17408
	ds_read_b128 v[174:177], v148 offset:18432
	ds_read_b128 v[178:181], v148 offset:19456
	ds_read_b128 v[182:185], v148 offset:20480
	ds_read_b128 v[186:189], v148 offset:21504
	ds_read_b128 v[190:193], v148 offset:22528
	ds_read_b128 v[198:201], v148 offset:23552
	global_load_lds_dwordx4 v[220:221], off
	v_lshl_add_u64 v[222:223], s[22:23], 0, v[130:131]
	s_mov_b32 m0, s35
	s_nop 0
	global_load_lds_dwordx4 v[222:223], off
	s_barrier
	s_setprio 1
	s_waitcnt lgkmcnt(7)
	v_mfma_f32_16x16x32_bf16 v[60:63], v[150:153], v[166:169], v[60:63]
	v_mfma_f32_16x16x32_bf16 v[56:59], v[158:161], v[166:169], v[56:59]
	s_waitcnt lgkmcnt(5)
	v_mfma_f32_16x16x32_bf16 v[52:55], v[150:153], v[174:177], v[52:55]
	v_mfma_f32_16x16x32_bf16 v[48:51], v[158:161], v[174:177], v[48:51]
	s_waitcnt lgkmcnt(3)
	v_mfma_f32_16x16x32_bf16 v[36:39], v[150:153], v[182:185], v[36:39]
	v_mfma_f32_16x16x32_bf16 v[32:35], v[158:161], v[182:185], v[32:35]
	s_waitcnt lgkmcnt(1)
	v_mfma_f32_16x16x32_bf16 v[20:23], v[150:153], v[190:193], v[20:23]
	v_mfma_f32_16x16x32_bf16 v[16:19], v[158:161], v[190:193], v[16:19]
	v_mfma_f32_16x16x32_bf16 v[60:63], v[154:157], v[170:173], v[60:63]
	v_mfma_f32_16x16x32_bf16 v[56:59], v[162:165], v[170:173], v[56:59]
	v_mfma_f32_16x16x32_bf16 v[52:55], v[154:157], v[178:181], v[52:55]
	v_mfma_f32_16x16x32_bf16 v[48:51], v[162:165], v[178:181], v[48:51]
	v_mfma_f32_16x16x32_bf16 v[36:39], v[154:157], v[186:189], v[36:39]
	v_mfma_f32_16x16x32_bf16 v[32:35], v[162:165], v[186:189], v[32:35]
	s_waitcnt lgkmcnt(0)
	v_mfma_f32_16x16x32_bf16 v[20:23], v[154:157], v[198:201], v[20:23]
	v_mfma_f32_16x16x32_bf16 v[16:19], v[162:165], v[198:201], v[16:19]
	s_setprio 0
	s_barrier
; #define PG8_STAGE(bufoff, gbase, voff) do { _Pragma("unroll") for (int _i = 0; _i < 2; ++_i) \
;         __builtin_amdgcn_global_load_lds((const unsigned*)((const char*)(gbase) + (voff)[_i]), (LAS unsigned*)(lds + (bufoff) + ldsw + _i * 8192), 16, 0, 0); } while (0)
; #define PG8_LDA(dst, b, h) do { _Pragma("unroll") for (int m = 0; m < 4; ++m) _Pragma("unroll") for (int k = 0; k < 2; ++k) dst[m][k] = *(const LAS bf16x8*)(lds + PG8_SA(b, h) + aoff + m * 2048 + k * 1024); } while (0)
; #define PG8_LDB(dst, b, h) do { _Pragma("unroll") for (int n = 0; n < 2; ++n) _Pragma("unroll") for (int k = 0; k < 2; ++k) dst[n][k] = *(const LAS bf16x8*)(lds + PG8_SB(b, h) + boff + n * 2048 + k * 1024); } while (0)
; #define PG8_MMA(ai, bj, At, Bt) do { __builtin_amdgcn_s_setprio(1); _Pragma("unroll") for (int m = 0; m < 4; ++m) _Pragma("unroll") for (int n = 0; n < 2; ++n) _Pragma("unroll") for (int k = 0; k < 2; ++k) \
;         acc[ai][bj][m][n] = __builtin_amdgcn_mfma_f32_16x16x32_bf16(Bt[n][k], At[m][k], acc[ai][bj][m][n], 0, 0, 0); __builtin_amdgcn_s_setprio(0); } while (0)
; #define PG8_WAIT_V(n) asm volatile("s_waitcnt vmcnt(" #n ")" ::: "memory")
; #define PG8_WAIT_L(n) asm volatile("s_waitcnt lgkmcnt(" #n ")" ::: "memory")
; #define PG8_BAR __builtin_amdgcn_s_barrier()
; #define PG8_SCHED __builtin_amdgcn_sched_barrier(0)
; template <class Map, class Epi>
; DI void gemm_phase(LAS unsigned char* lds, const Map& MP, const Epi& E, const int nM, const int nN, const int K, const int lda, const int ldb) {
;     ...
;             PG8_STAGE(PG8_SB(0, 1), b2 + hstepB, voffB);
;             PG8_WAIT_V(6); PG8_BAR; PG8_MMA(1, 1, At, B1); PG8_BAR;
;             PG8_LDB(B0, 1, 0); PG8_SCHED; PG8_LDA(At, 1, 0); PG8_STAGE(PG8_SA(0, 1), a2 + hstepA, voffA);
;             PG8_WAIT_L(8); PG8_BAR; PG8_WAIT_L(0); PG8_MMA(0, 0, At, B0); PG8_BAR; PG8_SCHED;
;             PG8_LDB(B1, 1, 1); PG8_STAGE(PG8_SB(1, 0), b3, voffB);
;             PG8_BAR; PG8_WAIT_L(0); PG8_MMA(0, 1, At, B1); PG8_BAR;
;             PG8_LDA(At, 1, 1); PG8_STAGE(PG8_SA(1, 0), a3, voffA);
;             PG8_BAR; PG8_WAIT_L(0); PG8_MMA(1, 0, At, B0); PG8_BAR; PG8_SCHED;
	s_add_u32 s58, s20, 0x20000
	s_addc_u32 s59, s21, 0
	s_add_i32 s57, s48, s31
	s_mov_b32 m0, s57
	s_nop 0
	global_load_lds_dwordx4 v132, s[58:59]
	s_add_i32 m0, s57, 0x2000
	s_nop 0
	global_load_lds_dwordx4 v128, s[58:59]
	s_waitcnt vmcnt(6)
	s_barrier
	s_setprio 1
	v_mfma_f32_16x16x32_bf16 v[44:47], v[202:205], v[166:169], v[44:47]
	v_mfma_f32_16x16x32_bf16 v[40:43], v[210:213], v[166:169], v[40:43]
	v_mfma_f32_16x16x32_bf16 v[28:31], v[202:205], v[174:177], v[28:31]
	v_mfma_f32_16x16x32_bf16 v[24:27], v[210:213], v[174:177], v[24:27]
	v_mfma_f32_16x16x32_bf16 v[12:15], v[202:205], v[182:185], v[12:15]
	v_mfma_f32_16x16x32_bf16 v[8:11], v[210:213], v[182:185], v[8:11]
	v_mfma_f32_16x16x32_bf16 v[4:7], v[202:205], v[190:193], v[4:7]
	v_mfma_f32_16x16x32_bf16 v[0:3], v[210:213], v[190:193], v[0:3]
	v_mfma_f32_16x16x32_bf16 v[44:47], v[206:209], v[170:173], v[44:47]
	v_mfma_f32_16x16x32_bf16 v[40:43], v[214:217], v[170:173], v[40:43]
	v_mfma_f32_16x16x32_bf16 v[28:31], v[206:209], v[178:181], v[28:31]
	v_mfma_f32_16x16x32_bf16 v[24:27], v[214:217], v[178:181], v[24:27]
	v_mfma_f32_16x16x32_bf16 v[12:15], v[206:209], v[186:189], v[12:15]
	v_mfma_f32_16x16x32_bf16 v[8:11], v[214:217], v[186:189], v[8:11]
	v_mfma_f32_16x16x32_bf16 v[4:7], v[206:209], v[198:201], v[4:7]
	v_mfma_f32_16x16x32_bf16 v[0:3], v[214:217], v[198:201], v[0:3]
	s_setprio 0
	s_add_i32 s57, 0, 0x18000
	v_add_u32_e32 v162, s57, v146
	s_barrier
	ds_read_b128 v[150:153], v162
	ds_read_b128 v[154:157], v162 offset:1024
	ds_read_b128 v[158:161], v162 offset:2048
	ds_read_b128 v[162:165], v162 offset:3072
	s_add_u32 s22, s22, 0x20000
	s_addc_u32 s23, s23, 0
	s_mov_b32 m0, s36
	ds_read_b128 v[166:169], v148 offset:32768
	ds_read_b128 v[170:173], v148 offset:33792
	ds_read_b128 v[174:177], v148 offset:34816
	ds_read_b128 v[178:181], v148 offset:35840
	ds_read_b128 v[182:185], v148 offset:36864
	ds_read_b128 v[186:189], v148 offset:37888
	ds_read_b128 v[190:193], v148 offset:38912
	ds_read_b128 v[198:201], v148 offset:39936
	global_load_lds_dwordx4 v134, s[22:23]
	s_mov_b32 m0, s37
	s_nop 0
	global_load_lds_dwordx4 v130, s[22:23]
	s_waitcnt lgkmcnt(8)
	s_barrier
	s_setprio 1
	s_waitcnt lgkmcnt(7)
	v_mfma_f32_16x16x32_bf16 v[124:127], v[150:153], v[166:169], v[124:127]
	v_mfma_f32_16x16x32_bf16 v[120:123], v[158:161], v[166:169], v[120:123]
	s_waitcnt lgkmcnt(5)
	v_mfma_f32_16x16x32_bf16 v[116:119], v[150:153], v[174:177], v[116:119]
	v_mfma_f32_16x16x32_bf16 v[112:115], v[158:161], v[174:177], v[112:115]
	s_waitcnt lgkmcnt(3)
	v_mfma_f32_16x16x32_bf16 v[100:103], v[150:153], v[182:185], v[100:103]
	v_mfma_f32_16x16x32_bf16 v[96:99], v[158:161], v[182:185], v[96:99]
	s_waitcnt lgkmcnt(1)
	v_mfma_f32_16x16x32_bf16 v[84:87], v[150:153], v[190:193], v[84:87]
	v_mfma_f32_16x16x32_bf16 v[80:83], v[158:161], v[190:193], v[80:83]
	v_mfma_f32_16x16x32_bf16 v[124:127], v[154:157], v[170:173], v[124:127]
	v_mfma_f32_16x16x32_bf16 v[120:123], v[162:165], v[170:173], v[120:123]
	v_mfma_f32_16x16x32_bf16 v[116:119], v[154:157], v[178:181], v[116:119]
	v_mfma_f32_16x16x32_bf16 v[112:115], v[162:165], v[178:181], v[112:115]
	v_mfma_f32_16x16x32_bf16 v[100:103], v[154:157], v[186:189], v[100:103]
	v_mfma_f32_16x16x32_bf16 v[96:99], v[162:165], v[186:189], v[96:99]
	s_waitcnt lgkmcnt(0)
	v_mfma_f32_16x16x32_bf16 v[84:87], v[154:157], v[198:201], v[84:87]
	v_mfma_f32_16x16x32_bf16 v[80:83], v[162:165], v[198:201], v[80:83]
	s_setprio 0
	s_barrier
	s_add_i32 s22, 0, 0x1c000
	s_add_i32 s23, s57, s31
	v_add_u32_e32 v196, s22, v146
	v_lshl_add_u64 v[194:195], v[194:195], 0, s[8:9]
	s_mov_b32 m0, s23
	ds_read_b128 v[202:205], v196
	ds_read_b128 v[206:209], v196 offset:1024
	ds_read_b128 v[210:213], v196 offset:2048
	ds_read_b128 v[214:217], v196 offset:3072
	global_load_lds_dwordx4 v[194:195], off
	v_lshl_add_u64 v[194:195], v[218:219], 0, s[8:9]
	s_add_i32 m0, s23, 0x2000
	s_nop 0
	global_load_lds_dwordx4 v[194:195], off
	s_barrier
	s_setprio 1
	s_waitcnt lgkmcnt(3)
	v_mfma_f32_16x16x32_bf16 v[108:111], v[202:205], v[166:169], v[108:111]
	s_waitcnt lgkmcnt(1)
	v_mfma_f32_16x16x32_bf16 v[104:107], v[210:213], v[166:169], v[104:107]
	v_mfma_f32_16x16x32_bf16 v[92:95], v[202:205], v[174:177], v[92:95]
	v_mfma_f32_16x16x32_bf16 v[88:91], v[210:213], v[174:177], v[88:91]
	v_mfma_f32_16x16x32_bf16 v[76:79], v[202:205], v[182:185], v[76:79]
	v_mfma_f32_16x16x32_bf16 v[72:75], v[210:213], v[182:185], v[72:75]
	v_mfma_f32_16x16x32_bf16 v[68:71], v[202:205], v[190:193], v[68:71]
	v_mfma_f32_16x16x32_bf16 v[64:67], v[210:213], v[190:193], v[64:67]
	v_mfma_f32_16x16x32_bf16 v[108:111], v[206:209], v[170:173], v[108:111]
	s_waitcnt lgkmcnt(0)
	v_mfma_f32_16x16x32_bf16 v[104:107], v[214:217], v[170:173], v[104:107]
	v_mfma_f32_16x16x32_bf16 v[92:95], v[206:209], v[178:181], v[92:95]
	v_mfma_f32_16x16x32_bf16 v[88:91], v[214:217], v[178:181], v[88:91]
	v_mfma_f32_16x16x32_bf16 v[76:79], v[206:209], v[186:189], v[76:79]
	v_mfma_f32_16x16x32_bf16 v[72:75], v[214:217], v[186:189], v[72:75]
	v_mfma_f32_16x16x32_bf16 v[68:71], v[206:209], v[198:201], v[68:71]
	v_mfma_f32_16x16x32_bf16 v[64:67], v[214:217], v[198:201], v[64:67]
	s_setprio 0
	s_mov_b32 m0, s43
	v_lshl_add_u64 v[194:195], v[220:221], 0, s[8:9]
	s_barrier
	ds_read_b128 v[166:169], v148 offset:49152
	ds_read_b128 v[170:173], v148 offset:50176
	ds_read_b128 v[174:177], v148 offset:51200
	ds_read_b128 v[178:181], v148 offset:52224
	ds_read_b128 v[182:185], v148 offset:53248
	ds_read_b128 v[186:189], v148 offset:54272
	ds_read_b128 v[190:193], v148 offset:55296
	ds_read_b128 v[198:201], v148 offset:56320
	global_load_lds_dwordx4 v[194:195], off
	v_lshl_add_u64 v[194:195], v[222:223], 0, s[8:9]
	s_mov_b32 m0, s44
	s_nop 0
	global_load_lds_dwordx4 v[194:195], off
	s_barrier
; #define PG8_STAGE(bufoff, gbase, voff) do { _Pragma("unroll") for (int _i = 0; _i < 2; ++_i) \
;         __builtin_amdgcn_global_load_lds((const unsigned*)((const char*)(gbase) + (voff)[_i]), (LAS unsigned*)(lds + (bufoff) + ldsw + _i * 8192), 16, 0, 0); } while (0)
; #define PG8_MMA(ai, bj, At, Bt) do { __builtin_amdgcn_s_setprio(1); _Pragma("unroll") for (int m = 0; m < 4; ++m) _Pragma("unroll") for (int n = 0; n < 2; ++n) _Pragma("unroll") for (int k = 0; k < 2; ++k) \
;         acc[ai][bj][m][n] = __builtin_amdgcn_mfma_f32_16x16x32_bf16(Bt[n][k], At[m][k], acc[ai][bj][m][n], 0, 0, 0); __builtin_amdgcn_s_setprio(0); } while (0)
; #define PG8_WAIT_V(n) asm volatile("s_waitcnt vmcnt(" #n ")" ::: "memory")
; #define PG8_WAIT_L(n) asm volatile("s_waitcnt lgkmcnt(" #n ")" ::: "memory")
; #define PG8_BAR __builtin_amdgcn_s_barrier()
; #define PG8_SCHED __builtin_amdgcn_sched_barrier(0)
; template <class Map, class Epi>
; DI void gemm_phase(LAS unsigned char* lds, const Map& MP, const Epi& E, const int nM, const int nN, const int K, const int lda, const int ldb) {
;     ...
;             PG8_BAR; PG8_WAIT_L(0); PG8_MMA(1, 0, At, B0); PG8_BAR; PG8_SCHED;
;             PG8_STAGE(PG8_SB(1, 1), b3 + hstepB, voffB);
;             PG8_WAIT_V(6); PG8_BAR; PG8_MMA(1, 1, At, B1); PG8_BAR;
	s_setprio 1
	s_waitcnt lgkmcnt(7)
	v_mfma_f32_16x16x32_bf16 v[60:63], v[150:153], v[166:169], v[60:63]
	v_mfma_f32_16x16x32_bf16 v[56:59], v[158:161], v[166:169], v[56:59]
	s_waitcnt lgkmcnt(5)
	v_mfma_f32_16x16x32_bf16 v[52:55], v[150:153], v[174:177], v[52:55]
	v_mfma_f32_16x16x32_bf16 v[48:51], v[158:161], v[174:177], v[48:51]
	s_waitcnt lgkmcnt(3)
	v_mfma_f32_16x16x32_bf16 v[36:39], v[150:153], v[182:185], v[36:39]
	v_mfma_f32_16x16x32_bf16 v[32:35], v[158:161], v[182:185], v[32:35]
	s_waitcnt lgkmcnt(1)
	v_mfma_f32_16x16x32_bf16 v[20:23], v[150:153], v[190:193], v[20:23]
	v_mfma_f32_16x16x32_bf16 v[16:19], v[158:161], v[190:193], v[16:19]
	v_mfma_f32_16x16x32_bf16 v[60:63], v[154:157], v[170:173], v[60:63]
	v_mfma_f32_16x16x32_bf16 v[56:59], v[162:165], v[170:173], v[56:59]
	v_mfma_f32_16x16x32_bf16 v[52:55], v[154:157], v[178:181], v[52:55]
	v_mfma_f32_16x16x32_bf16 v[48:51], v[162:165], v[178:181], v[48:51]
	v_mfma_f32_16x16x32_bf16 v[36:39], v[154:157], v[186:189], v[36:39]
	v_mfma_f32_16x16x32_bf16 v[32:35], v[162:165], v[186:189], v[32:35]
	s_waitcnt lgkmcnt(0)
	v_mfma_f32_16x16x32_bf16 v[20:23], v[154:157], v[198:201], v[20:23]
	v_mfma_f32_16x16x32_bf16 v[16:19], v[162:165], v[198:201], v[16:19]
	s_setprio 0
	s_barrier
	s_add_u32 s20, s20, 0x20080
	s_addc_u32 s21, s21, 0
	s_add_i32 s22, s22, s31
	s_mov_b32 m0, s22
	s_nop 0
	global_load_lds_dwordx4 v132, s[20:21]
	s_add_i32 m0, s22, 0x2000
	s_nop 0
	global_load_lds_dwordx4 v128, s[20:21]
	s_waitcnt vmcnt(6)
	s_barrier
	s_setprio 1
	v_mfma_f32_16x16x32_bf16 v[44:47], v[202:205], v[166:169], v[44:47]
	v_mfma_f32_16x16x32_bf16 v[40:43], v[210:213], v[166:169], v[40:43]
	v_mfma_f32_16x16x32_bf16 v[28:31], v[202:205], v[174:177], v[28:31]
	v_mfma_f32_16x16x32_bf16 v[24:27], v[210:213], v[174:177], v[24:27]
	v_mfma_f32_16x16x32_bf16 v[12:15], v[202:205], v[182:185], v[12:15]
	v_mfma_f32_16x16x32_bf16 v[8:11], v[210:213], v[182:185], v[8:11]
	v_mfma_f32_16x16x32_bf16 v[4:7], v[202:205], v[190:193], v[4:7]
	v_mfma_f32_16x16x32_bf16 v[0:3], v[210:213], v[190:193], v[0:3]
	v_mfma_f32_16x16x32_bf16 v[44:47], v[206:209], v[170:173], v[44:47]
	v_mfma_f32_16x16x32_bf16 v[40:43], v[214:217], v[170:173], v[40:43]
	v_mfma_f32_16x16x32_bf16 v[28:31], v[206:209], v[178:181], v[28:31]
	v_mfma_f32_16x16x32_bf16 v[24:27], v[214:217], v[178:181], v[24:27]
	v_mfma_f32_16x16x32_bf16 v[12:15], v[206:209], v[186:189], v[12:15]
	v_mfma_f32_16x16x32_bf16 v[8:11], v[214:217], v[186:189], v[8:11]
	v_mfma_f32_16x16x32_bf16 v[4:7], v[206:209], v[198:201], v[4:7]
	v_mfma_f32_16x16x32_bf16 v[0:3], v[214:217], v[198:201], v[0:3]
	s_setprio 0
	s_add_i32 s3, s3, 2
	s_add_u32 s55, s55, 0x100
	s_addc_u32 s56, s56, 0
	s_add_u32 s18, s18, 0x100
	s_addc_u32 s19, s19, 0
	s_cmp_gt_u32 s3, 5
	s_barrier
	s_cbranch_scc0 .LBB1_1529
; DI unsigned pack2(float a, float b) { f32x2 v = {a, b}; hwbf16x2 r = __builtin_convertvector(v, hwbf16x2); return __builtin_bit_cast(unsigned, r); }
;     DI void operator()(const f32x4 (&acc)[2][2][4][2], const Unit& u, int wr, int wc, int fr, int fq) const {
;         bf16_t* O = O1; int ldc = ldc1, pn = u.pn; if (pn >= split) { O = O2; ldc = ldc2; pn -= split; }
;         const int row0 = u.pm * BM + wr * 64 + fr, col0 = pn * BM + wc * 32 + 8 * fq;
; #pragma unroll
;         for (int ai = 0; ai < 2; ++ai)
; #pragma unroll
;             for (int m = 0; m < 4; ++m) { bf16_t* rowp = O + (size_t)(row0 + ai * HALF + m * 16) * ldc + col0;
; #pragma unroll
;                 for (int bj = 0; bj < 2; ++bj) { const f32x4 v0 = acc[ai][bj][m][0], v1 = acc[ai][bj][m][1];
;                     u32x4 o; o[0] = pack2(v0[0], v0[1]); o[1] = pack2(v0[2], v0[3]); o[2] = pack2(v1[0], v1[1]); o[3] = pack2(v1[2], v1[3]);
;                     *(u32x4*)(rowp + bj * HALF) = o; } }
	s_cmp_lt_i32 s45, 12
	s_cselect_b32 s3, 0, -12
	s_mov_b32 s13, 0x1e510000
	s_movk_i32 s18, 0xc00
	s_cselect_b32 s13, s13, 0x2a510000
	s_cselect_b32 s20, s18, 0x1000
	s_add_i32 s3, s3, s45
	s_add_u32 s18, s6, s13
	v_mov_b32_e32 v150, v144
	v_mov_b32_e32 v151, v145
	s_addc_u32 s19, s7, 0
	s_lshl_b32 s10, s10, 8
	s_lshl_b32 s3, s3, 8
	s_add_i32 s10, s10, s39
	s_or_b32 s3, s3, s42
	v_add_u32_e32 v154, s10, v150
	v_lshl_add_u32 v150, v151, 3, s3
	v_ashrrev_i32_e32 v151, 31, v150
	v_lshl_add_u64 v[150:151], v[150:151], 1, s[18:19]
	v_mad_i64_i32 v[152:153], s[18:19], s20, v154, 0
	v_cvt_pk_bf16_f32 v108, v108, v109
	v_cvt_pk_bf16_f32 v109, v110, v111
	v_cvt_pk_bf16_f32 v110, v104, v105
	v_add_u32_e32 v104, 16, v154
	v_lshl_add_u64 v[152:153], v[152:153], 1, v[150:151]
	v_cvt_pk_bf16_f32 v111, v106, v107
	v_mad_i64_i32 v[104:105], s[18:19], s20, v104, 0
	v_cvt_pk_bf16_f32 v92, v92, v93
	v_cvt_pk_bf16_f32 v93, v94, v95
	v_cvt_pk_bf16_f32 v94, v88, v89
	v_add_u32_e32 v88, 32, v154
	v_cvt_pk_bf16_f32 v124, v124, v125
	v_cvt_pk_bf16_f32 v125, v126, v127
	v_cvt_pk_bf16_f32 v126, v120, v121
	v_cvt_pk_bf16_f32 v127, v122, v123
	global_store_dwordx4 v[152:153], v[108:111], off offset:256
	v_cvt_pk_bf16_f32 v95, v90, v91
	v_mad_i64_i32 v[88:89], s[18:19], s20, v88, 0
	v_lshl_add_u64 v[108:109], v[104:105], 1, v[150:151]
	v_cvt_pk_bf16_f32 v76, v76, v77
	v_cvt_pk_bf16_f32 v77, v78, v79
	v_cvt_pk_bf16_f32 v78, v72, v73
	v_add_u32_e32 v72, 48, v154
	v_cvt_pk_bf16_f32 v68, v68, v69
	v_cvt_pk_bf16_f32 v69, v70, v71
	v_cvt_pk_bf16_f32 v70, v64, v65
	v_add_u32_e32 v64, 0x80, v154
	global_store_dwordx4 v[152:153], v[124:127], off
	v_cvt_pk_bf16_f32 v104, v116, v117
	v_cvt_pk_bf16_f32 v105, v118, v119
	v_cvt_pk_bf16_f32 v106, v112, v113
	v_cvt_pk_bf16_f32 v107, v114, v115
	global_store_dwordx4 v[108:109], v[92:95], off offset:256
	v_cvt_pk_bf16_f32 v79, v74, v75
	v_mad_i64_i32 v[72:73], s[18:19], s20, v72, 0
	v_lshl_add_u64 v[92:93], v[88:89], 1, v[150:151]
	v_mad_i64_i32 v[64:65], s[18:19], s20, v64, 0
	v_cvt_pk_bf16_f32 v44, v44, v45
	v_cvt_pk_bf16_f32 v45, v46, v47
	v_cvt_pk_bf16_f32 v46, v40, v41
	v_add_u32_e32 v40, 0x90, v154
	global_store_dwordx4 v[108:109], v[104:107], off
	v_cvt_pk_bf16_f32 v88, v100, v101
	v_cvt_pk_bf16_f32 v89, v102, v103
	v_cvt_pk_bf16_f32 v90, v96, v97
	v_cvt_pk_bf16_f32 v91, v98, v99
	global_store_dwordx4 v[92:93], v[76:79], off offset:256
	v_cvt_pk_bf16_f32 v74, v80, v81
	v_cvt_pk_bf16_f32 v75, v82, v83
	v_lshl_add_u64 v[76:77], v[72:73], 1, v[150:151]
	v_cvt_pk_bf16_f32 v72, v84, v85
	v_cvt_pk_bf16_f32 v73, v86, v87
	v_cvt_pk_bf16_f32 v71, v66, v67
	v_lshl_add_u64 v[64:65], v[64:65], 1, v[150:151]
	v_cvt_pk_bf16_f32 v47, v42, v43
	v_mad_i64_i32 v[40:41], s[18:19], s20, v40, 0
	v_cvt_pk_bf16_f32 v28, v28, v29
	v_cvt_pk_bf16_f32 v29, v30, v31
	v_cvt_pk_bf16_f32 v30, v24, v25
	v_add_u32_e32 v24, 0xa0, v154
	global_store_dwordx4 v[92:93], v[88:91], off
	global_store_dwordx4 v[76:77], v[72:75], off
	global_store_dwordx4 v[76:77], v[68:71], off offset:256
	v_cvt_pk_bf16_f32 v60, v60, v61
	v_cvt_pk_bf16_f32 v61, v62, v63
	v_cvt_pk_bf16_f32 v62, v56, v57
	v_cvt_pk_bf16_f32 v63, v58, v59
	global_store_dwordx4 v[64:65], v[44:47], off offset:256
	v_cvt_pk_bf16_f32 v31, v26, v27
	v_mad_i64_i32 v[24:25], s[18:19], s20, v24, 0
	v_lshl_add_u64 v[44:45], v[40:41], 1, v[150:151]
	v_cvt_pk_bf16_f32 v12, v12, v13
	v_cvt_pk_bf16_f32 v13, v14, v15
	v_cvt_pk_bf16_f32 v14, v8, v9
	v_add_u32_e32 v8, 0xb0, v154
	global_store_dwordx4 v[64:65], v[60:63], off
	v_cvt_pk_bf16_f32 v40, v52, v53
	v_cvt_pk_bf16_f32 v41, v54, v55
	v_cvt_pk_bf16_f32 v42, v48, v49
	v_cvt_pk_bf16_f32 v43, v50, v51
	global_store_dwordx4 v[44:45], v[28:31], off offset:256
	v_cvt_pk_bf16_f32 v15, v10, v11
	v_mad_i64_i32 v[8:9], s[18:19], s20, v8, 0
	v_lshl_add_u64 v[28:29], v[24:25], 1, v[150:151]
	global_store_dwordx4 v[44:45], v[40:43], off
	v_cvt_pk_bf16_f32 v24, v36, v37
	v_cvt_pk_bf16_f32 v25, v38, v39
	v_cvt_pk_bf16_f32 v26, v32, v33
	v_cvt_pk_bf16_f32 v27, v34, v35
	global_store_dwordx4 v[28:29], v[12:15], off offset:256
	v_cvt_pk_bf16_f32 v10, v16, v17
	v_cvt_pk_bf16_f32 v11, v18, v19
	v_lshl_add_u64 v[12:13], v[8:9], 1, v[150:151]
	v_cvt_pk_bf16_f32 v8, v20, v21
	v_cvt_pk_bf16_f32 v9, v22, v23
	v_cvt_pk_bf16_f32 v4, v4, v5
	v_cvt_pk_bf16_f32 v5, v6, v7
	v_cvt_pk_bf16_f32 v6, v0, v1
	v_cvt_pk_bf16_f32 v7, v2, v3
	s_and_b64 vcc, exec, s[40:41]
	s_mov_b32 s45, s49
	s_mov_b32 s10, s12
	s_mov_b64 s[18:19], s[16:17]
	s_mov_b64 s[20:21], s[14:15]
	global_store_dwordx4 v[28:29], v[24:27], off
	global_store_dwordx4 v[12:13], v[8:11], off
	global_store_dwordx4 v[12:13], v[4:7], off offset:256
	s_cbranch_vccz .LBB1_1526
	s_waitcnt vmcnt(0)
	s_cmpk_gt_u32 s4, 0xff
	s_cbranch_scc1 .LBB1_1533
	s_barrier

; #define PG8_STAGE(bufoff, gbase, voff) do { _Pragma("unroll") for (int _i = 0; _i < 2; ++_i) \
;         __builtin_amdgcn_global_load_lds((const unsigned*)((const char*)(gbase) + (voff)[_i]), (LAS unsigned*)(lds + (bufoff) + ldsw + _i * 8192), 16, 0, 0); } while (0)
; #define PG8_LDA(dst, b, h) do { _Pragma("unroll") for (int m = 0; m < 4; ++m) _Pragma("unroll") for (int k = 0; k < 2; ++k) dst[m][k] = *(const LAS bf16x8*)(lds + PG8_SA(b, h) + aoff + m * 2048 + k * 1024); } while (0)
; #define PG8_LDB(dst, b, h) do { _Pragma("unroll") for (int n = 0; n < 2; ++n) _Pragma("unroll") for (int k = 0; k < 2; ++k) dst[n][k] = *(const LAS bf16x8*)(lds + PG8_SB(b, h) + boff + n * 2048 + k * 1024); } while (0)
; #define PG8_MMA(ai, bj, At, Bt) do { __builtin_amdgcn_s_setprio(1); _Pragma("unroll") for (int m = 0; m < 4; ++m) _Pragma("unroll") for (int n = 0; n < 2; ++n) _Pragma("unroll") for (int k = 0; k < 2; ++k) \
;         acc[ai][bj][m][n] = __builtin_amdgcn_mfma_f32_16x16x32_bf16(Bt[n][k], At[m][k], acc[ai][bj][m][n], 0, 0, 0); __builtin_amdgcn_s_setprio(0); } while (0)
; #define PG8_WAIT_L(n) asm volatile("s_waitcnt lgkmcnt(" #n ")" ::: "memory")
; #define PG8_BAR __builtin_amdgcn_s_barrier()
; #define PG8_SCHED __builtin_amdgcn_sched_barrier(0)
; template <class Map, class Epi>
; DI void gemm_phase(LAS unsigned char* lds, const Map& MP, const Epi& E, const int nM, const int nN, const int K, const int lda, const int ldb) {
;     ...
;             const bool last = (t == nt - 2);
;             const char* a1 = cA + (size_t)(t + 1) * kstep;
;             const char* a2 = last ? nA : cA + (size_t)(t + 2) * kstep; const char* b2 = last ? nB : cB + (size_t)(t + 2) * kstep;
;             const char* a3 = a2 + kstep; const char* b3 = b2 + kstep;
;             PG8_LDB(B0, 0, 0); PG8_SCHED; PG8_LDA(At, 0, 0); PG8_STAGE(PG8_SA(1, 1), a1 + hstepA, voffA);
;             PG8_WAIT_L(8); PG8_BAR; PG8_WAIT_L(0); PG8_MMA(0, 0, At, B0); PG8_BAR; PG8_SCHED;
;             PG8_LDB(B1, 0, 1); PG8_STAGE(PG8_SB(0, 0), b2, voffB);
;             PG8_BAR; PG8_WAIT_L(0); PG8_MMA(0, 1, At, B1); PG8_BAR;
;             PG8_LDA(At, 0, 1); PG8_STAGE(PG8_SA(0, 0), a2, voffA);
;             PG8_BAR; PG8_WAIT_L(0); PG8_MMA(1, 0, At, B0); PG8_BAR; PG8_SCHED;
.LBB1_1764:
	ds_read_b128 v[152:155], v149
	ds_read_b128 v[156:159], v149 offset:1024
	ds_read_b128 v[160:163], v149 offset:2048
	ds_read_b128 v[164:167], v149 offset:3072
	s_add_u32 s12, s10, 0xfff80080
	s_addc_u32 s13, s11, -1
	s_cmp_eq_u32 s3, 28
	s_cselect_b32 s15, s37, s13
	s_cselect_b32 s14, s38, s12
	s_cselect_b32 s13, s39, s48
	s_cselect_b32 s12, s45, s47
	s_add_i32 m0, s24, 0xc000
	ds_read_b128 v[168:171], v150
	ds_read_b128 v[172:175], v150 offset:1024
	ds_read_b128 v[176:179], v150 offset:2048
	ds_read_b128 v[180:183], v150 offset:3072
	ds_read_b128 v[184:187], v150 offset:4096
	ds_read_b128 v[188:191], v150 offset:5120
	ds_read_b128 v[192:195], v150 offset:6144
	ds_read_b128 v[198:201], v150 offset:7168
	global_load_lds_dwordx4 v138, s[10:11]
	s_add_i32 m0, s24, 0xe000
	s_nop 0
	global_load_lds_dwordx4 v136, s[10:11]
	s_waitcnt lgkmcnt(8)
	s_barrier
	s_setprio 1
	s_waitcnt lgkmcnt(7)
	v_mfma_f32_16x16x32_bf16 v[124:127], v[152:155], v[168:171], v[124:127]
	v_mfma_f32_16x16x32_bf16 v[120:123], v[160:163], v[168:171], v[120:123]
	s_waitcnt lgkmcnt(5)
	v_mfma_f32_16x16x32_bf16 v[108:111], v[152:155], v[176:179], v[108:111]
	v_mfma_f32_16x16x32_bf16 v[104:107], v[160:163], v[176:179], v[104:107]
	s_waitcnt lgkmcnt(3)
	v_mfma_f32_16x16x32_bf16 v[92:95], v[152:155], v[184:187], v[92:95]
	v_mfma_f32_16x16x32_bf16 v[88:91], v[160:163], v[184:187], v[88:91]
	s_waitcnt lgkmcnt(1)
	v_mfma_f32_16x16x32_bf16 v[76:79], v[152:155], v[192:195], v[76:79]
	v_mfma_f32_16x16x32_bf16 v[72:75], v[160:163], v[192:195], v[72:75]
	v_mfma_f32_16x16x32_bf16 v[124:127], v[156:159], v[172:175], v[124:127]
	v_mfma_f32_16x16x32_bf16 v[120:123], v[164:167], v[172:175], v[120:123]
	v_mfma_f32_16x16x32_bf16 v[108:111], v[156:159], v[180:183], v[108:111]
	v_mfma_f32_16x16x32_bf16 v[104:107], v[164:167], v[180:183], v[104:107]
	v_mfma_f32_16x16x32_bf16 v[92:95], v[156:159], v[188:191], v[92:95]
	v_mfma_f32_16x16x32_bf16 v[88:91], v[164:167], v[188:191], v[88:91]
	s_waitcnt lgkmcnt(0)
	v_mfma_f32_16x16x32_bf16 v[76:79], v[156:159], v[198:201], v[76:79]
	v_mfma_f32_16x16x32_bf16 v[72:75], v[164:167], v[198:201], v[72:75]
	s_setprio 0
	s_barrier
	s_add_i32 s49, s35, s22
	v_lshl_add_u64 v[144:145], s[12:13], 0, v[132:133]
	s_mov_b32 m0, s49
	ds_read_b128 v[202:205], v151
	ds_read_b128 v[206:209], v151 offset:1024
	ds_read_b128 v[210:213], v151 offset:2048
	ds_read_b128 v[214:217], v151 offset:3072
	global_load_lds_dwordx4 v[144:145], off
	v_lshl_add_u64 v[218:219], s[12:13], 0, v[128:129]
	s_add_i32 m0, s49, 0x2000
	s_nop 0
	global_load_lds_dwordx4 v[218:219], off
	s_barrier
	s_setprio 1
	s_waitcnt lgkmcnt(3)
	v_mfma_f32_16x16x32_bf16 v[116:119], v[202:205], v[168:171], v[116:119]
	s_waitcnt lgkmcnt(1)
	v_mfma_f32_16x16x32_bf16 v[112:115], v[210:213], v[168:171], v[112:115]
	v_mfma_f32_16x16x32_bf16 v[100:103], v[202:205], v[176:179], v[100:103]
	v_mfma_f32_16x16x32_bf16 v[96:99], v[210:213], v[176:179], v[96:99]
	v_mfma_f32_16x16x32_bf16 v[84:87], v[202:205], v[184:187], v[84:87]
	v_mfma_f32_16x16x32_bf16 v[80:83], v[210:213], v[184:187], v[80:83]
	v_mfma_f32_16x16x32_bf16 v[68:71], v[202:205], v[192:195], v[68:71]
	v_mfma_f32_16x16x32_bf16 v[64:67], v[210:213], v[192:195], v[64:67]
	v_mfma_f32_16x16x32_bf16 v[116:119], v[206:209], v[172:175], v[116:119]
	s_waitcnt lgkmcnt(0)
	v_mfma_f32_16x16x32_bf16 v[112:115], v[214:217], v[172:175], v[112:115]
	v_mfma_f32_16x16x32_bf16 v[100:103], v[206:209], v[180:183], v[100:103]
	v_mfma_f32_16x16x32_bf16 v[96:99], v[214:217], v[180:183], v[96:99]
	v_mfma_f32_16x16x32_bf16 v[84:87], v[206:209], v[188:191], v[84:87]
	v_mfma_f32_16x16x32_bf16 v[80:83], v[214:217], v[188:191], v[80:83]
	v_mfma_f32_16x16x32_bf16 v[68:71], v[206:209], v[198:201], v[68:71]
	v_mfma_f32_16x16x32_bf16 v[64:67], v[214:217], v[198:201], v[64:67]
	s_setprio 0
	s_mov_b32 m0, s24
	v_lshl_add_u64 v[220:221], s[14:15], 0, v[134:135]
	s_barrier
	ds_read_b128 v[168:171], v150 offset:16384
	ds_read_b128 v[172:175], v150 offset:17408
	ds_read_b128 v[176:179], v150 offset:18432
	ds_read_b128 v[180:183], v150 offset:19456
	ds_read_b128 v[184:187], v150 offset:20480
	ds_read_b128 v[188:191], v150 offset:21504
	ds_read_b128 v[192:195], v150 offset:22528
	ds_read_b128 v[198:201], v150 offset:23552
	global_load_lds_dwordx4 v[220:221], off
	v_lshl_add_u64 v[222:223], s[14:15], 0, v[130:131]
	s_mov_b32 m0, s9
	s_nop 0
	global_load_lds_dwordx4 v[222:223], off
	s_barrier
	s_setprio 1
	s_waitcnt lgkmcnt(7)
	v_mfma_f32_16x16x32_bf16 v[60:63], v[152:155], v[168:171], v[60:63]
	v_mfma_f32_16x16x32_bf16 v[56:59], v[160:163], v[168:171], v[56:59]
	s_waitcnt lgkmcnt(5)
	v_mfma_f32_16x16x32_bf16 v[44:47], v[152:155], v[176:179], v[44:47]
	v_mfma_f32_16x16x32_bf16 v[40:43], v[160:163], v[176:179], v[40:43]
	s_waitcnt lgkmcnt(3)
	v_mfma_f32_16x16x32_bf16 v[28:31], v[152:155], v[184:187], v[28:31]
	v_mfma_f32_16x16x32_bf16 v[24:27], v[160:163], v[184:187], v[24:27]
	s_waitcnt lgkmcnt(1)
	v_mfma_f32_16x16x32_bf16 v[12:15], v[152:155], v[192:195], v[12:15]
	v_mfma_f32_16x16x32_bf16 v[8:11], v[160:163], v[192:195], v[8:11]
	v_mfma_f32_16x16x32_bf16 v[60:63], v[156:159], v[172:175], v[60:63]
	v_mfma_f32_16x16x32_bf16 v[56:59], v[164:167], v[172:175], v[56:59]
	v_mfma_f32_16x16x32_bf16 v[44:47], v[156:159], v[180:183], v[44:47]
	v_mfma_f32_16x16x32_bf16 v[40:43], v[164:167], v[180:183], v[40:43]
	v_mfma_f32_16x16x32_bf16 v[28:31], v[156:159], v[188:191], v[28:31]
	v_mfma_f32_16x16x32_bf16 v[24:27], v[164:167], v[188:191], v[24:27]
	s_waitcnt lgkmcnt(0)
	v_mfma_f32_16x16x32_bf16 v[12:15], v[156:159], v[198:201], v[12:15]
	v_mfma_f32_16x16x32_bf16 v[8:11], v[164:167], v[198:201], v[8:11]
	s_setprio 0
	s_barrier
; #define PG8_STAGE(bufoff, gbase, voff) do { _Pragma("unroll") for (int _i = 0; _i < 2; ++_i) \
;         __builtin_amdgcn_global_load_lds((const unsigned*)((const char*)(gbase) + (voff)[_i]), (LAS unsigned*)(lds + (bufoff) + ldsw + _i * 8192), 16, 0, 0); } while (0)
; #define PG8_LDA(dst, b, h) do { _Pragma("unroll") for (int m = 0; m < 4; ++m) _Pragma("unroll") for (int k = 0; k < 2; ++k) dst[m][k] = *(const LAS bf16x8*)(lds + PG8_SA(b, h) + aoff + m * 2048 + k * 1024); } while (0)
; #define PG8_LDB(dst, b, h) do { _Pragma("unroll") for (int n = 0; n < 2; ++n) _Pragma("unroll") for (int k = 0; k < 2; ++k) dst[n][k] = *(const LAS bf16x8*)(lds + PG8_SB(b, h) + boff + n * 2048 + k * 1024); } while (0)
; #define PG8_MMA(ai, bj, At, Bt) do { __builtin_amdgcn_s_setprio(1); _Pragma("unroll") for (int m = 0; m < 4; ++m) _Pragma("unroll") for (int n = 0; n < 2; ++n) _Pragma("unroll") for (int k = 0; k < 2; ++k) \
;         acc[ai][bj][m][n] = __builtin_amdgcn_mfma_f32_16x16x32_bf16(Bt[n][k], At[m][k], acc[ai][bj][m][n], 0, 0, 0); __builtin_amdgcn_s_setprio(0); } while (0)
; #define PG8_WAIT_V(n) asm volatile("s_waitcnt vmcnt(" #n ")" ::: "memory")
; #define PG8_WAIT_L(n) asm volatile("s_waitcnt lgkmcnt(" #n ")" ::: "memory")
; #define PG8_BAR __builtin_amdgcn_s_barrier()
; #define PG8_SCHED __builtin_amdgcn_sched_barrier(0)
; template <class Map, class Epi>
; DI void gemm_phase(LAS unsigned char* lds, const Map& MP, const Epi& E, const int nM, const int nN, const int K, const int lda, const int ldb) {
;     ...
;             PG8_STAGE(PG8_SB(0, 1), b2 + hstepB, voffB);
;             PG8_WAIT_V(6); PG8_BAR; PG8_MMA(1, 1, At, B1); PG8_BAR;
;             PG8_LDB(B0, 1, 0); PG8_SCHED; PG8_LDA(At, 1, 0); PG8_STAGE(PG8_SA(0, 1), a2 + hstepA, voffA);
;             PG8_WAIT_L(8); PG8_BAR; PG8_WAIT_L(0); PG8_MMA(0, 0, At, B0); PG8_BAR; PG8_SCHED;
;             PG8_LDB(B1, 1, 1); PG8_STAGE(PG8_SB(1, 0), b3, voffB);
;             PG8_BAR; PG8_WAIT_L(0); PG8_MMA(0, 1, At, B1); PG8_BAR;
;             PG8_LDA(At, 1, 1); PG8_STAGE(PG8_SA(1, 0), a3, voffA);
;             PG8_BAR; PG8_WAIT_L(0); PG8_MMA(1, 0, At, B0); PG8_BAR; PG8_SCHED;
	s_add_u32 s54, s12, 0x80000
	s_addc_u32 s55, s13, 0
	s_add_i32 s49, s36, s22
	s_mov_b32 m0, s49
	s_nop 0
	global_load_lds_dwordx4 v132, s[54:55]
	s_add_i32 m0, s49, 0x2000
	s_nop 0
	global_load_lds_dwordx4 v128, s[54:55]
	s_waitcnt vmcnt(6)
	s_barrier
	s_setprio 1
	v_mfma_f32_16x16x32_bf16 v[52:55], v[202:205], v[168:171], v[52:55]
	v_mfma_f32_16x16x32_bf16 v[48:51], v[210:213], v[168:171], v[48:51]
	v_mfma_f32_16x16x32_bf16 v[36:39], v[202:205], v[176:179], v[36:39]
	v_mfma_f32_16x16x32_bf16 v[32:35], v[210:213], v[176:179], v[32:35]
	v_mfma_f32_16x16x32_bf16 v[20:23], v[202:205], v[184:187], v[20:23]
	v_mfma_f32_16x16x32_bf16 v[16:19], v[210:213], v[184:187], v[16:19]
	v_mfma_f32_16x16x32_bf16 v[4:7], v[202:205], v[192:195], v[4:7]
	v_mfma_f32_16x16x32_bf16 v[0:3], v[210:213], v[192:195], v[0:3]
	v_mfma_f32_16x16x32_bf16 v[52:55], v[206:209], v[172:175], v[52:55]
	v_mfma_f32_16x16x32_bf16 v[48:51], v[214:217], v[172:175], v[48:51]
	v_mfma_f32_16x16x32_bf16 v[36:39], v[206:209], v[180:183], v[36:39]
	v_mfma_f32_16x16x32_bf16 v[32:35], v[214:217], v[180:183], v[32:35]
	v_mfma_f32_16x16x32_bf16 v[20:23], v[206:209], v[188:191], v[20:23]
	v_mfma_f32_16x16x32_bf16 v[16:19], v[214:217], v[188:191], v[16:19]
	v_mfma_f32_16x16x32_bf16 v[4:7], v[206:209], v[198:201], v[4:7]
	v_mfma_f32_16x16x32_bf16 v[0:3], v[214:217], v[198:201], v[0:3]
	s_setprio 0
	s_add_i32 s49, 0, 0x18000
	v_add_u32_e32 v164, s49, v148
	s_barrier
	ds_read_b128 v[152:155], v164
	ds_read_b128 v[156:159], v164 offset:1024
	ds_read_b128 v[160:163], v164 offset:2048
	ds_read_b128 v[164:167], v164 offset:3072
	s_add_u32 s14, s14, 0x80000
	s_addc_u32 s15, s15, 0
	s_mov_b32 m0, s25
	ds_read_b128 v[168:171], v150 offset:32768
	ds_read_b128 v[172:175], v150 offset:33792
	ds_read_b128 v[176:179], v150 offset:34816
	ds_read_b128 v[180:183], v150 offset:35840
	ds_read_b128 v[184:187], v150 offset:36864
	ds_read_b128 v[188:191], v150 offset:37888
	ds_read_b128 v[192:195], v150 offset:38912
	ds_read_b128 v[198:201], v150 offset:39936
	global_load_lds_dwordx4 v134, s[14:15]
	s_mov_b32 m0, s26
	s_nop 0
	global_load_lds_dwordx4 v130, s[14:15]
	s_waitcnt lgkmcnt(8)
	s_barrier
	s_setprio 1
	s_waitcnt lgkmcnt(7)
	v_mfma_f32_16x16x32_bf16 v[124:127], v[152:155], v[168:171], v[124:127]
	v_mfma_f32_16x16x32_bf16 v[120:123], v[160:163], v[168:171], v[120:123]
	s_waitcnt lgkmcnt(5)
	v_mfma_f32_16x16x32_bf16 v[108:111], v[152:155], v[176:179], v[108:111]
	v_mfma_f32_16x16x32_bf16 v[104:107], v[160:163], v[176:179], v[104:107]
	s_waitcnt lgkmcnt(3)
	v_mfma_f32_16x16x32_bf16 v[92:95], v[152:155], v[184:187], v[92:95]
	v_mfma_f32_16x16x32_bf16 v[88:91], v[160:163], v[184:187], v[88:91]
	s_waitcnt lgkmcnt(1)
	v_mfma_f32_16x16x32_bf16 v[76:79], v[152:155], v[192:195], v[76:79]
	v_mfma_f32_16x16x32_bf16 v[72:75], v[160:163], v[192:195], v[72:75]
	v_mfma_f32_16x16x32_bf16 v[124:127], v[156:159], v[172:175], v[124:127]
	v_mfma_f32_16x16x32_bf16 v[120:123], v[164:167], v[172:175], v[120:123]
	v_mfma_f32_16x16x32_bf16 v[108:111], v[156:159], v[180:183], v[108:111]
	v_mfma_f32_16x16x32_bf16 v[104:107], v[164:167], v[180:183], v[104:107]
	v_mfma_f32_16x16x32_bf16 v[92:95], v[156:159], v[188:191], v[92:95]
	v_mfma_f32_16x16x32_bf16 v[88:91], v[164:167], v[188:191], v[88:91]
	s_waitcnt lgkmcnt(0)
	v_mfma_f32_16x16x32_bf16 v[76:79], v[156:159], v[198:201], v[76:79]
	v_mfma_f32_16x16x32_bf16 v[72:75], v[164:167], v[198:201], v[72:75]
	s_setprio 0
	s_barrier
	s_add_i32 s14, 0, 0x1c000
	s_add_i32 s15, s49, s22
	v_add_u32_e32 v196, s14, v148
	v_lshl_add_u64 v[144:145], v[144:145], 0, s[42:43]
	s_mov_b32 m0, s15
	ds_read_b128 v[202:205], v196
	ds_read_b128 v[206:209], v196 offset:1024
	ds_read_b128 v[210:213], v196 offset:2048
	ds_read_b128 v[214:217], v196 offset:3072
	global_load_lds_dwordx4 v[144:145], off
	v_lshl_add_u64 v[144:145], v[218:219], 0, s[42:43]
	s_add_i32 m0, s15, 0x2000
	s_nop 0
	global_load_lds_dwordx4 v[144:145], off
	s_barrier
	s_setprio 1
	s_waitcnt lgkmcnt(3)
	v_mfma_f32_16x16x32_bf16 v[116:119], v[202:205], v[168:171], v[116:119]
	s_waitcnt lgkmcnt(1)
	v_mfma_f32_16x16x32_bf16 v[112:115], v[210:213], v[168:171], v[112:115]
	v_mfma_f32_16x16x32_bf16 v[100:103], v[202:205], v[176:179], v[100:103]
	v_mfma_f32_16x16x32_bf16 v[96:99], v[210:213], v[176:179], v[96:99]
	v_mfma_f32_16x16x32_bf16 v[84:87], v[202:205], v[184:187], v[84:87]
	v_mfma_f32_16x16x32_bf16 v[80:83], v[210:213], v[184:187], v[80:83]
	v_mfma_f32_16x16x32_bf16 v[68:71], v[202:205], v[192:195], v[68:71]
	v_mfma_f32_16x16x32_bf16 v[64:67], v[210:213], v[192:195], v[64:67]
	v_mfma_f32_16x16x32_bf16 v[116:119], v[206:209], v[172:175], v[116:119]
	s_waitcnt lgkmcnt(0)
	v_mfma_f32_16x16x32_bf16 v[112:115], v[214:217], v[172:175], v[112:115]
	v_mfma_f32_16x16x32_bf16 v[100:103], v[206:209], v[180:183], v[100:103]
	v_mfma_f32_16x16x32_bf16 v[96:99], v[214:217], v[180:183], v[96:99]
	v_mfma_f32_16x16x32_bf16 v[84:87], v[206:209], v[188:191], v[84:87]
	v_mfma_f32_16x16x32_bf16 v[80:83], v[214:217], v[188:191], v[80:83]
	v_mfma_f32_16x16x32_bf16 v[68:71], v[206:209], v[198:201], v[68:71]
	v_mfma_f32_16x16x32_bf16 v[64:67], v[214:217], v[198:201], v[64:67]
	s_setprio 0
	s_mov_b32 m0, s30
	v_lshl_add_u64 v[144:145], v[220:221], 0, s[42:43]
	s_barrier
	ds_read_b128 v[168:171], v150 offset:49152
	ds_read_b128 v[172:175], v150 offset:50176
	ds_read_b128 v[176:179], v150 offset:51200
	ds_read_b128 v[180:183], v150 offset:52224
	ds_read_b128 v[184:187], v150 offset:53248
	ds_read_b128 v[188:191], v150 offset:54272
	ds_read_b128 v[192:195], v150 offset:55296
	ds_read_b128 v[198:201], v150 offset:56320
	global_load_lds_dwordx4 v[144:145], off
	v_lshl_add_u64 v[144:145], v[222:223], 0, s[42:43]
	s_mov_b32 m0, s31
	s_nop 0
	global_load_lds_dwordx4 v[144:145], off
	s_barrier
; DI unsigned pack2(float a, float b) { f32x2 v = {a, b}; hwbf16x2 r = __builtin_convertvector(v, hwbf16x2); return __builtin_bit_cast(unsigned, r); }
; DI float bflo(unsigned w) { return __uint_as_float(w << 16); }
; DI float bfhi(unsigned w) { return __uint_as_float(w & 0xffff0000u); }
; #define PG8_STAGE(bufoff, gbase, voff) do { _Pragma("unroll") for (int _i = 0; _i < 2; ++_i) \
;         __builtin_amdgcn_global_load_lds((const unsigned*)((const char*)(gbase) + (voff)[_i]), (LAS unsigned*)(lds + (bufoff) + ldsw + _i * 8192), 16, 0, 0); } while (0)
;     DI void operator()(const f32x4 (&acc)[2][2][4][2], const Unit& u, int wr, int wc, int fr, int fq) const {
;     ...
;         for (int ai = 0; ai < 2; ++ai)
; #pragma unroll
;             for (int m = 0; m < 4; ++m) { const size_t ro = (size_t)(row0 + ai * HALF + m * 16) * D + col0;
; #pragma unroll
;                 for (int bj = 0; bj < 2; ++bj) {
;                     f32x4 x0, x1;
;                     if constexpr (IB) { const u32x4 w = *(const u32x4*)((const bf16_t*)Xin + ro + bj * HALF);
;                         x0 = (f32x4){bflo(w[0]), bfhi(w[0]), bflo(w[1]), bfhi(w[1])}; x1 = (f32x4){bflo(w[2]), bfhi(w[2]), bflo(w[3]), bfhi(w[3])}; }
;                     else { x0 = *(const f32x4*)((const float*)Xin + ro + bj * HALF); x1 = *(const f32x4*)((const float*)Xin + ro + bj * HALF + 4); }
;                     x0 += acc[ai][bj][m][0] * sc[bj][0]; x1 += acc[ai][bj][m][1] * sc[bj][1];
;                     if constexpr (OB) { u32x4 o; o[0] = pack2(x0[0], x0[1]); o[1] = pack2(x0[2], x0[3]); o[2] = pack2(x1[0], x1[1]); o[3] = pack2(x1[2], x1[3]);
;                         *(u32x4*)((bf16_t*)Xout + ro + bj * HALF) = o; }
;                     else { *(f32x4*)((float*)Xout + ro + bj * HALF) = x0; *(f32x4*)((float*)Xout + ro + bj * HALF + 4) = x1; } } }
; template <class Map, class Epi>
; DI void gemm_phase(LAS unsigned char* lds, const Map& MP, const Epi& E, const int nM, const int nN, const int K, const int lda, const int ldb) {
;     ...
;             PG8_BAR; PG8_WAIT_L(0); PG8_MMA(0, 1, At, B1); PG8_BAR;
;             PG8_LDA(At, 1, 1); PG8_STAGE(PG8_SA(1, 0), a3, voffA);
;             PG8_BAR; PG8_WAIT_L(0); PG8_MMA(1, 0, At, B0); PG8_BAR; PG8_SCHED;
;             PG8_STAGE(PG8_SB(1, 1), b3 + hstepB, voffB);
;             PG8_WAIT_V(6); PG8_BAR; PG8_MMA(1, 1, At, B1); PG8_BAR;
	s_setprio 1
	s_waitcnt lgkmcnt(7)
	v_mfma_f32_16x16x32_bf16 v[60:63], v[152:155], v[168:171], v[60:63]
	v_mfma_f32_16x16x32_bf16 v[56:59], v[160:163], v[168:171], v[56:59]
	s_waitcnt lgkmcnt(5)
	v_mfma_f32_16x16x32_bf16 v[44:47], v[152:155], v[176:179], v[44:47]
	v_mfma_f32_16x16x32_bf16 v[40:43], v[160:163], v[176:179], v[40:43]
	s_waitcnt lgkmcnt(3)
	v_mfma_f32_16x16x32_bf16 v[28:31], v[152:155], v[184:187], v[28:31]
	v_mfma_f32_16x16x32_bf16 v[24:27], v[160:163], v[184:187], v[24:27]
	s_waitcnt lgkmcnt(1)
	v_mfma_f32_16x16x32_bf16 v[12:15], v[152:155], v[192:195], v[12:15]
	v_mfma_f32_16x16x32_bf16 v[8:11], v[160:163], v[192:195], v[8:11]
	v_mfma_f32_16x16x32_bf16 v[60:63], v[156:159], v[172:175], v[60:63]
	v_mfma_f32_16x16x32_bf16 v[56:59], v[164:167], v[172:175], v[56:59]
	v_mfma_f32_16x16x32_bf16 v[44:47], v[156:159], v[180:183], v[44:47]
	v_mfma_f32_16x16x32_bf16 v[40:43], v[164:167], v[180:183], v[40:43]
	v_mfma_f32_16x16x32_bf16 v[28:31], v[156:159], v[188:191], v[28:31]
	v_mfma_f32_16x16x32_bf16 v[24:27], v[164:167], v[188:191], v[24:27]
	s_waitcnt lgkmcnt(0)
	v_mfma_f32_16x16x32_bf16 v[12:15], v[156:159], v[198:201], v[12:15]
	v_mfma_f32_16x16x32_bf16 v[8:11], v[164:167], v[198:201], v[8:11]
	s_setprio 0
	s_barrier
	s_add_u32 s12, s12, 0x80080
	s_addc_u32 s13, s13, 0
	s_add_i32 s14, s14, s22
	s_mov_b32 m0, s14
	s_nop 0
	global_load_lds_dwordx4 v132, s[12:13]
	s_add_i32 m0, s14, 0x2000
	s_nop 0
	global_load_lds_dwordx4 v128, s[12:13]
	s_waitcnt vmcnt(6)
	s_barrier
	s_setprio 1
	v_mfma_f32_16x16x32_bf16 v[52:55], v[202:205], v[168:171], v[52:55]
	v_mfma_f32_16x16x32_bf16 v[48:51], v[210:213], v[168:171], v[48:51]
	v_mfma_f32_16x16x32_bf16 v[36:39], v[202:205], v[176:179], v[36:39]
	v_mfma_f32_16x16x32_bf16 v[32:35], v[210:213], v[176:179], v[32:35]
	v_mfma_f32_16x16x32_bf16 v[20:23], v[202:205], v[184:187], v[20:23]
	v_mfma_f32_16x16x32_bf16 v[16:19], v[210:213], v[184:187], v[16:19]
	v_mfma_f32_16x16x32_bf16 v[4:7], v[202:205], v[192:195], v[4:7]
	v_mfma_f32_16x16x32_bf16 v[0:3], v[210:213], v[192:195], v[0:3]
	v_mfma_f32_16x16x32_bf16 v[52:55], v[206:209], v[172:175], v[52:55]
	v_mfma_f32_16x16x32_bf16 v[48:51], v[214:217], v[172:175], v[48:51]
	v_mfma_f32_16x16x32_bf16 v[36:39], v[206:209], v[180:183], v[36:39]
	v_mfma_f32_16x16x32_bf16 v[32:35], v[214:217], v[180:183], v[32:35]
	v_mfma_f32_16x16x32_bf16 v[20:23], v[206:209], v[188:191], v[20:23]
	v_mfma_f32_16x16x32_bf16 v[16:19], v[214:217], v[188:191], v[16:19]
	v_mfma_f32_16x16x32_bf16 v[4:7], v[206:209], v[198:201], v[4:7]
	v_mfma_f32_16x16x32_bf16 v[0:3], v[214:217], v[198:201], v[0:3]
	s_setprio 0
	s_add_i32 s3, s3, 2
	s_add_u32 s47, s47, 0x100
	s_addc_u32 s48, s48, 0
	s_add_u32 s10, s10, 0x100
	s_addc_u32 s11, s11, 0
	s_cmp_gt_u32 s3, 29
	s_barrier
	s_cbranch_scc0 .LBB1_1764
	v_mov_b32_e32 v152, v147
	v_mov_b32_e32 v144, v146
	s_lshl_b32 s2, s2, 8
	s_or_b32 s2, s2, s29
	v_lshl_add_u32 v144, v144, 3, s2
	s_lshl_b32 s2, s8, 8
	s_add_i32 s2, s2, s28
	v_add_u32_e32 v152, s2, v152
	v_ashrrev_i32_e32 v153, 31, v152
	v_lshlrev_b64 v[152:153], 12, v[152:153]
	v_ashrrev_i32_e32 v145, 31, v144
	v_lshl_add_u64 v[152:153], s[4:5], 0, v[152:153]
	v_lshl_add_u64 v[144:145], v[144:145], 1, v[152:153]
	global_load_dwordx4 v[160:163], v[144:145], off
	global_load_dwordx4 v[164:167], v[144:145], off offset:256
	s_mov_b64 s[98:99], 0x10000
	v_lshl_add_u64 v[154:155], v[144:145], 0, s[98:99]
	global_load_dwordx4 v[168:171], v[154:155], off
	global_load_dwordx4 v[172:175], v[154:155], off offset:256
	s_mov_b64 s[98:99], 0x20000
	v_lshl_add_u64 v[154:155], v[144:145], 0, s[98:99]
	global_load_dwordx4 v[176:179], v[154:155], off
	global_load_dwordx4 v[180:183], v[154:155], off offset:256
	s_mov_b64 s[98:99], 0x30000
	v_lshl_add_u64 v[154:155], v[144:145], 0, s[98:99]
	global_load_dwordx4 v[184:187], v[154:155], off
	global_load_dwordx4 v[188:191], v[154:155], off offset:256
	s_mov_b64 s[98:99], 0x80000
	v_lshl_add_u64 v[154:155], v[144:145], 0, s[98:99]
	global_load_dwordx4 v[192:195], v[154:155], off
	global_load_dwordx4 v[198:201], v[154:155], off offset:256
	s_mov_b64 s[98:99], 0x90000
	v_lshl_add_u64 v[154:155], v[144:145], 0, s[98:99]
	global_load_dwordx4 v[202:205], v[154:155], off
	global_load_dwordx4 v[206:209], v[154:155], off offset:256
	s_mov_b64 s[98:99], 0xa0000
	v_lshl_add_u64 v[154:155], v[144:145], 0, s[98:99]
	global_load_dwordx4 v[210:213], v[154:155], off
	global_load_dwordx4 v[214:217], v[154:155], off offset:256
	s_mov_b64 s[98:99], 0xb0000
	v_lshl_add_u64 v[154:155], v[144:145], 0, s[98:99]
	global_load_dwordx4 v[248:251], v[154:155], off
	global_load_dwordx4 v[252:255], v[154:155], off offset:256
	s_waitcnt vmcnt(15)
	s_nop 1
	v_mov_b32_e32 v152, v160
	v_mov_b32_e32 v153, v161
	v_mov_b32_e32 v154, v162
	v_mov_b32_e32 v155, v163
	s_mov_b64 s[2:3], 0x10000
	s_mov_b32 s8, s46
	s_mov_b64 s[10:11], s[6:7]
	s_mov_b64 s[12:13], s[52:53]
	s_waitcnt lgkmcnt(0)
	v_lshlrev_b32_e32 v156, 16, v152
	v_and_b32_e32 v157, 0xffff0000, v152
	v_lshlrev_b32_e32 v152, 16, v153
	v_and_b32_e32 v153, 0xffff0000, v153
	v_lshlrev_b32_e32 v158, 16, v154
	v_and_b32_e32 v159, 0xffff0000, v154
	v_lshlrev_b32_e32 v154, 16, v155
	v_and_b32_e32 v155, 0xffff0000, v155
	v_pk_add_f32 v[126:127], v[126:127], v[152:153]
	v_pk_add_f32 v[124:125], v[124:125], v[156:157]
	v_pk_add_f32 v[152:153], v[122:123], v[154:155]
	v_pk_add_f32 v[122:123], v[120:121], v[158:159]
	v_cvt_pk_bf16_f32 v120, v124, v125
	v_cvt_pk_bf16_f32 v121, v126, v127
	v_cvt_pk_bf16_f32 v122, v122, v123
	v_cvt_pk_bf16_f32 v123, v152, v153
	global_store_dwordx4 v[144:145], v[120:123], off
	s_waitcnt vmcnt(15)
; DI unsigned pack2(float a, float b) { f32x2 v = {a, b}; hwbf16x2 r = __builtin_convertvector(v, hwbf16x2); return __builtin_bit_cast(unsigned, r); }
; DI float bflo(unsigned w) { return __uint_as_float(w << 16); }
; DI float bfhi(unsigned w) { return __uint_as_float(w & 0xffff0000u); }
;     DI void operator()(const f32x4 (&acc)[2][2][4][2], const Unit& u, int wr, int wc, int fr, int fq) const {
;     ...
;         for (int ai = 0; ai < 2; ++ai)
; #pragma unroll
;             for (int m = 0; m < 4; ++m) { const size_t ro = (size_t)(row0 + ai * HALF + m * 16) * D + col0;
; #pragma unroll
;                 for (int bj = 0; bj < 2; ++bj) {
;                     f32x4 x0, x1;
;                     if constexpr (IB) { const u32x4 w = *(const u32x4*)((const bf16_t*)Xin + ro + bj * HALF);
;                         x0 = (f32x4){bflo(w[0]), bfhi(w[0]), bflo(w[1]), bfhi(w[1])}; x1 = (f32x4){bflo(w[2]), bfhi(w[2]), bflo(w[3]), bfhi(w[3])}; }
;                     else { x0 = *(const f32x4*)((const float*)Xin + ro + bj * HALF); x1 = *(const f32x4*)((const float*)Xin + ro + bj * HALF + 4); }
;                     x0 += acc[ai][bj][m][0] * sc[bj][0]; x1 += acc[ai][bj][m][1] * sc[bj][1];
;                     if constexpr (OB) { u32x4 o; o[0] = pack2(x0[0], x0[1]); o[1] = pack2(x0[2], x0[3]); o[2] = pack2(x1[0], x1[1]); o[3] = pack2(x1[2], x1[3]);
;                         *(u32x4*)((bf16_t*)Xout + ro + bj * HALF) = o; }
;                     else { *(f32x4*)((float*)Xout + ro + bj * HALF) = x0; *(f32x4*)((float*)Xout + ro + bj * HALF + 4) = x1; } } }
	s_nop 1
	v_mov_b32_e32 v120, v164
	v_mov_b32_e32 v121, v165
	v_mov_b32_e32 v122, v166
	v_mov_b32_e32 v123, v167
	s_waitcnt lgkmcnt(0)
	v_lshlrev_b32_e32 v124, 16, v120
	v_and_b32_e32 v125, 0xffff0000, v120
	v_lshlrev_b32_e32 v120, 16, v121
	v_and_b32_e32 v121, 0xffff0000, v121
	v_lshlrev_b32_e32 v126, 16, v122
	v_and_b32_e32 v127, 0xffff0000, v122
	v_lshlrev_b32_e32 v122, 16, v123
	v_and_b32_e32 v123, 0xffff0000, v123
	v_pk_add_f32 v[116:117], v[116:117], v[124:125]
	v_pk_add_f32 v[118:119], v[118:119], v[120:121]
	v_pk_add_f32 v[120:121], v[114:115], v[122:123]
	v_pk_add_f32 v[114:115], v[112:113], v[126:127]
	v_cvt_pk_bf16_f32 v112, v116, v117
	v_lshl_add_u64 v[116:117], v[144:145], 0, s[2:3]
	s_mov_b32 s2, 0x10000
	v_cvt_pk_bf16_f32 v113, v118, v119
	v_add_co_u32_e32 v118, vcc, s2, v144
	v_cvt_pk_bf16_f32 v114, v114, v115
	v_cvt_pk_bf16_f32 v115, v120, v121
	v_addc_co_u32_e32 v119, vcc, 0, v145, vcc
	global_store_dwordx4 v[144:145], v[112:115], off offset:256
	s_waitcnt vmcnt(15)
	s_nop 1
	v_mov_b32_e32 v112, v168
	v_mov_b32_e32 v113, v169
	v_mov_b32_e32 v114, v170
	v_mov_b32_e32 v115, v171
	s_mov_b64 s[2:3], 0x20000
	s_waitcnt lgkmcnt(0)
	v_lshlrev_b32_e32 v120, 16, v112
	v_and_b32_e32 v121, 0xffff0000, v112
	v_lshlrev_b32_e32 v112, 16, v113
	v_and_b32_e32 v113, 0xffff0000, v113
	v_lshlrev_b32_e32 v122, 16, v114
	v_and_b32_e32 v123, 0xffff0000, v114
	v_lshlrev_b32_e32 v114, 16, v115
	v_and_b32_e32 v115, 0xffff0000, v115
	v_pk_add_f32 v[110:111], v[110:111], v[112:113]
	v_pk_add_f32 v[108:109], v[108:109], v[120:121]
	v_pk_add_f32 v[112:113], v[106:107], v[114:115]
	v_pk_add_f32 v[106:107], v[104:105], v[122:123]
	v_cvt_pk_bf16_f32 v104, v108, v109
	v_cvt_pk_bf16_f32 v105, v110, v111
	v_cvt_pk_bf16_f32 v106, v106, v107
	v_cvt_pk_bf16_f32 v107, v112, v113
	global_store_dwordx4 v[118:119], v[104:107], off
	s_waitcnt vmcnt(15)
	s_nop 1
	v_mov_b32_e32 v104, v172
	v_mov_b32_e32 v105, v173
	v_mov_b32_e32 v106, v174
	v_mov_b32_e32 v107, v175
	s_waitcnt lgkmcnt(0)
	v_lshlrev_b32_e32 v108, 16, v104
	v_and_b32_e32 v109, 0xffff0000, v104
	v_lshlrev_b32_e32 v104, 16, v105
	v_and_b32_e32 v105, 0xffff0000, v105
	v_lshlrev_b32_e32 v110, 16, v106
	v_and_b32_e32 v111, 0xffff0000, v106
	v_lshlrev_b32_e32 v106, 16, v107
	v_and_b32_e32 v107, 0xffff0000, v107
	v_pk_add_f32 v[100:101], v[100:101], v[108:109]
	v_pk_add_f32 v[102:103], v[102:103], v[104:105]
	v_pk_add_f32 v[104:105], v[98:99], v[106:107]
	v_pk_add_f32 v[98:99], v[96:97], v[110:111]
	v_cvt_pk_bf16_f32 v96, v100, v101
	v_lshl_add_u64 v[100:101], v[144:145], 0, s[2:3]
	s_mov_b32 s2, 0x20000
	v_cvt_pk_bf16_f32 v97, v102, v103
	v_add_co_u32_e32 v102, vcc, s2, v144
	v_cvt_pk_bf16_f32 v98, v98, v99
	v_cvt_pk_bf16_f32 v99, v104, v105
	v_addc_co_u32_e32 v103, vcc, 0, v145, vcc
	global_store_dwordx4 v[116:117], v[96:99], off offset:256
	s_waitcnt vmcnt(15)
	s_nop 1
	v_mov_b32_e32 v96, v176
	v_mov_b32_e32 v97, v177
	v_mov_b32_e32 v98, v178
	v_mov_b32_e32 v99, v179
	s_mov_b64 s[2:3], 0x30000
	s_waitcnt lgkmcnt(0)
	v_lshlrev_b32_e32 v104, 16, v96
	v_and_b32_e32 v105, 0xffff0000, v96
	v_lshlrev_b32_e32 v96, 16, v97
	v_and_b32_e32 v97, 0xffff0000, v97
	v_lshlrev_b32_e32 v106, 16, v98
	v_and_b32_e32 v107, 0xffff0000, v98
	v_lshlrev_b32_e32 v98, 16, v99
	v_and_b32_e32 v99, 0xffff0000, v99
	v_pk_add_f32 v[94:95], v[94:95], v[96:97]
	v_pk_add_f32 v[92:93], v[92:93], v[104:105]
	v_pk_add_f32 v[96:97], v[90:91], v[98:99]
	v_pk_add_f32 v[90:91], v[88:89], v[106:107]
	v_cvt_pk_bf16_f32 v88, v92, v93
	v_cvt_pk_bf16_f32 v89, v94, v95
	v_cvt_pk_bf16_f32 v90, v90, v91
	v_cvt_pk_bf16_f32 v91, v96, v97
	global_store_dwordx4 v[102:103], v[88:91], off
	s_waitcnt vmcnt(15)
	s_nop 1
	v_mov_b32_e32 v88, v180
	v_mov_b32_e32 v89, v181
	v_mov_b32_e32 v90, v182
	v_mov_b32_e32 v91, v183
	s_waitcnt lgkmcnt(0)
	v_lshlrev_b32_e32 v92, 16, v88
	v_and_b32_e32 v93, 0xffff0000, v88
	v_lshlrev_b32_e32 v88, 16, v89
	v_and_b32_e32 v89, 0xffff0000, v89
	v_lshlrev_b32_e32 v94, 16, v90
	v_and_b32_e32 v95, 0xffff0000, v90
	v_lshlrev_b32_e32 v90, 16, v91
	v_and_b32_e32 v91, 0xffff0000, v91
	v_pk_add_f32 v[86:87], v[86:87], v[88:89]
	v_pk_add_f32 v[84:85], v[84:85], v[92:93]
	v_pk_add_f32 v[88:89], v[82:83], v[90:91]
	v_pk_add_f32 v[82:83], v[80:81], v[94:95]
	v_cvt_pk_bf16_f32 v80, v84, v85
	v_cvt_pk_bf16_f32 v81, v86, v87
	v_cvt_pk_bf16_f32 v82, v82, v83
	v_cvt_pk_bf16_f32 v83, v88, v89
	global_store_dwordx4 v[100:101], v[80:83], off offset:256
	s_nop 1
	v_lshl_add_u64 v[80:81], v[144:145], 0, s[2:3]
	s_mov_b32 s2, 0x30000
	v_add_co_u32_e32 v86, vcc, s2, v144
	s_mov_b64 s[2:3], 0x80000
	s_nop 0
	v_addc_co_u32_e32 v87, vcc, 0, v145, vcc
	s_waitcnt vmcnt(15)
	s_nop 1
	v_mov_b32_e32 v82, v184
	v_mov_b32_e32 v83, v185
	v_mov_b32_e32 v84, v186
	v_mov_b32_e32 v85, v187
	s_waitcnt lgkmcnt(0)
	v_lshlrev_b32_e32 v88, 16, v82
	v_and_b32_e32 v89, 0xffff0000, v82
	v_lshlrev_b32_e32 v82, 16, v83
	v_and_b32_e32 v83, 0xffff0000, v83
	v_lshlrev_b32_e32 v90, 16, v84
	v_and_b32_e32 v91, 0xffff0000, v84
	v_lshlrev_b32_e32 v84, 16, v85
	v_and_b32_e32 v85, 0xffff0000, v85
	v_pk_add_f32 v[78:79], v[78:79], v[82:83]
	v_pk_add_f32 v[76:77], v[76:77], v[88:89]
	v_pk_add_f32 v[82:83], v[74:75], v[84:85]
	v_pk_add_f32 v[74:75], v[72:73], v[90:91]
	v_cvt_pk_bf16_f32 v72, v76, v77
	v_cvt_pk_bf16_f32 v73, v78, v79
	v_cvt_pk_bf16_f32 v74, v74, v75
	v_cvt_pk_bf16_f32 v75, v82, v83
	global_store_dwordx4 v[86:87], v[72:75], off
	s_waitcnt vmcnt(15)
	s_nop 1
	v_mov_b32_e32 v72, v188
	v_mov_b32_e32 v73, v189
	v_mov_b32_e32 v74, v190
	v_mov_b32_e32 v75, v191
	s_waitcnt lgkmcnt(0)
; DI unsigned pack2(float a, float b) { f32x2 v = {a, b}; hwbf16x2 r = __builtin_convertvector(v, hwbf16x2); return __builtin_bit_cast(unsigned, r); }
; DI float bflo(unsigned w) { return __uint_as_float(w << 16); }
; DI float bfhi(unsigned w) { return __uint_as_float(w & 0xffff0000u); }
;     DI void operator()(const f32x4 (&acc)[2][2][4][2], const Unit& u, int wr, int wc, int fr, int fq) const {
;     ...
;         for (int ai = 0; ai < 2; ++ai)
; #pragma unroll
;             for (int m = 0; m < 4; ++m) { const size_t ro = (size_t)(row0 + ai * HALF + m * 16) * D + col0;
; #pragma unroll
;                 for (int bj = 0; bj < 2; ++bj) {
;                     f32x4 x0, x1;
;                     if constexpr (IB) { const u32x4 w = *(const u32x4*)((const bf16_t*)Xin + ro + bj * HALF);
;                         x0 = (f32x4){bflo(w[0]), bfhi(w[0]), bflo(w[1]), bfhi(w[1])}; x1 = (f32x4){bflo(w[2]), bfhi(w[2]), bflo(w[3]), bfhi(w[3])}; }
;                     else { x0 = *(const f32x4*)((const float*)Xin + ro + bj * HALF); x1 = *(const f32x4*)((const float*)Xin + ro + bj * HALF + 4); }
;                     x0 += acc[ai][bj][m][0] * sc[bj][0]; x1 += acc[ai][bj][m][1] * sc[bj][1];
;                     if constexpr (OB) { u32x4 o; o[0] = pack2(x0[0], x0[1]); o[1] = pack2(x0[2], x0[3]); o[2] = pack2(x1[0], x1[1]); o[3] = pack2(x1[2], x1[3]);
;                         *(u32x4*)((bf16_t*)Xout + ro + bj * HALF) = o; }
;                     else { *(f32x4*)((float*)Xout + ro + bj * HALF) = x0; *(f32x4*)((float*)Xout + ro + bj * HALF + 4) = x1; } } }
	v_lshlrev_b32_e32 v76, 16, v72
	v_and_b32_e32 v77, 0xffff0000, v72
	v_lshlrev_b32_e32 v72, 16, v73
	v_and_b32_e32 v73, 0xffff0000, v73
	v_lshlrev_b32_e32 v78, 16, v74
	v_and_b32_e32 v79, 0xffff0000, v74
	v_lshlrev_b32_e32 v74, 16, v75
	v_and_b32_e32 v75, 0xffff0000, v75
	v_pk_add_f32 v[70:71], v[70:71], v[72:73]
	v_pk_add_f32 v[68:69], v[68:69], v[76:77]
	v_pk_add_f32 v[72:73], v[66:67], v[74:75]
	v_pk_add_f32 v[66:67], v[64:65], v[78:79]
	v_cvt_pk_bf16_f32 v64, v68, v69
	v_cvt_pk_bf16_f32 v65, v70, v71
	v_cvt_pk_bf16_f32 v66, v66, v67
	v_cvt_pk_bf16_f32 v67, v72, v73
	global_store_dwordx4 v[80:81], v[64:67], off offset:256
	s_nop 1
	v_lshl_add_u64 v[64:65], v[144:145], 0, s[2:3]
	s_mov_b32 s2, 0x80000
	v_add_co_u32_e32 v70, vcc, s2, v144
	s_mov_b64 s[2:3], 0x90000
	s_nop 0
	v_addc_co_u32_e32 v71, vcc, 0, v145, vcc
	s_waitcnt vmcnt(15)
	s_nop 1
	v_mov_b32_e32 v66, v192
	v_mov_b32_e32 v67, v193
	v_mov_b32_e32 v68, v194
	v_mov_b32_e32 v69, v195
	s_waitcnt lgkmcnt(0)
	v_lshlrev_b32_e32 v72, 16, v66
	v_and_b32_e32 v73, 0xffff0000, v66
	v_lshlrev_b32_e32 v66, 16, v67
	v_and_b32_e32 v67, 0xffff0000, v67
	v_lshlrev_b32_e32 v74, 16, v68
	v_and_b32_e32 v75, 0xffff0000, v68
	v_lshlrev_b32_e32 v68, 16, v69
	v_and_b32_e32 v69, 0xffff0000, v69
	v_pk_add_f32 v[62:63], v[62:63], v[66:67]
	v_pk_add_f32 v[60:61], v[60:61], v[72:73]
	v_pk_add_f32 v[66:67], v[58:59], v[68:69]
	v_pk_add_f32 v[58:59], v[56:57], v[74:75]
	v_cvt_pk_bf16_f32 v56, v60, v61
	v_cvt_pk_bf16_f32 v57, v62, v63
	v_cvt_pk_bf16_f32 v58, v58, v59
	v_cvt_pk_bf16_f32 v59, v66, v67
	global_store_dwordx4 v[70:71], v[56:59], off
	s_waitcnt vmcnt(15)
	s_nop 1
	v_mov_b32_e32 v56, v198
	v_mov_b32_e32 v57, v199
	v_mov_b32_e32 v58, v200
	v_mov_b32_e32 v59, v201
	s_waitcnt lgkmcnt(0)
	v_lshlrev_b32_e32 v60, 16, v56
	v_and_b32_e32 v61, 0xffff0000, v56
	v_lshlrev_b32_e32 v56, 16, v57
	v_and_b32_e32 v57, 0xffff0000, v57
	v_lshlrev_b32_e32 v62, 16, v58
	v_and_b32_e32 v63, 0xffff0000, v58
	v_lshlrev_b32_e32 v58, 16, v59
	v_and_b32_e32 v59, 0xffff0000, v59
	v_pk_add_f32 v[54:55], v[54:55], v[56:57]
	v_pk_add_f32 v[52:53], v[52:53], v[60:61]
	v_pk_add_f32 v[56:57], v[50:51], v[58:59]
	v_pk_add_f32 v[50:51], v[48:49], v[62:63]
	v_cvt_pk_bf16_f32 v48, v52, v53
	v_cvt_pk_bf16_f32 v49, v54, v55
	v_cvt_pk_bf16_f32 v50, v50, v51
	v_cvt_pk_bf16_f32 v51, v56, v57
	global_store_dwordx4 v[64:65], v[48:51], off offset:256
	s_nop 1
	v_lshl_add_u64 v[48:49], v[144:145], 0, s[2:3]
	s_mov_b32 s2, 0x90000
	v_add_co_u32_e32 v54, vcc, s2, v144
	s_mov_b64 s[2:3], 0xa0000
	s_nop 0
	v_addc_co_u32_e32 v55, vcc, 0, v145, vcc
	s_waitcnt vmcnt(15)
	s_nop 1
	v_mov_b32_e32 v50, v202
	v_mov_b32_e32 v51, v203
	v_mov_b32_e32 v52, v204
	v_mov_b32_e32 v53, v205
	s_waitcnt lgkmcnt(0)
	v_lshlrev_b32_e32 v56, 16, v50
	v_and_b32_e32 v57, 0xffff0000, v50
	v_lshlrev_b32_e32 v50, 16, v51
	v_and_b32_e32 v51, 0xffff0000, v51
	v_lshlrev_b32_e32 v58, 16, v52
	v_and_b32_e32 v59, 0xffff0000, v52
	v_lshlrev_b32_e32 v52, 16, v53
	v_and_b32_e32 v53, 0xffff0000, v53
	v_pk_add_f32 v[46:47], v[46:47], v[50:51]
	v_pk_add_f32 v[44:45], v[44:45], v[56:57]
	v_pk_add_f32 v[50:51], v[42:43], v[52:53]
	v_pk_add_f32 v[42:43], v[40:41], v[58:59]
	v_cvt_pk_bf16_f32 v40, v44, v45
	v_cvt_pk_bf16_f32 v41, v46, v47
	v_cvt_pk_bf16_f32 v42, v42, v43
	v_cvt_pk_bf16_f32 v43, v50, v51
	global_store_dwordx4 v[54:55], v[40:43], off
	s_waitcnt vmcnt(15)
	s_nop 1
	v_mov_b32_e32 v40, v206
	v_mov_b32_e32 v41, v207
	v_mov_b32_e32 v42, v208
	v_mov_b32_e32 v43, v209
	s_waitcnt lgkmcnt(0)
; DI unsigned pack2(float a, float b) { f32x2 v = {a, b}; hwbf16x2 r = __builtin_convertvector(v, hwbf16x2); return __builtin_bit_cast(unsigned, r); }
; DI float bflo(unsigned w) { return __uint_as_float(w << 16); }
; DI float bfhi(unsigned w) { return __uint_as_float(w & 0xffff0000u); }
;     DI const char* a(const Unit& u) const { return (const char*)(A + (size_t)u.pm * BM * lda); }
;     DI const char* a(const Unit& u) const { return (const char*)(A + (size_t)u.pm * BM * 2048 + (u.pn >> 1) * 512); }
;     DI void operator()(const f32x4 (&acc)[2][2][4][2], const Unit& u, int wr, int wc, int fr, int fq) const {
;     ...
;         for (int ai = 0; ai < 2; ++ai)
; #pragma unroll
;             for (int m = 0; m < 4; ++m) { const size_t ro = (size_t)(row0 + ai * HALF + m * 16) * D + col0;
; #pragma unroll
;                 for (int bj = 0; bj < 2; ++bj) {
;                     f32x4 x0, x1;
;                     if constexpr (IB) { const u32x4 w = *(const u32x4*)((const bf16_t*)Xin + ro + bj * HALF);
;                         x0 = (f32x4){bflo(w[0]), bfhi(w[0]), bflo(w[1]), bfhi(w[1])}; x1 = (f32x4){bflo(w[2]), bfhi(w[2]), bflo(w[3]), bfhi(w[3])}; }
;                     else { x0 = *(const f32x4*)((const float*)Xin + ro + bj * HALF); x1 = *(const f32x4*)((const float*)Xin + ro + bj * HALF + 4); }
;                     x0 += acc[ai][bj][m][0] * sc[bj][0]; x1 += acc[ai][bj][m][1] * sc[bj][1];
;                     if constexpr (OB) { u32x4 o; o[0] = pack2(x0[0], x0[1]); o[1] = pack2(x0[2], x0[3]); o[2] = pack2(x1[0], x1[1]); o[3] = pack2(x1[2], x1[3]);
;                         *(u32x4*)((bf16_t*)Xout + ro + bj * HALF) = o; }
;                     else { *(f32x4*)((float*)Xout + ro + bj * HALF) = x0; *(f32x4*)((float*)Xout + ro + bj * HALF + 4) = x1; } } }
; template <class Map, class Epi>
; DI void gemm_phase(LAS unsigned char* lds, const Map& MP, const Epi& E, const int nM, const int nN, const int K, const int lda, const int ldb) {
;     ...
;         if (!has_next) break;
; #pragma unroll
;         for (int a = 0; a < 2; ++a)
; #pragma unroll
;             for (int b = 0; b < 2; ++b)
; #pragma unroll
;                 for (int m = 0; m < 4; ++m)
; #pragma unroll
;                     for (int n = 0; n < 2; ++n) acc[a][b][m][n] = (f32x4){0.f, 0.f, 0.f, 0.f};
;         cur = nxt; cA = nA; cB = nB; ++ui;
;     }
;     PG8_WAIT_V(0);
;     if (wr == 0) PG8_BAR;
;     PG8_BAR;
	v_lshlrev_b32_e32 v44, 16, v40
	v_and_b32_e32 v45, 0xffff0000, v40
	v_lshlrev_b32_e32 v40, 16, v41
	v_and_b32_e32 v41, 0xffff0000, v41
	v_lshlrev_b32_e32 v46, 16, v42
	v_and_b32_e32 v47, 0xffff0000, v42
	v_lshlrev_b32_e32 v42, 16, v43
	v_and_b32_e32 v43, 0xffff0000, v43
	v_pk_add_f32 v[38:39], v[38:39], v[40:41]
	v_pk_add_f32 v[36:37], v[36:37], v[44:45]
	v_pk_add_f32 v[40:41], v[34:35], v[42:43]
	v_pk_add_f32 v[34:35], v[32:33], v[46:47]
	v_cvt_pk_bf16_f32 v32, v36, v37
	v_cvt_pk_bf16_f32 v33, v38, v39
	v_cvt_pk_bf16_f32 v34, v34, v35
	v_cvt_pk_bf16_f32 v35, v40, v41
	global_store_dwordx4 v[48:49], v[32:35], off offset:256
	s_nop 1
	v_lshl_add_u64 v[32:33], v[144:145], 0, s[2:3]
	s_mov_b32 s2, 0xa0000
	v_add_co_u32_e32 v38, vcc, s2, v144
	s_mov_b64 s[2:3], 0xb0000
	s_nop 0
	v_addc_co_u32_e32 v39, vcc, 0, v145, vcc
	s_waitcnt vmcnt(15)
	s_nop 1
	v_mov_b32_e32 v34, v210
	v_mov_b32_e32 v35, v211
	v_mov_b32_e32 v36, v212
	v_mov_b32_e32 v37, v213
	s_waitcnt lgkmcnt(0)
	v_lshlrev_b32_e32 v40, 16, v34
	v_and_b32_e32 v41, 0xffff0000, v34
	v_lshlrev_b32_e32 v34, 16, v35
	v_and_b32_e32 v35, 0xffff0000, v35
	v_lshlrev_b32_e32 v42, 16, v36
	v_and_b32_e32 v43, 0xffff0000, v36
	v_lshlrev_b32_e32 v36, 16, v37
	v_and_b32_e32 v37, 0xffff0000, v37
	v_pk_add_f32 v[30:31], v[30:31], v[34:35]
	v_pk_add_f32 v[28:29], v[28:29], v[40:41]
	v_pk_add_f32 v[34:35], v[26:27], v[36:37]
	v_pk_add_f32 v[26:27], v[24:25], v[42:43]
	v_cvt_pk_bf16_f32 v24, v28, v29
	v_cvt_pk_bf16_f32 v25, v30, v31
	v_cvt_pk_bf16_f32 v26, v26, v27
	v_cvt_pk_bf16_f32 v27, v34, v35
	global_store_dwordx4 v[38:39], v[24:27], off
	s_waitcnt vmcnt(15)
	s_nop 1
	v_mov_b32_e32 v24, v214
	v_mov_b32_e32 v25, v215
	v_mov_b32_e32 v26, v216
	v_mov_b32_e32 v27, v217
	s_waitcnt lgkmcnt(0)
	v_lshlrev_b32_e32 v28, 16, v24
	v_and_b32_e32 v29, 0xffff0000, v24
	v_lshlrev_b32_e32 v24, 16, v25
	v_and_b32_e32 v25, 0xffff0000, v25
	v_lshlrev_b32_e32 v30, 16, v26
	v_and_b32_e32 v31, 0xffff0000, v26
	v_lshlrev_b32_e32 v26, 16, v27
	v_and_b32_e32 v27, 0xffff0000, v27
	v_pk_add_f32 v[22:23], v[22:23], v[24:25]
	v_pk_add_f32 v[20:21], v[20:21], v[28:29]
	v_pk_add_f32 v[24:25], v[18:19], v[26:27]
	v_pk_add_f32 v[18:19], v[16:17], v[30:31]
	v_cvt_pk_bf16_f32 v16, v20, v21
	v_cvt_pk_bf16_f32 v17, v22, v23
	v_cvt_pk_bf16_f32 v18, v18, v19
	v_cvt_pk_bf16_f32 v19, v24, v25
	global_store_dwordx4 v[32:33], v[16:19], off offset:256
	s_nop 1
	v_lshl_add_u64 v[16:17], v[144:145], 0, s[2:3]
	s_mov_b32 s2, 0xb0000
	v_add_co_u32_e32 v22, vcc, s2, v144
	s_mov_b32 s2, s44
	s_nop 0
	v_addc_co_u32_e32 v23, vcc, 0, v145, vcc
	s_waitcnt vmcnt(15)
	s_nop 1
	v_mov_b32_e32 v18, v248
	v_mov_b32_e32 v19, v249
	v_mov_b32_e32 v20, v250
	v_mov_b32_e32 v21, v251
	s_and_b64 vcc, exec, s[40:41]
	s_waitcnt lgkmcnt(0)
	v_lshlrev_b32_e32 v24, 16, v18
	v_and_b32_e32 v25, 0xffff0000, v18
	v_lshlrev_b32_e32 v18, 16, v19
	v_and_b32_e32 v19, 0xffff0000, v19
	v_lshlrev_b32_e32 v26, 16, v20
	v_and_b32_e32 v27, 0xffff0000, v20
	v_lshlrev_b32_e32 v20, 16, v21
	v_and_b32_e32 v21, 0xffff0000, v21
	v_pk_add_f32 v[14:15], v[14:15], v[18:19]
	v_pk_add_f32 v[12:13], v[12:13], v[24:25]
	v_pk_add_f32 v[18:19], v[10:11], v[20:21]
	v_pk_add_f32 v[10:11], v[8:9], v[26:27]
	v_cvt_pk_bf16_f32 v8, v12, v13
	v_cvt_pk_bf16_f32 v9, v14, v15
	v_cvt_pk_bf16_f32 v10, v10, v11
	v_cvt_pk_bf16_f32 v11, v18, v19
	global_store_dwordx4 v[22:23], v[8:11], off
	s_waitcnt vmcnt(15)
	s_nop 1
	v_mov_b32_e32 v8, v252
	v_mov_b32_e32 v9, v253
	v_mov_b32_e32 v10, v254
	v_mov_b32_e32 v11, v255
	s_waitcnt lgkmcnt(0)
	v_lshlrev_b32_e32 v12, 16, v8
	v_and_b32_e32 v13, 0xffff0000, v8
	v_lshlrev_b32_e32 v8, 16, v9
	v_and_b32_e32 v9, 0xffff0000, v9
	v_lshlrev_b32_e32 v14, 16, v10
	v_and_b32_e32 v15, 0xffff0000, v10
	v_lshlrev_b32_e32 v10, 16, v11
	v_and_b32_e32 v11, 0xffff0000, v11
	v_pk_add_f32 v[6:7], v[6:7], v[8:9]
	v_pk_add_f32 v[4:5], v[4:5], v[12:13]
	v_pk_add_f32 v[8:9], v[2:3], v[10:11]
	v_pk_add_f32 v[2:3], v[0:1], v[14:15]
	v_cvt_pk_bf16_f32 v0, v4, v5
	v_cvt_pk_bf16_f32 v1, v6, v7
	v_cvt_pk_bf16_f32 v2, v2, v3
	v_cvt_pk_bf16_f32 v3, v8, v9
	global_store_dwordx4 v[16:17], v[0:3], off offset:256
	s_cbranch_vccz .LBB1_1761
	s_waitcnt vmcnt(0)
	s_cmpk_gt_u32 s17, 0xff
	s_cbranch_scc1 .LBB1_1768
	s_barrier

; #define PG8_STAGE(bufoff, gbase, voff) do { _Pragma("unroll") for (int _i = 0; _i < 2; ++_i) \
;         __builtin_amdgcn_global_load_lds((const unsigned*)((const char*)(gbase) + (voff)[_i]), (LAS unsigned*)(lds + (bufoff) + ldsw + _i * 8192), 16, 0, 0); } while (0)
; #define PG8_LDA(dst, b, h) do { _Pragma("unroll") for (int m = 0; m < 4; ++m) _Pragma("unroll") for (int k = 0; k < 2; ++k) dst[m][k] = *(const LAS bf16x8*)(lds + PG8_SA(b, h) + aoff + m * 2048 + k * 1024); } while (0)
; #define PG8_LDB(dst, b, h) do { _Pragma("unroll") for (int n = 0; n < 2; ++n) _Pragma("unroll") for (int k = 0; k < 2; ++k) dst[n][k] = *(const LAS bf16x8*)(lds + PG8_SB(b, h) + boff + n * 2048 + k * 1024); } while (0)
; #define PG8_MMA(ai, bj, At, Bt) do { __builtin_amdgcn_s_setprio(1); _Pragma("unroll") for (int m = 0; m < 4; ++m) _Pragma("unroll") for (int n = 0; n < 2; ++n) _Pragma("unroll") for (int k = 0; k < 2; ++k) \
;         acc[ai][bj][m][n] = __builtin_amdgcn_mfma_f32_16x16x32_bf16(Bt[n][k], At[m][k], acc[ai][bj][m][n], 0, 0, 0); __builtin_amdgcn_s_setprio(0); } while (0)
; #define PG8_WAIT_L(n) asm volatile("s_waitcnt lgkmcnt(" #n ")" ::: "memory")
; #define PG8_BAR __builtin_amdgcn_s_barrier()
; #define PG8_SCHED __builtin_amdgcn_sched_barrier(0)
; template <class Map, class Epi>
; DI void gemm_phase(LAS unsigned char* lds, const Map& MP, const Epi& E, const int nM, const int nN, const int K, const int lda, const int ldb) {
;     ...
;             PG8_LDB(B0, 0, 0); PG8_SCHED; PG8_LDA(At, 0, 0); PG8_STAGE(PG8_SA(1, 1), a1 + hstepA, voffA);
;             PG8_WAIT_L(8); PG8_BAR; PG8_WAIT_L(0); PG8_MMA(0, 0, At, B0); PG8_BAR; PG8_SCHED;
;             PG8_LDB(B1, 0, 1); PG8_STAGE(PG8_SB(0, 0), b2, voffB);
;             PG8_BAR; PG8_WAIT_L(0); PG8_MMA(0, 1, At, B1); PG8_BAR;
;             PG8_LDA(At, 0, 1); PG8_STAGE(PG8_SA(0, 0), a2, voffA);
;             PG8_BAR; PG8_WAIT_L(0); PG8_MMA(1, 0, At, B0); PG8_BAR; PG8_SCHED;
.LBB1_1908:
	ds_read_b128 v[80:83], v189
	ds_read_b128 v[84:87], v189 offset:1024
	ds_read_b128 v[88:91], v189 offset:2048
	ds_read_b128 v[92:95], v189 offset:3072
	s_add_u32 s28, s42, 0xfff80080
	s_addc_u32 s29, s43, -1
	s_cmp_eq_u32 s3, 28
	s_cselect_b32 s47, s23, s29
	s_cselect_b32 s46, s58, s28
	s_cselect_b32 s29, s21, vcc_hi
	s_cselect_b32 s28, s59, vcc_lo
	s_add_i32 m0, s38, 0xc000
	ds_read_b128 v[96:99], v190
	ds_read_b128 v[100:103], v190 offset:1024
	ds_read_b128 v[108:111], v190 offset:2048
	ds_read_b128 v[112:115], v190 offset:3072
	ds_read_b128 v[160:163], v190 offset:4096
	ds_read_b128 v[164:167], v190 offset:5120
	ds_read_b128 v[198:201], v190 offset:6144
	ds_read_b128 v[202:205], v190 offset:7168
	global_load_lds_dwordx4 v178, s[42:43]
	s_add_i32 m0, s38, 0xe000
	s_nop 0
	global_load_lds_dwordx4 v176, s[42:43]
	s_waitcnt lgkmcnt(8)
	s_barrier
	s_setprio 1
	s_waitcnt lgkmcnt(7)
	v_mfma_f32_16x16x32_bf16 v[148:151], v[80:83], v[96:99], v[148:151]
	v_mfma_f32_16x16x32_bf16 v[144:147], v[88:91], v[96:99], v[144:147]
	s_waitcnt lgkmcnt(5)
	v_mfma_f32_16x16x32_bf16 v[136:139], v[80:83], v[108:111], v[136:139]
	v_mfma_f32_16x16x32_bf16 v[128:131], v[88:91], v[108:111], v[128:131]
	s_waitcnt lgkmcnt(3)
	v_mfma_f32_16x16x32_bf16 v[120:123], v[80:83], v[160:163], v[120:123]
	v_mfma_f32_16x16x32_bf16 v[104:107], v[88:91], v[160:163], v[104:107]
	s_waitcnt lgkmcnt(1)
	v_mfma_f32_16x16x32_bf16 v[76:79], v[80:83], v[198:201], v[76:79]
	v_mfma_f32_16x16x32_bf16 v[72:75], v[88:91], v[198:201], v[72:75]
	v_mfma_f32_16x16x32_bf16 v[148:151], v[84:87], v[100:103], v[148:151]
	v_mfma_f32_16x16x32_bf16 v[144:147], v[92:95], v[100:103], v[144:147]
	v_mfma_f32_16x16x32_bf16 v[136:139], v[84:87], v[112:115], v[136:139]
	v_mfma_f32_16x16x32_bf16 v[128:131], v[92:95], v[112:115], v[128:131]
	v_mfma_f32_16x16x32_bf16 v[120:123], v[84:87], v[164:167], v[120:123]
	v_mfma_f32_16x16x32_bf16 v[104:107], v[92:95], v[164:167], v[104:107]
	s_waitcnt lgkmcnt(0)
	v_mfma_f32_16x16x32_bf16 v[76:79], v[84:87], v[202:205], v[76:79]
	v_mfma_f32_16x16x32_bf16 v[72:75], v[92:95], v[202:205], v[72:75]
	s_setprio 0
	s_barrier
	s_add_i32 s68, s2, s54
	v_lshl_add_u64 v[184:185], s[28:29], 0, v[172:173]
	s_mov_b32 m0, s68
	ds_read_b128 v[206:209], v191
	ds_read_b128 v[210:213], v191 offset:1024
	ds_read_b128 v[214:217], v191 offset:2048
	ds_read_b128 v[218:221], v191 offset:3072
	global_load_lds_dwordx4 v[184:185], off
	v_lshl_add_u64 v[194:195], s[28:29], 0, v[168:169]
	s_add_i32 m0, s68, 0x2000
	s_nop 0
	global_load_lds_dwordx4 v[194:195], off
	s_barrier
	s_setprio 1
	s_waitcnt lgkmcnt(3)
	v_mfma_f32_16x16x32_bf16 v[156:159], v[206:209], v[96:99], v[156:159]
	s_waitcnt lgkmcnt(1)
	v_mfma_f32_16x16x32_bf16 v[96:99], v[214:217], v[96:99], v[152:155]
	v_mfma_f32_16x16x32_bf16 v[156:159], v[210:213], v[100:103], v[156:159]
	s_waitcnt lgkmcnt(0)
	v_mfma_f32_16x16x32_bf16 v[96:99], v[218:221], v[100:103], v[96:99]
	v_mfma_f32_16x16x32_bf16 v[100:103], v[206:209], v[108:111], v[140:143]
	v_mfma_f32_16x16x32_bf16 v[108:111], v[214:217], v[108:111], v[132:135]
	v_mfma_f32_16x16x32_bf16 v[116:119], v[214:217], v[160:163], v[116:119]
	v_mfma_f32_16x16x32_bf16 v[68:71], v[206:209], v[198:201], v[68:71]
	v_mfma_f32_16x16x32_bf16 v[64:67], v[214:217], v[198:201], v[64:67]
	v_mfma_f32_16x16x32_bf16 v[100:103], v[210:213], v[112:115], v[100:103]
	v_mfma_f32_16x16x32_bf16 v[108:111], v[218:221], v[112:115], v[108:111]
	v_mfma_f32_16x16x32_bf16 v[112:115], v[206:209], v[160:163], v[124:127]
	v_mfma_f32_16x16x32_bf16 v[116:119], v[218:221], v[164:167], v[116:119]
	v_mfma_f32_16x16x32_bf16 v[68:71], v[210:213], v[202:205], v[68:71]
	v_mfma_f32_16x16x32_bf16 v[64:67], v[218:221], v[202:205], v[64:67]
	v_mfma_f32_16x16x32_bf16 v[112:115], v[210:213], v[164:167], v[112:115]
	s_setprio 0
	s_mov_b32 m0, s38
	v_lshl_add_u64 v[226:227], s[46:47], 0, v[174:175]
	s_barrier
	ds_read_b128 v[124:127], v190 offset:16384
	ds_read_b128 v[132:135], v190 offset:17408
	ds_read_b128 v[140:143], v190 offset:18432
	ds_read_b128 v[152:155], v190 offset:19456
	ds_read_b128 v[160:163], v190 offset:20480
	ds_read_b128 v[164:167], v190 offset:21504
	ds_read_b128 v[198:201], v190 offset:22528
	ds_read_b128 v[202:205], v190 offset:23552
	global_load_lds_dwordx4 v[226:227], off
	v_lshl_add_u64 v[234:235], s[46:47], 0, v[170:171]
	s_mov_b32 m0, s39
	s_nop 0
	global_load_lds_dwordx4 v[234:235], off
	s_barrier
	s_setprio 1
	s_waitcnt lgkmcnt(7)
	v_mfma_f32_16x16x32_bf16 v[60:63], v[80:83], v[124:127], v[60:63]
	v_mfma_f32_16x16x32_bf16 v[48:51], v[88:91], v[124:127], v[48:51]
	s_waitcnt lgkmcnt(5)
	v_mfma_f32_16x16x32_bf16 v[40:43], v[80:83], v[140:143], v[40:43]
	v_mfma_f32_16x16x32_bf16 v[32:35], v[88:91], v[140:143], v[32:35]
	s_waitcnt lgkmcnt(3)
	v_mfma_f32_16x16x32_bf16 v[24:27], v[80:83], v[160:163], v[24:27]
	v_mfma_f32_16x16x32_bf16 v[16:19], v[88:91], v[160:163], v[16:19]
	s_waitcnt lgkmcnt(1)
	v_mfma_f32_16x16x32_bf16 v[12:15], v[80:83], v[198:201], v[12:15]
	v_mfma_f32_16x16x32_bf16 v[8:11], v[88:91], v[198:201], v[8:11]
	v_mfma_f32_16x16x32_bf16 v[60:63], v[84:87], v[132:135], v[60:63]
	v_mfma_f32_16x16x32_bf16 v[48:51], v[92:95], v[132:135], v[48:51]
	v_mfma_f32_16x16x32_bf16 v[40:43], v[84:87], v[152:155], v[40:43]
	v_mfma_f32_16x16x32_bf16 v[32:35], v[92:95], v[152:155], v[32:35]
	v_mfma_f32_16x16x32_bf16 v[24:27], v[84:87], v[164:167], v[24:27]
	v_mfma_f32_16x16x32_bf16 v[16:19], v[92:95], v[164:167], v[16:19]
	s_waitcnt lgkmcnt(0)
	v_mfma_f32_16x16x32_bf16 v[12:15], v[84:87], v[202:205], v[12:15]
	v_mfma_f32_16x16x32_bf16 v[8:11], v[92:95], v[202:205], v[8:11]
	s_setprio 0
	s_barrier
; #define PG8_STAGE(bufoff, gbase, voff) do { _Pragma("unroll") for (int _i = 0; _i < 2; ++_i) \
;         __builtin_amdgcn_global_load_lds((const unsigned*)((const char*)(gbase) + (voff)[_i]), (LAS unsigned*)(lds + (bufoff) + ldsw + _i * 8192), 16, 0, 0); } while (0)
; #define PG8_LDA(dst, b, h) do { _Pragma("unroll") for (int m = 0; m < 4; ++m) _Pragma("unroll") for (int k = 0; k < 2; ++k) dst[m][k] = *(const LAS bf16x8*)(lds + PG8_SA(b, h) + aoff + m * 2048 + k * 1024); } while (0)
; #define PG8_LDB(dst, b, h) do { _Pragma("unroll") for (int n = 0; n < 2; ++n) _Pragma("unroll") for (int k = 0; k < 2; ++k) dst[n][k] = *(const LAS bf16x8*)(lds + PG8_SB(b, h) + boff + n * 2048 + k * 1024); } while (0)
; #define PG8_MMA(ai, bj, At, Bt) do { __builtin_amdgcn_s_setprio(1); _Pragma("unroll") for (int m = 0; m < 4; ++m) _Pragma("unroll") for (int n = 0; n < 2; ++n) _Pragma("unroll") for (int k = 0; k < 2; ++k) \
;         acc[ai][bj][m][n] = __builtin_amdgcn_mfma_f32_16x16x32_bf16(Bt[n][k], At[m][k], acc[ai][bj][m][n], 0, 0, 0); __builtin_amdgcn_s_setprio(0); } while (0)
; #define PG8_WAIT_V(n) asm volatile("s_waitcnt vmcnt(" #n ")" ::: "memory")
; #define PG8_WAIT_L(n) asm volatile("s_waitcnt lgkmcnt(" #n ")" ::: "memory")
; #define PG8_BAR __builtin_amdgcn_s_barrier()
; #define PG8_SCHED __builtin_amdgcn_sched_barrier(0)
; template <class Map, class Epi>
; DI void gemm_phase(LAS unsigned char* lds, const Map& MP, const Epi& E, const int nM, const int nN, const int K, const int lda, const int ldb) {
;     ...
;             PG8_STAGE(PG8_SB(0, 1), b2 + hstepB, voffB);
;             PG8_WAIT_V(6); PG8_BAR; PG8_MMA(1, 1, At, B1); PG8_BAR;
;             PG8_LDB(B0, 1, 0); PG8_SCHED; PG8_LDA(At, 1, 0); PG8_STAGE(PG8_SA(0, 1), a2 + hstepA, voffA);
;             PG8_WAIT_L(8); PG8_BAR; PG8_WAIT_L(0); PG8_MMA(0, 0, At, B0); PG8_BAR; PG8_SCHED;
;             PG8_LDB(B1, 1, 1); PG8_STAGE(PG8_SB(1, 0), b3, voffB);
;             PG8_BAR; PG8_WAIT_L(0); PG8_MMA(0, 1, At, B1); PG8_BAR;
;             PG8_LDA(At, 1, 1); PG8_STAGE(PG8_SA(1, 0), a3, voffA);
;             PG8_BAR; PG8_WAIT_L(0); PG8_MMA(1, 0, At, B0); PG8_BAR; PG8_SCHED;
	s_add_u32 s68, s28, 0x80000
	s_addc_u32 s69, s29, 0
	s_add_i32 s70, s31, s54
	s_mov_b32 m0, s70
	s_nop 0
	global_load_lds_dwordx4 v172, s[68:69]
	s_add_i32 m0, s70, 0x2000
	s_nop 0
	global_load_lds_dwordx4 v168, s[68:69]
	s_waitcnt vmcnt(6)
	s_barrier
	s_setprio 1
	v_mfma_f32_16x16x32_bf16 v[56:59], v[206:209], v[124:127], v[56:59]
	v_mfma_f32_16x16x32_bf16 v[52:55], v[214:217], v[124:127], v[52:55]
	v_mfma_f32_16x16x32_bf16 v[44:47], v[206:209], v[140:143], v[44:47]
	v_mfma_f32_16x16x32_bf16 v[36:39], v[214:217], v[140:143], v[36:39]
	v_mfma_f32_16x16x32_bf16 v[28:31], v[206:209], v[160:163], v[28:31]
	v_mfma_f32_16x16x32_bf16 v[20:23], v[214:217], v[160:163], v[20:23]
	v_mfma_f32_16x16x32_bf16 v[4:7], v[206:209], v[198:201], v[4:7]
	v_mfma_f32_16x16x32_bf16 v[0:3], v[214:217], v[198:201], v[0:3]
	v_mfma_f32_16x16x32_bf16 v[56:59], v[210:213], v[132:135], v[56:59]
	v_mfma_f32_16x16x32_bf16 v[52:55], v[218:221], v[132:135], v[52:55]
	v_mfma_f32_16x16x32_bf16 v[44:47], v[210:213], v[152:155], v[44:47]
	v_mfma_f32_16x16x32_bf16 v[36:39], v[218:221], v[152:155], v[36:39]
	v_mfma_f32_16x16x32_bf16 v[28:31], v[210:213], v[164:167], v[28:31]
	v_mfma_f32_16x16x32_bf16 v[20:23], v[218:221], v[164:167], v[20:23]
	v_mfma_f32_16x16x32_bf16 v[4:7], v[210:213], v[202:205], v[4:7]
	v_mfma_f32_16x16x32_bf16 v[0:3], v[218:221], v[202:205], v[0:3]
	s_setprio 0
	s_add_i32 s68, 0, 0x18000
	v_add_u32_e32 v92, s68, v188
	s_barrier
	ds_read_b128 v[80:83], v92
	ds_read_b128 v[84:87], v92 offset:1024
	ds_read_b128 v[88:91], v92 offset:2048
	ds_read_b128 v[92:95], v92 offset:3072
	s_add_u32 s46, s46, 0x80000
	s_addc_u32 s47, s47, 0
	s_mov_b32 m0, s56
	ds_read_b128 v[124:127], v190 offset:32768
	ds_read_b128 v[132:135], v190 offset:33792
	ds_read_b128 v[160:163], v190 offset:34816
	ds_read_b128 v[164:167], v190 offset:35840
	ds_read_b128 v[198:201], v190 offset:36864
	ds_read_b128 v[202:205], v190 offset:37888
	ds_read_b128 v[206:209], v190 offset:38912
	ds_read_b128 v[210:213], v190 offset:39936
	global_load_lds_dwordx4 v174, s[46:47]
	s_mov_b32 m0, s57
	s_nop 0
	global_load_lds_dwordx4 v170, s[46:47]
	s_waitcnt lgkmcnt(8)
	s_barrier
	s_setprio 1
	s_waitcnt lgkmcnt(7)
	v_mfma_f32_16x16x32_bf16 v[140:143], v[80:83], v[124:127], v[148:151]
	s_waitcnt lgkmcnt(6)
	v_mfma_f32_16x16x32_bf16 v[148:151], v[84:87], v[132:135], v[140:143]
	v_mfma_f32_16x16x32_bf16 v[140:143], v[88:91], v[124:127], v[144:147]
	s_waitcnt lgkmcnt(5)
	v_mfma_f32_16x16x32_bf16 v[136:139], v[80:83], v[160:163], v[136:139]
	v_mfma_f32_16x16x32_bf16 v[128:131], v[88:91], v[160:163], v[128:131]
	s_waitcnt lgkmcnt(3)
	v_mfma_f32_16x16x32_bf16 v[120:123], v[80:83], v[198:201], v[120:123]
	v_mfma_f32_16x16x32_bf16 v[104:107], v[88:91], v[198:201], v[104:107]
	s_waitcnt lgkmcnt(1)
	v_mfma_f32_16x16x32_bf16 v[76:79], v[80:83], v[206:209], v[76:79]
	v_mfma_f32_16x16x32_bf16 v[72:75], v[88:91], v[206:209], v[72:75]
	v_mfma_f32_16x16x32_bf16 v[144:147], v[92:95], v[132:135], v[140:143]
	v_mfma_f32_16x16x32_bf16 v[136:139], v[84:87], v[164:167], v[136:139]
	v_mfma_f32_16x16x32_bf16 v[128:131], v[92:95], v[164:167], v[128:131]
	v_mfma_f32_16x16x32_bf16 v[120:123], v[84:87], v[202:205], v[120:123]
	v_mfma_f32_16x16x32_bf16 v[104:107], v[92:95], v[202:205], v[104:107]
	s_waitcnt lgkmcnt(0)
	v_mfma_f32_16x16x32_bf16 v[76:79], v[84:87], v[210:213], v[76:79]
	v_mfma_f32_16x16x32_bf16 v[72:75], v[92:95], v[210:213], v[72:75]
	s_setprio 0
	s_barrier
	s_add_i32 s46, 0, 0x1c000
	v_add_u32_e32 v140, s46, v188
	s_add_i32 s47, s68, s54
	ds_read_b128 v[214:217], v140
	ds_read_b128 v[218:221], v140 offset:1024
	ds_read_b128 v[222:225], v140 offset:2048
	ds_read_b128 v[230:233], v140 offset:3072
	v_lshl_add_u64 v[140:141], v[184:185], 0, s[14:15]
	s_mov_b32 m0, s47
	s_nop 0
	global_load_lds_dwordx4 v[140:141], off
	v_lshl_add_u64 v[140:141], v[194:195], 0, s[14:15]
	s_add_i32 m0, s47, 0x2000
	s_nop 0
	global_load_lds_dwordx4 v[140:141], off
	s_barrier
	s_setprio 1
	s_waitcnt lgkmcnt(1)
	v_mfma_f32_16x16x32_bf16 v[96:99], v[222:225], v[124:127], v[96:99]
	v_mfma_f32_16x16x32_bf16 v[140:143], v[214:217], v[124:127], v[156:159]
	s_waitcnt lgkmcnt(0)
	v_mfma_f32_16x16x32_bf16 v[152:155], v[230:233], v[132:135], v[96:99]
	v_mfma_f32_16x16x32_bf16 v[96:99], v[214:217], v[160:163], v[100:103]
	v_mfma_f32_16x16x32_bf16 v[156:159], v[218:221], v[132:135], v[140:143]
	v_mfma_f32_16x16x32_bf16 v[140:143], v[218:221], v[164:167], v[96:99]
	v_mfma_f32_16x16x32_bf16 v[96:99], v[222:225], v[160:163], v[108:111]
	v_mfma_f32_16x16x32_bf16 v[132:135], v[230:233], v[164:167], v[96:99]
	v_mfma_f32_16x16x32_bf16 v[96:99], v[214:217], v[198:201], v[112:115]
	v_mfma_f32_16x16x32_bf16 v[124:127], v[218:221], v[202:205], v[96:99]
	v_mfma_f32_16x16x32_bf16 v[96:99], v[222:225], v[198:201], v[116:119]
	v_mfma_f32_16x16x32_bf16 v[68:71], v[214:217], v[206:209], v[68:71]
	v_mfma_f32_16x16x32_bf16 v[64:67], v[222:225], v[206:209], v[64:67]
	v_mfma_f32_16x16x32_bf16 v[116:119], v[230:233], v[202:205], v[96:99]
	v_mfma_f32_16x16x32_bf16 v[68:71], v[218:221], v[210:213], v[68:71]
	v_mfma_f32_16x16x32_bf16 v[64:67], v[230:233], v[210:213], v[64:67]
	s_setprio 0
	s_mov_b32 m0, s63
	v_lshl_add_u64 v[184:185], v[226:227], 0, s[14:15]
	s_barrier
	ds_read_b128 v[96:99], v190 offset:49152
	ds_read_b128 v[100:103], v190 offset:50176
	ds_read_b128 v[108:111], v190 offset:51200
	ds_read_b128 v[112:115], v190 offset:52224
	ds_read_b128 v[160:163], v190 offset:53248
	ds_read_b128 v[164:167], v190 offset:54272
	ds_read_b128 v[198:201], v190 offset:55296
	ds_read_b128 v[202:205], v190 offset:56320
	global_load_lds_dwordx4 v[184:185], off
	v_lshl_add_u64 v[184:185], v[234:235], 0, s[14:15]
	s_mov_b32 m0, s66
	s_nop 0
	global_load_lds_dwordx4 v[184:185], off
	s_barrier
; #define PG8_STAGE(bufoff, gbase, voff) do { _Pragma("unroll") for (int _i = 0; _i < 2; ++_i) \
;         __builtin_amdgcn_global_load_lds((const unsigned*)((const char*)(gbase) + (voff)[_i]), (LAS unsigned*)(lds + (bufoff) + ldsw + _i * 8192), 16, 0, 0); } while (0)
; #define PG8_MMA(ai, bj, At, Bt) do { __builtin_amdgcn_s_setprio(1); _Pragma("unroll") for (int m = 0; m < 4; ++m) _Pragma("unroll") for (int n = 0; n < 2; ++n) _Pragma("unroll") for (int k = 0; k < 2; ++k) \
;         acc[ai][bj][m][n] = __builtin_amdgcn_mfma_f32_16x16x32_bf16(Bt[n][k], At[m][k], acc[ai][bj][m][n], 0, 0, 0); __builtin_amdgcn_s_setprio(0); } while (0)
; #define PG8_WAIT_V(n) asm volatile("s_waitcnt vmcnt(" #n ")" ::: "memory")
; #define PG8_WAIT_L(n) asm volatile("s_waitcnt lgkmcnt(" #n ")" ::: "memory")
; #define PG8_BAR __builtin_amdgcn_s_barrier()
; #define PG8_SCHED __builtin_amdgcn_sched_barrier(0)
; template <class Map, class Epi>
; DI void gemm_phase(LAS unsigned char* lds, const Map& MP, const Epi& E, const int nM, const int nN, const int K, const int lda, const int ldb) {
;     ...
;             PG8_BAR; PG8_WAIT_L(0); PG8_MMA(1, 0, At, B0); PG8_BAR; PG8_SCHED;
;             PG8_STAGE(PG8_SB(1, 1), b3 + hstepB, voffB);
;             PG8_WAIT_V(6); PG8_BAR; PG8_MMA(1, 1, At, B1); PG8_BAR;
	s_setprio 1
	s_waitcnt lgkmcnt(7)
	v_mfma_f32_16x16x32_bf16 v[60:63], v[80:83], v[96:99], v[60:63]
	v_mfma_f32_16x16x32_bf16 v[48:51], v[88:91], v[96:99], v[48:51]
	s_waitcnt lgkmcnt(5)
	v_mfma_f32_16x16x32_bf16 v[40:43], v[80:83], v[108:111], v[40:43]
	v_mfma_f32_16x16x32_bf16 v[32:35], v[88:91], v[108:111], v[32:35]
	s_waitcnt lgkmcnt(3)
	v_mfma_f32_16x16x32_bf16 v[24:27], v[80:83], v[160:163], v[24:27]
	v_mfma_f32_16x16x32_bf16 v[16:19], v[88:91], v[160:163], v[16:19]
	s_waitcnt lgkmcnt(1)
	v_mfma_f32_16x16x32_bf16 v[12:15], v[80:83], v[198:201], v[12:15]
	v_mfma_f32_16x16x32_bf16 v[8:11], v[88:91], v[198:201], v[8:11]
	v_mfma_f32_16x16x32_bf16 v[60:63], v[84:87], v[100:103], v[60:63]
	v_mfma_f32_16x16x32_bf16 v[48:51], v[92:95], v[100:103], v[48:51]
	v_mfma_f32_16x16x32_bf16 v[40:43], v[84:87], v[112:115], v[40:43]
	v_mfma_f32_16x16x32_bf16 v[32:35], v[92:95], v[112:115], v[32:35]
	v_mfma_f32_16x16x32_bf16 v[24:27], v[84:87], v[164:167], v[24:27]
	v_mfma_f32_16x16x32_bf16 v[16:19], v[92:95], v[164:167], v[16:19]
	s_waitcnt lgkmcnt(0)
	v_mfma_f32_16x16x32_bf16 v[12:15], v[84:87], v[202:205], v[12:15]
	v_mfma_f32_16x16x32_bf16 v[8:11], v[92:95], v[202:205], v[8:11]
	s_setprio 0
	s_barrier
	s_add_u32 s28, s28, 0x80080
	s_addc_u32 s29, s29, 0
	s_add_i32 s46, s46, s54
	s_mov_b32 m0, s46
	s_nop 0
	global_load_lds_dwordx4 v172, s[28:29]
	s_add_i32 m0, s46, 0x2000
	s_nop 0
	global_load_lds_dwordx4 v168, s[28:29]
	s_waitcnt vmcnt(6)
	s_barrier
	s_setprio 1
	v_mfma_f32_16x16x32_bf16 v[56:59], v[214:217], v[96:99], v[56:59]
	v_mfma_f32_16x16x32_bf16 v[52:55], v[222:225], v[96:99], v[52:55]
	v_mfma_f32_16x16x32_bf16 v[44:47], v[214:217], v[108:111], v[44:47]
	v_mfma_f32_16x16x32_bf16 v[36:39], v[222:225], v[108:111], v[36:39]
	v_mfma_f32_16x16x32_bf16 v[28:31], v[214:217], v[160:163], v[28:31]
	v_mfma_f32_16x16x32_bf16 v[20:23], v[222:225], v[160:163], v[20:23]
	v_mfma_f32_16x16x32_bf16 v[4:7], v[214:217], v[198:201], v[4:7]
	v_mfma_f32_16x16x32_bf16 v[0:3], v[222:225], v[198:201], v[0:3]
	v_mfma_f32_16x16x32_bf16 v[56:59], v[218:221], v[100:103], v[56:59]
	v_mfma_f32_16x16x32_bf16 v[52:55], v[230:233], v[100:103], v[52:55]
	v_mfma_f32_16x16x32_bf16 v[44:47], v[218:221], v[112:115], v[44:47]
	v_mfma_f32_16x16x32_bf16 v[36:39], v[230:233], v[112:115], v[36:39]
	v_mfma_f32_16x16x32_bf16 v[28:31], v[218:221], v[164:167], v[28:31]
	v_mfma_f32_16x16x32_bf16 v[20:23], v[230:233], v[164:167], v[20:23]
	v_mfma_f32_16x16x32_bf16 v[4:7], v[218:221], v[202:205], v[4:7]
	v_mfma_f32_16x16x32_bf16 v[0:3], v[230:233], v[202:205], v[0:3]
	s_setprio 0
	s_add_i32 s3, s3, 2
	s_add_u32 vcc_lo, vcc_lo, 0x100
	s_addc_u32 vcc_hi, vcc_hi, 0
	s_add_u32 s42, s42, 0x100
	s_addc_u32 s43, s43, 0
	s_cmp_gt_u32 s3, 29
	s_barrier
	s_cbranch_scc0 .LBB1_1908
; DI float silu_mul(float g, float v) { return g * v * __builtin_amdgcn_rcpf(1.0f + __builtin_amdgcn_exp2f(-LOG2E * g)); }
;     DI void operator()(const f32x4 (&acc)[2][2][4][2], const Unit& u, int wr, int wc, int fr, int fq) const {
;         const int row0 = u.pm * BM + wr * 64 + fr, ch0 = u.pn * 128 + wc * 32 + 8 * fq;
;         f32x4 w0[2], w1[2], w2[2], bb[2];
; #pragma unroll
;         for (int n = 0; n < 2; ++n) { w0[n] = *(const f32x4*)(cw + ch0 + 4 * n); w1[n] = *(const f32x4*)(cw + DFF + ch0 + 4 * n); w2[n] = *(const f32x4*)(cw + 2 * DFF + ch0 + 4 * n); bb[n] = *(const f32x4*)(cb + ch0 + 4 * n); }
; #pragma unroll
;         for (int ai = 0; ai < 2; ++ai)
; #pragma unroll
;             for (int m = 0; m < 4; ++m) {
;                 const bool efirst = (m == 0) && (fr == 0), elast = (m == 3) && (fr == 15);
;                 const int row = row0 + ai * HALF + m * 16;
;                 f32x4 gc[2];
; #pragma unroll
;                 for (int n = 0; n < 2; ++n) {
;                     const f32x4 g = acc[ai][0][m][n];
;                     const f32x4 gprev = acc[ai][0][m > 0 ? m - 1 : 0][n], gnext = acc[ai][0][m < 3 ? m + 1 : 3][n];
;                     f32x4 up, dn;
; #pragma unroll
;                     for (int e = 0; e < 4; ++e) {
;                         const float pu = (m > 0 && fr == 15) ? gprev[e] : g[e];
;                         const float pd = (m < 3 && fr == 0) ? gnext[e] : g[e];
;                         up[e] = dpp_ror1(pu); dn[e] = dpp_ror15(pd);
;                     }
;                     if (efirst) up = (f32x4){0.f, 0.f, 0.f, 0.f};
;                     if (elast) dn = (f32x4){0.f, 0.f, 0.f, 0.f};
;                     gc[n] = w0[n] * up + w1[n] * g + w2[n] * dn + bb[n];
;                 }
;                 if (efirst || elast) {
;                     const size_t eo = (size_t)((row >> 6) * 2 + (elast ? 1 : 0)) * DFF + ch0;
; #pragma unroll
;                     for (int n = 0; n < 2; ++n) { *(f32x4*)(EP + eo + 4 * n) = gc[n]; *(f32x4*)(ER + eo + 4 * n) = acc[ai][0][m][n]; *(f32x4*)(EV + eo + 4 * n) = acc[ai][1][m][n]; }
;                 } else {
;                     const f32x4 v0 = acc[ai][1][m][0], v1 = acc[ai][1][m][1];
;                     u32x4 o;
;                     o[0] = pack2(silu_mul(gc[0][0], v0[0]), silu_mul(gc[0][1], v0[1])); o[1] = pack2(silu_mul(gc[0][2], v0[2]), silu_mul(gc[0][3], v0[3]));
	s_lshl_b32 s21, s45, 7
	v_mov_b32_e32 v194, v186
	v_mov_b32_e32 v80, v187
	s_or_b32 s21, s21, s62
	v_mov_b32_e32 v160, 0
	v_lshl_add_u32 v184, v80, 3, s21
	v_ashrrev_i32_e32 v185, 31, v184
	v_lshlrev_b64 v[80:81], 2, v[184:185]
	v_lshl_add_u64 v[84:85], s[4:5], 0, v[80:81]
	v_lshl_add_u64 v[88:89], s[16:17], 0, v[80:81]
	v_lshl_add_u64 v[92:93], s[18:19], 0, v[80:81]
	v_lshl_add_u64 v[112:113], s[6:7], 0, v[80:81]
	global_load_dwordx4 v[80:83], v[84:85], off offset:16
	global_load_dwordx4 v[96:99], v[84:85], off
	s_nop 0
	global_load_dwordx4 v[84:87], v[88:89], off offset:16
	global_load_dwordx4 v[100:103], v[88:89], off
	s_nop 0
	global_load_dwordx4 v[88:91], v[92:93], off offset:16
	global_load_dwordx4 v[108:111], v[92:93], off
	s_nop 0
	global_load_dwordx4 v[92:95], v[112:113], off offset:16
	s_nop 0
	global_load_dwordx4 v[112:115], v[112:113], off
	v_cmp_eq_u32_e32 vcc, 0, v194
	v_mov_b32_e32 v164, 0
	v_mov_b32_e32 v195, 0
	v_cndmask_b32_e32 v161, v148, v136, vcc
	v_cndmask_b32_e32 v162, v149, v137, vcc
	v_cndmask_b32_e32 v163, v150, v138, vcc
	v_mov_b32_dpp v160, v161 row_ror:15 row_mask:0xf bank_mask:0xf
	v_mov_b32_e32 v161, 0
	v_mov_b32_e32 v166, 0
	v_mov_b32_e32 v167, 0
	v_mov_b32_dpp v161, v162 row_ror:15 row_mask:0xf bank_mask:0xf
	v_mov_b32_e32 v162, 0
	v_mov_b32_dpp v164, v150 row_ror:1 row_mask:0xf bank_mask:0xf
	v_cndmask_b32_e32 v165, v151, v139, vcc
	v_mov_b32_dpp v162, v163 row_ror:15 row_mask:0xf bank_mask:0xf
	v_mov_b32_dpp v195, v151 row_ror:1 row_mask:0xf bank_mask:0xf
	v_mov_b32_e32 v163, 0
	v_mov_b32_dpp v166, v148 row_ror:1 row_mask:0xf bank_mask:0xf
	v_mov_b32_dpp v167, v149 row_ror:1 row_mask:0xf bank_mask:0xf
	v_mov_b32_dpp v163, v165 row_ror:15 row_mask:0xf bank_mask:0xf
	v_cndmask_b32_e64 v165, v195, 0, vcc
	v_cndmask_b32_e64 v164, v164, 0, vcc
	v_cndmask_b32_e64 v167, v167, 0, vcc
	v_cndmask_b32_e64 v166, v166, 0, vcc
	v_mov_b32_e32 v195, 0
	v_mov_b32_e32 v196, 0
	v_mov_b32_e32 v198, 0
	v_mov_b32_e32 v200, 0
	v_mov_b32_dpp v195, v144 row_ror:1 row_mask:0xf bank_mask:0xf
	v_mov_b32_dpp v196, v145 row_ror:1 row_mask:0xf bank_mask:0xf
	v_mov_b32_dpp v198, v146 row_ror:1 row_mask:0xf bank_mask:0xf
	v_cndmask_b32_e32 v199, v147, v131, vcc
	v_mov_b32_dpp v200, v147 row_ror:1 row_mask:0xf bank_mask:0xf
	v_cndmask_b32_e64 v198, v198, 0, vcc
	v_cndmask_b32_e64 v201, v196, 0, vcc
	s_lshl_b32 s3, s44, 8
	s_add_i32 s3, s3, s49
	v_add_u32_e32 v193, s3, v194
	v_cmp_ne_u32_e64 s[46:47], 0, v194
	s_waitcnt vmcnt(0)
	v_pk_mul_f32 v[164:165], v[98:99], v[164:165]
	v_pk_mul_f32 v[166:167], v[96:97], v[166:167]
	v_pk_fma_f32 v[164:165], v[150:151], v[102:103], v[164:165]
	v_pk_fma_f32 v[166:167], v[148:149], v[100:101], v[166:167]
	v_pk_fma_f32 v[162:163], v[110:111], v[162:163], v[164:165]
	v_cndmask_b32_e32 v165, v144, v128, vcc
	v_mov_b32_e32 v164, 0
	v_pk_fma_f32 v[160:161], v[108:109], v[160:161], v[166:167]
	v_cndmask_b32_e32 v166, v145, v129, vcc
	v_mov_b32_dpp v164, v165 row_ror:15 row_mask:0xf bank_mask:0xf
	v_mov_b32_e32 v165, 0
	v_cndmask_b32_e32 v167, v146, v130, vcc
	v_pk_add_f32 v[162:163], v[114:115], v[162:163]
	v_mov_b32_dpp v165, v166 row_ror:15 row_mask:0xf bank_mask:0xf
	v_mov_b32_e32 v166, 0
	v_pk_add_f32 v[160:161], v[112:113], v[160:161]
	s_nop 0
	v_mov_b32_dpp v166, v167 row_ror:15 row_mask:0xf bank_mask:0xf
	v_mov_b32_e32 v167, 0
	s_nop 1
	v_mov_b32_dpp v167, v199 row_ror:15 row_mask:0xf bank_mask:0xf
	v_cndmask_b32_e64 v199, v200, 0, vcc
	v_cndmask_b32_e64 v200, v195, 0, vcc
	v_pk_mul_f32 v[200:201], v[80:81], v[200:201]
	v_pk_mul_f32 v[198:199], v[82:83], v[198:199]
	v_pk_fma_f32 v[200:201], v[144:145], v[84:85], v[200:201]
	v_pk_fma_f32 v[198:199], v[146:147], v[86:87], v[198:199]
	v_pk_fma_f32 v[164:165], v[88:89], v[164:165], v[200:201]
	v_pk_fma_f32 v[166:167], v[90:91], v[166:167], v[198:199]
	v_pk_add_f32 v[164:165], v[92:93], v[164:165]
	v_pk_add_f32 v[166:167], v[94:95], v[166:167]
	s_and_saveexec_b64 s[28:29], s[46:47]
	s_xor_b64 s[28:29], exec, s[28:29]
	s_cbranch_execz .LBB1_1911
	v_mul_f32_e32 v195, 0xbfb8aa3b, v160
	v_exp_f32_e32 v195, v195
	v_mul_f32_e32 v196, 0xbfb8aa3b, v161
	v_exp_f32_e32 v196, v196
	v_pk_mul_f32 v[160:161], v[156:157], v[160:161]
	v_add_f32_e32 v195, 1.0, v195
	v_rcp_f32_e32 v198, v195
	v_add_f32_e32 v196, 1.0, v196
	v_mul_f32_e32 v195, 0xbfb8aa3b, v162
	v_rcp_f32_e32 v199, v196
	v_exp_f32_e32 v195, v195
	v_mul_f32_e32 v196, 0xbfb8aa3b, v163
	v_exp_f32_e32 v196, v196
	v_pk_mul_f32 v[160:161], v[160:161], v[198:199]
	v_add_f32_e32 v195, 1.0, v195
	v_rcp_f32_e32 v200, v195
	v_add_f32_e32 v195, 1.0, v196
	v_rcp_f32_e32 v201, v195
	v_cvt_pk_bf16_f32 v160, v160, v161
	v_mul_f32_e32 v161, 0xbfb8aa3b, v164
	v_exp_f32_e32 v195, v161
	v_mul_f32_e32 v161, 0xbfb8aa3b, v165
	v_exp_f32_e32 v196, v161
	v_pk_mul_f32 v[162:163], v[158:159], v[162:163]
	v_pk_mul_f32 v[164:165], v[152:153], v[164:165]
	v_pk_mul_f32 v[162:163], v[162:163], v[200:201]
	s_nop 0
	v_cvt_pk_bf16_f32 v161, v162, v163
	v_add_f32_e32 v162, 1.0, v195
	v_mul_f32_e32 v195, 0xbfb8aa3b, v166
	v_add_f32_e32 v163, 1.0, v196
	v_exp_f32_e32 v195, v195
	v_mul_f32_e32 v196, 0xbfb8aa3b, v167
	v_exp_f32_e32 v196, v196
	v_rcp_f32_e32 v162, v162
	v_add_f32_e32 v195, 1.0, v195
	v_rcp_f32_e32 v198, v195
	v_add_f32_e32 v195, 1.0, v196
	v_rcp_f32_e32 v163, v163
	v_rcp_f32_e32 v199, v195
	v_pk_mul_f32 v[166:167], v[154:155], v[166:167]
	v_pk_mul_f32 v[162:163], v[164:165], v[162:163]
	v_pk_mul_f32 v[164:165], v[166:167], v[198:199]
	v_cvt_pk_bf16_f32 v162, v162, v163
	v_cvt_pk_bf16_f32 v163, v164, v165
	v_mov_b64_e32 v[164:165], s[52:53]
	v_mad_i64_i32 v[164:165], s[42:43], v193, s60, v[164:165]
	v_lshl_add_u64 v[164:165], v[184:185], 1, v[164:165]
	global_store_dwordx4 v[164:165], v[160:163], off

; #define PG8_STAGE(bufoff, gbase, voff) do { _Pragma("unroll") for (int _i = 0; _i < 2; ++_i) \
;         __builtin_amdgcn_global_load_lds((const unsigned*)((const char*)(gbase) + (voff)[_i]), (LAS unsigned*)(lds + (bufoff) + ldsw + _i * 8192), 16, 0, 0); } while (0)
; #define PG8_LDA(dst, b, h) do { _Pragma("unroll") for (int m = 0; m < 4; ++m) _Pragma("unroll") for (int k = 0; k < 2; ++k) dst[m][k] = *(const LAS bf16x8*)(lds + PG8_SA(b, h) + aoff + m * 2048 + k * 1024); } while (0)
; #define PG8_LDB(dst, b, h) do { _Pragma("unroll") for (int n = 0; n < 2; ++n) _Pragma("unroll") for (int k = 0; k < 2; ++k) dst[n][k] = *(const LAS bf16x8*)(lds + PG8_SB(b, h) + boff + n * 2048 + k * 1024); } while (0)
; #define PG8_MMA(ai, bj, At, Bt) do { __builtin_amdgcn_s_setprio(1); _Pragma("unroll") for (int m = 0; m < 4; ++m) _Pragma("unroll") for (int n = 0; n < 2; ++n) _Pragma("unroll") for (int k = 0; k < 2; ++k) \
;         acc[ai][bj][m][n] = __builtin_amdgcn_mfma_f32_16x16x32_bf16(Bt[n][k], At[m][k], acc[ai][bj][m][n], 0, 0, 0); __builtin_amdgcn_s_setprio(0); } while (0)
; #define PG8_WAIT_L(n) asm volatile("s_waitcnt lgkmcnt(" #n ")" ::: "memory")
; #define PG8_BAR __builtin_amdgcn_s_barrier()
; #define PG8_SCHED __builtin_amdgcn_sched_barrier(0)
; template <class Map, class Epi>
; DI void gemm_phase(LAS unsigned char* lds, const Map& MP, const Epi& E, const int nM, const int nN, const int K, const int lda, const int ldb) {
;     ...
;             PG8_LDB(B0, 0, 0); PG8_SCHED; PG8_LDA(At, 0, 0); PG8_STAGE(PG8_SA(1, 1), a1 + hstepA, voffA);
;             PG8_WAIT_L(8); PG8_BAR; PG8_WAIT_L(0); PG8_MMA(0, 0, At, B0); PG8_BAR; PG8_SCHED;
;             PG8_LDB(B1, 0, 1); PG8_STAGE(PG8_SB(0, 0), b2, voffB);
;             PG8_BAR; PG8_WAIT_L(0); PG8_MMA(0, 1, At, B1); PG8_BAR;
;             PG8_LDA(At, 0, 1); PG8_STAGE(PG8_SA(0, 0), a2, voffA);
;             PG8_BAR; PG8_WAIT_L(0); PG8_MMA(1, 0, At, B0); PG8_BAR; PG8_SCHED;
.LBB1_2078:
	ds_read_b128 v[152:155], v149
	ds_read_b128 v[156:159], v149 offset:1024
	ds_read_b128 v[160:163], v149 offset:2048
	ds_read_b128 v[164:167], v149 offset:3072
	s_add_u32 s10, s8, 0x100
	s_addc_u32 s11, s9, 0
	s_cmpk_eq_i32 s3, 0x54
	s_cselect_b32 s15, s43, s11
	s_cselect_b32 s14, s42, s10
	s_cselect_b32 s13, s7, s44
	s_cselect_b32 s12, s6, s39
	s_add_i32 m0, s24, 0xc000
	ds_read_b128 v[168:171], v150
	ds_read_b128 v[172:175], v150 offset:1024
	ds_read_b128 v[176:179], v150 offset:2048
	ds_read_b128 v[180:183], v150 offset:3072
	ds_read_b128 v[184:187], v150 offset:4096
	ds_read_b128 v[188:191], v150 offset:5120
	ds_read_b128 v[192:195], v150 offset:6144
	ds_read_b128 v[198:201], v150 offset:7168
	global_load_lds_dwordx4 v138, s[8:9]
	s_add_i32 m0, s24, 0xe000
	s_nop 0
	global_load_lds_dwordx4 v136, s[8:9]
	s_waitcnt lgkmcnt(8)
	s_barrier
	s_setprio 1
	s_waitcnt lgkmcnt(7)
	v_mfma_f32_16x16x32_bf16 v[124:127], v[152:155], v[168:171], v[124:127]
	v_mfma_f32_16x16x32_bf16 v[120:123], v[160:163], v[168:171], v[120:123]
	s_waitcnt lgkmcnt(5)
	v_mfma_f32_16x16x32_bf16 v[108:111], v[152:155], v[176:179], v[108:111]
	v_mfma_f32_16x16x32_bf16 v[104:107], v[160:163], v[176:179], v[104:107]
	s_waitcnt lgkmcnt(3)
	v_mfma_f32_16x16x32_bf16 v[92:95], v[152:155], v[184:187], v[92:95]
	v_mfma_f32_16x16x32_bf16 v[88:91], v[160:163], v[184:187], v[88:91]
	s_waitcnt lgkmcnt(1)
	v_mfma_f32_16x16x32_bf16 v[76:79], v[152:155], v[192:195], v[76:79]
	v_mfma_f32_16x16x32_bf16 v[72:75], v[160:163], v[192:195], v[72:75]
	v_mfma_f32_16x16x32_bf16 v[124:127], v[156:159], v[172:175], v[124:127]
	v_mfma_f32_16x16x32_bf16 v[120:123], v[164:167], v[172:175], v[120:123]
	v_mfma_f32_16x16x32_bf16 v[108:111], v[156:159], v[180:183], v[108:111]
	v_mfma_f32_16x16x32_bf16 v[104:107], v[164:167], v[180:183], v[104:107]
	v_mfma_f32_16x16x32_bf16 v[92:95], v[156:159], v[188:191], v[92:95]
	v_mfma_f32_16x16x32_bf16 v[88:91], v[164:167], v[188:191], v[88:91]
	s_waitcnt lgkmcnt(0)
	v_mfma_f32_16x16x32_bf16 v[76:79], v[156:159], v[198:201], v[76:79]
	v_mfma_f32_16x16x32_bf16 v[72:75], v[164:167], v[198:201], v[72:75]
	s_setprio 0
	s_barrier
	s_add_i32 s8, s35, s22
	v_lshl_add_u64 v[144:145], s[12:13], 0, v[132:133]
	s_mov_b32 m0, s8
	ds_read_b128 v[202:205], v151
	ds_read_b128 v[206:209], v151 offset:1024
	ds_read_b128 v[210:213], v151 offset:2048
	ds_read_b128 v[214:217], v151 offset:3072
	global_load_lds_dwordx4 v[144:145], off
	v_lshl_add_u64 v[218:219], s[12:13], 0, v[128:129]
	s_add_i32 m0, s8, 0x2000
	s_nop 0
	global_load_lds_dwordx4 v[218:219], off
	s_barrier
	s_setprio 1
	s_waitcnt lgkmcnt(3)
	v_mfma_f32_16x16x32_bf16 v[116:119], v[202:205], v[168:171], v[116:119]
	s_waitcnt lgkmcnt(1)
	v_mfma_f32_16x16x32_bf16 v[112:115], v[210:213], v[168:171], v[112:115]
	v_mfma_f32_16x16x32_bf16 v[100:103], v[202:205], v[176:179], v[100:103]
	v_mfma_f32_16x16x32_bf16 v[96:99], v[210:213], v[176:179], v[96:99]
	v_mfma_f32_16x16x32_bf16 v[84:87], v[202:205], v[184:187], v[84:87]
	v_mfma_f32_16x16x32_bf16 v[80:83], v[210:213], v[184:187], v[80:83]
	v_mfma_f32_16x16x32_bf16 v[68:71], v[202:205], v[192:195], v[68:71]
	v_mfma_f32_16x16x32_bf16 v[64:67], v[210:213], v[192:195], v[64:67]
	v_mfma_f32_16x16x32_bf16 v[116:119], v[206:209], v[172:175], v[116:119]
	s_waitcnt lgkmcnt(0)
	v_mfma_f32_16x16x32_bf16 v[112:115], v[214:217], v[172:175], v[112:115]
	v_mfma_f32_16x16x32_bf16 v[100:103], v[206:209], v[180:183], v[100:103]
	v_mfma_f32_16x16x32_bf16 v[96:99], v[214:217], v[180:183], v[96:99]
	v_mfma_f32_16x16x32_bf16 v[84:87], v[206:209], v[188:191], v[84:87]
	v_mfma_f32_16x16x32_bf16 v[80:83], v[214:217], v[188:191], v[80:83]
	v_mfma_f32_16x16x32_bf16 v[68:71], v[206:209], v[198:201], v[68:71]
	v_mfma_f32_16x16x32_bf16 v[64:67], v[214:217], v[198:201], v[64:67]
	s_setprio 0
	s_mov_b32 m0, s24
	v_lshl_add_u64 v[220:221], s[14:15], 0, v[134:135]
	s_barrier
	ds_read_b128 v[168:171], v150 offset:16384
	ds_read_b128 v[172:175], v150 offset:17408
	ds_read_b128 v[176:179], v150 offset:18432
	ds_read_b128 v[180:183], v150 offset:19456
	ds_read_b128 v[184:187], v150 offset:20480
	ds_read_b128 v[188:191], v150 offset:21504
	ds_read_b128 v[192:195], v150 offset:22528
	ds_read_b128 v[198:201], v150 offset:23552
	global_load_lds_dwordx4 v[220:221], off
	v_lshl_add_u64 v[222:223], s[14:15], 0, v[130:131]
	s_mov_b32 m0, s25
	s_nop 0
	global_load_lds_dwordx4 v[222:223], off
	s_barrier
	s_setprio 1
	s_waitcnt lgkmcnt(7)
	v_mfma_f32_16x16x32_bf16 v[60:63], v[152:155], v[168:171], v[60:63]
	v_mfma_f32_16x16x32_bf16 v[56:59], v[160:163], v[168:171], v[56:59]
	s_waitcnt lgkmcnt(5)
	v_mfma_f32_16x16x32_bf16 v[44:47], v[152:155], v[176:179], v[44:47]
	v_mfma_f32_16x16x32_bf16 v[40:43], v[160:163], v[176:179], v[40:43]
	s_waitcnt lgkmcnt(3)
	v_mfma_f32_16x16x32_bf16 v[28:31], v[152:155], v[184:187], v[28:31]
	v_mfma_f32_16x16x32_bf16 v[24:27], v[160:163], v[184:187], v[24:27]
	s_waitcnt lgkmcnt(1)
	v_mfma_f32_16x16x32_bf16 v[12:15], v[152:155], v[192:195], v[12:15]
	v_mfma_f32_16x16x32_bf16 v[8:11], v[160:163], v[192:195], v[8:11]
	v_mfma_f32_16x16x32_bf16 v[60:63], v[156:159], v[172:175], v[60:63]
	v_mfma_f32_16x16x32_bf16 v[56:59], v[164:167], v[172:175], v[56:59]
	v_mfma_f32_16x16x32_bf16 v[44:47], v[156:159], v[180:183], v[44:47]
	v_mfma_f32_16x16x32_bf16 v[40:43], v[164:167], v[180:183], v[40:43]
	v_mfma_f32_16x16x32_bf16 v[28:31], v[156:159], v[188:191], v[28:31]
	v_mfma_f32_16x16x32_bf16 v[24:27], v[164:167], v[188:191], v[24:27]
	s_waitcnt lgkmcnt(0)
	v_mfma_f32_16x16x32_bf16 v[12:15], v[156:159], v[198:201], v[12:15]
	v_mfma_f32_16x16x32_bf16 v[8:11], v[164:167], v[198:201], v[8:11]
	s_setprio 0
	s_barrier
; #define PG8_STAGE(bufoff, gbase, voff) do { _Pragma("unroll") for (int _i = 0; _i < 2; ++_i) \
;         __builtin_amdgcn_global_load_lds((const unsigned*)((const char*)(gbase) + (voff)[_i]), (LAS unsigned*)(lds + (bufoff) + ldsw + _i * 8192), 16, 0, 0); } while (0)
; #define PG8_LDA(dst, b, h) do { _Pragma("unroll") for (int m = 0; m < 4; ++m) _Pragma("unroll") for (int k = 0; k < 2; ++k) dst[m][k] = *(const LAS bf16x8*)(lds + PG8_SA(b, h) + aoff + m * 2048 + k * 1024); } while (0)
; #define PG8_LDB(dst, b, h) do { _Pragma("unroll") for (int n = 0; n < 2; ++n) _Pragma("unroll") for (int k = 0; k < 2; ++k) dst[n][k] = *(const LAS bf16x8*)(lds + PG8_SB(b, h) + boff + n * 2048 + k * 1024); } while (0)
; #define PG8_MMA(ai, bj, At, Bt) do { __builtin_amdgcn_s_setprio(1); _Pragma("unroll") for (int m = 0; m < 4; ++m) _Pragma("unroll") for (int n = 0; n < 2; ++n) _Pragma("unroll") for (int k = 0; k < 2; ++k) \
;         acc[ai][bj][m][n] = __builtin_amdgcn_mfma_f32_16x16x32_bf16(Bt[n][k], At[m][k], acc[ai][bj][m][n], 0, 0, 0); __builtin_amdgcn_s_setprio(0); } while (0)
; #define PG8_WAIT_V(n) asm volatile("s_waitcnt vmcnt(" #n ")" ::: "memory")
; #define PG8_WAIT_L(n) asm volatile("s_waitcnt lgkmcnt(" #n ")" ::: "memory")
; #define PG8_BAR __builtin_amdgcn_s_barrier()
; #define PG8_SCHED __builtin_amdgcn_sched_barrier(0)
; template <class Map, class Epi>
; DI void gemm_phase(LAS unsigned char* lds, const Map& MP, const Epi& E, const int nM, const int nN, const int K, const int lda, const int ldb) {
;     ...
;             PG8_STAGE(PG8_SB(0, 1), b2 + hstepB, voffB);
;             PG8_WAIT_V(6); PG8_BAR; PG8_MMA(1, 1, At, B1); PG8_BAR;
;             PG8_LDB(B0, 1, 0); PG8_SCHED; PG8_LDA(At, 1, 0); PG8_STAGE(PG8_SA(0, 1), a2 + hstepA, voffA);
;             PG8_WAIT_L(8); PG8_BAR; PG8_WAIT_L(0); PG8_MMA(0, 0, At, B0); PG8_BAR; PG8_SCHED;
;             PG8_LDB(B1, 1, 1); PG8_STAGE(PG8_SB(1, 0), b3, voffB);
;             PG8_BAR; PG8_WAIT_L(0); PG8_MMA(0, 1, At, B1); PG8_BAR;
;             PG8_LDA(At, 1, 1); PG8_STAGE(PG8_SA(1, 0), a3, voffA);
;             PG8_BAR; PG8_WAIT_L(0); PG8_MMA(1, 0, At, B0); PG8_BAR; PG8_SCHED;
	s_add_u32 s8, s12, 0x160000
	s_addc_u32 s9, s13, 0
	s_add_i32 s45, s36, s22
	s_mov_b32 m0, s45
	s_nop 0
	global_load_lds_dwordx4 v132, s[8:9]
	s_add_i32 m0, s45, 0x2000
	s_nop 0
	global_load_lds_dwordx4 v128, s[8:9]
	s_waitcnt vmcnt(6)
	s_barrier
	s_setprio 1
	v_mfma_f32_16x16x32_bf16 v[52:55], v[202:205], v[168:171], v[52:55]
	v_mfma_f32_16x16x32_bf16 v[48:51], v[210:213], v[168:171], v[48:51]
	v_mfma_f32_16x16x32_bf16 v[36:39], v[202:205], v[176:179], v[36:39]
	v_mfma_f32_16x16x32_bf16 v[32:35], v[210:213], v[176:179], v[32:35]
	v_mfma_f32_16x16x32_bf16 v[20:23], v[202:205], v[184:187], v[20:23]
	v_mfma_f32_16x16x32_bf16 v[16:19], v[210:213], v[184:187], v[16:19]
	v_mfma_f32_16x16x32_bf16 v[4:7], v[202:205], v[192:195], v[4:7]
	v_mfma_f32_16x16x32_bf16 v[0:3], v[210:213], v[192:195], v[0:3]
	v_mfma_f32_16x16x32_bf16 v[52:55], v[206:209], v[172:175], v[52:55]
	v_mfma_f32_16x16x32_bf16 v[48:51], v[214:217], v[172:175], v[48:51]
	v_mfma_f32_16x16x32_bf16 v[36:39], v[206:209], v[180:183], v[36:39]
	v_mfma_f32_16x16x32_bf16 v[32:35], v[214:217], v[180:183], v[32:35]
	v_mfma_f32_16x16x32_bf16 v[20:23], v[206:209], v[188:191], v[20:23]
	v_mfma_f32_16x16x32_bf16 v[16:19], v[214:217], v[188:191], v[16:19]
	v_mfma_f32_16x16x32_bf16 v[4:7], v[206:209], v[198:201], v[4:7]
	v_mfma_f32_16x16x32_bf16 v[0:3], v[214:217], v[198:201], v[0:3]
	s_setprio 0
	s_add_i32 s45, 0, 0x18000
	v_add_u32_e32 v164, s45, v148
	s_barrier
	ds_read_b128 v[152:155], v164
	ds_read_b128 v[156:159], v164 offset:1024
	ds_read_b128 v[160:163], v164 offset:2048
	ds_read_b128 v[164:167], v164 offset:3072
	s_add_u32 s8, s14, 0x160000
	s_addc_u32 s9, s15, 0
	s_mov_b32 m0, s26
	ds_read_b128 v[168:171], v150 offset:32768
	ds_read_b128 v[172:175], v150 offset:33792
	ds_read_b128 v[176:179], v150 offset:34816
	ds_read_b128 v[180:183], v150 offset:35840
	ds_read_b128 v[184:187], v150 offset:36864
	ds_read_b128 v[188:191], v150 offset:37888
	ds_read_b128 v[192:195], v150 offset:38912
	ds_read_b128 v[198:201], v150 offset:39936
	global_load_lds_dwordx4 v134, s[8:9]
	s_mov_b32 m0, s27
	s_nop 0
	global_load_lds_dwordx4 v130, s[8:9]
	s_waitcnt lgkmcnt(8)
	s_barrier
	s_setprio 1
	s_waitcnt lgkmcnt(7)
	v_mfma_f32_16x16x32_bf16 v[124:127], v[152:155], v[168:171], v[124:127]
	v_mfma_f32_16x16x32_bf16 v[120:123], v[160:163], v[168:171], v[120:123]
	s_waitcnt lgkmcnt(5)
	v_mfma_f32_16x16x32_bf16 v[108:111], v[152:155], v[176:179], v[108:111]
	v_mfma_f32_16x16x32_bf16 v[104:107], v[160:163], v[176:179], v[104:107]
	s_waitcnt lgkmcnt(3)
	v_mfma_f32_16x16x32_bf16 v[92:95], v[152:155], v[184:187], v[92:95]
	v_mfma_f32_16x16x32_bf16 v[88:91], v[160:163], v[184:187], v[88:91]
	s_waitcnt lgkmcnt(1)
	v_mfma_f32_16x16x32_bf16 v[76:79], v[152:155], v[192:195], v[76:79]
	v_mfma_f32_16x16x32_bf16 v[72:75], v[160:163], v[192:195], v[72:75]
	v_mfma_f32_16x16x32_bf16 v[124:127], v[156:159], v[172:175], v[124:127]
	v_mfma_f32_16x16x32_bf16 v[120:123], v[164:167], v[172:175], v[120:123]
	v_mfma_f32_16x16x32_bf16 v[108:111], v[156:159], v[180:183], v[108:111]
	v_mfma_f32_16x16x32_bf16 v[104:107], v[164:167], v[180:183], v[104:107]
	v_mfma_f32_16x16x32_bf16 v[92:95], v[156:159], v[188:191], v[92:95]
	v_mfma_f32_16x16x32_bf16 v[88:91], v[164:167], v[188:191], v[88:91]
	s_waitcnt lgkmcnt(0)
	v_mfma_f32_16x16x32_bf16 v[76:79], v[156:159], v[198:201], v[76:79]
	v_mfma_f32_16x16x32_bf16 v[72:75], v[164:167], v[198:201], v[72:75]
	s_setprio 0
	s_barrier
	s_add_i32 s14, 0, 0x1c000
	s_add_i32 s8, s45, s22
	v_add_u32_e32 v196, s14, v148
	v_lshl_add_u64 v[144:145], v[144:145], 0, s[46:47]
	s_mov_b32 m0, s8
	ds_read_b128 v[202:205], v196
	ds_read_b128 v[206:209], v196 offset:1024
	ds_read_b128 v[210:213], v196 offset:2048
	ds_read_b128 v[214:217], v196 offset:3072
	global_load_lds_dwordx4 v[144:145], off
	v_lshl_add_u64 v[144:145], v[218:219], 0, s[46:47]
	s_add_i32 m0, s8, 0x2000
	s_nop 0
	global_load_lds_dwordx4 v[144:145], off
	s_barrier
	s_setprio 1
	s_waitcnt lgkmcnt(3)
	v_mfma_f32_16x16x32_bf16 v[116:119], v[202:205], v[168:171], v[116:119]
	s_waitcnt lgkmcnt(1)
	v_mfma_f32_16x16x32_bf16 v[112:115], v[210:213], v[168:171], v[112:115]
	v_mfma_f32_16x16x32_bf16 v[100:103], v[202:205], v[176:179], v[100:103]
	v_mfma_f32_16x16x32_bf16 v[96:99], v[210:213], v[176:179], v[96:99]
	v_mfma_f32_16x16x32_bf16 v[84:87], v[202:205], v[184:187], v[84:87]
	v_mfma_f32_16x16x32_bf16 v[80:83], v[210:213], v[184:187], v[80:83]
	v_mfma_f32_16x16x32_bf16 v[68:71], v[202:205], v[192:195], v[68:71]
	v_mfma_f32_16x16x32_bf16 v[64:67], v[210:213], v[192:195], v[64:67]
	v_mfma_f32_16x16x32_bf16 v[116:119], v[206:209], v[172:175], v[116:119]
	s_waitcnt lgkmcnt(0)
	v_mfma_f32_16x16x32_bf16 v[112:115], v[214:217], v[172:175], v[112:115]
	v_mfma_f32_16x16x32_bf16 v[100:103], v[206:209], v[180:183], v[100:103]
	v_mfma_f32_16x16x32_bf16 v[96:99], v[214:217], v[180:183], v[96:99]
	v_mfma_f32_16x16x32_bf16 v[84:87], v[206:209], v[188:191], v[84:87]
	v_mfma_f32_16x16x32_bf16 v[80:83], v[214:217], v[188:191], v[80:83]
	v_mfma_f32_16x16x32_bf16 v[68:71], v[206:209], v[198:201], v[68:71]
	v_mfma_f32_16x16x32_bf16 v[64:67], v[214:217], v[198:201], v[64:67]
	s_setprio 0
	s_mov_b32 m0, s30
	v_lshl_add_u64 v[144:145], v[220:221], 0, s[46:47]
	s_barrier
	ds_read_b128 v[168:171], v150 offset:49152
	ds_read_b128 v[172:175], v150 offset:50176
	ds_read_b128 v[176:179], v150 offset:51200
	ds_read_b128 v[180:183], v150 offset:52224
	ds_read_b128 v[184:187], v150 offset:53248
	ds_read_b128 v[188:191], v150 offset:54272
	ds_read_b128 v[192:195], v150 offset:55296
	ds_read_b128 v[198:201], v150 offset:56320
	global_load_lds_dwordx4 v[144:145], off
	v_lshl_add_u64 v[144:145], v[222:223], 0, s[46:47]
	s_mov_b32 m0, s31
	s_nop 0
	global_load_lds_dwordx4 v[144:145], off
	s_barrier
; DI unsigned pack2(float a, float b) { f32x2 v = {a, b}; hwbf16x2 r = __builtin_convertvector(v, hwbf16x2); return __builtin_bit_cast(unsigned, r); }
; DI float bflo(unsigned w) { return __uint_as_float(w << 16); }
; DI float bfhi(unsigned w) { return __uint_as_float(w & 0xffff0000u); }
; #define PG8_STAGE(bufoff, gbase, voff) do { _Pragma("unroll") for (int _i = 0; _i < 2; ++_i) \
;         __builtin_amdgcn_global_load_lds((const unsigned*)((const char*)(gbase) + (voff)[_i]), (LAS unsigned*)(lds + (bufoff) + ldsw + _i * 8192), 16, 0, 0); } while (0)
; #define PG8_WAIT_V(n) asm volatile("s_waitcnt vmcnt(" #n ")" ::: "memory")
; #define PG8_WAIT_L(n) asm volatile("s_waitcnt lgkmcnt(" #n ")" ::: "memory")
;     DI void operator()(const f32x4 (&acc)[2][2][4][2], const Unit& u, int wr, int wc, int fr, int fq) const {
;     ...
;         for (int ai = 0; ai < 2; ++ai)
; #pragma unroll
;             for (int m = 0; m < 4; ++m) { const size_t ro = (size_t)(row0 + ai * HALF + m * 16) * D + col0;
; #pragma unroll
;                 for (int bj = 0; bj < 2; ++bj) {
;                     f32x4 x0, x1;
;                     if constexpr (IB) { const u32x4 w = *(const u32x4*)((const bf16_t*)Xin + ro + bj * HALF);
;                         x0 = (f32x4){bflo(w[0]), bfhi(w[0]), bflo(w[1]), bfhi(w[1])}; x1 = (f32x4){bflo(w[2]), bfhi(w[2]), bflo(w[3]), bfhi(w[3])}; }
;                     else { x0 = *(const f32x4*)((const float*)Xin + ro + bj * HALF); x1 = *(const f32x4*)((const float*)Xin + ro + bj * HALF + 4); }
;                     x0 += acc[ai][bj][m][0] * sc[bj][0]; x1 += acc[ai][bj][m][1] * sc[bj][1];
;                     if constexpr (OB) { u32x4 o; o[0] = pack2(x0[0], x0[1]); o[1] = pack2(x0[2], x0[3]); o[2] = pack2(x1[0], x1[1]); o[3] = pack2(x1[2], x1[3]);
;                         *(u32x4*)((bf16_t*)Xout + ro + bj * HALF) = o; }
;                     else { *(f32x4*)((float*)Xout + ro + bj * HALF) = x0; *(f32x4*)((float*)Xout + ro + bj * HALF + 4) = x1; } } }
; template <class Map, class Epi>
; DI void gemm_phase(LAS unsigned char* lds, const Map& MP, const Epi& E, const int nM, const int nN, const int K, const int lda, const int ldb) {
;     ...
;             PG8_BAR; PG8_WAIT_L(0); PG8_MMA(1, 0, At, B0); PG8_BAR; PG8_SCHED;
;             PG8_STAGE(PG8_SB(1, 1), b3 + hstepB, voffB);
;             PG8_WAIT_V(6); PG8_BAR; PG8_MMA(1, 1, At, B1); PG8_BAR;
	s_setprio 1
	s_waitcnt lgkmcnt(7)
	v_mfma_f32_16x16x32_bf16 v[60:63], v[152:155], v[168:171], v[60:63]
	v_mfma_f32_16x16x32_bf16 v[56:59], v[160:163], v[168:171], v[56:59]
	s_waitcnt lgkmcnt(5)
	v_mfma_f32_16x16x32_bf16 v[44:47], v[152:155], v[176:179], v[44:47]
	v_mfma_f32_16x16x32_bf16 v[40:43], v[160:163], v[176:179], v[40:43]
	s_waitcnt lgkmcnt(3)
	v_mfma_f32_16x16x32_bf16 v[28:31], v[152:155], v[184:187], v[28:31]
	v_mfma_f32_16x16x32_bf16 v[24:27], v[160:163], v[184:187], v[24:27]
	s_waitcnt lgkmcnt(1)
	v_mfma_f32_16x16x32_bf16 v[12:15], v[152:155], v[192:195], v[12:15]
	v_mfma_f32_16x16x32_bf16 v[8:11], v[160:163], v[192:195], v[8:11]
	v_mfma_f32_16x16x32_bf16 v[60:63], v[156:159], v[172:175], v[60:63]
	v_mfma_f32_16x16x32_bf16 v[56:59], v[164:167], v[172:175], v[56:59]
	v_mfma_f32_16x16x32_bf16 v[44:47], v[156:159], v[180:183], v[44:47]
	v_mfma_f32_16x16x32_bf16 v[40:43], v[164:167], v[180:183], v[40:43]
	v_mfma_f32_16x16x32_bf16 v[28:31], v[156:159], v[188:191], v[28:31]
	v_mfma_f32_16x16x32_bf16 v[24:27], v[164:167], v[188:191], v[24:27]
	s_waitcnt lgkmcnt(0)
	v_mfma_f32_16x16x32_bf16 v[12:15], v[156:159], v[198:201], v[12:15]
	v_mfma_f32_16x16x32_bf16 v[8:11], v[164:167], v[198:201], v[8:11]
	s_setprio 0
	s_barrier
	s_add_u32 s8, s12, 0x160080
	s_addc_u32 s9, s13, 0
	s_add_i32 s12, s14, s22
	s_mov_b32 m0, s12
	s_nop 0
	global_load_lds_dwordx4 v132, s[8:9]
	s_add_i32 m0, s12, 0x2000
	s_nop 0
	global_load_lds_dwordx4 v128, s[8:9]
	s_waitcnt vmcnt(6)
	s_barrier
	s_setprio 1
	v_mfma_f32_16x16x32_bf16 v[52:55], v[202:205], v[168:171], v[52:55]
	v_mfma_f32_16x16x32_bf16 v[48:51], v[210:213], v[168:171], v[48:51]
	v_mfma_f32_16x16x32_bf16 v[36:39], v[202:205], v[176:179], v[36:39]
	v_mfma_f32_16x16x32_bf16 v[32:35], v[210:213], v[176:179], v[32:35]
	v_mfma_f32_16x16x32_bf16 v[20:23], v[202:205], v[184:187], v[20:23]
	v_mfma_f32_16x16x32_bf16 v[16:19], v[210:213], v[184:187], v[16:19]
	v_mfma_f32_16x16x32_bf16 v[4:7], v[202:205], v[192:195], v[4:7]
	v_mfma_f32_16x16x32_bf16 v[0:3], v[210:213], v[192:195], v[0:3]
	v_mfma_f32_16x16x32_bf16 v[52:55], v[206:209], v[172:175], v[52:55]
	v_mfma_f32_16x16x32_bf16 v[48:51], v[214:217], v[172:175], v[48:51]
	v_mfma_f32_16x16x32_bf16 v[36:39], v[206:209], v[180:183], v[36:39]
	v_mfma_f32_16x16x32_bf16 v[32:35], v[214:217], v[180:183], v[32:35]
	v_mfma_f32_16x16x32_bf16 v[20:23], v[206:209], v[188:191], v[20:23]
	v_mfma_f32_16x16x32_bf16 v[16:19], v[214:217], v[188:191], v[16:19]
	v_mfma_f32_16x16x32_bf16 v[4:7], v[206:209], v[198:201], v[4:7]
	v_mfma_f32_16x16x32_bf16 v[0:3], v[214:217], v[198:201], v[0:3]
	s_setprio 0
	s_add_i32 s3, s3, 2
	s_add_u32 s39, s39, 0x100
	s_addc_u32 s44, s44, 0
	s_cmpk_gt_u32 s3, 0x55
	s_mov_b64 s[8:9], s[10:11]
	s_barrier
	s_cbranch_scc0 .LBB1_2078
	v_mov_b32_e32 v152, v147
	v_mov_b32_e32 v144, v146
	s_lshl_b32 s2, s2, 8
	s_add_i32 s2, s2, s29
	s_lshl_b32 s3, s38, 8
	v_add_u32_e32 v152, s2, v152
	s_or_b32 s3, s3, s52
	v_ashrrev_i32_e32 v153, 31, v152
	v_lshl_add_u32 v144, v144, 3, s3
	v_lshlrev_b64 v[152:153], 12, v[152:153]
	v_ashrrev_i32_e32 v145, 31, v144
	v_lshl_add_u64 v[152:153], s[4:5], 0, v[152:153]
	v_lshl_add_u64 v[144:145], v[144:145], 1, v[152:153]
	global_load_dwordx4 v[160:163], v[144:145], off
	global_load_dwordx4 v[164:167], v[144:145], off offset:256
	s_mov_b64 s[98:99], 0x10000
	v_lshl_add_u64 v[154:155], v[144:145], 0, s[98:99]
	global_load_dwordx4 v[168:171], v[154:155], off
	global_load_dwordx4 v[172:175], v[154:155], off offset:256
	s_mov_b64 s[98:99], 0x20000
	v_lshl_add_u64 v[154:155], v[144:145], 0, s[98:99]
	global_load_dwordx4 v[176:179], v[154:155], off
	global_load_dwordx4 v[180:183], v[154:155], off offset:256
	s_mov_b64 s[98:99], 0x30000
	v_lshl_add_u64 v[154:155], v[144:145], 0, s[98:99]
	global_load_dwordx4 v[184:187], v[154:155], off
	global_load_dwordx4 v[188:191], v[154:155], off offset:256
	s_mov_b64 s[98:99], 0x80000
	v_lshl_add_u64 v[154:155], v[144:145], 0, s[98:99]
	global_load_dwordx4 v[192:195], v[154:155], off
	global_load_dwordx4 v[198:201], v[154:155], off offset:256
	s_mov_b64 s[98:99], 0x90000
	v_lshl_add_u64 v[154:155], v[144:145], 0, s[98:99]
	global_load_dwordx4 v[202:205], v[154:155], off
	global_load_dwordx4 v[206:209], v[154:155], off offset:256
	s_mov_b64 s[98:99], 0xa0000
	v_lshl_add_u64 v[154:155], v[144:145], 0, s[98:99]
	global_load_dwordx4 v[210:213], v[154:155], off
	global_load_dwordx4 v[214:217], v[154:155], off offset:256
	s_mov_b64 s[98:99], 0xb0000
	v_lshl_add_u64 v[154:155], v[144:145], 0, s[98:99]
	global_load_dwordx4 v[248:251], v[154:155], off
	global_load_dwordx4 v[252:255], v[154:155], off offset:256
	s_waitcnt vmcnt(15)
	s_nop 1
	v_mov_b32_e32 v152, v160
	v_mov_b32_e32 v153, v161
	v_mov_b32_e32 v154, v162
	v_mov_b32_e32 v155, v163
	s_mov_b64 s[2:3], 0x10000
	s_mov_b32 s38, s37
	s_mov_b64 s[10:11], s[6:7]
	s_mov_b64 s[8:9], s[42:43]
	s_waitcnt lgkmcnt(0)
	v_lshlrev_b32_e32 v156, 16, v152
	v_and_b32_e32 v157, 0xffff0000, v152
	v_lshlrev_b32_e32 v152, 16, v153
	v_and_b32_e32 v153, 0xffff0000, v153
	v_lshlrev_b32_e32 v158, 16, v154
	v_and_b32_e32 v159, 0xffff0000, v154
	v_lshlrev_b32_e32 v154, 16, v155
	v_and_b32_e32 v155, 0xffff0000, v155
	v_pk_add_f32 v[126:127], v[126:127], v[152:153]
	v_pk_add_f32 v[124:125], v[124:125], v[156:157]
	v_pk_add_f32 v[152:153], v[122:123], v[154:155]
	v_pk_add_f32 v[122:123], v[120:121], v[158:159]
	v_cvt_pk_bf16_f32 v120, v124, v125
	v_cvt_pk_bf16_f32 v121, v126, v127
	v_cvt_pk_bf16_f32 v122, v122, v123
	v_cvt_pk_bf16_f32 v123, v152, v153
	global_store_dwordx4 v[144:145], v[120:123], off
	s_waitcnt vmcnt(15)
; DI unsigned pack2(float a, float b) { f32x2 v = {a, b}; hwbf16x2 r = __builtin_convertvector(v, hwbf16x2); return __builtin_bit_cast(unsigned, r); }
; DI float bflo(unsigned w) { return __uint_as_float(w << 16); }
; DI float bfhi(unsigned w) { return __uint_as_float(w & 0xffff0000u); }
;     DI void operator()(const f32x4 (&acc)[2][2][4][2], const Unit& u, int wr, int wc, int fr, int fq) const {
;     ...
;         for (int ai = 0; ai < 2; ++ai)
; #pragma unroll
;             for (int m = 0; m < 4; ++m) { const size_t ro = (size_t)(row0 + ai * HALF + m * 16) * D + col0;
; #pragma unroll
;                 for (int bj = 0; bj < 2; ++bj) {
;                     f32x4 x0, x1;
;                     if constexpr (IB) { const u32x4 w = *(const u32x4*)((const bf16_t*)Xin + ro + bj * HALF);
;                         x0 = (f32x4){bflo(w[0]), bfhi(w[0]), bflo(w[1]), bfhi(w[1])}; x1 = (f32x4){bflo(w[2]), bfhi(w[2]), bflo(w[3]), bfhi(w[3])}; }
;                     else { x0 = *(const f32x4*)((const float*)Xin + ro + bj * HALF); x1 = *(const f32x4*)((const float*)Xin + ro + bj * HALF + 4); }
;                     x0 += acc[ai][bj][m][0] * sc[bj][0]; x1 += acc[ai][bj][m][1] * sc[bj][1];
;                     if constexpr (OB) { u32x4 o; o[0] = pack2(x0[0], x0[1]); o[1] = pack2(x0[2], x0[3]); o[2] = pack2(x1[0], x1[1]); o[3] = pack2(x1[2], x1[3]);
;                         *(u32x4*)((bf16_t*)Xout + ro + bj * HALF) = o; }
;                     else { *(f32x4*)((float*)Xout + ro + bj * HALF) = x0; *(f32x4*)((float*)Xout + ro + bj * HALF + 4) = x1; } } }
	s_nop 1
	v_mov_b32_e32 v120, v164
	v_mov_b32_e32 v121, v165
	v_mov_b32_e32 v122, v166
	v_mov_b32_e32 v123, v167
	s_waitcnt lgkmcnt(0)
	v_lshlrev_b32_e32 v124, 16, v120
	v_and_b32_e32 v125, 0xffff0000, v120
	v_lshlrev_b32_e32 v120, 16, v121
	v_and_b32_e32 v121, 0xffff0000, v121
	v_lshlrev_b32_e32 v126, 16, v122
	v_and_b32_e32 v127, 0xffff0000, v122
	v_lshlrev_b32_e32 v122, 16, v123
	v_and_b32_e32 v123, 0xffff0000, v123
	v_pk_add_f32 v[116:117], v[116:117], v[124:125]
	v_pk_add_f32 v[118:119], v[118:119], v[120:121]
	v_pk_add_f32 v[120:121], v[114:115], v[122:123]
	v_pk_add_f32 v[114:115], v[112:113], v[126:127]
	v_cvt_pk_bf16_f32 v112, v116, v117
	v_lshl_add_u64 v[116:117], v[144:145], 0, s[2:3]
	s_mov_b32 s2, 0x10000
	v_cvt_pk_bf16_f32 v113, v118, v119
	v_add_co_u32_e32 v118, vcc, s2, v144
	v_cvt_pk_bf16_f32 v114, v114, v115
	v_cvt_pk_bf16_f32 v115, v120, v121
	v_addc_co_u32_e32 v119, vcc, 0, v145, vcc
	global_store_dwordx4 v[144:145], v[112:115], off offset:256
	s_waitcnt vmcnt(15)
	s_nop 1
	v_mov_b32_e32 v112, v168
	v_mov_b32_e32 v113, v169
	v_mov_b32_e32 v114, v170
	v_mov_b32_e32 v115, v171
	s_mov_b64 s[2:3], 0x20000
	s_waitcnt lgkmcnt(0)
	v_lshlrev_b32_e32 v120, 16, v112
	v_and_b32_e32 v121, 0xffff0000, v112
	v_lshlrev_b32_e32 v112, 16, v113
	v_and_b32_e32 v113, 0xffff0000, v113
	v_lshlrev_b32_e32 v122, 16, v114
	v_and_b32_e32 v123, 0xffff0000, v114
	v_lshlrev_b32_e32 v114, 16, v115
	v_and_b32_e32 v115, 0xffff0000, v115
	v_pk_add_f32 v[110:111], v[110:111], v[112:113]
	v_pk_add_f32 v[108:109], v[108:109], v[120:121]
	v_pk_add_f32 v[112:113], v[106:107], v[114:115]
	v_pk_add_f32 v[106:107], v[104:105], v[122:123]
	v_cvt_pk_bf16_f32 v104, v108, v109
	v_cvt_pk_bf16_f32 v105, v110, v111
	v_cvt_pk_bf16_f32 v106, v106, v107
	v_cvt_pk_bf16_f32 v107, v112, v113
	global_store_dwordx4 v[118:119], v[104:107], off
	s_waitcnt vmcnt(15)
	s_nop 1
	v_mov_b32_e32 v104, v172
	v_mov_b32_e32 v105, v173
	v_mov_b32_e32 v106, v174
	v_mov_b32_e32 v107, v175
	s_waitcnt lgkmcnt(0)
	v_lshlrev_b32_e32 v108, 16, v104
	v_and_b32_e32 v109, 0xffff0000, v104
	v_lshlrev_b32_e32 v104, 16, v105
	v_and_b32_e32 v105, 0xffff0000, v105
	v_lshlrev_b32_e32 v110, 16, v106
	v_and_b32_e32 v111, 0xffff0000, v106
	v_lshlrev_b32_e32 v106, 16, v107
	v_and_b32_e32 v107, 0xffff0000, v107
	v_pk_add_f32 v[100:101], v[100:101], v[108:109]
	v_pk_add_f32 v[102:103], v[102:103], v[104:105]
	v_pk_add_f32 v[104:105], v[98:99], v[106:107]
	v_pk_add_f32 v[98:99], v[96:97], v[110:111]
	v_cvt_pk_bf16_f32 v96, v100, v101
	v_lshl_add_u64 v[100:101], v[144:145], 0, s[2:3]
	s_mov_b32 s2, 0x20000
	v_cvt_pk_bf16_f32 v97, v102, v103
	v_add_co_u32_e32 v102, vcc, s2, v144
	v_cvt_pk_bf16_f32 v98, v98, v99
	v_cvt_pk_bf16_f32 v99, v104, v105
	v_addc_co_u32_e32 v103, vcc, 0, v145, vcc
	global_store_dwordx4 v[116:117], v[96:99], off offset:256
	s_waitcnt vmcnt(15)
	s_nop 1
	v_mov_b32_e32 v96, v176
	v_mov_b32_e32 v97, v177
	v_mov_b32_e32 v98, v178
	v_mov_b32_e32 v99, v179
	s_mov_b64 s[2:3], 0x30000
	s_waitcnt lgkmcnt(0)
	v_lshlrev_b32_e32 v104, 16, v96
	v_and_b32_e32 v105, 0xffff0000, v96
	v_lshlrev_b32_e32 v96, 16, v97
	v_and_b32_e32 v97, 0xffff0000, v97
	v_lshlrev_b32_e32 v106, 16, v98
	v_and_b32_e32 v107, 0xffff0000, v98
	v_lshlrev_b32_e32 v98, 16, v99
	v_and_b32_e32 v99, 0xffff0000, v99
	v_pk_add_f32 v[94:95], v[94:95], v[96:97]
	v_pk_add_f32 v[92:93], v[92:93], v[104:105]
	v_pk_add_f32 v[96:97], v[90:91], v[98:99]
	v_pk_add_f32 v[90:91], v[88:89], v[106:107]
	v_cvt_pk_bf16_f32 v88, v92, v93
	v_cvt_pk_bf16_f32 v89, v94, v95
	v_cvt_pk_bf16_f32 v90, v90, v91
	v_cvt_pk_bf16_f32 v91, v96, v97
	global_store_dwordx4 v[102:103], v[88:91], off
	s_waitcnt vmcnt(15)
	s_nop 1
	v_mov_b32_e32 v88, v180
	v_mov_b32_e32 v89, v181
	v_mov_b32_e32 v90, v182
	v_mov_b32_e32 v91, v183
	s_waitcnt lgkmcnt(0)
	v_lshlrev_b32_e32 v92, 16, v88
	v_and_b32_e32 v93, 0xffff0000, v88
	v_lshlrev_b32_e32 v88, 16, v89
	v_and_b32_e32 v89, 0xffff0000, v89
	v_lshlrev_b32_e32 v94, 16, v90
	v_and_b32_e32 v95, 0xffff0000, v90
	v_lshlrev_b32_e32 v90, 16, v91
	v_and_b32_e32 v91, 0xffff0000, v91
	v_pk_add_f32 v[86:87], v[86:87], v[88:89]
	v_pk_add_f32 v[84:85], v[84:85], v[92:93]
	v_pk_add_f32 v[88:89], v[82:83], v[90:91]
	v_pk_add_f32 v[82:83], v[80:81], v[94:95]
	v_cvt_pk_bf16_f32 v80, v84, v85
	v_cvt_pk_bf16_f32 v81, v86, v87
	v_cvt_pk_bf16_f32 v82, v82, v83
	v_cvt_pk_bf16_f32 v83, v88, v89
	global_store_dwordx4 v[100:101], v[80:83], off offset:256
	s_nop 1
	v_lshl_add_u64 v[80:81], v[144:145], 0, s[2:3]
	s_mov_b32 s2, 0x30000
	v_add_co_u32_e32 v86, vcc, s2, v144
	s_mov_b64 s[2:3], 0x80000
	s_nop 0
	v_addc_co_u32_e32 v87, vcc, 0, v145, vcc
	s_waitcnt vmcnt(15)
	s_nop 1
	v_mov_b32_e32 v82, v184
	v_mov_b32_e32 v83, v185
	v_mov_b32_e32 v84, v186
	v_mov_b32_e32 v85, v187
	s_waitcnt lgkmcnt(0)
	v_lshlrev_b32_e32 v88, 16, v82
	v_and_b32_e32 v89, 0xffff0000, v82
	v_lshlrev_b32_e32 v82, 16, v83
	v_and_b32_e32 v83, 0xffff0000, v83
	v_lshlrev_b32_e32 v90, 16, v84
	v_and_b32_e32 v91, 0xffff0000, v84
	v_lshlrev_b32_e32 v84, 16, v85
	v_and_b32_e32 v85, 0xffff0000, v85
	v_pk_add_f32 v[78:79], v[78:79], v[82:83]
	v_pk_add_f32 v[76:77], v[76:77], v[88:89]
	v_pk_add_f32 v[82:83], v[74:75], v[84:85]
	v_pk_add_f32 v[74:75], v[72:73], v[90:91]
	v_cvt_pk_bf16_f32 v72, v76, v77
	v_cvt_pk_bf16_f32 v73, v78, v79
	v_cvt_pk_bf16_f32 v74, v74, v75
	v_cvt_pk_bf16_f32 v75, v82, v83
	global_store_dwordx4 v[86:87], v[72:75], off
	s_waitcnt vmcnt(15)
	s_nop 1
	v_mov_b32_e32 v72, v188
	v_mov_b32_e32 v73, v189
	v_mov_b32_e32 v74, v190
	v_mov_b32_e32 v75, v191
	s_waitcnt lgkmcnt(0)
; DI unsigned pack2(float a, float b) { f32x2 v = {a, b}; hwbf16x2 r = __builtin_convertvector(v, hwbf16x2); return __builtin_bit_cast(unsigned, r); }
; DI float bflo(unsigned w) { return __uint_as_float(w << 16); }
; DI float bfhi(unsigned w) { return __uint_as_float(w & 0xffff0000u); }
;     DI void operator()(const f32x4 (&acc)[2][2][4][2], const Unit& u, int wr, int wc, int fr, int fq) const {
;     ...
;         for (int ai = 0; ai < 2; ++ai)
; #pragma unroll
;             for (int m = 0; m < 4; ++m) { const size_t ro = (size_t)(row0 + ai * HALF + m * 16) * D + col0;
; #pragma unroll
;                 for (int bj = 0; bj < 2; ++bj) {
;                     f32x4 x0, x1;
;                     if constexpr (IB) { const u32x4 w = *(const u32x4*)((const bf16_t*)Xin + ro + bj * HALF);
;                         x0 = (f32x4){bflo(w[0]), bfhi(w[0]), bflo(w[1]), bfhi(w[1])}; x1 = (f32x4){bflo(w[2]), bfhi(w[2]), bflo(w[3]), bfhi(w[3])}; }
;                     else { x0 = *(const f32x4*)((const float*)Xin + ro + bj * HALF); x1 = *(const f32x4*)((const float*)Xin + ro + bj * HALF + 4); }
;                     x0 += acc[ai][bj][m][0] * sc[bj][0]; x1 += acc[ai][bj][m][1] * sc[bj][1];
;                     if constexpr (OB) { u32x4 o; o[0] = pack2(x0[0], x0[1]); o[1] = pack2(x0[2], x0[3]); o[2] = pack2(x1[0], x1[1]); o[3] = pack2(x1[2], x1[3]);
;                         *(u32x4*)((bf16_t*)Xout + ro + bj * HALF) = o; }
;                     else { *(f32x4*)((float*)Xout + ro + bj * HALF) = x0; *(f32x4*)((float*)Xout + ro + bj * HALF + 4) = x1; } } }
	v_lshlrev_b32_e32 v76, 16, v72
	v_and_b32_e32 v77, 0xffff0000, v72
	v_lshlrev_b32_e32 v72, 16, v73
	v_and_b32_e32 v73, 0xffff0000, v73
	v_lshlrev_b32_e32 v78, 16, v74
	v_and_b32_e32 v79, 0xffff0000, v74
	v_lshlrev_b32_e32 v74, 16, v75
	v_and_b32_e32 v75, 0xffff0000, v75
	v_pk_add_f32 v[70:71], v[70:71], v[72:73]
	v_pk_add_f32 v[68:69], v[68:69], v[76:77]
	v_pk_add_f32 v[72:73], v[66:67], v[74:75]
	v_pk_add_f32 v[66:67], v[64:65], v[78:79]
	v_cvt_pk_bf16_f32 v64, v68, v69
	v_cvt_pk_bf16_f32 v65, v70, v71
	v_cvt_pk_bf16_f32 v66, v66, v67
	v_cvt_pk_bf16_f32 v67, v72, v73
	global_store_dwordx4 v[80:81], v[64:67], off offset:256
	s_nop 1
	v_lshl_add_u64 v[64:65], v[144:145], 0, s[2:3]
	s_mov_b32 s2, 0x80000
	v_add_co_u32_e32 v70, vcc, s2, v144
	s_mov_b64 s[2:3], 0x90000
	s_nop 0
	v_addc_co_u32_e32 v71, vcc, 0, v145, vcc
	s_waitcnt vmcnt(15)
	s_nop 1
	v_mov_b32_e32 v66, v192
	v_mov_b32_e32 v67, v193
	v_mov_b32_e32 v68, v194
	v_mov_b32_e32 v69, v195
	s_waitcnt lgkmcnt(0)
	v_lshlrev_b32_e32 v72, 16, v66
	v_and_b32_e32 v73, 0xffff0000, v66
	v_lshlrev_b32_e32 v66, 16, v67
	v_and_b32_e32 v67, 0xffff0000, v67
	v_lshlrev_b32_e32 v74, 16, v68
	v_and_b32_e32 v75, 0xffff0000, v68
	v_lshlrev_b32_e32 v68, 16, v69
	v_and_b32_e32 v69, 0xffff0000, v69
	v_pk_add_f32 v[62:63], v[62:63], v[66:67]
	v_pk_add_f32 v[60:61], v[60:61], v[72:73]
	v_pk_add_f32 v[66:67], v[58:59], v[68:69]
	v_pk_add_f32 v[58:59], v[56:57], v[74:75]
	v_cvt_pk_bf16_f32 v56, v60, v61
	v_cvt_pk_bf16_f32 v57, v62, v63
	v_cvt_pk_bf16_f32 v58, v58, v59
	v_cvt_pk_bf16_f32 v59, v66, v67
	global_store_dwordx4 v[70:71], v[56:59], off
	s_waitcnt vmcnt(15)
	s_nop 1
	v_mov_b32_e32 v56, v198
	v_mov_b32_e32 v57, v199
	v_mov_b32_e32 v58, v200
	v_mov_b32_e32 v59, v201
	s_waitcnt lgkmcnt(0)
	v_lshlrev_b32_e32 v60, 16, v56
	v_and_b32_e32 v61, 0xffff0000, v56
	v_lshlrev_b32_e32 v56, 16, v57
	v_and_b32_e32 v57, 0xffff0000, v57
	v_lshlrev_b32_e32 v62, 16, v58
	v_and_b32_e32 v63, 0xffff0000, v58
	v_lshlrev_b32_e32 v58, 16, v59
	v_and_b32_e32 v59, 0xffff0000, v59
	v_pk_add_f32 v[54:55], v[54:55], v[56:57]
	v_pk_add_f32 v[52:53], v[52:53], v[60:61]
	v_pk_add_f32 v[56:57], v[50:51], v[58:59]
	v_pk_add_f32 v[50:51], v[48:49], v[62:63]
	v_cvt_pk_bf16_f32 v48, v52, v53
	v_cvt_pk_bf16_f32 v49, v54, v55
	v_cvt_pk_bf16_f32 v50, v50, v51
	v_cvt_pk_bf16_f32 v51, v56, v57
	global_store_dwordx4 v[64:65], v[48:51], off offset:256
	s_nop 1
	v_lshl_add_u64 v[48:49], v[144:145], 0, s[2:3]
	s_mov_b32 s2, 0x90000
	v_add_co_u32_e32 v54, vcc, s2, v144
	s_mov_b64 s[2:3], 0xa0000
	s_nop 0
	v_addc_co_u32_e32 v55, vcc, 0, v145, vcc
	s_waitcnt vmcnt(15)
	s_nop 1
	v_mov_b32_e32 v50, v202
	v_mov_b32_e32 v51, v203
	v_mov_b32_e32 v52, v204
	v_mov_b32_e32 v53, v205
	s_waitcnt lgkmcnt(0)
	v_lshlrev_b32_e32 v56, 16, v50
	v_and_b32_e32 v57, 0xffff0000, v50
	v_lshlrev_b32_e32 v50, 16, v51
	v_and_b32_e32 v51, 0xffff0000, v51
	v_lshlrev_b32_e32 v58, 16, v52
	v_and_b32_e32 v59, 0xffff0000, v52
	v_lshlrev_b32_e32 v52, 16, v53
	v_and_b32_e32 v53, 0xffff0000, v53
	v_pk_add_f32 v[46:47], v[46:47], v[50:51]
	v_pk_add_f32 v[44:45], v[44:45], v[56:57]
	v_pk_add_f32 v[50:51], v[42:43], v[52:53]
	v_pk_add_f32 v[42:43], v[40:41], v[58:59]
	v_cvt_pk_bf16_f32 v40, v44, v45
	v_cvt_pk_bf16_f32 v41, v46, v47
	v_cvt_pk_bf16_f32 v42, v42, v43
	v_cvt_pk_bf16_f32 v43, v50, v51
	global_store_dwordx4 v[54:55], v[40:43], off
	s_waitcnt vmcnt(15)
	s_nop 1
	v_mov_b32_e32 v40, v206
	v_mov_b32_e32 v41, v207
	v_mov_b32_e32 v42, v208
	v_mov_b32_e32 v43, v209
	s_waitcnt lgkmcnt(0)
; DI unsigned pack2(float a, float b) { f32x2 v = {a, b}; hwbf16x2 r = __builtin_convertvector(v, hwbf16x2); return __builtin_bit_cast(unsigned, r); }
; DI float bflo(unsigned w) { return __uint_as_float(w << 16); }
; DI float bfhi(unsigned w) { return __uint_as_float(w & 0xffff0000u); }
;     DI const char* a(const Unit& u) const { return (const char*)(A + (size_t)u.pm * BM * lda); }
;     DI const char* a(const Unit& u) const { return (const char*)(A + (size_t)u.pm * BM * 2048 + (u.pn >> 1) * 512); }
;     DI void operator()(const f32x4 (&acc)[2][2][4][2], const Unit& u, int wr, int wc, int fr, int fq) const {
;     ...
;         for (int ai = 0; ai < 2; ++ai)
; #pragma unroll
;             for (int m = 0; m < 4; ++m) { const size_t ro = (size_t)(row0 + ai * HALF + m * 16) * D + col0;
; #pragma unroll
;                 for (int bj = 0; bj < 2; ++bj) {
;                     f32x4 x0, x1;
;                     if constexpr (IB) { const u32x4 w = *(const u32x4*)((const bf16_t*)Xin + ro + bj * HALF);
;                         x0 = (f32x4){bflo(w[0]), bfhi(w[0]), bflo(w[1]), bfhi(w[1])}; x1 = (f32x4){bflo(w[2]), bfhi(w[2]), bflo(w[3]), bfhi(w[3])}; }
;                     else { x0 = *(const f32x4*)((const float*)Xin + ro + bj * HALF); x1 = *(const f32x4*)((const float*)Xin + ro + bj * HALF + 4); }
;                     x0 += acc[ai][bj][m][0] * sc[bj][0]; x1 += acc[ai][bj][m][1] * sc[bj][1];
;                     if constexpr (OB) { u32x4 o; o[0] = pack2(x0[0], x0[1]); o[1] = pack2(x0[2], x0[3]); o[2] = pack2(x1[0], x1[1]); o[3] = pack2(x1[2], x1[3]);
;                         *(u32x4*)((bf16_t*)Xout + ro + bj * HALF) = o; }
;                     else { *(f32x4*)((float*)Xout + ro + bj * HALF) = x0; *(f32x4*)((float*)Xout + ro + bj * HALF + 4) = x1; } } }
; template <class Map, class Epi>
; DI void gemm_phase(LAS unsigned char* lds, const Map& MP, const Epi& E, const int nM, const int nN, const int K, const int lda, const int ldb) {
;     ...
;         if (!has_next) break;
; #pragma unroll
;         for (int a = 0; a < 2; ++a)
; #pragma unroll
;             for (int b = 0; b < 2; ++b)
; #pragma unroll
;                 for (int m = 0; m < 4; ++m)
; #pragma unroll
;                     for (int n = 0; n < 2; ++n) acc[a][b][m][n] = (f32x4){0.f, 0.f, 0.f, 0.f};
;         cur = nxt; cA = nA; cB = nB; ++ui;
;     }
;     PG8_WAIT_V(0);
;     if (wr == 0) PG8_BAR;
;     PG8_BAR;
	v_lshlrev_b32_e32 v44, 16, v40
	v_and_b32_e32 v45, 0xffff0000, v40
	v_lshlrev_b32_e32 v40, 16, v41
	v_and_b32_e32 v41, 0xffff0000, v41
	v_lshlrev_b32_e32 v46, 16, v42
	v_and_b32_e32 v47, 0xffff0000, v42
	v_lshlrev_b32_e32 v42, 16, v43
	v_and_b32_e32 v43, 0xffff0000, v43
	v_pk_add_f32 v[38:39], v[38:39], v[40:41]
	v_pk_add_f32 v[36:37], v[36:37], v[44:45]
	v_pk_add_f32 v[40:41], v[34:35], v[42:43]
	v_pk_add_f32 v[34:35], v[32:33], v[46:47]
	v_cvt_pk_bf16_f32 v32, v36, v37
	v_cvt_pk_bf16_f32 v33, v38, v39
	v_cvt_pk_bf16_f32 v34, v34, v35
	v_cvt_pk_bf16_f32 v35, v40, v41
	global_store_dwordx4 v[48:49], v[32:35], off offset:256
	s_nop 1
	v_lshl_add_u64 v[32:33], v[144:145], 0, s[2:3]
	s_mov_b32 s2, 0xa0000
	v_add_co_u32_e32 v38, vcc, s2, v144
	s_mov_b64 s[2:3], 0xb0000
	s_nop 0
	v_addc_co_u32_e32 v39, vcc, 0, v145, vcc
	s_waitcnt vmcnt(15)
	s_nop 1
	v_mov_b32_e32 v34, v210
	v_mov_b32_e32 v35, v211
	v_mov_b32_e32 v36, v212
	v_mov_b32_e32 v37, v213
	s_waitcnt lgkmcnt(0)
	v_lshlrev_b32_e32 v40, 16, v34
	v_and_b32_e32 v41, 0xffff0000, v34
	v_lshlrev_b32_e32 v34, 16, v35
	v_and_b32_e32 v35, 0xffff0000, v35
	v_lshlrev_b32_e32 v42, 16, v36
	v_and_b32_e32 v43, 0xffff0000, v36
	v_lshlrev_b32_e32 v36, 16, v37
	v_and_b32_e32 v37, 0xffff0000, v37
	v_pk_add_f32 v[30:31], v[30:31], v[34:35]
	v_pk_add_f32 v[28:29], v[28:29], v[40:41]
	v_pk_add_f32 v[34:35], v[26:27], v[36:37]
	v_pk_add_f32 v[26:27], v[24:25], v[42:43]
	v_cvt_pk_bf16_f32 v24, v28, v29
	v_cvt_pk_bf16_f32 v25, v30, v31
	v_cvt_pk_bf16_f32 v26, v26, v27
	v_cvt_pk_bf16_f32 v27, v34, v35
	global_store_dwordx4 v[38:39], v[24:27], off
	s_waitcnt vmcnt(15)
	s_nop 1
	v_mov_b32_e32 v24, v214
	v_mov_b32_e32 v25, v215
	v_mov_b32_e32 v26, v216
	v_mov_b32_e32 v27, v217
	s_waitcnt lgkmcnt(0)
	v_lshlrev_b32_e32 v28, 16, v24
	v_and_b32_e32 v29, 0xffff0000, v24
	v_lshlrev_b32_e32 v24, 16, v25
	v_and_b32_e32 v25, 0xffff0000, v25
	v_lshlrev_b32_e32 v30, 16, v26
	v_and_b32_e32 v31, 0xffff0000, v26
	v_lshlrev_b32_e32 v26, 16, v27
	v_and_b32_e32 v27, 0xffff0000, v27
	v_pk_add_f32 v[22:23], v[22:23], v[24:25]
	v_pk_add_f32 v[20:21], v[20:21], v[28:29]
	v_pk_add_f32 v[24:25], v[18:19], v[26:27]
	v_pk_add_f32 v[18:19], v[16:17], v[30:31]
	v_cvt_pk_bf16_f32 v16, v20, v21
	v_cvt_pk_bf16_f32 v17, v22, v23
	v_cvt_pk_bf16_f32 v18, v18, v19
	v_cvt_pk_bf16_f32 v19, v24, v25
	global_store_dwordx4 v[32:33], v[16:19], off offset:256
	s_nop 1
	v_lshl_add_u64 v[16:17], v[144:145], 0, s[2:3]
	s_mov_b32 s2, 0xb0000
	v_add_co_u32_e32 v22, vcc, s2, v144
	s_mov_b32 s2, s53
	s_nop 0
	v_addc_co_u32_e32 v23, vcc, 0, v145, vcc
	s_waitcnt vmcnt(15)
	s_nop 1
	v_mov_b32_e32 v18, v248
	v_mov_b32_e32 v19, v249
	v_mov_b32_e32 v20, v250
	v_mov_b32_e32 v21, v251
	s_and_b64 vcc, exec, s[40:41]
	s_waitcnt lgkmcnt(0)
	v_lshlrev_b32_e32 v24, 16, v18
	v_and_b32_e32 v25, 0xffff0000, v18
	v_lshlrev_b32_e32 v18, 16, v19
	v_and_b32_e32 v19, 0xffff0000, v19
	v_lshlrev_b32_e32 v26, 16, v20
	v_and_b32_e32 v27, 0xffff0000, v20
	v_lshlrev_b32_e32 v20, 16, v21
	v_and_b32_e32 v21, 0xffff0000, v21
	v_pk_add_f32 v[14:15], v[14:15], v[18:19]
	v_pk_add_f32 v[12:13], v[12:13], v[24:25]
	v_pk_add_f32 v[18:19], v[10:11], v[20:21]
	v_pk_add_f32 v[10:11], v[8:9], v[26:27]
	v_cvt_pk_bf16_f32 v8, v12, v13
	v_cvt_pk_bf16_f32 v9, v14, v15
	v_cvt_pk_bf16_f32 v10, v10, v11
	v_cvt_pk_bf16_f32 v11, v18, v19
	global_store_dwordx4 v[22:23], v[8:11], off
	s_waitcnt vmcnt(15)
	s_nop 1
	v_mov_b32_e32 v8, v252
	v_mov_b32_e32 v9, v253
	v_mov_b32_e32 v10, v254
	v_mov_b32_e32 v11, v255
	s_waitcnt lgkmcnt(0)
	v_lshlrev_b32_e32 v12, 16, v8
	v_and_b32_e32 v13, 0xffff0000, v8
	v_lshlrev_b32_e32 v8, 16, v9
	v_and_b32_e32 v9, 0xffff0000, v9
	v_lshlrev_b32_e32 v14, 16, v10
	v_and_b32_e32 v15, 0xffff0000, v10
	v_lshlrev_b32_e32 v10, 16, v11
	v_and_b32_e32 v11, 0xffff0000, v11
	v_pk_add_f32 v[6:7], v[6:7], v[8:9]
	v_pk_add_f32 v[4:5], v[4:5], v[12:13]
	v_pk_add_f32 v[8:9], v[2:3], v[10:11]
	v_pk_add_f32 v[2:3], v[0:1], v[14:15]
	v_cvt_pk_bf16_f32 v0, v4, v5
	v_cvt_pk_bf16_f32 v1, v6, v7
	v_cvt_pk_bf16_f32 v2, v2, v3
	v_cvt_pk_bf16_f32 v3, v8, v9
	global_store_dwordx4 v[16:17], v[0:3], off offset:256
	s_cbranch_vccz .LBB1_2071
	s_waitcnt vmcnt(0)
	s_cmpk_gt_u32 s17, 0xff
	s_cbranch_scc1 .LBB1_2082
	s_barrier

; #define PG8_STAGE(bufoff, gbase, voff) do { _Pragma("unroll") for (int _i = 0; _i < 2; ++_i) \
;         __builtin_amdgcn_global_load_lds((const unsigned*)((const char*)(gbase) + (voff)[_i]), (LAS unsigned*)(lds + (bufoff) + ldsw + _i * 8192), 16, 0, 0); } while (0)
; #define PG8_LDA(dst, b, h) do { _Pragma("unroll") for (int m = 0; m < 4; ++m) _Pragma("unroll") for (int k = 0; k < 2; ++k) dst[m][k] = *(const LAS bf16x8*)(lds + PG8_SA(b, h) + aoff + m * 2048 + k * 1024); } while (0)
; #define PG8_LDB(dst, b, h) do { _Pragma("unroll") for (int n = 0; n < 2; ++n) _Pragma("unroll") for (int k = 0; k < 2; ++k) dst[n][k] = *(const LAS bf16x8*)(lds + PG8_SB(b, h) + boff + n * 2048 + k * 1024); } while (0)
; #define PG8_MMA(ai, bj, At, Bt) do { __builtin_amdgcn_s_setprio(1); _Pragma("unroll") for (int m = 0; m < 4; ++m) _Pragma("unroll") for (int n = 0; n < 2; ++n) _Pragma("unroll") for (int k = 0; k < 2; ++k) \
;         acc[ai][bj][m][n] = __builtin_amdgcn_mfma_f32_16x16x32_bf16(Bt[n][k], At[m][k], acc[ai][bj][m][n], 0, 0, 0); __builtin_amdgcn_s_setprio(0); } while (0)
; #define PG8_WAIT_L(n) asm volatile("s_waitcnt lgkmcnt(" #n ")" ::: "memory")
; #define PG8_BAR __builtin_amdgcn_s_barrier()
; #define PG8_SCHED __builtin_amdgcn_sched_barrier(0)
; template <class Map, class Epi>
; DI void gemm_phase(LAS unsigned char* lds, const Map& MP, const Epi& E, const int nM, const int nN, const int K, const int lda, const int ldb) {
;     ...
;             PG8_LDB(B0, 0, 0); PG8_SCHED; PG8_LDA(At, 0, 0); PG8_STAGE(PG8_SA(1, 1), a1 + hstepA, voffA);
;             PG8_WAIT_L(8); PG8_BAR; PG8_WAIT_L(0); PG8_MMA(0, 0, At, B0); PG8_BAR; PG8_SCHED;
;             PG8_LDB(B1, 0, 1); PG8_STAGE(PG8_SB(0, 0), b2, voffB);
;             PG8_BAR; PG8_WAIT_L(0); PG8_MMA(0, 1, At, B1); PG8_BAR;
;             PG8_LDA(At, 0, 1); PG8_STAGE(PG8_SA(0, 0), a2, voffA);
;             PG8_BAR; PG8_WAIT_L(0); PG8_MMA(1, 0, At, B0); PG8_BAR; PG8_SCHED;
.LBB1_2339:
	ds_read_b128 v[40:43], v165
	ds_read_b128 v[44:47], v165 offset:1024
	ds_read_b128 v[56:59], v165 offset:2048
	ds_read_b128 v[60:63], v165 offset:3072
	s_add_u32 s12, s10, 0xfff80080
	s_addc_u32 s13, s11, -1
	s_cmp_eq_u32 s3, 4
	s_cselect_b32 s15, s38, s13
	s_cselect_b32 s14, s39, s12
	s_cselect_b32 s13, s48, s56
	s_cselect_b32 s12, s49, s53
	s_add_i32 m0, s9, 0xc000
	ds_read_b128 v[168:171], v166
	ds_read_b128 v[172:175], v166 offset:1024
	ds_read_b128 v[176:179], v166 offset:2048
	ds_read_b128 v[180:183], v166 offset:3072
	ds_read_b128 v[184:187], v166 offset:4096
	ds_read_b128 v[188:191], v166 offset:5120
	ds_read_b128 v[192:195], v166 offset:6144
	ds_read_b128 v[198:201], v166 offset:7168
	global_load_lds_dwordx4 v154, s[10:11]
	s_add_i32 m0, s9, 0xe000
	s_nop 0
	global_load_lds_dwordx4 v152, s[10:11]
	s_waitcnt lgkmcnt(8)
	s_barrier
	s_setprio 1
	s_waitcnt lgkmcnt(7)
	v_mfma_f32_16x16x32_bf16 v[140:143], v[40:43], v[168:171], v[140:143]
	v_mfma_f32_16x16x32_bf16 v[136:139], v[56:59], v[168:171], v[136:139]
	s_waitcnt lgkmcnt(5)
	v_mfma_f32_16x16x32_bf16 v[124:127], v[40:43], v[176:179], v[124:127]
	v_mfma_f32_16x16x32_bf16 v[120:123], v[56:59], v[176:179], v[120:123]
	s_waitcnt lgkmcnt(3)
	v_mfma_f32_16x16x32_bf16 v[108:111], v[40:43], v[184:187], v[108:111]
	v_mfma_f32_16x16x32_bf16 v[104:107], v[56:59], v[184:187], v[104:107]
	s_waitcnt lgkmcnt(1)
	v_mfma_f32_16x16x32_bf16 v[92:95], v[40:43], v[192:195], v[92:95]
	v_mfma_f32_16x16x32_bf16 v[88:91], v[56:59], v[192:195], v[88:91]
	v_mfma_f32_16x16x32_bf16 v[140:143], v[44:47], v[172:175], v[140:143]
	v_mfma_f32_16x16x32_bf16 v[136:139], v[60:63], v[172:175], v[136:139]
	v_mfma_f32_16x16x32_bf16 v[124:127], v[44:47], v[180:183], v[124:127]
	v_mfma_f32_16x16x32_bf16 v[120:123], v[60:63], v[180:183], v[120:123]
	v_mfma_f32_16x16x32_bf16 v[108:111], v[44:47], v[188:191], v[108:111]
	v_mfma_f32_16x16x32_bf16 v[104:107], v[60:63], v[188:191], v[104:107]
	s_waitcnt lgkmcnt(0)
	v_mfma_f32_16x16x32_bf16 v[92:95], v[44:47], v[198:201], v[92:95]
	v_mfma_f32_16x16x32_bf16 v[88:91], v[60:63], v[198:201], v[88:91]
	s_setprio 0
	s_barrier
	s_add_i32 s57, s35, s22
	v_lshl_add_u64 v[160:161], s[12:13], 0, v[148:149]
	s_mov_b32 m0, s57
	ds_read_b128 v[202:205], v167
	ds_read_b128 v[206:209], v167 offset:1024
	ds_read_b128 v[210:213], v167 offset:2048
	ds_read_b128 v[214:217], v167 offset:3072
	global_load_lds_dwordx4 v[160:161], off
	v_lshl_add_u64 v[218:219], s[12:13], 0, v[144:145]
	s_add_i32 m0, s57, 0x2000
	s_nop 0
	global_load_lds_dwordx4 v[218:219], off
	s_barrier
	s_setprio 1
	s_waitcnt lgkmcnt(3)
	v_mfma_f32_16x16x32_bf16 v[132:135], v[202:205], v[168:171], v[132:135]
	s_waitcnt lgkmcnt(1)
	v_mfma_f32_16x16x32_bf16 v[128:131], v[210:213], v[168:171], v[128:131]
	v_mfma_f32_16x16x32_bf16 v[116:119], v[202:205], v[176:179], v[116:119]
	v_mfma_f32_16x16x32_bf16 v[112:115], v[210:213], v[176:179], v[112:115]
	v_mfma_f32_16x16x32_bf16 v[100:103], v[202:205], v[184:187], v[100:103]
	v_mfma_f32_16x16x32_bf16 v[96:99], v[210:213], v[184:187], v[96:99]
	v_mfma_f32_16x16x32_bf16 v[84:87], v[202:205], v[192:195], v[84:87]
	v_mfma_f32_16x16x32_bf16 v[80:83], v[210:213], v[192:195], v[80:83]
	v_mfma_f32_16x16x32_bf16 v[132:135], v[206:209], v[172:175], v[132:135]
	s_waitcnt lgkmcnt(0)
	v_mfma_f32_16x16x32_bf16 v[128:131], v[214:217], v[172:175], v[128:131]
	v_mfma_f32_16x16x32_bf16 v[116:119], v[206:209], v[180:183], v[116:119]
	v_mfma_f32_16x16x32_bf16 v[112:115], v[214:217], v[180:183], v[112:115]
	v_mfma_f32_16x16x32_bf16 v[100:103], v[206:209], v[188:191], v[100:103]
	v_mfma_f32_16x16x32_bf16 v[96:99], v[214:217], v[188:191], v[96:99]
	v_mfma_f32_16x16x32_bf16 v[84:87], v[206:209], v[198:201], v[84:87]
	v_mfma_f32_16x16x32_bf16 v[80:83], v[214:217], v[198:201], v[80:83]
	s_setprio 0
	s_mov_b32 m0, s9
	v_lshl_add_u64 v[220:221], s[14:15], 0, v[150:151]
	s_barrier
	ds_read_b128 v[168:171], v166 offset:16384
	ds_read_b128 v[172:175], v166 offset:17408
	ds_read_b128 v[176:179], v166 offset:18432
	ds_read_b128 v[180:183], v166 offset:19456
	ds_read_b128 v[184:187], v166 offset:20480
	ds_read_b128 v[188:191], v166 offset:21504
	ds_read_b128 v[192:195], v166 offset:22528
	ds_read_b128 v[198:201], v166 offset:23552
	global_load_lds_dwordx4 v[220:221], off
	v_lshl_add_u64 v[222:223], s[14:15], 0, v[146:147]
	s_mov_b32 m0, s24
	s_nop 0
	global_load_lds_dwordx4 v[222:223], off
	s_barrier
	s_setprio 1
	s_waitcnt lgkmcnt(7)
	v_mfma_f32_16x16x32_bf16 v[76:79], v[40:43], v[168:171], v[76:79]
	v_mfma_f32_16x16x32_bf16 v[72:75], v[56:59], v[168:171], v[72:75]
	s_waitcnt lgkmcnt(5)
	v_mfma_f32_16x16x32_bf16 v[52:55], v[40:43], v[176:179], v[52:55]
	v_mfma_f32_16x16x32_bf16 v[48:51], v[56:59], v[176:179], v[48:51]
	s_waitcnt lgkmcnt(3)
	v_mfma_f32_16x16x32_bf16 v[28:31], v[40:43], v[184:187], v[28:31]
	v_mfma_f32_16x16x32_bf16 v[24:27], v[56:59], v[184:187], v[24:27]
	s_waitcnt lgkmcnt(1)
	v_mfma_f32_16x16x32_bf16 v[12:15], v[40:43], v[192:195], v[12:15]
	v_mfma_f32_16x16x32_bf16 v[8:11], v[56:59], v[192:195], v[8:11]
	v_mfma_f32_16x16x32_bf16 v[76:79], v[44:47], v[172:175], v[76:79]
	v_mfma_f32_16x16x32_bf16 v[72:75], v[60:63], v[172:175], v[72:75]
	v_mfma_f32_16x16x32_bf16 v[52:55], v[44:47], v[180:183], v[52:55]
	v_mfma_f32_16x16x32_bf16 v[48:51], v[60:63], v[180:183], v[48:51]
	v_mfma_f32_16x16x32_bf16 v[28:31], v[44:47], v[188:191], v[28:31]
	v_mfma_f32_16x16x32_bf16 v[24:27], v[60:63], v[188:191], v[24:27]
	s_waitcnt lgkmcnt(0)
	v_mfma_f32_16x16x32_bf16 v[12:15], v[44:47], v[198:201], v[12:15]
	v_mfma_f32_16x16x32_bf16 v[8:11], v[60:63], v[198:201], v[8:11]
	s_setprio 0
	s_barrier
; #define PG8_STAGE(bufoff, gbase, voff) do { _Pragma("unroll") for (int _i = 0; _i < 2; ++_i) \
;         __builtin_amdgcn_global_load_lds((const unsigned*)((const char*)(gbase) + (voff)[_i]), (LAS unsigned*)(lds + (bufoff) + ldsw + _i * 8192), 16, 0, 0); } while (0)
; #define PG8_LDA(dst, b, h) do { _Pragma("unroll") for (int m = 0; m < 4; ++m) _Pragma("unroll") for (int k = 0; k < 2; ++k) dst[m][k] = *(const LAS bf16x8*)(lds + PG8_SA(b, h) + aoff + m * 2048 + k * 1024); } while (0)
; #define PG8_LDB(dst, b, h) do { _Pragma("unroll") for (int n = 0; n < 2; ++n) _Pragma("unroll") for (int k = 0; k < 2; ++k) dst[n][k] = *(const LAS bf16x8*)(lds + PG8_SB(b, h) + boff + n * 2048 + k * 1024); } while (0)
; #define PG8_MMA(ai, bj, At, Bt) do { __builtin_amdgcn_s_setprio(1); _Pragma("unroll") for (int m = 0; m < 4; ++m) _Pragma("unroll") for (int n = 0; n < 2; ++n) _Pragma("unroll") for (int k = 0; k < 2; ++k) \
;         acc[ai][bj][m][n] = __builtin_amdgcn_mfma_f32_16x16x32_bf16(Bt[n][k], At[m][k], acc[ai][bj][m][n], 0, 0, 0); __builtin_amdgcn_s_setprio(0); } while (0)
; #define PG8_WAIT_V(n) asm volatile("s_waitcnt vmcnt(" #n ")" ::: "memory")
; #define PG8_WAIT_L(n) asm volatile("s_waitcnt lgkmcnt(" #n ")" ::: "memory")
; #define PG8_BAR __builtin_amdgcn_s_barrier()
; #define PG8_SCHED __builtin_amdgcn_sched_barrier(0)
; template <class Map, class Epi>
; DI void gemm_phase(LAS unsigned char* lds, const Map& MP, const Epi& E, const int nM, const int nN, const int K, const int lda, const int ldb) {
;     ...
;             PG8_STAGE(PG8_SB(0, 1), b2 + hstepB, voffB);
;             PG8_WAIT_V(6); PG8_BAR; PG8_MMA(1, 1, At, B1); PG8_BAR;
;             PG8_LDB(B0, 1, 0); PG8_SCHED; PG8_LDA(At, 1, 0); PG8_STAGE(PG8_SA(0, 1), a2 + hstepA, voffA);
;             PG8_WAIT_L(8); PG8_BAR; PG8_WAIT_L(0); PG8_MMA(0, 0, At, B0); PG8_BAR; PG8_SCHED;
;             PG8_LDB(B1, 1, 1); PG8_STAGE(PG8_SB(1, 0), b3, voffB);
;             PG8_BAR; PG8_WAIT_L(0); PG8_MMA(0, 1, At, B1); PG8_BAR;
;             PG8_LDA(At, 1, 1); PG8_STAGE(PG8_SA(1, 0), a3, voffA);
;             PG8_BAR; PG8_WAIT_L(0); PG8_MMA(1, 0, At, B0); PG8_BAR; PG8_SCHED;
	s_add_u32 s58, s12, 0x20000
	s_addc_u32 s59, s13, 0
	s_add_i32 s57, s36, s22
	s_mov_b32 m0, s57
	s_nop 0
	global_load_lds_dwordx4 v148, s[58:59]
	s_add_i32 m0, s57, 0x2000
	s_nop 0
	global_load_lds_dwordx4 v144, s[58:59]
	s_waitcnt vmcnt(6)
	s_barrier
	s_setprio 1
	v_mfma_f32_16x16x32_bf16 v[36:39], v[202:205], v[176:179], v[36:39]
	v_mfma_f32_16x16x32_bf16 v[32:35], v[210:213], v[176:179], v[32:35]
	v_mfma_f32_16x16x32_bf16 v[20:23], v[202:205], v[184:187], v[20:23]
	v_mfma_f32_16x16x32_bf16 v[16:19], v[210:213], v[184:187], v[16:19]
	v_mfma_f32_16x16x32_bf16 v[4:7], v[202:205], v[192:195], v[4:7]
	v_mfma_f32_16x16x32_bf16 v[0:3], v[210:213], v[192:195], v[0:3]
	v_mfma_f32_16x16x32_bf16 v[40:43], v[202:205], v[168:171], v[68:71]
	v_mfma_f32_16x16x32_bf16 v[44:47], v[210:213], v[168:171], v[64:67]
	v_mfma_f32_16x16x32_bf16 v[36:39], v[206:209], v[180:183], v[36:39]
	v_mfma_f32_16x16x32_bf16 v[32:35], v[214:217], v[180:183], v[32:35]
	v_mfma_f32_16x16x32_bf16 v[20:23], v[206:209], v[188:191], v[20:23]
	v_mfma_f32_16x16x32_bf16 v[16:19], v[214:217], v[188:191], v[16:19]
	v_mfma_f32_16x16x32_bf16 v[4:7], v[206:209], v[198:201], v[4:7]
	v_mfma_f32_16x16x32_bf16 v[0:3], v[214:217], v[198:201], v[0:3]
	v_mfma_f32_16x16x32_bf16 v[40:43], v[206:209], v[172:175], v[40:43]
	v_mfma_f32_16x16x32_bf16 v[44:47], v[214:217], v[172:175], v[44:47]
	s_setprio 0
	s_add_i32 s57, 0, 0x18000
	v_add_u32_e32 v68, s57, v164
	s_barrier
	ds_read_b128 v[56:59], v68
	ds_read_b128 v[60:63], v68 offset:1024
	ds_read_b128 v[64:67], v68 offset:2048
	ds_read_b128 v[68:71], v68 offset:3072
	s_add_u32 s14, s14, 0x80000
	s_addc_u32 s15, s15, 0
	s_mov_b32 m0, s25
	ds_read_b128 v[168:171], v166 offset:32768
	ds_read_b128 v[172:175], v166 offset:33792
	ds_read_b128 v[176:179], v166 offset:34816
	ds_read_b128 v[180:183], v166 offset:35840
	ds_read_b128 v[184:187], v166 offset:36864
	ds_read_b128 v[188:191], v166 offset:37888
	ds_read_b128 v[192:195], v166 offset:38912
	ds_read_b128 v[198:201], v166 offset:39936
	global_load_lds_dwordx4 v150, s[14:15]
	s_mov_b32 m0, s26
	s_nop 0
	global_load_lds_dwordx4 v146, s[14:15]
	s_waitcnt lgkmcnt(8)
	s_barrier
	s_setprio 1
	s_waitcnt lgkmcnt(7)
	v_mfma_f32_16x16x32_bf16 v[140:143], v[56:59], v[168:171], v[140:143]
	v_mfma_f32_16x16x32_bf16 v[136:139], v[64:67], v[168:171], v[136:139]
	s_waitcnt lgkmcnt(5)
	v_mfma_f32_16x16x32_bf16 v[124:127], v[56:59], v[176:179], v[124:127]
	v_mfma_f32_16x16x32_bf16 v[120:123], v[64:67], v[176:179], v[120:123]
	s_waitcnt lgkmcnt(3)
	v_mfma_f32_16x16x32_bf16 v[108:111], v[56:59], v[184:187], v[108:111]
	v_mfma_f32_16x16x32_bf16 v[104:107], v[64:67], v[184:187], v[104:107]
	s_waitcnt lgkmcnt(1)
	v_mfma_f32_16x16x32_bf16 v[92:95], v[56:59], v[192:195], v[92:95]
	v_mfma_f32_16x16x32_bf16 v[88:91], v[64:67], v[192:195], v[88:91]
	v_mfma_f32_16x16x32_bf16 v[140:143], v[60:63], v[172:175], v[140:143]
	v_mfma_f32_16x16x32_bf16 v[136:139], v[68:71], v[172:175], v[136:139]
	v_mfma_f32_16x16x32_bf16 v[124:127], v[60:63], v[180:183], v[124:127]
	v_mfma_f32_16x16x32_bf16 v[120:123], v[68:71], v[180:183], v[120:123]
	v_mfma_f32_16x16x32_bf16 v[108:111], v[60:63], v[188:191], v[108:111]
	v_mfma_f32_16x16x32_bf16 v[104:107], v[68:71], v[188:191], v[104:107]
	s_waitcnt lgkmcnt(0)
	v_mfma_f32_16x16x32_bf16 v[92:95], v[60:63], v[198:201], v[92:95]
	v_mfma_f32_16x16x32_bf16 v[88:91], v[68:71], v[198:201], v[88:91]
	s_setprio 0
	s_barrier
	s_add_i32 s14, 0, 0x1c000
	s_add_i32 s15, s57, s22
	v_add_u32_e32 v196, s14, v164
	v_lshl_add_u64 v[160:161], v[160:161], 0, s[46:47]
	s_mov_b32 m0, s15
	ds_read_b128 v[202:205], v196
	ds_read_b128 v[206:209], v196 offset:1024
	ds_read_b128 v[210:213], v196 offset:2048
	ds_read_b128 v[214:217], v196 offset:3072
	global_load_lds_dwordx4 v[160:161], off
	v_lshl_add_u64 v[160:161], v[218:219], 0, s[46:47]
	s_add_i32 m0, s15, 0x2000
	s_nop 0
	global_load_lds_dwordx4 v[160:161], off
	s_barrier
	s_setprio 1
	s_waitcnt lgkmcnt(3)
	v_mfma_f32_16x16x32_bf16 v[132:135], v[202:205], v[168:171], v[132:135]
	s_waitcnt lgkmcnt(1)
	v_mfma_f32_16x16x32_bf16 v[128:131], v[210:213], v[168:171], v[128:131]
	v_mfma_f32_16x16x32_bf16 v[116:119], v[202:205], v[176:179], v[116:119]
	v_mfma_f32_16x16x32_bf16 v[112:115], v[210:213], v[176:179], v[112:115]
	v_mfma_f32_16x16x32_bf16 v[100:103], v[202:205], v[184:187], v[100:103]
	v_mfma_f32_16x16x32_bf16 v[96:99], v[210:213], v[184:187], v[96:99]
	v_mfma_f32_16x16x32_bf16 v[84:87], v[202:205], v[192:195], v[84:87]
	v_mfma_f32_16x16x32_bf16 v[80:83], v[210:213], v[192:195], v[80:83]
	v_mfma_f32_16x16x32_bf16 v[132:135], v[206:209], v[172:175], v[132:135]
	s_waitcnt lgkmcnt(0)
	v_mfma_f32_16x16x32_bf16 v[128:131], v[214:217], v[172:175], v[128:131]
	v_mfma_f32_16x16x32_bf16 v[116:119], v[206:209], v[180:183], v[116:119]
	v_mfma_f32_16x16x32_bf16 v[112:115], v[214:217], v[180:183], v[112:115]
	v_mfma_f32_16x16x32_bf16 v[100:103], v[206:209], v[188:191], v[100:103]
	v_mfma_f32_16x16x32_bf16 v[96:99], v[214:217], v[188:191], v[96:99]
	v_mfma_f32_16x16x32_bf16 v[84:87], v[206:209], v[198:201], v[84:87]
	v_mfma_f32_16x16x32_bf16 v[80:83], v[214:217], v[198:201], v[80:83]
	s_setprio 0
	s_mov_b32 m0, s30
	v_lshl_add_u64 v[160:161], v[220:221], 0, s[46:47]
	s_barrier
	ds_read_b128 v[168:171], v166 offset:49152
	ds_read_b128 v[172:175], v166 offset:50176
	ds_read_b128 v[176:179], v166 offset:51200
	ds_read_b128 v[180:183], v166 offset:52224
	ds_read_b128 v[184:187], v166 offset:53248
	ds_read_b128 v[188:191], v166 offset:54272
	ds_read_b128 v[192:195], v166 offset:55296
	ds_read_b128 v[198:201], v166 offset:56320
	global_load_lds_dwordx4 v[160:161], off
	v_lshl_add_u64 v[160:161], v[222:223], 0, s[46:47]
	s_mov_b32 m0, s31
	s_nop 0
	global_load_lds_dwordx4 v[160:161], off
	s_barrier
; DI unsigned pack2(float a, float b) { f32x2 v = {a, b}; hwbf16x2 r = __builtin_convertvector(v, hwbf16x2); return __builtin_bit_cast(unsigned, r); }
; DI float bflo(unsigned w) { return __uint_as_float(w << 16); }
; DI float bfhi(unsigned w) { return __uint_as_float(w & 0xffff0000u); }
; #define PG8_WAIT_V(n) asm volatile("s_waitcnt vmcnt(" #n ")" ::: "memory")
;     DI void operator()(const f32x4 (&acc)[2][2][4][2], const Unit& u, int wr, int wc, int fr, int fq) const {
;         const int row0 = u.pm * BM + wr * 64 + fr, col0 = u.pn * BM + wc * 32 + 8 * fq;
;         f32x4 sc[2][2];
; #pragma unroll
;         for (int bj = 0; bj < 2; ++bj)
; #pragma unroll
;             for (int n = 0; n < 2; ++n) sc[bj][n] = scale ? *(const f32x4*)(scale + col0 + bj * HALF + 4 * n) : (f32x4){1.f, 1.f, 1.f, 1.f};
; #pragma unroll
;         for (int ai = 0; ai < 2; ++ai)
; #pragma unroll
;             for (int m = 0; m < 4; ++m) { const size_t ro = (size_t)(row0 + ai * HALF + m * 16) * D + col0;
; #pragma unroll
;                 for (int bj = 0; bj < 2; ++bj) {
;                     f32x4 x0, x1;
;                     if constexpr (IB) { const u32x4 w = *(const u32x4*)((const bf16_t*)Xin + ro + bj * HALF);
;                         x0 = (f32x4){bflo(w[0]), bfhi(w[0]), bflo(w[1]), bfhi(w[1])}; x1 = (f32x4){bflo(w[2]), bfhi(w[2]), bflo(w[3]), bfhi(w[3])}; }
;                     else { x0 = *(const f32x4*)((const float*)Xin + ro + bj * HALF); x1 = *(const f32x4*)((const float*)Xin + ro + bj * HALF + 4); }
;                     x0 += acc[ai][bj][m][0] * sc[bj][0]; x1 += acc[ai][bj][m][1] * sc[bj][1];
;                     if constexpr (OB) { u32x4 o; o[0] = pack2(x0[0], x0[1]); o[1] = pack2(x0[2], x0[3]); o[2] = pack2(x1[0], x1[1]); o[3] = pack2(x1[2], x1[3]);
;                         *(u32x4*)((bf16_t*)Xout + ro + bj * HALF) = o; }
;                     else { *(f32x4*)((float*)Xout + ro + bj * HALF) = x0; *(f32x4*)((float*)Xout + ro + bj * HALF + 4) = x1; } } }
; template <class Map, class Epi>
; DI void gemm_phase(LAS unsigned char* lds, const Map& MP, const Epi& E, const int nM, const int nN, const int K, const int lda, const int ldb) {
;     ...
;             PG8_BAR; PG8_WAIT_L(0); PG8_MMA(1, 0, At, B0); PG8_BAR; PG8_SCHED;
;             PG8_STAGE(PG8_SB(1, 1), b3 + hstepB, voffB);
;             PG8_WAIT_V(6); PG8_BAR; PG8_MMA(1, 1, At, B1); PG8_BAR;
	s_setprio 1
	s_waitcnt lgkmcnt(7)
	v_mfma_f32_16x16x32_bf16 v[76:79], v[56:59], v[168:171], v[76:79]
	v_mfma_f32_16x16x32_bf16 v[72:75], v[64:67], v[168:171], v[72:75]
	s_waitcnt lgkmcnt(5)
	v_mfma_f32_16x16x32_bf16 v[52:55], v[56:59], v[176:179], v[52:55]
	v_mfma_f32_16x16x32_bf16 v[48:51], v[64:67], v[176:179], v[48:51]
	s_waitcnt lgkmcnt(3)
	v_mfma_f32_16x16x32_bf16 v[28:31], v[56:59], v[184:187], v[28:31]
	v_mfma_f32_16x16x32_bf16 v[24:27], v[64:67], v[184:187], v[24:27]
	s_waitcnt lgkmcnt(1)
	v_mfma_f32_16x16x32_bf16 v[12:15], v[56:59], v[192:195], v[12:15]
	v_mfma_f32_16x16x32_bf16 v[8:11], v[64:67], v[192:195], v[8:11]
	v_mfma_f32_16x16x32_bf16 v[76:79], v[60:63], v[172:175], v[76:79]
	v_mfma_f32_16x16x32_bf16 v[72:75], v[68:71], v[172:175], v[72:75]
	v_mfma_f32_16x16x32_bf16 v[52:55], v[60:63], v[180:183], v[52:55]
	v_mfma_f32_16x16x32_bf16 v[48:51], v[68:71], v[180:183], v[48:51]
	v_mfma_f32_16x16x32_bf16 v[28:31], v[60:63], v[188:191], v[28:31]
	v_mfma_f32_16x16x32_bf16 v[24:27], v[68:71], v[188:191], v[24:27]
	s_waitcnt lgkmcnt(0)
	v_mfma_f32_16x16x32_bf16 v[12:15], v[60:63], v[198:201], v[12:15]
	v_mfma_f32_16x16x32_bf16 v[8:11], v[68:71], v[198:201], v[8:11]
	s_setprio 0
	s_barrier
	s_add_u32 s12, s12, 0x20080
	s_addc_u32 s13, s13, 0
	s_add_i32 s14, s14, s22
	s_mov_b32 m0, s14
	s_nop 0
	global_load_lds_dwordx4 v148, s[12:13]
	s_add_i32 m0, s14, 0x2000
	s_nop 0
	global_load_lds_dwordx4 v144, s[12:13]
	s_waitcnt vmcnt(6)
	s_barrier
	s_setprio 1
	v_mfma_f32_16x16x32_bf16 v[40:43], v[202:205], v[168:171], v[40:43]
	v_mfma_f32_16x16x32_bf16 v[68:71], v[206:209], v[172:175], v[40:43]
	v_mfma_f32_16x16x32_bf16 v[40:43], v[210:213], v[168:171], v[44:47]
	v_mfma_f32_16x16x32_bf16 v[36:39], v[202:205], v[176:179], v[36:39]
	v_mfma_f32_16x16x32_bf16 v[32:35], v[210:213], v[176:179], v[32:35]
	v_mfma_f32_16x16x32_bf16 v[20:23], v[202:205], v[184:187], v[20:23]
	v_mfma_f32_16x16x32_bf16 v[16:19], v[210:213], v[184:187], v[16:19]
	v_mfma_f32_16x16x32_bf16 v[4:7], v[202:205], v[192:195], v[4:7]
	v_mfma_f32_16x16x32_bf16 v[0:3], v[210:213], v[192:195], v[0:3]
	v_mfma_f32_16x16x32_bf16 v[64:67], v[214:217], v[172:175], v[40:43]
	v_mfma_f32_16x16x32_bf16 v[36:39], v[206:209], v[180:183], v[36:39]
	v_mfma_f32_16x16x32_bf16 v[32:35], v[214:217], v[180:183], v[32:35]
	v_mfma_f32_16x16x32_bf16 v[20:23], v[206:209], v[188:191], v[20:23]
	v_mfma_f32_16x16x32_bf16 v[16:19], v[214:217], v[188:191], v[16:19]
	v_mfma_f32_16x16x32_bf16 v[4:7], v[206:209], v[198:201], v[4:7]
	v_mfma_f32_16x16x32_bf16 v[0:3], v[214:217], v[198:201], v[0:3]
	s_setprio 0
	s_add_i32 s3, s3, 2
	s_add_u32 s53, s53, 0x100
	s_addc_u32 s56, s56, 0
	s_add_u32 s10, s10, 0x100
	s_addc_u32 s11, s11, 0
	s_cmp_gt_u32 s3, 5
	s_barrier
	s_cbranch_scc0 .LBB1_2339
	s_lshl_b32 s2, s2, 8
	v_mov_b32_e32 v40, v163
	v_mov_b32_e32 v168, v162
	s_or_b32 s2, s2, s29
	s_and_b64 vcc, exec, s[40:41]
	v_lshl_add_u32 v160, v40, 3, s2
	s_lshl_b32 s2, s8, 8
	s_add_i32 s2, s2, s28
	v_add_u32_e32 v168, s2, v168
	v_ashrrev_i32_e32 v169, 31, v168
	v_ashrrev_i32_e32 v161, 31, v160
	v_lshlrev_b64 v[168:169], 11, v[168:169]
	v_lshl_add_u64 v[44:45], v[160:161], 2, s[44:45]
	v_lshl_add_u64 v[160:161], v[168:169], 0, v[160:161]
	v_lshlrev_b64 v[160:161], 1, v[160:161]
	v_lshl_add_u64 v[172:173], s[4:5], 0, v[160:161]
	global_load_dwordx4 v[56:59], v[44:45], off offset:16
	global_load_dwordx4 v[60:63], v[44:45], off
	global_load_dwordx4 v[40:43], v[44:45], off offset:528
	s_nop 0
	global_load_dwordx4 v[44:47], v[44:45], off offset:512
	s_mov_b64 s[2:3], 0x10000
	global_load_dwordx4 v[178:181], v[172:173], off
	global_load_dwordx4 v[182:185], v[172:173], off offset:256
	s_mov_b64 s[98:99], 0x10000
	v_lshl_add_u64 v[170:171], v[172:173], 0, s[98:99]
	global_load_dwordx4 v[186:189], v[170:171], off
	global_load_dwordx4 v[190:193], v[170:171], off offset:256
	s_mov_b64 s[98:99], 0x20000
	v_lshl_add_u64 v[170:171], v[172:173], 0, s[98:99]
	global_load_dwordx4 v[198:201], v[170:171], off
	global_load_dwordx4 v[202:205], v[170:171], off offset:256
	s_mov_b64 s[98:99], 0x30000
	v_lshl_add_u64 v[170:171], v[172:173], 0, s[98:99]
	global_load_dwordx4 v[206:209], v[170:171], off
	global_load_dwordx4 v[210:213], v[170:171], off offset:256
	s_mov_b64 s[98:99], 0x80000
	v_lshl_add_u64 v[170:171], v[172:173], 0, s[98:99]
	global_load_dwordx4 v[214:217], v[170:171], off
	global_load_dwordx4 v[248:251], v[170:171], off offset:256
	s_mov_b64 s[98:99], 0x90000
	v_lshl_add_u64 v[170:171], v[172:173], 0, s[98:99]
	global_load_dwordx4 v[252:255], v[170:171], off
	s_waitcnt vmcnt(10)
	s_nop 1
	v_mov_b32_e32 v168, v178
	v_mov_b32_e32 v169, v179
	v_mov_b32_e32 v170, v180
	v_mov_b32_e32 v171, v181
	s_mov_b32 s8, s52
	s_mov_b64 s[10:11], s[54:55]
	s_mov_b64 s[12:13], s[6:7]
	s_waitcnt lgkmcnt(0)
	v_lshlrev_b32_e32 v174, 16, v168
	v_and_b32_e32 v175, 0xffff0000, v168
	v_lshlrev_b32_e32 v168, 16, v169
	v_and_b32_e32 v169, 0xffff0000, v169
	v_lshlrev_b32_e32 v176, 16, v170
	v_and_b32_e32 v177, 0xffff0000, v170
	v_lshlrev_b32_e32 v170, 16, v171
	v_and_b32_e32 v171, 0xffff0000, v171
	v_pk_fma_f32 v[142:143], v[142:143], v[62:63], v[168:169]
	v_pk_fma_f32 v[140:141], v[140:141], v[60:61], v[174:175]
	v_pk_fma_f32 v[168:169], v[138:139], v[58:59], v[170:171]
	v_pk_fma_f32 v[138:139], v[136:137], v[56:57], v[176:177]
	v_cvt_pk_bf16_f32 v136, v140, v141
	v_cvt_pk_bf16_f32 v137, v142, v143
	v_cvt_pk_bf16_f32 v138, v138, v139
	v_cvt_pk_bf16_f32 v139, v168, v169
	v_lshl_add_u64 v[140:141], s[42:43], 0, v[160:161]
	global_store_dwordx4 v[140:141], v[136:139], off
	s_waitcnt vmcnt(10)
; DI unsigned pack2(float a, float b) { f32x2 v = {a, b}; hwbf16x2 r = __builtin_convertvector(v, hwbf16x2); return __builtin_bit_cast(unsigned, r); }
; DI float bflo(unsigned w) { return __uint_as_float(w << 16); }
; DI float bfhi(unsigned w) { return __uint_as_float(w & 0xffff0000u); }
;     DI void operator()(const f32x4 (&acc)[2][2][4][2], const Unit& u, int wr, int wc, int fr, int fq) const {
;     ...
;         for (int ai = 0; ai < 2; ++ai)
; #pragma unroll
;             for (int m = 0; m < 4; ++m) { const size_t ro = (size_t)(row0 + ai * HALF + m * 16) * D + col0;
; #pragma unroll
;                 for (int bj = 0; bj < 2; ++bj) {
;                     f32x4 x0, x1;
;                     if constexpr (IB) { const u32x4 w = *(const u32x4*)((const bf16_t*)Xin + ro + bj * HALF);
;                         x0 = (f32x4){bflo(w[0]), bfhi(w[0]), bflo(w[1]), bfhi(w[1])}; x1 = (f32x4){bflo(w[2]), bfhi(w[2]), bflo(w[3]), bfhi(w[3])}; }
;                     else { x0 = *(const f32x4*)((const float*)Xin + ro + bj * HALF); x1 = *(const f32x4*)((const float*)Xin + ro + bj * HALF + 4); }
;                     x0 += acc[ai][bj][m][0] * sc[bj][0]; x1 += acc[ai][bj][m][1] * sc[bj][1];
;                     if constexpr (OB) { u32x4 o; o[0] = pack2(x0[0], x0[1]); o[1] = pack2(x0[2], x0[3]); o[2] = pack2(x1[0], x1[1]); o[3] = pack2(x1[2], x1[3]);
;                         *(u32x4*)((bf16_t*)Xout + ro + bj * HALF) = o; }
;                     else { *(f32x4*)((float*)Xout + ro + bj * HALF) = x0; *(f32x4*)((float*)Xout + ro + bj * HALF + 4) = x1; } } }
	s_nop 1
	v_mov_b32_e32 v136, v182
	v_mov_b32_e32 v137, v183
	v_mov_b32_e32 v138, v184
	v_mov_b32_e32 v139, v185
	s_waitcnt lgkmcnt(0)
	v_lshlrev_b32_e32 v142, 16, v136
	v_and_b32_e32 v143, 0xffff0000, v136
	v_lshlrev_b32_e32 v136, 16, v137
	v_and_b32_e32 v137, 0xffff0000, v137
	v_lshlrev_b32_e32 v168, 16, v138
	v_and_b32_e32 v169, 0xffff0000, v138
	v_lshlrev_b32_e32 v138, 16, v139
	v_and_b32_e32 v139, 0xffff0000, v139
	v_pk_fma_f32 v[134:135], v[134:135], v[46:47], v[136:137]
	v_pk_fma_f32 v[132:133], v[132:133], v[44:45], v[142:143]
	v_pk_fma_f32 v[136:137], v[130:131], v[42:43], v[138:139]
	v_pk_fma_f32 v[130:131], v[128:129], v[40:41], v[168:169]
	v_cvt_pk_bf16_f32 v128, v132, v133
	v_cvt_pk_bf16_f32 v129, v134, v135
	v_cvt_pk_bf16_f32 v130, v130, v131
	v_cvt_pk_bf16_f32 v131, v136, v137
	v_lshl_add_u64 v[132:133], v[160:161], 0, s[2:3]
	global_store_dwordx4 v[140:141], v[128:131], off offset:256
	v_lshl_add_u64 v[134:135], s[4:5], 0, v[132:133]
	s_waitcnt vmcnt(10)
	s_nop 1
	v_mov_b32_e32 v128, v186
	v_mov_b32_e32 v129, v187
	v_mov_b32_e32 v130, v188
	v_mov_b32_e32 v131, v189
	s_mov_b64 s[2:3], 0x20000
	s_waitcnt lgkmcnt(0)
	v_lshlrev_b32_e32 v136, 16, v128
	v_and_b32_e32 v137, 0xffff0000, v128
	v_lshlrev_b32_e32 v128, 16, v129
	v_and_b32_e32 v129, 0xffff0000, v129
	v_lshlrev_b32_e32 v138, 16, v130
	v_and_b32_e32 v139, 0xffff0000, v130
	v_lshlrev_b32_e32 v130, 16, v131
	v_and_b32_e32 v131, 0xffff0000, v131
	v_pk_fma_f32 v[126:127], v[126:127], v[62:63], v[128:129]
	v_pk_fma_f32 v[124:125], v[124:125], v[60:61], v[136:137]
	v_pk_fma_f32 v[128:129], v[122:123], v[58:59], v[130:131]
	v_pk_fma_f32 v[122:123], v[120:121], v[56:57], v[138:139]
	v_cvt_pk_bf16_f32 v120, v124, v125
	v_cvt_pk_bf16_f32 v121, v126, v127
	v_cvt_pk_bf16_f32 v122, v122, v123
	v_cvt_pk_bf16_f32 v123, v128, v129
	v_lshl_add_u64 v[124:125], s[42:43], 0, v[132:133]
	global_store_dwordx4 v[124:125], v[120:123], off
	s_waitcnt vmcnt(10)
	s_nop 1
	v_mov_b32_e32 v120, v190
	v_mov_b32_e32 v121, v191
	v_mov_b32_e32 v122, v192
	v_mov_b32_e32 v123, v193
	s_waitcnt lgkmcnt(0)
	v_lshlrev_b32_e32 v126, 16, v120
	v_and_b32_e32 v127, 0xffff0000, v120
	v_lshlrev_b32_e32 v120, 16, v121
	v_and_b32_e32 v121, 0xffff0000, v121
	v_lshlrev_b32_e32 v128, 16, v122
	v_and_b32_e32 v129, 0xffff0000, v122
	v_lshlrev_b32_e32 v122, 16, v123
	v_and_b32_e32 v123, 0xffff0000, v123
	v_pk_fma_f32 v[118:119], v[118:119], v[46:47], v[120:121]
	v_pk_fma_f32 v[116:117], v[116:117], v[44:45], v[126:127]
	v_pk_fma_f32 v[120:121], v[114:115], v[42:43], v[122:123]
	v_pk_fma_f32 v[114:115], v[112:113], v[40:41], v[128:129]
	v_cvt_pk_bf16_f32 v112, v116, v117
	v_cvt_pk_bf16_f32 v113, v118, v119
	v_cvt_pk_bf16_f32 v114, v114, v115
	v_cvt_pk_bf16_f32 v115, v120, v121
	v_lshl_add_u64 v[116:117], v[160:161], 0, s[2:3]
	global_store_dwordx4 v[124:125], v[112:115], off offset:256
	v_lshl_add_u64 v[118:119], s[4:5], 0, v[116:117]
	s_waitcnt vmcnt(10)
	s_nop 1
	v_mov_b32_e32 v112, v198
	v_mov_b32_e32 v113, v199
	v_mov_b32_e32 v114, v200
	v_mov_b32_e32 v115, v201
	s_mov_b64 s[2:3], 0x30000
	s_waitcnt lgkmcnt(0)
	v_lshlrev_b32_e32 v120, 16, v112
	v_and_b32_e32 v121, 0xffff0000, v112
	v_lshlrev_b32_e32 v112, 16, v113
	v_and_b32_e32 v113, 0xffff0000, v113
	v_lshlrev_b32_e32 v122, 16, v114
	v_and_b32_e32 v123, 0xffff0000, v114
	v_lshlrev_b32_e32 v114, 16, v115
	v_and_b32_e32 v115, 0xffff0000, v115
	v_pk_fma_f32 v[110:111], v[110:111], v[62:63], v[112:113]
	v_pk_fma_f32 v[108:109], v[108:109], v[60:61], v[120:121]
	v_pk_fma_f32 v[112:113], v[106:107], v[58:59], v[114:115]
	v_pk_fma_f32 v[106:107], v[104:105], v[56:57], v[122:123]
	v_cvt_pk_bf16_f32 v104, v108, v109
	v_cvt_pk_bf16_f32 v105, v110, v111
	v_cvt_pk_bf16_f32 v106, v106, v107
	v_cvt_pk_bf16_f32 v107, v112, v113
	v_lshl_add_u64 v[108:109], s[42:43], 0, v[116:117]
	global_store_dwordx4 v[108:109], v[104:107], off
	s_waitcnt vmcnt(10)
	s_nop 1
	v_mov_b32_e32 v104, v202
	v_mov_b32_e32 v105, v203
	v_mov_b32_e32 v106, v204
	v_mov_b32_e32 v107, v205
	s_waitcnt lgkmcnt(0)
	v_lshlrev_b32_e32 v110, 16, v104
	v_and_b32_e32 v111, 0xffff0000, v104
	v_lshlrev_b32_e32 v104, 16, v105
	v_and_b32_e32 v105, 0xffff0000, v105
	v_lshlrev_b32_e32 v112, 16, v106
	v_and_b32_e32 v113, 0xffff0000, v106
	v_lshlrev_b32_e32 v106, 16, v107
	v_and_b32_e32 v107, 0xffff0000, v107
	v_pk_fma_f32 v[102:103], v[102:103], v[46:47], v[104:105]
	v_pk_fma_f32 v[100:101], v[100:101], v[44:45], v[110:111]
	v_pk_fma_f32 v[104:105], v[98:99], v[42:43], v[106:107]
	v_pk_fma_f32 v[98:99], v[96:97], v[40:41], v[112:113]
	v_cvt_pk_bf16_f32 v96, v100, v101
	v_cvt_pk_bf16_f32 v97, v102, v103
	v_cvt_pk_bf16_f32 v98, v98, v99
	v_cvt_pk_bf16_f32 v99, v104, v105
	v_lshl_add_u64 v[100:101], v[160:161], 0, s[2:3]
	global_store_dwordx4 v[108:109], v[96:99], off offset:256
	v_lshl_add_u64 v[102:103], s[4:5], 0, v[100:101]
	s_waitcnt vmcnt(10)
	s_nop 1
	v_mov_b32_e32 v96, v206
	v_mov_b32_e32 v97, v207
	v_mov_b32_e32 v98, v208
	v_mov_b32_e32 v99, v209
	s_mov_b64 s[2:3], 0x80000
	s_waitcnt lgkmcnt(0)
	v_lshlrev_b32_e32 v104, 16, v96
	v_and_b32_e32 v105, 0xffff0000, v96
	v_lshlrev_b32_e32 v96, 16, v97
	v_and_b32_e32 v97, 0xffff0000, v97
	v_lshlrev_b32_e32 v106, 16, v98
	v_and_b32_e32 v107, 0xffff0000, v98
	v_lshlrev_b32_e32 v98, 16, v99
	v_and_b32_e32 v99, 0xffff0000, v99
	v_pk_fma_f32 v[94:95], v[94:95], v[62:63], v[96:97]
	v_pk_fma_f32 v[92:93], v[92:93], v[60:61], v[104:105]
	v_pk_fma_f32 v[96:97], v[90:91], v[58:59], v[98:99]
	v_pk_fma_f32 v[90:91], v[88:89], v[56:57], v[106:107]
	v_cvt_pk_bf16_f32 v88, v92, v93
	v_cvt_pk_bf16_f32 v89, v94, v95
	v_cvt_pk_bf16_f32 v90, v90, v91
	v_cvt_pk_bf16_f32 v91, v96, v97
	v_lshl_add_u64 v[92:93], s[42:43], 0, v[100:101]
	global_store_dwordx4 v[92:93], v[88:91], off
	s_waitcnt vmcnt(10)
; DI unsigned pack2(float a, float b) { f32x2 v = {a, b}; hwbf16x2 r = __builtin_convertvector(v, hwbf16x2); return __builtin_bit_cast(unsigned, r); }
; DI float bflo(unsigned w) { return __uint_as_float(w << 16); }
; DI float bfhi(unsigned w) { return __uint_as_float(w & 0xffff0000u); }
;     DI void operator()(const f32x4 (&acc)[2][2][4][2], const Unit& u, int wr, int wc, int fr, int fq) const {
;     ...
;         for (int ai = 0; ai < 2; ++ai)
; #pragma unroll
;             for (int m = 0; m < 4; ++m) { const size_t ro = (size_t)(row0 + ai * HALF + m * 16) * D + col0;
; #pragma unroll
;                 for (int bj = 0; bj < 2; ++bj) {
;                     f32x4 x0, x1;
;                     if constexpr (IB) { const u32x4 w = *(const u32x4*)((const bf16_t*)Xin + ro + bj * HALF);
;                         x0 = (f32x4){bflo(w[0]), bfhi(w[0]), bflo(w[1]), bfhi(w[1])}; x1 = (f32x4){bflo(w[2]), bfhi(w[2]), bflo(w[3]), bfhi(w[3])}; }
;                     else { x0 = *(const f32x4*)((const float*)Xin + ro + bj * HALF); x1 = *(const f32x4*)((const float*)Xin + ro + bj * HALF + 4); }
;                     x0 += acc[ai][bj][m][0] * sc[bj][0]; x1 += acc[ai][bj][m][1] * sc[bj][1];
;                     if constexpr (OB) { u32x4 o; o[0] = pack2(x0[0], x0[1]); o[1] = pack2(x0[2], x0[3]); o[2] = pack2(x1[0], x1[1]); o[3] = pack2(x1[2], x1[3]);
;                         *(u32x4*)((bf16_t*)Xout + ro + bj * HALF) = o; }
;                     else { *(f32x4*)((float*)Xout + ro + bj * HALF) = x0; *(f32x4*)((float*)Xout + ro + bj * HALF + 4) = x1; } } }
	s_nop 1
	v_mov_b32_e32 v88, v210
	v_mov_b32_e32 v89, v211
	v_mov_b32_e32 v90, v212
	v_mov_b32_e32 v91, v213
	s_waitcnt lgkmcnt(0)
	v_lshlrev_b32_e32 v94, 16, v88
	v_and_b32_e32 v95, 0xffff0000, v88
	v_lshlrev_b32_e32 v88, 16, v89
	v_and_b32_e32 v89, 0xffff0000, v89
	v_lshlrev_b32_e32 v96, 16, v90
	v_and_b32_e32 v97, 0xffff0000, v90
	v_lshlrev_b32_e32 v90, 16, v91
	v_and_b32_e32 v91, 0xffff0000, v91
	v_pk_fma_f32 v[86:87], v[86:87], v[46:47], v[88:89]
	v_pk_fma_f32 v[84:85], v[84:85], v[44:45], v[94:95]
	v_pk_fma_f32 v[88:89], v[82:83], v[42:43], v[90:91]
	v_pk_fma_f32 v[82:83], v[80:81], v[40:41], v[96:97]
	v_cvt_pk_bf16_f32 v80, v84, v85
	v_cvt_pk_bf16_f32 v81, v86, v87
	v_cvt_pk_bf16_f32 v82, v82, v83
	v_cvt_pk_bf16_f32 v83, v88, v89
	v_lshl_add_u64 v[84:85], v[160:161], 0, s[2:3]
	global_store_dwordx4 v[92:93], v[80:83], off offset:256
	v_lshl_add_u64 v[86:87], s[4:5], 0, v[84:85]
	s_waitcnt vmcnt(10)
	s_nop 1
	v_mov_b32_e32 v80, v214
	v_mov_b32_e32 v81, v215
	v_mov_b32_e32 v82, v216
	v_mov_b32_e32 v83, v217
	s_mov_b64 s[2:3], 0x90000
	s_waitcnt lgkmcnt(0)
	v_lshlrev_b32_e32 v88, 16, v80
	v_and_b32_e32 v89, 0xffff0000, v80
	v_lshlrev_b32_e32 v80, 16, v81
	v_and_b32_e32 v81, 0xffff0000, v81
	v_lshlrev_b32_e32 v90, 16, v82
	v_and_b32_e32 v91, 0xffff0000, v82
	v_lshlrev_b32_e32 v82, 16, v83
	v_and_b32_e32 v83, 0xffff0000, v83
	v_pk_fma_f32 v[78:79], v[78:79], v[62:63], v[80:81]
	v_pk_fma_f32 v[76:77], v[76:77], v[60:61], v[88:89]
	v_pk_fma_f32 v[80:81], v[74:75], v[58:59], v[82:83]
	v_pk_fma_f32 v[74:75], v[72:73], v[56:57], v[90:91]
	v_cvt_pk_bf16_f32 v72, v76, v77
	v_cvt_pk_bf16_f32 v73, v78, v79
	v_cvt_pk_bf16_f32 v74, v74, v75
	v_cvt_pk_bf16_f32 v75, v80, v81
	v_lshl_add_u64 v[76:77], s[42:43], 0, v[84:85]
	global_store_dwordx4 v[76:77], v[72:75], off
	s_waitcnt vmcnt(10)
	s_nop 1
	v_mov_b32_e32 v72, v248
	v_mov_b32_e32 v73, v249
	v_mov_b32_e32 v74, v250
	v_mov_b32_e32 v75, v251
	s_waitcnt lgkmcnt(0)
	v_lshlrev_b32_e32 v78, 16, v72
	v_and_b32_e32 v79, 0xffff0000, v72
	v_lshlrev_b32_e32 v72, 16, v73
	v_and_b32_e32 v73, 0xffff0000, v73
	v_lshlrev_b32_e32 v80, 16, v74
	v_and_b32_e32 v81, 0xffff0000, v74
	v_lshlrev_b32_e32 v74, 16, v75
	v_and_b32_e32 v75, 0xffff0000, v75
	v_pk_fma_f32 v[70:71], v[70:71], v[46:47], v[72:73]
	v_pk_fma_f32 v[68:69], v[68:69], v[44:45], v[78:79]
	v_pk_fma_f32 v[72:73], v[66:67], v[42:43], v[74:75]
	v_pk_fma_f32 v[66:67], v[64:65], v[40:41], v[80:81]
	v_cvt_pk_bf16_f32 v64, v68, v69
	v_cvt_pk_bf16_f32 v65, v70, v71
	v_cvt_pk_bf16_f32 v66, v66, v67
	v_cvt_pk_bf16_f32 v67, v72, v73
	v_lshl_add_u64 v[68:69], v[160:161], 0, s[2:3]
	global_store_dwordx4 v[76:77], v[64:67], off offset:256
	v_lshl_add_u64 v[70:71], s[4:5], 0, v[68:69]
	s_waitcnt vmcnt(10)
	s_nop 1
	v_mov_b32_e32 v64, v252
	v_mov_b32_e32 v65, v253
	v_mov_b32_e32 v66, v254
	v_mov_b32_e32 v67, v255
	s_mov_b64 s[2:3], 0xa0000
	s_waitcnt lgkmcnt(0)
	v_lshlrev_b32_e32 v72, 16, v64
	v_and_b32_e32 v73, 0xffff0000, v64
	v_lshlrev_b32_e32 v64, 16, v65
	v_and_b32_e32 v65, 0xffff0000, v65
	v_lshlrev_b32_e32 v74, 16, v66
	v_and_b32_e32 v75, 0xffff0000, v66
	v_lshlrev_b32_e32 v66, 16, v67
	v_and_b32_e32 v67, 0xffff0000, v67
	v_pk_fma_f32 v[54:55], v[54:55], v[62:63], v[64:65]
	v_pk_fma_f32 v[52:53], v[52:53], v[60:61], v[72:73]
	v_pk_fma_f32 v[64:65], v[50:51], v[58:59], v[66:67]
	v_pk_fma_f32 v[50:51], v[48:49], v[56:57], v[74:75]
	v_cvt_pk_bf16_f32 v48, v52, v53
	v_cvt_pk_bf16_f32 v49, v54, v55
	v_cvt_pk_bf16_f32 v50, v50, v51
	v_cvt_pk_bf16_f32 v51, v64, v65
	v_lshl_add_u64 v[52:53], s[42:43], 0, v[68:69]
	global_store_dwordx4 v[52:53], v[48:51], off
	global_load_dwordx4 v[48:51], v[70:71], off offset:256
	s_waitcnt vmcnt(0) lgkmcnt(0)
; DI unsigned pack2(float a, float b) { f32x2 v = {a, b}; hwbf16x2 r = __builtin_convertvector(v, hwbf16x2); return __builtin_bit_cast(unsigned, r); }
; DI float bflo(unsigned w) { return __uint_as_float(w << 16); }
; DI float bfhi(unsigned w) { return __uint_as_float(w & 0xffff0000u); }
;     DI const char* a(const Unit& u) const { return (const char*)(A + (size_t)u.pm * BM * lda); }
;     DI const char* a(const Unit& u) const { return (const char*)(A + (size_t)u.pm * BM * 2048 + (u.pn >> 1) * 512); }
;     DI void operator()(const f32x4 (&acc)[2][2][4][2], const Unit& u, int wr, int wc, int fr, int fq) const {
;     ...
;         for (int ai = 0; ai < 2; ++ai)
; #pragma unroll
;             for (int m = 0; m < 4; ++m) { const size_t ro = (size_t)(row0 + ai * HALF + m * 16) * D + col0;
; #pragma unroll
;                 for (int bj = 0; bj < 2; ++bj) {
;                     f32x4 x0, x1;
;                     if constexpr (IB) { const u32x4 w = *(const u32x4*)((const bf16_t*)Xin + ro + bj * HALF);
;                         x0 = (f32x4){bflo(w[0]), bfhi(w[0]), bflo(w[1]), bfhi(w[1])}; x1 = (f32x4){bflo(w[2]), bfhi(w[2]), bflo(w[3]), bfhi(w[3])}; }
;                     else { x0 = *(const f32x4*)((const float*)Xin + ro + bj * HALF); x1 = *(const f32x4*)((const float*)Xin + ro + bj * HALF + 4); }
;                     x0 += acc[ai][bj][m][0] * sc[bj][0]; x1 += acc[ai][bj][m][1] * sc[bj][1];
;                     if constexpr (OB) { u32x4 o; o[0] = pack2(x0[0], x0[1]); o[1] = pack2(x0[2], x0[3]); o[2] = pack2(x1[0], x1[1]); o[3] = pack2(x1[2], x1[3]);
;                         *(u32x4*)((bf16_t*)Xout + ro + bj * HALF) = o; }
;                     else { *(f32x4*)((float*)Xout + ro + bj * HALF) = x0; *(f32x4*)((float*)Xout + ro + bj * HALF + 4) = x1; } } }
; template <class Map, class Epi>
; DI void gemm_phase(LAS unsigned char* lds, const Map& MP, const Epi& E, const int nM, const int nN, const int K, const int lda, const int ldb) {
;     ...
;         if (!has_next) break;
; #pragma unroll
;         for (int a = 0; a < 2; ++a)
; #pragma unroll
;             for (int b = 0; b < 2; ++b)
; #pragma unroll
;                 for (int m = 0; m < 4; ++m)
; #pragma unroll
;                     for (int n = 0; n < 2; ++n) acc[a][b][m][n] = (f32x4){0.f, 0.f, 0.f, 0.f};
;         cur = nxt; cA = nA; cB = nB; ++ui;
;     }
;     PG8_WAIT_V(0);
;     if (wr == 0) PG8_BAR;
;     PG8_BAR;
	v_lshlrev_b32_e32 v54, 16, v48
	v_and_b32_e32 v55, 0xffff0000, v48
	v_lshlrev_b32_e32 v48, 16, v49
	v_and_b32_e32 v49, 0xffff0000, v49
	v_lshlrev_b32_e32 v64, 16, v50
	v_and_b32_e32 v65, 0xffff0000, v50
	v_lshlrev_b32_e32 v50, 16, v51
	v_and_b32_e32 v51, 0xffff0000, v51
	v_pk_fma_f32 v[38:39], v[38:39], v[46:47], v[48:49]
	v_pk_fma_f32 v[36:37], v[36:37], v[44:45], v[54:55]
	v_pk_fma_f32 v[48:49], v[34:35], v[42:43], v[50:51]
	v_pk_fma_f32 v[34:35], v[32:33], v[40:41], v[64:65]
	v_cvt_pk_bf16_f32 v32, v36, v37
	v_cvt_pk_bf16_f32 v33, v38, v39
	v_cvt_pk_bf16_f32 v34, v34, v35
	v_cvt_pk_bf16_f32 v35, v48, v49
	v_lshl_add_u64 v[36:37], v[160:161], 0, s[2:3]
	global_store_dwordx4 v[52:53], v[32:35], off offset:256
	v_lshl_add_u64 v[38:39], s[4:5], 0, v[36:37]
	global_load_dwordx4 v[32:35], v[38:39], off
	s_mov_b64 s[2:3], 0xb0000
	s_waitcnt vmcnt(0) lgkmcnt(0)
	v_lshlrev_b32_e32 v48, 16, v32
	v_and_b32_e32 v49, 0xffff0000, v32
	v_lshlrev_b32_e32 v32, 16, v33
	v_and_b32_e32 v33, 0xffff0000, v33
	v_lshlrev_b32_e32 v50, 16, v34
	v_and_b32_e32 v51, 0xffff0000, v34
	v_lshlrev_b32_e32 v34, 16, v35
	v_and_b32_e32 v35, 0xffff0000, v35
	v_pk_fma_f32 v[30:31], v[30:31], v[62:63], v[32:33]
	v_pk_fma_f32 v[28:29], v[28:29], v[60:61], v[48:49]
	v_pk_fma_f32 v[32:33], v[26:27], v[58:59], v[34:35]
	v_pk_fma_f32 v[26:27], v[24:25], v[56:57], v[50:51]
	v_cvt_pk_bf16_f32 v24, v28, v29
	v_cvt_pk_bf16_f32 v25, v30, v31
	v_cvt_pk_bf16_f32 v26, v26, v27
	v_cvt_pk_bf16_f32 v27, v32, v33
	v_lshl_add_u64 v[28:29], s[42:43], 0, v[36:37]
	global_store_dwordx4 v[28:29], v[24:27], off
	global_load_dwordx4 v[24:27], v[38:39], off offset:256
	s_waitcnt vmcnt(0) lgkmcnt(0)
	v_lshlrev_b32_e32 v30, 16, v24
	v_and_b32_e32 v31, 0xffff0000, v24
	v_lshlrev_b32_e32 v24, 16, v25
	v_and_b32_e32 v25, 0xffff0000, v25
	v_lshlrev_b32_e32 v32, 16, v26
	v_and_b32_e32 v33, 0xffff0000, v26
	v_lshlrev_b32_e32 v26, 16, v27
	v_and_b32_e32 v27, 0xffff0000, v27
	v_pk_fma_f32 v[22:23], v[22:23], v[46:47], v[24:25]
	v_pk_fma_f32 v[20:21], v[20:21], v[44:45], v[30:31]
	v_pk_fma_f32 v[24:25], v[18:19], v[42:43], v[26:27]
	v_pk_fma_f32 v[18:19], v[16:17], v[40:41], v[32:33]
	v_cvt_pk_bf16_f32 v16, v20, v21
	v_cvt_pk_bf16_f32 v17, v22, v23
	v_cvt_pk_bf16_f32 v18, v18, v19
	v_cvt_pk_bf16_f32 v19, v24, v25
	v_lshl_add_u64 v[20:21], v[160:161], 0, s[2:3]
	global_store_dwordx4 v[28:29], v[16:19], off offset:256
	v_lshl_add_u64 v[22:23], s[4:5], 0, v[20:21]
	global_load_dwordx4 v[16:19], v[22:23], off
	s_mov_b32 s2, s37
	s_waitcnt vmcnt(0) lgkmcnt(0)
	v_lshlrev_b32_e32 v24, 16, v16
	v_and_b32_e32 v25, 0xffff0000, v16
	v_lshlrev_b32_e32 v16, 16, v17
	v_and_b32_e32 v17, 0xffff0000, v17
	v_lshlrev_b32_e32 v26, 16, v18
	v_and_b32_e32 v27, 0xffff0000, v18
	v_lshlrev_b32_e32 v18, 16, v19
	v_and_b32_e32 v19, 0xffff0000, v19
	v_pk_fma_f32 v[14:15], v[14:15], v[62:63], v[16:17]
	v_pk_fma_f32 v[12:13], v[12:13], v[60:61], v[24:25]
	v_pk_fma_f32 v[16:17], v[10:11], v[58:59], v[18:19]
	v_pk_fma_f32 v[10:11], v[8:9], v[56:57], v[26:27]
	v_cvt_pk_bf16_f32 v8, v12, v13
	v_cvt_pk_bf16_f32 v9, v14, v15
	v_cvt_pk_bf16_f32 v10, v10, v11
	v_cvt_pk_bf16_f32 v11, v16, v17
	v_lshl_add_u64 v[12:13], s[42:43], 0, v[20:21]
	global_store_dwordx4 v[12:13], v[8:11], off
	global_load_dwordx4 v[8:11], v[22:23], off offset:256
	s_waitcnt vmcnt(0) lgkmcnt(0)
	v_lshlrev_b32_e32 v14, 16, v8
	v_and_b32_e32 v15, 0xffff0000, v8
	v_lshlrev_b32_e32 v8, 16, v9
	v_and_b32_e32 v9, 0xffff0000, v9
	v_lshlrev_b32_e32 v16, 16, v10
	v_and_b32_e32 v17, 0xffff0000, v10
	v_lshlrev_b32_e32 v10, 16, v11
	v_and_b32_e32 v11, 0xffff0000, v11
	v_pk_fma_f32 v[6:7], v[6:7], v[46:47], v[8:9]
	v_pk_fma_f32 v[4:5], v[4:5], v[44:45], v[14:15]
	v_pk_fma_f32 v[8:9], v[2:3], v[42:43], v[10:11]
	v_pk_fma_f32 v[2:3], v[0:1], v[40:41], v[16:17]
	v_cvt_pk_bf16_f32 v0, v4, v5
	v_cvt_pk_bf16_f32 v1, v6, v7
	v_cvt_pk_bf16_f32 v2, v2, v3
	v_cvt_pk_bf16_f32 v3, v8, v9
	global_store_dwordx4 v[12:13], v[0:3], off offset:256
	s_cbranch_vccz .LBB1_2336
	s_waitcnt vmcnt(0)
	s_cmpk_gt_u32 s17, 0xff
	s_cbranch_scc1 .LBB1_2343
	s_barrier

; #define PG8_STAGE(bufoff, gbase, voff) do { _Pragma("unroll") for (int _i = 0; _i < 2; ++_i) \
;         __builtin_amdgcn_global_load_lds((const unsigned*)((const char*)(gbase) + (voff)[_i]), (LAS unsigned*)(lds + (bufoff) + ldsw + _i * 8192), 16, 0, 0); } while (0)
; #define PG8_LDA(dst, b, h) do { _Pragma("unroll") for (int m = 0; m < 4; ++m) _Pragma("unroll") for (int k = 0; k < 2; ++k) dst[m][k] = *(const LAS bf16x8*)(lds + PG8_SA(b, h) + aoff + m * 2048 + k * 1024); } while (0)
; #define PG8_LDB(dst, b, h) do { _Pragma("unroll") for (int n = 0; n < 2; ++n) _Pragma("unroll") for (int k = 0; k < 2; ++k) dst[n][k] = *(const LAS bf16x8*)(lds + PG8_SB(b, h) + boff + n * 2048 + k * 1024); } while (0)
; #define PG8_MMA(ai, bj, At, Bt) do { __builtin_amdgcn_s_setprio(1); _Pragma("unroll") for (int m = 0; m < 4; ++m) _Pragma("unroll") for (int n = 0; n < 2; ++n) _Pragma("unroll") for (int k = 0; k < 2; ++k) \
;         acc[ai][bj][m][n] = __builtin_amdgcn_mfma_f32_16x16x32_bf16(Bt[n][k], At[m][k], acc[ai][bj][m][n], 0, 0, 0); __builtin_amdgcn_s_setprio(0); } while (0)
; #define PG8_WAIT_L(n) asm volatile("s_waitcnt lgkmcnt(" #n ")" ::: "memory")
; #define PG8_BAR __builtin_amdgcn_s_barrier()
; #define PG8_SCHED __builtin_amdgcn_sched_barrier(0)
; template <class Map, class Epi>
; DI void gemm_phase(LAS unsigned char* lds, const Map& MP, const Epi& E, const int nM, const int nN, const int K, const int lda, const int ldb) {
;     ...
;             PG8_LDB(B0, 0, 0); PG8_SCHED; PG8_LDA(At, 0, 0); PG8_STAGE(PG8_SA(1, 1), a1 + hstepA, voffA);
;             PG8_WAIT_L(8); PG8_BAR; PG8_WAIT_L(0); PG8_MMA(0, 0, At, B0); PG8_BAR; PG8_SCHED;
;             PG8_LDB(B1, 0, 1); PG8_STAGE(PG8_SB(0, 0), b2, voffB);
;             PG8_BAR; PG8_WAIT_L(0); PG8_MMA(0, 1, At, B1); PG8_BAR;
;             PG8_LDA(At, 0, 1); PG8_STAGE(PG8_SA(0, 0), a2, voffA);
;             PG8_BAR; PG8_WAIT_L(0); PG8_MMA(1, 0, At, B0); PG8_BAR; PG8_SCHED;
.LBB1_2483:
	ds_read_b128 v[80:83], v189
	ds_read_b128 v[84:87], v189 offset:1024
	ds_read_b128 v[88:91], v189 offset:2048
	ds_read_b128 v[92:95], v189 offset:3072
	s_add_u32 s28, s42, 0xfff80080
	s_addc_u32 s29, s43, -1
	s_cmp_eq_u32 s3, 28
	s_cselect_b32 s47, s23, s29
	s_cselect_b32 s46, s58, s28
	s_cselect_b32 s29, s21, vcc_hi
	s_cselect_b32 s28, s59, vcc_lo
	s_add_i32 m0, s38, 0xc000
	ds_read_b128 v[96:99], v190
	ds_read_b128 v[100:103], v190 offset:1024
	ds_read_b128 v[108:111], v190 offset:2048
	ds_read_b128 v[112:115], v190 offset:3072
	ds_read_b128 v[160:163], v190 offset:4096
	ds_read_b128 v[164:167], v190 offset:5120
	ds_read_b128 v[198:201], v190 offset:6144
	ds_read_b128 v[202:205], v190 offset:7168
	global_load_lds_dwordx4 v178, s[42:43]
	s_add_i32 m0, s38, 0xe000
	s_nop 0
	global_load_lds_dwordx4 v176, s[42:43]
	s_waitcnt lgkmcnt(8)
	s_barrier
	s_setprio 1
	s_waitcnt lgkmcnt(7)
	v_mfma_f32_16x16x32_bf16 v[148:151], v[80:83], v[96:99], v[148:151]
	v_mfma_f32_16x16x32_bf16 v[144:147], v[88:91], v[96:99], v[144:147]
	s_waitcnt lgkmcnt(5)
	v_mfma_f32_16x16x32_bf16 v[136:139], v[80:83], v[108:111], v[136:139]
	v_mfma_f32_16x16x32_bf16 v[128:131], v[88:91], v[108:111], v[128:131]
	s_waitcnt lgkmcnt(3)
	v_mfma_f32_16x16x32_bf16 v[120:123], v[80:83], v[160:163], v[120:123]
	v_mfma_f32_16x16x32_bf16 v[104:107], v[88:91], v[160:163], v[104:107]
	s_waitcnt lgkmcnt(1)
	v_mfma_f32_16x16x32_bf16 v[76:79], v[80:83], v[198:201], v[76:79]
	v_mfma_f32_16x16x32_bf16 v[72:75], v[88:91], v[198:201], v[72:75]
	v_mfma_f32_16x16x32_bf16 v[148:151], v[84:87], v[100:103], v[148:151]
	v_mfma_f32_16x16x32_bf16 v[144:147], v[92:95], v[100:103], v[144:147]
	v_mfma_f32_16x16x32_bf16 v[136:139], v[84:87], v[112:115], v[136:139]
	v_mfma_f32_16x16x32_bf16 v[128:131], v[92:95], v[112:115], v[128:131]
	v_mfma_f32_16x16x32_bf16 v[120:123], v[84:87], v[164:167], v[120:123]
	v_mfma_f32_16x16x32_bf16 v[104:107], v[92:95], v[164:167], v[104:107]
	s_waitcnt lgkmcnt(0)
	v_mfma_f32_16x16x32_bf16 v[76:79], v[84:87], v[202:205], v[76:79]
	v_mfma_f32_16x16x32_bf16 v[72:75], v[92:95], v[202:205], v[72:75]
	s_setprio 0
	s_barrier
	s_add_i32 s68, s2, s37
	v_lshl_add_u64 v[184:185], s[28:29], 0, v[172:173]
	s_mov_b32 m0, s68
	ds_read_b128 v[206:209], v191
	ds_read_b128 v[210:213], v191 offset:1024
	ds_read_b128 v[214:217], v191 offset:2048
	ds_read_b128 v[218:221], v191 offset:3072
	global_load_lds_dwordx4 v[184:185], off
	v_lshl_add_u64 v[194:195], s[28:29], 0, v[168:169]
	s_add_i32 m0, s68, 0x2000
	s_nop 0
	global_load_lds_dwordx4 v[194:195], off
	s_barrier
	s_setprio 1
	s_waitcnt lgkmcnt(3)
	v_mfma_f32_16x16x32_bf16 v[156:159], v[206:209], v[96:99], v[156:159]
	s_waitcnt lgkmcnt(1)
	v_mfma_f32_16x16x32_bf16 v[96:99], v[214:217], v[96:99], v[152:155]
	v_mfma_f32_16x16x32_bf16 v[156:159], v[210:213], v[100:103], v[156:159]
	s_waitcnt lgkmcnt(0)
	v_mfma_f32_16x16x32_bf16 v[96:99], v[218:221], v[100:103], v[96:99]
	v_mfma_f32_16x16x32_bf16 v[100:103], v[206:209], v[108:111], v[140:143]
	v_mfma_f32_16x16x32_bf16 v[108:111], v[214:217], v[108:111], v[132:135]
	v_mfma_f32_16x16x32_bf16 v[116:119], v[214:217], v[160:163], v[116:119]
	v_mfma_f32_16x16x32_bf16 v[68:71], v[206:209], v[198:201], v[68:71]
	v_mfma_f32_16x16x32_bf16 v[64:67], v[214:217], v[198:201], v[64:67]
	v_mfma_f32_16x16x32_bf16 v[100:103], v[210:213], v[112:115], v[100:103]
	v_mfma_f32_16x16x32_bf16 v[108:111], v[218:221], v[112:115], v[108:111]
	v_mfma_f32_16x16x32_bf16 v[112:115], v[206:209], v[160:163], v[124:127]
	v_mfma_f32_16x16x32_bf16 v[116:119], v[218:221], v[164:167], v[116:119]
	v_mfma_f32_16x16x32_bf16 v[68:71], v[210:213], v[202:205], v[68:71]
	v_mfma_f32_16x16x32_bf16 v[64:67], v[218:221], v[202:205], v[64:67]
	v_mfma_f32_16x16x32_bf16 v[112:115], v[210:213], v[164:167], v[112:115]
	s_setprio 0
	s_mov_b32 m0, s38
	v_lshl_add_u64 v[230:231], s[46:47], 0, v[174:175]
	s_barrier
	ds_read_b128 v[124:127], v190 offset:16384
	ds_read_b128 v[132:135], v190 offset:17408
	ds_read_b128 v[140:143], v190 offset:18432
	ds_read_b128 v[152:155], v190 offset:19456
	ds_read_b128 v[160:163], v190 offset:20480
	ds_read_b128 v[164:167], v190 offset:21504
	ds_read_b128 v[198:201], v190 offset:22528
	ds_read_b128 v[202:205], v190 offset:23552
	global_load_lds_dwordx4 v[230:231], off
	v_lshl_add_u64 v[232:233], s[46:47], 0, v[170:171]
	s_mov_b32 m0, s39
	s_nop 0
	global_load_lds_dwordx4 v[232:233], off
	s_barrier
	s_setprio 1
	s_waitcnt lgkmcnt(7)
	v_mfma_f32_16x16x32_bf16 v[60:63], v[80:83], v[124:127], v[60:63]
	v_mfma_f32_16x16x32_bf16 v[48:51], v[88:91], v[124:127], v[48:51]
	s_waitcnt lgkmcnt(5)
	v_mfma_f32_16x16x32_bf16 v[40:43], v[80:83], v[140:143], v[40:43]
	v_mfma_f32_16x16x32_bf16 v[32:35], v[88:91], v[140:143], v[32:35]
	s_waitcnt lgkmcnt(3)
	v_mfma_f32_16x16x32_bf16 v[24:27], v[80:83], v[160:163], v[24:27]
	v_mfma_f32_16x16x32_bf16 v[16:19], v[88:91], v[160:163], v[16:19]
	s_waitcnt lgkmcnt(1)
	v_mfma_f32_16x16x32_bf16 v[12:15], v[80:83], v[198:201], v[12:15]
	v_mfma_f32_16x16x32_bf16 v[8:11], v[88:91], v[198:201], v[8:11]
	v_mfma_f32_16x16x32_bf16 v[60:63], v[84:87], v[132:135], v[60:63]
	v_mfma_f32_16x16x32_bf16 v[48:51], v[92:95], v[132:135], v[48:51]
	v_mfma_f32_16x16x32_bf16 v[40:43], v[84:87], v[152:155], v[40:43]
	v_mfma_f32_16x16x32_bf16 v[32:35], v[92:95], v[152:155], v[32:35]
	v_mfma_f32_16x16x32_bf16 v[24:27], v[84:87], v[164:167], v[24:27]
	v_mfma_f32_16x16x32_bf16 v[16:19], v[92:95], v[164:167], v[16:19]
	s_waitcnt lgkmcnt(0)
	v_mfma_f32_16x16x32_bf16 v[12:15], v[84:87], v[202:205], v[12:15]
	v_mfma_f32_16x16x32_bf16 v[8:11], v[92:95], v[202:205], v[8:11]
	s_setprio 0
	s_barrier
; #define PG8_STAGE(bufoff, gbase, voff) do { _Pragma("unroll") for (int _i = 0; _i < 2; ++_i) \
;         __builtin_amdgcn_global_load_lds((const unsigned*)((const char*)(gbase) + (voff)[_i]), (LAS unsigned*)(lds + (bufoff) + ldsw + _i * 8192), 16, 0, 0); } while (0)
; #define PG8_LDA(dst, b, h) do { _Pragma("unroll") for (int m = 0; m < 4; ++m) _Pragma("unroll") for (int k = 0; k < 2; ++k) dst[m][k] = *(const LAS bf16x8*)(lds + PG8_SA(b, h) + aoff + m * 2048 + k * 1024); } while (0)
; #define PG8_LDB(dst, b, h) do { _Pragma("unroll") for (int n = 0; n < 2; ++n) _Pragma("unroll") for (int k = 0; k < 2; ++k) dst[n][k] = *(const LAS bf16x8*)(lds + PG8_SB(b, h) + boff + n * 2048 + k * 1024); } while (0)
; #define PG8_MMA(ai, bj, At, Bt) do { __builtin_amdgcn_s_setprio(1); _Pragma("unroll") for (int m = 0; m < 4; ++m) _Pragma("unroll") for (int n = 0; n < 2; ++n) _Pragma("unroll") for (int k = 0; k < 2; ++k) \
;         acc[ai][bj][m][n] = __builtin_amdgcn_mfma_f32_16x16x32_bf16(Bt[n][k], At[m][k], acc[ai][bj][m][n], 0, 0, 0); __builtin_amdgcn_s_setprio(0); } while (0)
; #define PG8_WAIT_V(n) asm volatile("s_waitcnt vmcnt(" #n ")" ::: "memory")
; #define PG8_WAIT_L(n) asm volatile("s_waitcnt lgkmcnt(" #n ")" ::: "memory")
; #define PG8_BAR __builtin_amdgcn_s_barrier()
; #define PG8_SCHED __builtin_amdgcn_sched_barrier(0)
; template <class Map, class Epi>
; DI void gemm_phase(LAS unsigned char* lds, const Map& MP, const Epi& E, const int nM, const int nN, const int K, const int lda, const int ldb) {
;     ...
;             PG8_STAGE(PG8_SB(0, 1), b2 + hstepB, voffB);
;             PG8_WAIT_V(6); PG8_BAR; PG8_MMA(1, 1, At, B1); PG8_BAR;
;             PG8_LDB(B0, 1, 0); PG8_SCHED; PG8_LDA(At, 1, 0); PG8_STAGE(PG8_SA(0, 1), a2 + hstepA, voffA);
;             PG8_WAIT_L(8); PG8_BAR; PG8_WAIT_L(0); PG8_MMA(0, 0, At, B0); PG8_BAR; PG8_SCHED;
;             PG8_LDB(B1, 1, 1); PG8_STAGE(PG8_SB(1, 0), b3, voffB);
;             PG8_BAR; PG8_WAIT_L(0); PG8_MMA(0, 1, At, B1); PG8_BAR;
;             PG8_LDA(At, 1, 1); PG8_STAGE(PG8_SA(1, 0), a3, voffA);
;             PG8_BAR; PG8_WAIT_L(0); PG8_MMA(1, 0, At, B0); PG8_BAR; PG8_SCHED;
	s_add_u32 s68, s28, 0x80000
	s_addc_u32 s69, s29, 0
	s_add_i32 s70, s67, s37
	s_mov_b32 m0, s70
	s_nop 0
	global_load_lds_dwordx4 v172, s[68:69]
	s_add_i32 m0, s70, 0x2000
	s_nop 0
	global_load_lds_dwordx4 v168, s[68:69]
	s_waitcnt vmcnt(6)
	s_barrier
	s_setprio 1
	v_mfma_f32_16x16x32_bf16 v[56:59], v[206:209], v[124:127], v[56:59]
	v_mfma_f32_16x16x32_bf16 v[52:55], v[214:217], v[124:127], v[52:55]
	v_mfma_f32_16x16x32_bf16 v[44:47], v[206:209], v[140:143], v[44:47]
	v_mfma_f32_16x16x32_bf16 v[36:39], v[214:217], v[140:143], v[36:39]
	v_mfma_f32_16x16x32_bf16 v[28:31], v[206:209], v[160:163], v[28:31]
	v_mfma_f32_16x16x32_bf16 v[20:23], v[214:217], v[160:163], v[20:23]
	v_mfma_f32_16x16x32_bf16 v[4:7], v[206:209], v[198:201], v[4:7]
	v_mfma_f32_16x16x32_bf16 v[0:3], v[214:217], v[198:201], v[0:3]
	v_mfma_f32_16x16x32_bf16 v[56:59], v[210:213], v[132:135], v[56:59]
	v_mfma_f32_16x16x32_bf16 v[52:55], v[218:221], v[132:135], v[52:55]
	v_mfma_f32_16x16x32_bf16 v[44:47], v[210:213], v[152:155], v[44:47]
	v_mfma_f32_16x16x32_bf16 v[36:39], v[218:221], v[152:155], v[36:39]
	v_mfma_f32_16x16x32_bf16 v[28:31], v[210:213], v[164:167], v[28:31]
	v_mfma_f32_16x16x32_bf16 v[20:23], v[218:221], v[164:167], v[20:23]
	v_mfma_f32_16x16x32_bf16 v[4:7], v[210:213], v[202:205], v[4:7]
	v_mfma_f32_16x16x32_bf16 v[0:3], v[218:221], v[202:205], v[0:3]
	s_setprio 0
	s_add_i32 s68, 0, 0x18000
	v_add_u32_e32 v92, s68, v188
	s_barrier
	ds_read_b128 v[80:83], v92
	ds_read_b128 v[84:87], v92 offset:1024
	ds_read_b128 v[88:91], v92 offset:2048
	ds_read_b128 v[92:95], v92 offset:3072
	s_add_u32 s46, s46, 0x80000
	s_addc_u32 s47, s47, 0
	s_mov_b32 m0, s55
	ds_read_b128 v[124:127], v190 offset:32768
	ds_read_b128 v[132:135], v190 offset:33792
	ds_read_b128 v[160:163], v190 offset:34816
	ds_read_b128 v[164:167], v190 offset:35840
	ds_read_b128 v[198:201], v190 offset:36864
	ds_read_b128 v[202:205], v190 offset:37888
	ds_read_b128 v[206:209], v190 offset:38912
	ds_read_b128 v[210:213], v190 offset:39936
	global_load_lds_dwordx4 v174, s[46:47]
	s_mov_b32 m0, s56
	s_nop 0
	global_load_lds_dwordx4 v170, s[46:47]
	s_waitcnt lgkmcnt(8)
	s_barrier
	s_setprio 1
	s_waitcnt lgkmcnt(7)
	v_mfma_f32_16x16x32_bf16 v[140:143], v[80:83], v[124:127], v[148:151]
	s_waitcnt lgkmcnt(6)
	v_mfma_f32_16x16x32_bf16 v[148:151], v[84:87], v[132:135], v[140:143]
	v_mfma_f32_16x16x32_bf16 v[140:143], v[88:91], v[124:127], v[144:147]
	s_waitcnt lgkmcnt(5)
	v_mfma_f32_16x16x32_bf16 v[136:139], v[80:83], v[160:163], v[136:139]
	v_mfma_f32_16x16x32_bf16 v[128:131], v[88:91], v[160:163], v[128:131]
	s_waitcnt lgkmcnt(3)
	v_mfma_f32_16x16x32_bf16 v[120:123], v[80:83], v[198:201], v[120:123]
	v_mfma_f32_16x16x32_bf16 v[104:107], v[88:91], v[198:201], v[104:107]
	s_waitcnt lgkmcnt(1)
	v_mfma_f32_16x16x32_bf16 v[76:79], v[80:83], v[206:209], v[76:79]
	v_mfma_f32_16x16x32_bf16 v[72:75], v[88:91], v[206:209], v[72:75]
	v_mfma_f32_16x16x32_bf16 v[144:147], v[92:95], v[132:135], v[140:143]
	v_mfma_f32_16x16x32_bf16 v[136:139], v[84:87], v[164:167], v[136:139]
	v_mfma_f32_16x16x32_bf16 v[128:131], v[92:95], v[164:167], v[128:131]
	v_mfma_f32_16x16x32_bf16 v[120:123], v[84:87], v[202:205], v[120:123]
	v_mfma_f32_16x16x32_bf16 v[104:107], v[92:95], v[202:205], v[104:107]
	s_waitcnt lgkmcnt(0)
	v_mfma_f32_16x16x32_bf16 v[76:79], v[84:87], v[210:213], v[76:79]
	v_mfma_f32_16x16x32_bf16 v[72:75], v[92:95], v[210:213], v[72:75]
	s_setprio 0
	s_barrier
	s_add_i32 s46, 0, 0x1c000
	v_add_u32_e32 v140, s46, v188
	s_add_i32 s47, s68, s37
	ds_read_b128 v[214:217], v140
	ds_read_b128 v[218:221], v140 offset:1024
	ds_read_b128 v[222:225], v140 offset:2048
	ds_read_b128 v[226:229], v140 offset:3072
	v_lshl_add_u64 v[140:141], v[184:185], 0, s[14:15]
	s_mov_b32 m0, s47
	s_nop 0
	global_load_lds_dwordx4 v[140:141], off
	v_lshl_add_u64 v[140:141], v[194:195], 0, s[14:15]
	s_add_i32 m0, s47, 0x2000
	s_nop 0
	global_load_lds_dwordx4 v[140:141], off
	s_barrier
	s_setprio 1
	s_waitcnt lgkmcnt(1)
	v_mfma_f32_16x16x32_bf16 v[96:99], v[222:225], v[124:127], v[96:99]
	v_mfma_f32_16x16x32_bf16 v[140:143], v[214:217], v[124:127], v[156:159]
	s_waitcnt lgkmcnt(0)
	v_mfma_f32_16x16x32_bf16 v[152:155], v[226:229], v[132:135], v[96:99]
	v_mfma_f32_16x16x32_bf16 v[96:99], v[214:217], v[160:163], v[100:103]
	v_mfma_f32_16x16x32_bf16 v[156:159], v[218:221], v[132:135], v[140:143]
	v_mfma_f32_16x16x32_bf16 v[140:143], v[218:221], v[164:167], v[96:99]
	v_mfma_f32_16x16x32_bf16 v[96:99], v[222:225], v[160:163], v[108:111]
	v_mfma_f32_16x16x32_bf16 v[132:135], v[226:229], v[164:167], v[96:99]
	v_mfma_f32_16x16x32_bf16 v[96:99], v[214:217], v[198:201], v[112:115]
	v_mfma_f32_16x16x32_bf16 v[124:127], v[218:221], v[202:205], v[96:99]
	v_mfma_f32_16x16x32_bf16 v[96:99], v[222:225], v[198:201], v[116:119]
	v_mfma_f32_16x16x32_bf16 v[68:71], v[214:217], v[206:209], v[68:71]
	v_mfma_f32_16x16x32_bf16 v[64:67], v[222:225], v[206:209], v[64:67]
	v_mfma_f32_16x16x32_bf16 v[116:119], v[226:229], v[202:205], v[96:99]
	v_mfma_f32_16x16x32_bf16 v[68:71], v[218:221], v[210:213], v[68:71]
	v_mfma_f32_16x16x32_bf16 v[64:67], v[226:229], v[210:213], v[64:67]
	s_setprio 0
	s_mov_b32 m0, s62
	v_lshl_add_u64 v[184:185], v[230:231], 0, s[14:15]
	s_barrier
	ds_read_b128 v[96:99], v190 offset:49152
	ds_read_b128 v[100:103], v190 offset:50176
	ds_read_b128 v[108:111], v190 offset:51200
	ds_read_b128 v[112:115], v190 offset:52224
	ds_read_b128 v[160:163], v190 offset:53248
	ds_read_b128 v[164:167], v190 offset:54272
	ds_read_b128 v[198:201], v190 offset:55296
	ds_read_b128 v[202:205], v190 offset:56320
	global_load_lds_dwordx4 v[184:185], off
	v_lshl_add_u64 v[184:185], v[232:233], 0, s[14:15]
	s_mov_b32 m0, s63
	s_nop 0
	global_load_lds_dwordx4 v[184:185], off
	s_barrier
; #define PG8_STAGE(bufoff, gbase, voff) do { _Pragma("unroll") for (int _i = 0; _i < 2; ++_i) \
;         __builtin_amdgcn_global_load_lds((const unsigned*)((const char*)(gbase) + (voff)[_i]), (LAS unsigned*)(lds + (bufoff) + ldsw + _i * 8192), 16, 0, 0); } while (0)
; #define PG8_MMA(ai, bj, At, Bt) do { __builtin_amdgcn_s_setprio(1); _Pragma("unroll") for (int m = 0; m < 4; ++m) _Pragma("unroll") for (int n = 0; n < 2; ++n) _Pragma("unroll") for (int k = 0; k < 2; ++k) \
;         acc[ai][bj][m][n] = __builtin_amdgcn_mfma_f32_16x16x32_bf16(Bt[n][k], At[m][k], acc[ai][bj][m][n], 0, 0, 0); __builtin_amdgcn_s_setprio(0); } while (0)
; #define PG8_WAIT_V(n) asm volatile("s_waitcnt vmcnt(" #n ")" ::: "memory")
; #define PG8_WAIT_L(n) asm volatile("s_waitcnt lgkmcnt(" #n ")" ::: "memory")
; #define PG8_BAR __builtin_amdgcn_s_barrier()
; #define PG8_SCHED __builtin_amdgcn_sched_barrier(0)
; template <class Map, class Epi>
; DI void gemm_phase(LAS unsigned char* lds, const Map& MP, const Epi& E, const int nM, const int nN, const int K, const int lda, const int ldb) {
;     ...
;             PG8_BAR; PG8_WAIT_L(0); PG8_MMA(1, 0, At, B0); PG8_BAR; PG8_SCHED;
;             PG8_STAGE(PG8_SB(1, 1), b3 + hstepB, voffB);
;             PG8_WAIT_V(6); PG8_BAR; PG8_MMA(1, 1, At, B1); PG8_BAR;
	s_setprio 1
	s_waitcnt lgkmcnt(7)
	v_mfma_f32_16x16x32_bf16 v[60:63], v[80:83], v[96:99], v[60:63]
	v_mfma_f32_16x16x32_bf16 v[48:51], v[88:91], v[96:99], v[48:51]
	s_waitcnt lgkmcnt(5)
	v_mfma_f32_16x16x32_bf16 v[40:43], v[80:83], v[108:111], v[40:43]
	v_mfma_f32_16x16x32_bf16 v[32:35], v[88:91], v[108:111], v[32:35]
	s_waitcnt lgkmcnt(3)
	v_mfma_f32_16x16x32_bf16 v[24:27], v[80:83], v[160:163], v[24:27]
	v_mfma_f32_16x16x32_bf16 v[16:19], v[88:91], v[160:163], v[16:19]
	s_waitcnt lgkmcnt(1)
	v_mfma_f32_16x16x32_bf16 v[12:15], v[80:83], v[198:201], v[12:15]
	v_mfma_f32_16x16x32_bf16 v[8:11], v[88:91], v[198:201], v[8:11]
	v_mfma_f32_16x16x32_bf16 v[60:63], v[84:87], v[100:103], v[60:63]
	v_mfma_f32_16x16x32_bf16 v[48:51], v[92:95], v[100:103], v[48:51]
	v_mfma_f32_16x16x32_bf16 v[40:43], v[84:87], v[112:115], v[40:43]
	v_mfma_f32_16x16x32_bf16 v[32:35], v[92:95], v[112:115], v[32:35]
	v_mfma_f32_16x16x32_bf16 v[24:27], v[84:87], v[164:167], v[24:27]
	v_mfma_f32_16x16x32_bf16 v[16:19], v[92:95], v[164:167], v[16:19]
	s_waitcnt lgkmcnt(0)
	v_mfma_f32_16x16x32_bf16 v[12:15], v[84:87], v[202:205], v[12:15]
	v_mfma_f32_16x16x32_bf16 v[8:11], v[92:95], v[202:205], v[8:11]
	s_setprio 0
	s_barrier
	s_add_u32 s28, s28, 0x80080
	s_addc_u32 s29, s29, 0
	s_add_i32 s46, s46, s37
	s_mov_b32 m0, s46
	s_nop 0
	global_load_lds_dwordx4 v172, s[28:29]
	s_add_i32 m0, s46, 0x2000
	s_nop 0
	global_load_lds_dwordx4 v168, s[28:29]
	s_waitcnt vmcnt(6)
	s_barrier
	s_setprio 1
	v_mfma_f32_16x16x32_bf16 v[56:59], v[214:217], v[96:99], v[56:59]
	v_mfma_f32_16x16x32_bf16 v[52:55], v[222:225], v[96:99], v[52:55]
	v_mfma_f32_16x16x32_bf16 v[44:47], v[214:217], v[108:111], v[44:47]
	v_mfma_f32_16x16x32_bf16 v[36:39], v[222:225], v[108:111], v[36:39]
	v_mfma_f32_16x16x32_bf16 v[28:31], v[214:217], v[160:163], v[28:31]
	v_mfma_f32_16x16x32_bf16 v[20:23], v[222:225], v[160:163], v[20:23]
	v_mfma_f32_16x16x32_bf16 v[4:7], v[214:217], v[198:201], v[4:7]
	v_mfma_f32_16x16x32_bf16 v[0:3], v[222:225], v[198:201], v[0:3]
	v_mfma_f32_16x16x32_bf16 v[56:59], v[218:221], v[100:103], v[56:59]
	v_mfma_f32_16x16x32_bf16 v[52:55], v[226:229], v[100:103], v[52:55]
	v_mfma_f32_16x16x32_bf16 v[44:47], v[218:221], v[112:115], v[44:47]
	v_mfma_f32_16x16x32_bf16 v[36:39], v[226:229], v[112:115], v[36:39]
	v_mfma_f32_16x16x32_bf16 v[28:31], v[218:221], v[164:167], v[28:31]
	v_mfma_f32_16x16x32_bf16 v[20:23], v[226:229], v[164:167], v[20:23]
	v_mfma_f32_16x16x32_bf16 v[4:7], v[218:221], v[202:205], v[4:7]
	v_mfma_f32_16x16x32_bf16 v[0:3], v[226:229], v[202:205], v[0:3]
	s_setprio 0
	s_add_i32 s3, s3, 2
	s_add_u32 vcc_lo, vcc_lo, 0x100
	s_addc_u32 vcc_hi, vcc_hi, 0
	s_add_u32 s42, s42, 0x100
	s_addc_u32 s43, s43, 0
	s_cmp_gt_u32 s3, 29
	s_barrier
	s_cbranch_scc0 .LBB1_2483
; DI float silu_mul(float g, float v) { return g * v * __builtin_amdgcn_rcpf(1.0f + __builtin_amdgcn_exp2f(-LOG2E * g)); }
;     DI void operator()(const f32x4 (&acc)[2][2][4][2], const Unit& u, int wr, int wc, int fr, int fq) const {
;         const int row0 = u.pm * BM + wr * 64 + fr, ch0 = u.pn * 128 + wc * 32 + 8 * fq;
;         f32x4 w0[2], w1[2], w2[2], bb[2];
; #pragma unroll
;         for (int n = 0; n < 2; ++n) { w0[n] = *(const f32x4*)(cw + ch0 + 4 * n); w1[n] = *(const f32x4*)(cw + DFF + ch0 + 4 * n); w2[n] = *(const f32x4*)(cw + 2 * DFF + ch0 + 4 * n); bb[n] = *(const f32x4*)(cb + ch0 + 4 * n); }
; #pragma unroll
;         for (int ai = 0; ai < 2; ++ai)
; #pragma unroll
;             for (int m = 0; m < 4; ++m) {
;                 const bool efirst = (m == 0) && (fr == 0), elast = (m == 3) && (fr == 15);
;                 const int row = row0 + ai * HALF + m * 16;
;                 f32x4 gc[2];
; #pragma unroll
;                 for (int n = 0; n < 2; ++n) {
;                     const f32x4 g = acc[ai][0][m][n];
;                     const f32x4 gprev = acc[ai][0][m > 0 ? m - 1 : 0][n], gnext = acc[ai][0][m < 3 ? m + 1 : 3][n];
;                     f32x4 up, dn;
; #pragma unroll
;                     for (int e = 0; e < 4; ++e) {
;                         const float pu = (m > 0 && fr == 15) ? gprev[e] : g[e];
;                         const float pd = (m < 3 && fr == 0) ? gnext[e] : g[e];
;                         up[e] = dpp_ror1(pu); dn[e] = dpp_ror15(pd);
;                     }
;                     if (efirst) up = (f32x4){0.f, 0.f, 0.f, 0.f};
;                     if (elast) dn = (f32x4){0.f, 0.f, 0.f, 0.f};
;                     gc[n] = w0[n] * up + w1[n] * g + w2[n] * dn + bb[n];
;                 }
;                 if (efirst || elast) {
;                     const size_t eo = (size_t)((row >> 6) * 2 + (elast ? 1 : 0)) * DFF + ch0;
; #pragma unroll
;                     for (int n = 0; n < 2; ++n) { *(f32x4*)(EP + eo + 4 * n) = gc[n]; *(f32x4*)(ER + eo + 4 * n) = acc[ai][0][m][n]; *(f32x4*)(EV + eo + 4 * n) = acc[ai][1][m][n]; }
;                 } else {
;                     const f32x4 v0 = acc[ai][1][m][0], v1 = acc[ai][1][m][1];
;                     u32x4 o;
;                     o[0] = pack2(silu_mul(gc[0][0], v0[0]), silu_mul(gc[0][1], v0[1])); o[1] = pack2(silu_mul(gc[0][2], v0[2]), silu_mul(gc[0][3], v0[3]));
	s_lshl_b32 s21, s45, 7
	v_mov_b32_e32 v80, v187
	v_mov_b32_e32 v194, v186
	s_or_b32 s21, s21, s57
	v_mov_b32_e32 v160, 0
	v_lshl_add_u32 v184, v80, 3, s21
	v_ashrrev_i32_e32 v185, 31, v184
	v_lshlrev_b64 v[80:81], 2, v[184:185]
	v_lshl_add_u64 v[84:85], s[4:5], 0, v[80:81]
	v_lshl_add_u64 v[88:89], s[16:17], 0, v[80:81]
	v_lshl_add_u64 v[92:93], s[18:19], 0, v[80:81]
	v_lshl_add_u64 v[112:113], s[6:7], 0, v[80:81]
	global_load_dwordx4 v[80:83], v[84:85], off offset:16
	global_load_dwordx4 v[96:99], v[84:85], off
	s_nop 0
	global_load_dwordx4 v[84:87], v[88:89], off offset:16
	global_load_dwordx4 v[100:103], v[88:89], off
	s_nop 0
	global_load_dwordx4 v[88:91], v[92:93], off offset:16
	global_load_dwordx4 v[108:111], v[92:93], off
	s_nop 0
	global_load_dwordx4 v[92:95], v[112:113], off offset:16
	s_nop 0
	global_load_dwordx4 v[112:115], v[112:113], off
	v_cmp_eq_u32_e32 vcc, 0, v194
	v_mov_b32_e32 v164, 0
	v_mov_b32_e32 v195, 0
	v_cndmask_b32_e32 v161, v148, v136, vcc
	v_cndmask_b32_e32 v162, v149, v137, vcc
	v_cndmask_b32_e32 v163, v150, v138, vcc
	v_mov_b32_dpp v160, v161 row_ror:15 row_mask:0xf bank_mask:0xf
	v_mov_b32_e32 v161, 0
	v_mov_b32_e32 v166, 0
	v_mov_b32_e32 v167, 0
	v_mov_b32_dpp v161, v162 row_ror:15 row_mask:0xf bank_mask:0xf
	v_mov_b32_e32 v162, 0
	v_mov_b32_dpp v164, v150 row_ror:1 row_mask:0xf bank_mask:0xf
	v_cndmask_b32_e32 v165, v151, v139, vcc
	v_mov_b32_dpp v162, v163 row_ror:15 row_mask:0xf bank_mask:0xf
	v_mov_b32_dpp v195, v151 row_ror:1 row_mask:0xf bank_mask:0xf
	v_mov_b32_e32 v163, 0
	v_mov_b32_dpp v166, v148 row_ror:1 row_mask:0xf bank_mask:0xf
	v_mov_b32_dpp v167, v149 row_ror:1 row_mask:0xf bank_mask:0xf
	v_mov_b32_dpp v163, v165 row_ror:15 row_mask:0xf bank_mask:0xf
	v_cndmask_b32_e64 v165, v195, 0, vcc
	v_cndmask_b32_e64 v164, v164, 0, vcc
	v_cndmask_b32_e64 v167, v167, 0, vcc
	v_cndmask_b32_e64 v166, v166, 0, vcc
	v_mov_b32_e32 v195, 0
	v_mov_b32_e32 v196, 0
	v_mov_b32_e32 v198, 0
	v_mov_b32_e32 v200, 0
	v_mov_b32_dpp v195, v144 row_ror:1 row_mask:0xf bank_mask:0xf
	v_mov_b32_dpp v196, v145 row_ror:1 row_mask:0xf bank_mask:0xf
	v_mov_b32_dpp v198, v146 row_ror:1 row_mask:0xf bank_mask:0xf
	v_cndmask_b32_e32 v199, v147, v131, vcc
	v_mov_b32_dpp v200, v147 row_ror:1 row_mask:0xf bank_mask:0xf
	v_cndmask_b32_e64 v198, v198, 0, vcc
	v_cndmask_b32_e64 v201, v196, 0, vcc
	s_lshl_b32 s3, s44, 8
	s_add_i32 s3, s3, s49
	v_add_u32_e32 v193, s3, v194
	v_cmp_ne_u32_e64 s[46:47], 0, v194
	s_waitcnt vmcnt(0)
	v_pk_mul_f32 v[164:165], v[98:99], v[164:165]
	v_pk_mul_f32 v[166:167], v[96:97], v[166:167]
	v_pk_fma_f32 v[164:165], v[150:151], v[102:103], v[164:165]
	v_pk_fma_f32 v[166:167], v[148:149], v[100:101], v[166:167]
	v_pk_fma_f32 v[162:163], v[110:111], v[162:163], v[164:165]
	v_cndmask_b32_e32 v165, v144, v128, vcc
	v_mov_b32_e32 v164, 0
	v_pk_fma_f32 v[160:161], v[108:109], v[160:161], v[166:167]
	v_cndmask_b32_e32 v166, v145, v129, vcc
	v_mov_b32_dpp v164, v165 row_ror:15 row_mask:0xf bank_mask:0xf
	v_mov_b32_e32 v165, 0
	v_cndmask_b32_e32 v167, v146, v130, vcc
	v_pk_add_f32 v[162:163], v[114:115], v[162:163]
	v_mov_b32_dpp v165, v166 row_ror:15 row_mask:0xf bank_mask:0xf
	v_mov_b32_e32 v166, 0
	v_pk_add_f32 v[160:161], v[112:113], v[160:161]
	s_nop 0
	v_mov_b32_dpp v166, v167 row_ror:15 row_mask:0xf bank_mask:0xf
	v_mov_b32_e32 v167, 0
	s_nop 1
	v_mov_b32_dpp v167, v199 row_ror:15 row_mask:0xf bank_mask:0xf
	v_cndmask_b32_e64 v199, v200, 0, vcc
	v_cndmask_b32_e64 v200, v195, 0, vcc
	v_pk_mul_f32 v[200:201], v[80:81], v[200:201]
	v_pk_mul_f32 v[198:199], v[82:83], v[198:199]
	v_pk_fma_f32 v[200:201], v[144:145], v[84:85], v[200:201]
	v_pk_fma_f32 v[198:199], v[146:147], v[86:87], v[198:199]
	v_pk_fma_f32 v[164:165], v[88:89], v[164:165], v[200:201]
	v_pk_fma_f32 v[166:167], v[90:91], v[166:167], v[198:199]
	v_pk_add_f32 v[164:165], v[92:93], v[164:165]
	v_pk_add_f32 v[166:167], v[94:95], v[166:167]
	s_and_saveexec_b64 s[28:29], s[46:47]
	s_xor_b64 s[28:29], exec, s[28:29]
	s_cbranch_execz .LBB1_2486
	v_mul_f32_e32 v195, 0xbfb8aa3b, v160
	v_exp_f32_e32 v195, v195
	v_mul_f32_e32 v196, 0xbfb8aa3b, v161
	v_exp_f32_e32 v196, v196
	v_pk_mul_f32 v[160:161], v[156:157], v[160:161]
	v_add_f32_e32 v195, 1.0, v195
	v_rcp_f32_e32 v198, v195
	v_add_f32_e32 v196, 1.0, v196
	v_mul_f32_e32 v195, 0xbfb8aa3b, v162
	v_rcp_f32_e32 v199, v196
	v_exp_f32_e32 v195, v195
	v_mul_f32_e32 v196, 0xbfb8aa3b, v163
	v_exp_f32_e32 v196, v196
	v_pk_mul_f32 v[160:161], v[160:161], v[198:199]
	v_add_f32_e32 v195, 1.0, v195
	v_rcp_f32_e32 v200, v195
	v_add_f32_e32 v195, 1.0, v196
	v_rcp_f32_e32 v201, v195
	v_cvt_pk_bf16_f32 v160, v160, v161
	v_mul_f32_e32 v161, 0xbfb8aa3b, v164
	v_exp_f32_e32 v195, v161
	v_mul_f32_e32 v161, 0xbfb8aa3b, v165
	v_exp_f32_e32 v196, v161
	v_pk_mul_f32 v[162:163], v[158:159], v[162:163]
	v_pk_mul_f32 v[164:165], v[152:153], v[164:165]
	v_pk_mul_f32 v[162:163], v[162:163], v[200:201]
	s_nop 0
	v_cvt_pk_bf16_f32 v161, v162, v163
	v_add_f32_e32 v162, 1.0, v195
	v_mul_f32_e32 v195, 0xbfb8aa3b, v166
	v_add_f32_e32 v163, 1.0, v196
	v_exp_f32_e32 v195, v195
	v_mul_f32_e32 v196, 0xbfb8aa3b, v167
	v_exp_f32_e32 v196, v196
	v_rcp_f32_e32 v162, v162
	v_add_f32_e32 v195, 1.0, v195
	v_rcp_f32_e32 v198, v195
	v_add_f32_e32 v195, 1.0, v196
	v_rcp_f32_e32 v163, v163
	v_rcp_f32_e32 v199, v195
	v_pk_mul_f32 v[166:167], v[154:155], v[166:167]
	v_pk_mul_f32 v[162:163], v[164:165], v[162:163]
	v_pk_mul_f32 v[164:165], v[166:167], v[198:199]
	v_cvt_pk_bf16_f32 v162, v162, v163
	v_cvt_pk_bf16_f32 v163, v164, v165
	v_mov_b64_e32 v[164:165], s[52:53]
	v_mad_i64_i32 v[164:165], s[42:43], v193, s60, v[164:165]
	v_lshl_add_u64 v[164:165], v[184:185], 1, v[164:165]
	global_store_dwordx4 v[164:165], v[160:163], off

; #define PG8_STAGE(bufoff, gbase, voff) do { _Pragma("unroll") for (int _i = 0; _i < 2; ++_i) \
;         __builtin_amdgcn_global_load_lds((const unsigned*)((const char*)(gbase) + (voff)[_i]), (LAS unsigned*)(lds + (bufoff) + ldsw + _i * 8192), 16, 0, 0); } while (0)
; #define PG8_LDA(dst, b, h) do { _Pragma("unroll") for (int m = 0; m < 4; ++m) _Pragma("unroll") for (int k = 0; k < 2; ++k) dst[m][k] = *(const LAS bf16x8*)(lds + PG8_SA(b, h) + aoff + m * 2048 + k * 1024); } while (0)
; #define PG8_LDB(dst, b, h) do { _Pragma("unroll") for (int n = 0; n < 2; ++n) _Pragma("unroll") for (int k = 0; k < 2; ++k) dst[n][k] = *(const LAS bf16x8*)(lds + PG8_SB(b, h) + boff + n * 2048 + k * 1024); } while (0)
; #define PG8_MMA(ai, bj, At, Bt) do { __builtin_amdgcn_s_setprio(1); _Pragma("unroll") for (int m = 0; m < 4; ++m) _Pragma("unroll") for (int n = 0; n < 2; ++n) _Pragma("unroll") for (int k = 0; k < 2; ++k) \
;         acc[ai][bj][m][n] = __builtin_amdgcn_mfma_f32_16x16x32_bf16(Bt[n][k], At[m][k], acc[ai][bj][m][n], 0, 0, 0); __builtin_amdgcn_s_setprio(0); } while (0)
; #define PG8_WAIT_L(n) asm volatile("s_waitcnt lgkmcnt(" #n ")" ::: "memory")
; #define PG8_BAR __builtin_amdgcn_s_barrier()
; #define PG8_SCHED __builtin_amdgcn_sched_barrier(0)
; template <class Map, class Epi>
; DI void gemm_phase(LAS unsigned char* lds, const Map& MP, const Epi& E, const int nM, const int nN, const int K, const int lda, const int ldb) {
;     ...
;             PG8_LDB(B0, 0, 0); PG8_SCHED; PG8_LDA(At, 0, 0); PG8_STAGE(PG8_SA(1, 1), a1 + hstepA, voffA);
;             PG8_WAIT_L(8); PG8_BAR; PG8_WAIT_L(0); PG8_MMA(0, 0, At, B0); PG8_BAR; PG8_SCHED;
;             PG8_LDB(B1, 0, 1); PG8_STAGE(PG8_SB(0, 0), b2, voffB);
;             PG8_BAR; PG8_WAIT_L(0); PG8_MMA(0, 1, At, B1); PG8_BAR;
;             PG8_LDA(At, 0, 1); PG8_STAGE(PG8_SA(0, 0), a2, voffA);
;             PG8_BAR; PG8_WAIT_L(0); PG8_MMA(1, 0, At, B0); PG8_BAR; PG8_SCHED;
.LBB1_2653:
	ds_read_b128 v[152:155], v149
	ds_read_b128 v[156:159], v149 offset:1024
	ds_read_b128 v[160:163], v149 offset:2048
	ds_read_b128 v[164:167], v149 offset:3072
	s_add_u32 s10, s8, 0x100
	s_addc_u32 s11, s9, 0
	s_cmpk_eq_i32 s48, 0x54
	s_cselect_b32 s15, s43, s11
	s_cselect_b32 s14, s42, s10
	s_cselect_b32 s13, s45, s39
	s_cselect_b32 s12, s44, s38
	s_add_i32 m0, s22, 0xc000
	ds_read_b128 v[168:171], v150
	ds_read_b128 v[172:175], v150 offset:1024
	ds_read_b128 v[176:179], v150 offset:2048
	ds_read_b128 v[180:183], v150 offset:3072
	ds_read_b128 v[184:187], v150 offset:4096
	ds_read_b128 v[188:191], v150 offset:5120
	ds_read_b128 v[192:195], v150 offset:6144
	ds_read_b128 v[196:199], v150 offset:7168
	global_load_lds_dwordx4 v138, s[8:9]
	s_add_i32 m0, s22, 0xe000
	s_nop 0
	global_load_lds_dwordx4 v136, s[8:9]
	s_waitcnt lgkmcnt(8)
	s_barrier
	s_setprio 1
	s_waitcnt lgkmcnt(7)
	v_mfma_f32_16x16x32_bf16 v[124:127], v[152:155], v[168:171], v[124:127]
	v_mfma_f32_16x16x32_bf16 v[120:123], v[160:163], v[168:171], v[120:123]
	s_waitcnt lgkmcnt(5)
	v_mfma_f32_16x16x32_bf16 v[108:111], v[152:155], v[176:179], v[108:111]
	v_mfma_f32_16x16x32_bf16 v[104:107], v[160:163], v[176:179], v[104:107]
	s_waitcnt lgkmcnt(3)
	v_mfma_f32_16x16x32_bf16 v[92:95], v[152:155], v[184:187], v[92:95]
	v_mfma_f32_16x16x32_bf16 v[88:91], v[160:163], v[184:187], v[88:91]
	s_waitcnt lgkmcnt(1)
	v_mfma_f32_16x16x32_bf16 v[76:79], v[152:155], v[192:195], v[76:79]
	v_mfma_f32_16x16x32_bf16 v[72:75], v[160:163], v[192:195], v[72:75]
	v_mfma_f32_16x16x32_bf16 v[124:127], v[156:159], v[172:175], v[124:127]
	v_mfma_f32_16x16x32_bf16 v[120:123], v[164:167], v[172:175], v[120:123]
	v_mfma_f32_16x16x32_bf16 v[108:111], v[156:159], v[180:183], v[108:111]
	v_mfma_f32_16x16x32_bf16 v[104:107], v[164:167], v[180:183], v[104:107]
	v_mfma_f32_16x16x32_bf16 v[92:95], v[156:159], v[188:191], v[92:95]
	v_mfma_f32_16x16x32_bf16 v[88:91], v[164:167], v[188:191], v[88:91]
	s_waitcnt lgkmcnt(0)
	v_mfma_f32_16x16x32_bf16 v[76:79], v[156:159], v[196:199], v[76:79]
	v_mfma_f32_16x16x32_bf16 v[72:75], v[164:167], v[196:199], v[72:75]
	s_setprio 0
	s_barrier
	s_add_i32 s8, s33, s20
	v_lshl_add_u64 v[144:145], s[12:13], 0, v[132:133]
	s_mov_b32 m0, s8
	ds_read_b128 v[200:203], v151
	ds_read_b128 v[204:207], v151 offset:1024
	ds_read_b128 v[208:211], v151 offset:2048
	ds_read_b128 v[212:215], v151 offset:3072
	global_load_lds_dwordx4 v[144:145], off
	v_lshl_add_u64 v[216:217], s[12:13], 0, v[128:129]
	s_add_i32 m0, s8, 0x2000
	s_nop 0
	global_load_lds_dwordx4 v[216:217], off
	s_barrier
	s_setprio 1
	s_waitcnt lgkmcnt(3)
	v_mfma_f32_16x16x32_bf16 v[116:119], v[200:203], v[168:171], v[116:119]
	s_waitcnt lgkmcnt(1)
	v_mfma_f32_16x16x32_bf16 v[112:115], v[208:211], v[168:171], v[112:115]
	v_mfma_f32_16x16x32_bf16 v[100:103], v[200:203], v[176:179], v[100:103]
	v_mfma_f32_16x16x32_bf16 v[96:99], v[208:211], v[176:179], v[96:99]
	v_mfma_f32_16x16x32_bf16 v[84:87], v[200:203], v[184:187], v[84:87]
	v_mfma_f32_16x16x32_bf16 v[80:83], v[208:211], v[184:187], v[80:83]
	v_mfma_f32_16x16x32_bf16 v[68:71], v[200:203], v[192:195], v[68:71]
	v_mfma_f32_16x16x32_bf16 v[64:67], v[208:211], v[192:195], v[64:67]
	v_mfma_f32_16x16x32_bf16 v[116:119], v[204:207], v[172:175], v[116:119]
	s_waitcnt lgkmcnt(0)
	v_mfma_f32_16x16x32_bf16 v[112:115], v[212:215], v[172:175], v[112:115]
	v_mfma_f32_16x16x32_bf16 v[100:103], v[204:207], v[180:183], v[100:103]
	v_mfma_f32_16x16x32_bf16 v[96:99], v[212:215], v[180:183], v[96:99]
	v_mfma_f32_16x16x32_bf16 v[84:87], v[204:207], v[188:191], v[84:87]
	v_mfma_f32_16x16x32_bf16 v[80:83], v[212:215], v[188:191], v[80:83]
	v_mfma_f32_16x16x32_bf16 v[68:71], v[204:207], v[196:199], v[68:71]
	v_mfma_f32_16x16x32_bf16 v[64:67], v[212:215], v[196:199], v[64:67]
	s_setprio 0
	s_mov_b32 m0, s22
	v_lshl_add_u64 v[218:219], s[14:15], 0, v[134:135]
	s_barrier
	ds_read_b128 v[168:171], v150 offset:16384
	ds_read_b128 v[172:175], v150 offset:17408
	ds_read_b128 v[176:179], v150 offset:18432
	ds_read_b128 v[180:183], v150 offset:19456
	ds_read_b128 v[184:187], v150 offset:20480
	ds_read_b128 v[188:191], v150 offset:21504
	ds_read_b128 v[192:195], v150 offset:22528
	ds_read_b128 v[196:199], v150 offset:23552
	global_load_lds_dwordx4 v[218:219], off
	v_lshl_add_u64 v[220:221], s[14:15], 0, v[130:131]
	s_mov_b32 m0, s23
	s_nop 0
	global_load_lds_dwordx4 v[220:221], off
	s_barrier
	s_setprio 1
	s_waitcnt lgkmcnt(7)
	v_mfma_f32_16x16x32_bf16 v[60:63], v[152:155], v[168:171], v[60:63]
	v_mfma_f32_16x16x32_bf16 v[56:59], v[160:163], v[168:171], v[56:59]
	s_waitcnt lgkmcnt(5)
	v_mfma_f32_16x16x32_bf16 v[44:47], v[152:155], v[176:179], v[44:47]
	v_mfma_f32_16x16x32_bf16 v[40:43], v[160:163], v[176:179], v[40:43]
	s_waitcnt lgkmcnt(3)
	v_mfma_f32_16x16x32_bf16 v[28:31], v[152:155], v[184:187], v[28:31]
	v_mfma_f32_16x16x32_bf16 v[24:27], v[160:163], v[184:187], v[24:27]
	s_waitcnt lgkmcnt(1)
	v_mfma_f32_16x16x32_bf16 v[12:15], v[152:155], v[192:195], v[12:15]
	v_mfma_f32_16x16x32_bf16 v[8:11], v[160:163], v[192:195], v[8:11]
	v_mfma_f32_16x16x32_bf16 v[60:63], v[156:159], v[172:175], v[60:63]
	v_mfma_f32_16x16x32_bf16 v[56:59], v[164:167], v[172:175], v[56:59]
	v_mfma_f32_16x16x32_bf16 v[44:47], v[156:159], v[180:183], v[44:47]
	v_mfma_f32_16x16x32_bf16 v[40:43], v[164:167], v[180:183], v[40:43]
	v_mfma_f32_16x16x32_bf16 v[28:31], v[156:159], v[188:191], v[28:31]
	v_mfma_f32_16x16x32_bf16 v[24:27], v[164:167], v[188:191], v[24:27]
	s_waitcnt lgkmcnt(0)
	v_mfma_f32_16x16x32_bf16 v[12:15], v[156:159], v[196:199], v[12:15]
	v_mfma_f32_16x16x32_bf16 v[8:11], v[164:167], v[196:199], v[8:11]
	s_setprio 0
	s_barrier
; #define PG8_STAGE(bufoff, gbase, voff) do { _Pragma("unroll") for (int _i = 0; _i < 2; ++_i) \
;         __builtin_amdgcn_global_load_lds((const unsigned*)((const char*)(gbase) + (voff)[_i]), (LAS unsigned*)(lds + (bufoff) + ldsw + _i * 8192), 16, 0, 0); } while (0)
; #define PG8_LDA(dst, b, h) do { _Pragma("unroll") for (int m = 0; m < 4; ++m) _Pragma("unroll") for (int k = 0; k < 2; ++k) dst[m][k] = *(const LAS bf16x8*)(lds + PG8_SA(b, h) + aoff + m * 2048 + k * 1024); } while (0)
; #define PG8_LDB(dst, b, h) do { _Pragma("unroll") for (int n = 0; n < 2; ++n) _Pragma("unroll") for (int k = 0; k < 2; ++k) dst[n][k] = *(const LAS bf16x8*)(lds + PG8_SB(b, h) + boff + n * 2048 + k * 1024); } while (0)
; #define PG8_MMA(ai, bj, At, Bt) do { __builtin_amdgcn_s_setprio(1); _Pragma("unroll") for (int m = 0; m < 4; ++m) _Pragma("unroll") for (int n = 0; n < 2; ++n) _Pragma("unroll") for (int k = 0; k < 2; ++k) \
;         acc[ai][bj][m][n] = __builtin_amdgcn_mfma_f32_16x16x32_bf16(Bt[n][k], At[m][k], acc[ai][bj][m][n], 0, 0, 0); __builtin_amdgcn_s_setprio(0); } while (0)
; #define PG8_WAIT_V(n) asm volatile("s_waitcnt vmcnt(" #n ")" ::: "memory")
; #define PG8_WAIT_L(n) asm volatile("s_waitcnt lgkmcnt(" #n ")" ::: "memory")
; #define PG8_BAR __builtin_amdgcn_s_barrier()
; #define PG8_SCHED __builtin_amdgcn_sched_barrier(0)
; template <class Map, class Epi>
; DI void gemm_phase(LAS unsigned char* lds, const Map& MP, const Epi& E, const int nM, const int nN, const int K, const int lda, const int ldb) {
;     ...
;             PG8_STAGE(PG8_SB(0, 1), b2 + hstepB, voffB);
;             PG8_WAIT_V(6); PG8_BAR; PG8_MMA(1, 1, At, B1); PG8_BAR;
;             PG8_LDB(B0, 1, 0); PG8_SCHED; PG8_LDA(At, 1, 0); PG8_STAGE(PG8_SA(0, 1), a2 + hstepA, voffA);
;             PG8_WAIT_L(8); PG8_BAR; PG8_WAIT_L(0); PG8_MMA(0, 0, At, B0); PG8_BAR; PG8_SCHED;
;             PG8_LDB(B1, 1, 1); PG8_STAGE(PG8_SB(1, 0), b3, voffB);
;             PG8_BAR; PG8_WAIT_L(0); PG8_MMA(0, 1, At, B1); PG8_BAR;
;             PG8_LDA(At, 1, 1); PG8_STAGE(PG8_SA(1, 0), a3, voffA);
	s_add_u32 s8, s12, 0x160000
	s_addc_u32 s9, s13, 0
	s_add_i32 s49, s34, s20
	s_mov_b32 m0, s49
	s_nop 0
	global_load_lds_dwordx4 v132, s[8:9]
	s_add_i32 m0, s49, 0x2000
	s_nop 0
	global_load_lds_dwordx4 v128, s[8:9]
	s_waitcnt vmcnt(6)
	s_barrier
	s_setprio 1
	v_mfma_f32_16x16x32_bf16 v[52:55], v[200:203], v[168:171], v[52:55]
	v_mfma_f32_16x16x32_bf16 v[48:51], v[208:211], v[168:171], v[48:51]
	v_mfma_f32_16x16x32_bf16 v[36:39], v[200:203], v[176:179], v[36:39]
	v_mfma_f32_16x16x32_bf16 v[32:35], v[208:211], v[176:179], v[32:35]
	v_mfma_f32_16x16x32_bf16 v[20:23], v[200:203], v[184:187], v[20:23]
	v_mfma_f32_16x16x32_bf16 v[16:19], v[208:211], v[184:187], v[16:19]
	v_mfma_f32_16x16x32_bf16 v[4:7], v[200:203], v[192:195], v[4:7]
	v_mfma_f32_16x16x32_bf16 v[0:3], v[208:211], v[192:195], v[0:3]
	v_mfma_f32_16x16x32_bf16 v[52:55], v[204:207], v[172:175], v[52:55]
	v_mfma_f32_16x16x32_bf16 v[48:51], v[212:215], v[172:175], v[48:51]
	v_mfma_f32_16x16x32_bf16 v[36:39], v[204:207], v[180:183], v[36:39]
	v_mfma_f32_16x16x32_bf16 v[32:35], v[212:215], v[180:183], v[32:35]
	v_mfma_f32_16x16x32_bf16 v[20:23], v[204:207], v[188:191], v[20:23]
	v_mfma_f32_16x16x32_bf16 v[16:19], v[212:215], v[188:191], v[16:19]
	v_mfma_f32_16x16x32_bf16 v[4:7], v[204:207], v[196:199], v[4:7]
	v_mfma_f32_16x16x32_bf16 v[0:3], v[212:215], v[196:199], v[0:3]
	s_setprio 0
	s_add_i32 s49, 0, 0x18000
	v_add_u32_e32 v164, s49, v148
	s_barrier
	ds_read_b128 v[152:155], v164
	ds_read_b128 v[156:159], v164 offset:1024
	ds_read_b128 v[160:163], v164 offset:2048
	ds_read_b128 v[164:167], v164 offset:3072
	s_add_u32 s8, s14, 0x160000
	s_addc_u32 s9, s15, 0
	s_mov_b32 m0, s24
	ds_read_b128 v[168:171], v150 offset:32768
	ds_read_b128 v[172:175], v150 offset:33792
	ds_read_b128 v[176:179], v150 offset:34816
	ds_read_b128 v[180:183], v150 offset:35840
	ds_read_b128 v[184:187], v150 offset:36864
	ds_read_b128 v[188:191], v150 offset:37888
	ds_read_b128 v[192:195], v150 offset:38912
	ds_read_b128 v[196:199], v150 offset:39936
	global_load_lds_dwordx4 v134, s[8:9]
	s_mov_b32 m0, s25
	s_nop 0
	global_load_lds_dwordx4 v130, s[8:9]
	s_waitcnt lgkmcnt(8)
	s_barrier
	s_setprio 1
	s_waitcnt lgkmcnt(7)
	v_mfma_f32_16x16x32_bf16 v[124:127], v[152:155], v[168:171], v[124:127]
	v_mfma_f32_16x16x32_bf16 v[120:123], v[160:163], v[168:171], v[120:123]
	s_waitcnt lgkmcnt(5)
	v_mfma_f32_16x16x32_bf16 v[108:111], v[152:155], v[176:179], v[108:111]
	v_mfma_f32_16x16x32_bf16 v[104:107], v[160:163], v[176:179], v[104:107]
	s_waitcnt lgkmcnt(3)
	v_mfma_f32_16x16x32_bf16 v[92:95], v[152:155], v[184:187], v[92:95]
	v_mfma_f32_16x16x32_bf16 v[88:91], v[160:163], v[184:187], v[88:91]
	s_waitcnt lgkmcnt(1)
	v_mfma_f32_16x16x32_bf16 v[76:79], v[152:155], v[192:195], v[76:79]
	v_mfma_f32_16x16x32_bf16 v[72:75], v[160:163], v[192:195], v[72:75]
	v_mfma_f32_16x16x32_bf16 v[124:127], v[156:159], v[172:175], v[124:127]
	v_mfma_f32_16x16x32_bf16 v[120:123], v[164:167], v[172:175], v[120:123]
	v_mfma_f32_16x16x32_bf16 v[108:111], v[156:159], v[180:183], v[108:111]
	v_mfma_f32_16x16x32_bf16 v[104:107], v[164:167], v[180:183], v[104:107]
	v_mfma_f32_16x16x32_bf16 v[92:95], v[156:159], v[188:191], v[92:95]
	v_mfma_f32_16x16x32_bf16 v[88:91], v[164:167], v[188:191], v[88:91]
	s_waitcnt lgkmcnt(0)
	v_mfma_f32_16x16x32_bf16 v[76:79], v[156:159], v[196:199], v[76:79]
	v_mfma_f32_16x16x32_bf16 v[72:75], v[164:167], v[196:199], v[72:75]
	s_setprio 0
	s_barrier
	s_add_i32 s14, 0, 0x1c000
	s_add_i32 s8, s49, s20
	v_add_u32_e32 v212, s14, v148
	v_lshl_add_u64 v[144:145], v[144:145], 0, s[46:47]
	s_mov_b32 m0, s8
	ds_read_b128 v[200:203], v212
	ds_read_b128 v[204:207], v212 offset:1024
	ds_read_b128 v[208:211], v212 offset:2048
	ds_read_b128 v[212:215], v212 offset:3072
	global_load_lds_dwordx4 v[144:145], off
	v_lshl_add_u64 v[144:145], v[216:217], 0, s[46:47]
	s_add_i32 m0, s8, 0x2000
	s_nop 0
	global_load_lds_dwordx4 v[144:145], off
	s_barrier
	s_setprio 1
	s_waitcnt lgkmcnt(3)
	v_mfma_f32_16x16x32_bf16 v[116:119], v[200:203], v[168:171], v[116:119]
	s_waitcnt lgkmcnt(1)
	v_mfma_f32_16x16x32_bf16 v[112:115], v[208:211], v[168:171], v[112:115]
	v_mfma_f32_16x16x32_bf16 v[100:103], v[200:203], v[176:179], v[100:103]
	v_mfma_f32_16x16x32_bf16 v[96:99], v[208:211], v[176:179], v[96:99]
	v_mfma_f32_16x16x32_bf16 v[84:87], v[200:203], v[184:187], v[84:87]
	v_mfma_f32_16x16x32_bf16 v[80:83], v[208:211], v[184:187], v[80:83]
	v_mfma_f32_16x16x32_bf16 v[68:71], v[200:203], v[192:195], v[68:71]
	v_mfma_f32_16x16x32_bf16 v[64:67], v[208:211], v[192:195], v[64:67]
	v_mfma_f32_16x16x32_bf16 v[116:119], v[204:207], v[172:175], v[116:119]
	s_waitcnt lgkmcnt(0)
	v_mfma_f32_16x16x32_bf16 v[112:115], v[212:215], v[172:175], v[112:115]
	v_mfma_f32_16x16x32_bf16 v[100:103], v[204:207], v[180:183], v[100:103]
	v_mfma_f32_16x16x32_bf16 v[96:99], v[212:215], v[180:183], v[96:99]
	v_mfma_f32_16x16x32_bf16 v[84:87], v[204:207], v[188:191], v[84:87]
	v_mfma_f32_16x16x32_bf16 v[80:83], v[212:215], v[188:191], v[80:83]
	v_mfma_f32_16x16x32_bf16 v[68:71], v[204:207], v[196:199], v[68:71]
	v_mfma_f32_16x16x32_bf16 v[64:67], v[212:215], v[196:199], v[64:67]
	s_setprio 0
	s_mov_b32 m0, s29
	v_lshl_add_u64 v[144:145], v[218:219], 0, s[46:47]
	s_barrier
	ds_read_b128 v[168:171], v150 offset:49152
	ds_read_b128 v[172:175], v150 offset:50176
	ds_read_b128 v[176:179], v150 offset:51200
	ds_read_b128 v[180:183], v150 offset:52224
	ds_read_b128 v[184:187], v150 offset:53248
	ds_read_b128 v[188:191], v150 offset:54272
	ds_read_b128 v[192:195], v150 offset:55296
	ds_read_b128 v[196:199], v150 offset:56320
	global_load_lds_dwordx4 v[144:145], off
	v_lshl_add_u64 v[144:145], v[220:221], 0, s[46:47]
	s_mov_b32 m0, s30
	s_nop 0
	global_load_lds_dwordx4 v[144:145], off
	s_barrier
; DI unsigned pack2(float a, float b) { f32x2 v = {a, b}; hwbf16x2 r = __builtin_convertvector(v, hwbf16x2); return __builtin_bit_cast(unsigned, r); }
; DI float bflo(unsigned w) { return __uint_as_float(w << 16); }
; DI float bfhi(unsigned w) { return __uint_as_float(w & 0xffff0000u); }
; #define PG8_STAGE(bufoff, gbase, voff) do { _Pragma("unroll") for (int _i = 0; _i < 2; ++_i) \
;         __builtin_amdgcn_global_load_lds((const unsigned*)((const char*)(gbase) + (voff)[_i]), (LAS unsigned*)(lds + (bufoff) + ldsw + _i * 8192), 16, 0, 0); } while (0)
; #define PG8_BAR __builtin_amdgcn_s_barrier()
;     DI void operator()(const f32x4 (&acc)[2][2][4][2], const Unit& u, int wr, int wc, int fr, int fq) const {
;     ...
;         for (int ai = 0; ai < 2; ++ai)
; #pragma unroll
;             for (int m = 0; m < 4; ++m) { const size_t ro = (size_t)(row0 + ai * HALF + m * 16) * D + col0;
; #pragma unroll
;                 for (int bj = 0; bj < 2; ++bj) {
;                     f32x4 x0, x1;
;                     if constexpr (IB) { const u32x4 w = *(const u32x4*)((const bf16_t*)Xin + ro + bj * HALF);
;                         x0 = (f32x4){bflo(w[0]), bfhi(w[0]), bflo(w[1]), bfhi(w[1])}; x1 = (f32x4){bflo(w[2]), bfhi(w[2]), bflo(w[3]), bfhi(w[3])}; }
;                     else { x0 = *(const f32x4*)((const float*)Xin + ro + bj * HALF); x1 = *(const f32x4*)((const float*)Xin + ro + bj * HALF + 4); }
;                     x0 += acc[ai][bj][m][0] * sc[bj][0]; x1 += acc[ai][bj][m][1] * sc[bj][1];
;                     if constexpr (OB) { u32x4 o; o[0] = pack2(x0[0], x0[1]); o[1] = pack2(x0[2], x0[3]); o[2] = pack2(x1[0], x1[1]); o[3] = pack2(x1[2], x1[3]);
;                         *(u32x4*)((bf16_t*)Xout + ro + bj * HALF) = o; }
;                     else { *(f32x4*)((float*)Xout + ro + bj * HALF) = x0; *(f32x4*)((float*)Xout + ro + bj * HALF + 4) = x1; } } }
; template <class Map, class Epi>
; DI void gemm_phase(LAS unsigned char* lds, const Map& MP, const Epi& E, const int nM, const int nN, const int K, const int lda, const int ldb) {
;     ...
;             PG8_BAR; PG8_WAIT_L(0); PG8_MMA(1, 0, At, B0); PG8_BAR; PG8_SCHED;
;             PG8_STAGE(PG8_SB(1, 1), b3 + hstepB, voffB);
;             PG8_WAIT_V(6); PG8_BAR; PG8_MMA(1, 1, At, B1); PG8_BAR;
;         }
;         { int frr = fr, fqq = fq; asm volatile("" : "+v"(frr), "+v"(fqq)); E(acc, cur, wr, wc, frr, fqq); }
	s_setprio 1
	s_waitcnt lgkmcnt(7)
	v_mfma_f32_16x16x32_bf16 v[60:63], v[152:155], v[168:171], v[60:63]
	v_mfma_f32_16x16x32_bf16 v[56:59], v[160:163], v[168:171], v[56:59]
	s_waitcnt lgkmcnt(5)
	v_mfma_f32_16x16x32_bf16 v[44:47], v[152:155], v[176:179], v[44:47]
	v_mfma_f32_16x16x32_bf16 v[40:43], v[160:163], v[176:179], v[40:43]
	s_waitcnt lgkmcnt(3)
	v_mfma_f32_16x16x32_bf16 v[28:31], v[152:155], v[184:187], v[28:31]
	v_mfma_f32_16x16x32_bf16 v[24:27], v[160:163], v[184:187], v[24:27]
	s_waitcnt lgkmcnt(1)
	v_mfma_f32_16x16x32_bf16 v[12:15], v[152:155], v[192:195], v[12:15]
	v_mfma_f32_16x16x32_bf16 v[8:11], v[160:163], v[192:195], v[8:11]
	v_mfma_f32_16x16x32_bf16 v[60:63], v[156:159], v[172:175], v[60:63]
	v_mfma_f32_16x16x32_bf16 v[56:59], v[164:167], v[172:175], v[56:59]
	v_mfma_f32_16x16x32_bf16 v[44:47], v[156:159], v[180:183], v[44:47]
	v_mfma_f32_16x16x32_bf16 v[40:43], v[164:167], v[180:183], v[40:43]
	v_mfma_f32_16x16x32_bf16 v[28:31], v[156:159], v[188:191], v[28:31]
	v_mfma_f32_16x16x32_bf16 v[24:27], v[164:167], v[188:191], v[24:27]
	s_waitcnt lgkmcnt(0)
	v_mfma_f32_16x16x32_bf16 v[12:15], v[156:159], v[196:199], v[12:15]
	v_mfma_f32_16x16x32_bf16 v[8:11], v[164:167], v[196:199], v[8:11]
	s_setprio 0
	s_barrier
	s_add_u32 s8, s12, 0x160080
	s_addc_u32 s9, s13, 0
	s_add_i32 s12, s14, s20
	s_mov_b32 m0, s12
	s_nop 0
	global_load_lds_dwordx4 v132, s[8:9]
	s_add_i32 m0, s12, 0x2000
	s_nop 0
	global_load_lds_dwordx4 v128, s[8:9]
	s_waitcnt vmcnt(6)
	s_barrier
	s_setprio 1
	v_mfma_f32_16x16x32_bf16 v[52:55], v[200:203], v[168:171], v[52:55]
	v_mfma_f32_16x16x32_bf16 v[48:51], v[208:211], v[168:171], v[48:51]
	v_mfma_f32_16x16x32_bf16 v[36:39], v[200:203], v[176:179], v[36:39]
	v_mfma_f32_16x16x32_bf16 v[32:35], v[208:211], v[176:179], v[32:35]
	v_mfma_f32_16x16x32_bf16 v[20:23], v[200:203], v[184:187], v[20:23]
	v_mfma_f32_16x16x32_bf16 v[16:19], v[208:211], v[184:187], v[16:19]
	v_mfma_f32_16x16x32_bf16 v[4:7], v[200:203], v[192:195], v[4:7]
	v_mfma_f32_16x16x32_bf16 v[0:3], v[208:211], v[192:195], v[0:3]
	v_mfma_f32_16x16x32_bf16 v[52:55], v[204:207], v[172:175], v[52:55]
	v_mfma_f32_16x16x32_bf16 v[48:51], v[212:215], v[172:175], v[48:51]
	v_mfma_f32_16x16x32_bf16 v[36:39], v[204:207], v[180:183], v[36:39]
	v_mfma_f32_16x16x32_bf16 v[32:35], v[212:215], v[180:183], v[32:35]
	v_mfma_f32_16x16x32_bf16 v[20:23], v[204:207], v[188:191], v[20:23]
	v_mfma_f32_16x16x32_bf16 v[16:19], v[212:215], v[188:191], v[16:19]
	v_mfma_f32_16x16x32_bf16 v[4:7], v[204:207], v[196:199], v[4:7]
	v_mfma_f32_16x16x32_bf16 v[0:3], v[212:215], v[196:199], v[0:3]
	s_setprio 0
	s_add_i32 s48, s48, 2
	s_add_u32 s38, s38, 0x100
	s_addc_u32 s39, s39, 0
	s_cmpk_gt_u32 s48, 0x55
	s_mov_b64 s[8:9], s[10:11]
	s_barrier
	s_cbranch_scc0 .LBB1_2653
	v_mov_b32_e32 v144, v147
	v_mov_b32_e32 v152, v146
	s_lshl_b32 s2, s2, 8
	s_lshl_b32 s8, s37, 8
	s_add_i32 s2, s2, s27
	s_or_b32 s8, s8, s28
	v_add_u32_e32 v152, s2, v152
	v_lshl_add_u32 v144, v144, 3, s8
	v_ashrrev_i32_e32 v153, 31, v152
	v_ashrrev_i32_e32 v145, 31, v144
	v_lshlrev_b64 v[152:153], 11, v[152:153]
	v_lshl_add_u64 v[144:145], v[152:153], 0, v[144:145]
	v_lshl_add_u64 v[156:157], v[144:145], 1, s[6:7]
	global_load_dwordx4 v[162:165], v[156:157], off
	global_load_dwordx4 v[166:169], v[156:157], off offset:256
	s_mov_b64 s[98:99], 0x10000
	v_lshl_add_u64 v[154:155], v[156:157], 0, s[98:99]
	global_load_dwordx4 v[170:173], v[154:155], off
	global_load_dwordx4 v[174:177], v[154:155], off offset:256
	s_mov_b64 s[98:99], 0x20000
	v_lshl_add_u64 v[154:155], v[156:157], 0, s[98:99]
	global_load_dwordx4 v[178:181], v[154:155], off
	global_load_dwordx4 v[182:185], v[154:155], off offset:256
	s_mov_b64 s[98:99], 0x30000
	v_lshl_add_u64 v[154:155], v[156:157], 0, s[98:99]
	global_load_dwordx4 v[186:189], v[154:155], off
	global_load_dwordx4 v[190:193], v[154:155], off offset:256
	s_mov_b64 s[98:99], 0x80000
	v_lshl_add_u64 v[154:155], v[156:157], 0, s[98:99]
	global_load_dwordx4 v[194:197], v[154:155], off
	global_load_dwordx4 v[198:201], v[154:155], off offset:256
	s_mov_b64 s[98:99], 0x90000
	v_lshl_add_u64 v[154:155], v[156:157], 0, s[98:99]
	global_load_dwordx4 v[202:205], v[154:155], off
	global_load_dwordx4 v[206:209], v[154:155], off offset:256
	s_mov_b64 s[98:99], 0xa0000
	v_lshl_add_u64 v[154:155], v[156:157], 0, s[98:99]
	global_load_dwordx4 v[210:213], v[154:155], off
	global_load_dwordx4 v[248:251], v[154:155], off offset:256
	s_mov_b64 s[98:99], 0xb0000
	v_lshl_add_u64 v[154:155], v[156:157], 0, s[98:99]
	global_load_dwordx4 v[252:255], v[154:155], off
	s_waitcnt vmcnt(14)
	s_nop 1
	v_mov_b32_e32 v152, v162
	v_mov_b32_e32 v153, v163
	v_mov_b32_e32 v154, v164
	v_mov_b32_e32 v155, v165
	s_mov_b64 s[8:9], 0x8000
	s_and_b64 vcc, exec, s[40:41]
	s_mov_b32 s37, s35
	s_mov_b32 s2, s36
	s_mov_b64 s[10:11], s[44:45]
	s_waitcnt lgkmcnt(0)
	v_lshlrev_b32_e32 v158, 16, v152
	v_and_b32_e32 v159, 0xffff0000, v152
	v_lshlrev_b32_e32 v152, 16, v153
	v_and_b32_e32 v153, 0xffff0000, v153
	v_lshlrev_b32_e32 v160, 16, v154
	v_and_b32_e32 v161, 0xffff0000, v154
	v_lshlrev_b32_e32 v154, 16, v155
	v_and_b32_e32 v155, 0xffff0000, v155
	v_pk_add_f32 v[126:127], v[126:127], v[152:153]
	v_pk_add_f32 v[124:125], v[124:125], v[158:159]
	v_lshl_add_u64 v[152:153], v[144:145], 2, s[4:5]
	v_pk_add_f32 v[122:123], v[122:123], v[154:155]
	v_pk_add_f32 v[120:121], v[120:121], v[160:161]
	global_store_dwordx4 v[152:153], v[124:127], off
	global_store_dwordx4 v[152:153], v[120:123], off offset:16
	s_waitcnt vmcnt(15)
	s_nop 1
	v_mov_b32_e32 v120, v166
	v_mov_b32_e32 v121, v167
	v_mov_b32_e32 v122, v168
	v_mov_b32_e32 v123, v169
	s_waitcnt lgkmcnt(0)
; DI unsigned pack2(float a, float b) { f32x2 v = {a, b}; hwbf16x2 r = __builtin_convertvector(v, hwbf16x2); return __builtin_bit_cast(unsigned, r); }
; DI float bflo(unsigned w) { return __uint_as_float(w << 16); }
; DI float bfhi(unsigned w) { return __uint_as_float(w & 0xffff0000u); }
;     DI void operator()(const f32x4 (&acc)[2][2][4][2], const Unit& u, int wr, int wc, int fr, int fq) const {
;     ...
;         for (int ai = 0; ai < 2; ++ai)
; #pragma unroll
;             for (int m = 0; m < 4; ++m) { const size_t ro = (size_t)(row0 + ai * HALF + m * 16) * D + col0;
; #pragma unroll
;                 for (int bj = 0; bj < 2; ++bj) {
;                     f32x4 x0, x1;
;                     if constexpr (IB) { const u32x4 w = *(const u32x4*)((const bf16_t*)Xin + ro + bj * HALF);
;                         x0 = (f32x4){bflo(w[0]), bfhi(w[0]), bflo(w[1]), bfhi(w[1])}; x1 = (f32x4){bflo(w[2]), bfhi(w[2]), bflo(w[3]), bfhi(w[3])}; }
;                     else { x0 = *(const f32x4*)((const float*)Xin + ro + bj * HALF); x1 = *(const f32x4*)((const float*)Xin + ro + bj * HALF + 4); }
;                     x0 += acc[ai][bj][m][0] * sc[bj][0]; x1 += acc[ai][bj][m][1] * sc[bj][1];
;                     if constexpr (OB) { u32x4 o; o[0] = pack2(x0[0], x0[1]); o[1] = pack2(x0[2], x0[3]); o[2] = pack2(x1[0], x1[1]); o[3] = pack2(x1[2], x1[3]);
;                         *(u32x4*)((bf16_t*)Xout + ro + bj * HALF) = o; }
;                     else { *(f32x4*)((float*)Xout + ro + bj * HALF) = x0; *(f32x4*)((float*)Xout + ro + bj * HALF + 4) = x1; } } }
	v_lshlrev_b32_e32 v124, 16, v120
	v_and_b32_e32 v125, 0xffff0000, v120
	v_lshlrev_b32_e32 v120, 16, v121
	v_and_b32_e32 v121, 0xffff0000, v121
	v_lshlrev_b32_e32 v126, 16, v122
	v_and_b32_e32 v127, 0xffff0000, v122
	v_lshlrev_b32_e32 v122, 16, v123
	v_and_b32_e32 v123, 0xffff0000, v123
	v_pk_add_f32 v[118:119], v[118:119], v[120:121]
	v_pk_add_f32 v[116:117], v[116:117], v[124:125]
	v_pk_add_f32 v[114:115], v[114:115], v[122:123]
	v_pk_add_f32 v[112:113], v[112:113], v[126:127]
	global_store_dwordx4 v[152:153], v[116:119], off offset:512
	global_store_dwordx4 v[152:153], v[112:115], off offset:528
	s_nop 0
	v_lshl_add_u64 v[116:117], v[144:145], 0, s[8:9]
	v_lshl_add_u64 v[118:119], v[116:117], 1, s[6:7]
	s_waitcnt vmcnt(16)
	s_nop 1
	v_mov_b32_e32 v112, v170
	v_mov_b32_e32 v113, v171
	v_mov_b32_e32 v114, v172
	v_mov_b32_e32 v115, v173
	s_mov_b64 s[8:9], 0x10000
	s_waitcnt lgkmcnt(0)
	v_lshlrev_b32_e32 v120, 16, v112
	v_and_b32_e32 v121, 0xffff0000, v112
	v_lshlrev_b32_e32 v112, 16, v113
	v_and_b32_e32 v113, 0xffff0000, v113
	v_lshlrev_b32_e32 v122, 16, v114
	v_and_b32_e32 v123, 0xffff0000, v114
	v_lshlrev_b32_e32 v114, 16, v115
	v_and_b32_e32 v115, 0xffff0000, v115
	v_pk_add_f32 v[110:111], v[110:111], v[112:113]
	v_pk_add_f32 v[108:109], v[108:109], v[120:121]
	v_lshl_add_u64 v[112:113], v[116:117], 2, s[4:5]
	v_pk_add_f32 v[106:107], v[106:107], v[114:115]
	v_pk_add_f32 v[104:105], v[104:105], v[122:123]
	global_store_dwordx4 v[112:113], v[108:111], off
	global_store_dwordx4 v[112:113], v[104:107], off offset:16
	s_waitcnt vmcnt(17)
	s_nop 1
	v_mov_b32_e32 v104, v174
	v_mov_b32_e32 v105, v175
	v_mov_b32_e32 v106, v176
	v_mov_b32_e32 v107, v177
	s_waitcnt lgkmcnt(0)
	v_lshlrev_b32_e32 v108, 16, v104
	v_and_b32_e32 v109, 0xffff0000, v104
	v_lshlrev_b32_e32 v104, 16, v105
	v_and_b32_e32 v105, 0xffff0000, v105
	v_lshlrev_b32_e32 v110, 16, v106
	v_and_b32_e32 v111, 0xffff0000, v106
	v_lshlrev_b32_e32 v106, 16, v107
	v_and_b32_e32 v107, 0xffff0000, v107
	v_pk_add_f32 v[102:103], v[102:103], v[104:105]
	v_pk_add_f32 v[100:101], v[100:101], v[108:109]
	v_pk_add_f32 v[98:99], v[98:99], v[106:107]
	v_pk_add_f32 v[96:97], v[96:97], v[110:111]
	global_store_dwordx4 v[112:113], v[100:103], off offset:512
	global_store_dwordx4 v[112:113], v[96:99], off offset:528
	s_nop 0
	v_lshl_add_u64 v[100:101], v[144:145], 0, s[8:9]
	v_lshl_add_u64 v[102:103], v[100:101], 1, s[6:7]
	s_waitcnt vmcnt(18)
	s_nop 1
	v_mov_b32_e32 v96, v178
	v_mov_b32_e32 v97, v179
	v_mov_b32_e32 v98, v180
	v_mov_b32_e32 v99, v181
	s_mov_b64 s[8:9], 0x18000
	s_waitcnt lgkmcnt(0)
	v_lshlrev_b32_e32 v104, 16, v96
	v_and_b32_e32 v105, 0xffff0000, v96
	v_lshlrev_b32_e32 v96, 16, v97
	v_and_b32_e32 v97, 0xffff0000, v97
	v_lshlrev_b32_e32 v106, 16, v98
	v_and_b32_e32 v107, 0xffff0000, v98
	v_lshlrev_b32_e32 v98, 16, v99
	v_and_b32_e32 v99, 0xffff0000, v99
	v_pk_add_f32 v[94:95], v[94:95], v[96:97]
	v_pk_add_f32 v[92:93], v[92:93], v[104:105]
	v_lshl_add_u64 v[96:97], v[100:101], 2, s[4:5]
	v_pk_add_f32 v[90:91], v[90:91], v[98:99]
	v_pk_add_f32 v[88:89], v[88:89], v[106:107]
	global_store_dwordx4 v[96:97], v[92:95], off
	global_store_dwordx4 v[96:97], v[88:91], off offset:16
	s_waitcnt vmcnt(19)
	s_nop 1
	v_mov_b32_e32 v88, v182
	v_mov_b32_e32 v89, v183
	v_mov_b32_e32 v90, v184
	v_mov_b32_e32 v91, v185
	s_waitcnt lgkmcnt(0)
	v_lshlrev_b32_e32 v92, 16, v88
	v_and_b32_e32 v93, 0xffff0000, v88
	v_lshlrev_b32_e32 v88, 16, v89
	v_and_b32_e32 v89, 0xffff0000, v89
	v_lshlrev_b32_e32 v94, 16, v90
	v_and_b32_e32 v95, 0xffff0000, v90
	v_lshlrev_b32_e32 v90, 16, v91
	v_and_b32_e32 v91, 0xffff0000, v91
	v_pk_add_f32 v[86:87], v[86:87], v[88:89]
	v_pk_add_f32 v[84:85], v[84:85], v[92:93]
	v_pk_add_f32 v[82:83], v[82:83], v[90:91]
	v_pk_add_f32 v[80:81], v[80:81], v[94:95]
	global_store_dwordx4 v[96:97], v[84:87], off offset:512
	global_store_dwordx4 v[96:97], v[80:83], off offset:528
	s_nop 0
	v_lshl_add_u64 v[84:85], v[144:145], 0, s[8:9]
	v_lshl_add_u64 v[86:87], v[84:85], 1, s[6:7]
	s_waitcnt vmcnt(20)
	s_nop 1
	v_mov_b32_e32 v80, v186
	v_mov_b32_e32 v81, v187
	v_mov_b32_e32 v82, v188
	v_mov_b32_e32 v83, v189
	s_mov_b64 s[8:9], 0x40000
	s_waitcnt lgkmcnt(0)
	v_lshlrev_b32_e32 v88, 16, v80
	v_and_b32_e32 v89, 0xffff0000, v80
	v_lshlrev_b32_e32 v80, 16, v81
	v_and_b32_e32 v81, 0xffff0000, v81
	v_lshlrev_b32_e32 v90, 16, v82
	v_and_b32_e32 v91, 0xffff0000, v82
	v_lshlrev_b32_e32 v82, 16, v83
	v_and_b32_e32 v83, 0xffff0000, v83
	v_pk_add_f32 v[78:79], v[78:79], v[80:81]
	v_pk_add_f32 v[76:77], v[76:77], v[88:89]
	v_lshl_add_u64 v[80:81], v[84:85], 2, s[4:5]
	v_pk_add_f32 v[74:75], v[74:75], v[82:83]
	v_pk_add_f32 v[72:73], v[72:73], v[90:91]
	global_store_dwordx4 v[80:81], v[76:79], off
	global_store_dwordx4 v[80:81], v[72:75], off offset:16
	s_waitcnt vmcnt(21)
	s_nop 1
	v_mov_b32_e32 v72, v190
	v_mov_b32_e32 v73, v191
	v_mov_b32_e32 v74, v192
	v_mov_b32_e32 v75, v193
	s_waitcnt lgkmcnt(0)
	v_lshlrev_b32_e32 v76, 16, v72
	v_and_b32_e32 v77, 0xffff0000, v72
	v_lshlrev_b32_e32 v72, 16, v73
	v_and_b32_e32 v73, 0xffff0000, v73
	v_lshlrev_b32_e32 v78, 16, v74
	v_and_b32_e32 v79, 0xffff0000, v74
	v_lshlrev_b32_e32 v74, 16, v75
	v_and_b32_e32 v75, 0xffff0000, v75
	v_pk_add_f32 v[70:71], v[70:71], v[72:73]
	v_pk_add_f32 v[68:69], v[68:69], v[76:77]
	v_pk_add_f32 v[66:67], v[66:67], v[74:75]
	v_pk_add_f32 v[64:65], v[64:65], v[78:79]
	global_store_dwordx4 v[80:81], v[68:71], off offset:512
	global_store_dwordx4 v[80:81], v[64:67], off offset:528
	s_nop 0
	v_lshl_add_u64 v[68:69], v[144:145], 0, s[8:9]
	v_lshl_add_u64 v[70:71], v[68:69], 1, s[6:7]
	s_waitcnt vmcnt(22)
; DI unsigned pack2(float a, float b) { f32x2 v = {a, b}; hwbf16x2 r = __builtin_convertvector(v, hwbf16x2); return __builtin_bit_cast(unsigned, r); }
; DI float bflo(unsigned w) { return __uint_as_float(w << 16); }
; DI float bfhi(unsigned w) { return __uint_as_float(w & 0xffff0000u); }
; #define PG8_WAIT_V(n) asm volatile("s_waitcnt vmcnt(" #n ")" ::: "memory")
; #define PG8_BAR __builtin_amdgcn_s_barrier()
;     DI void operator()(const f32x4 (&acc)[2][2][4][2], const Unit& u, int wr, int wc, int fr, int fq) const {
;     ...
;         for (int ai = 0; ai < 2; ++ai)
; #pragma unroll
;             for (int m = 0; m < 4; ++m) { const size_t ro = (size_t)(row0 + ai * HALF + m * 16) * D + col0;
; #pragma unroll
;                 for (int bj = 0; bj < 2; ++bj) {
;                     f32x4 x0, x1;
;                     if constexpr (IB) { const u32x4 w = *(const u32x4*)((const bf16_t*)Xin + ro + bj * HALF);
;                         x0 = (f32x4){bflo(w[0]), bfhi(w[0]), bflo(w[1]), bfhi(w[1])}; x1 = (f32x4){bflo(w[2]), bfhi(w[2]), bflo(w[3]), bfhi(w[3])}; }
;                     else { x0 = *(const f32x4*)((const float*)Xin + ro + bj * HALF); x1 = *(const f32x4*)((const float*)Xin + ro + bj * HALF + 4); }
;                     x0 += acc[ai][bj][m][0] * sc[bj][0]; x1 += acc[ai][bj][m][1] * sc[bj][1];
;                     if constexpr (OB) { u32x4 o; o[0] = pack2(x0[0], x0[1]); o[1] = pack2(x0[2], x0[3]); o[2] = pack2(x1[0], x1[1]); o[3] = pack2(x1[2], x1[3]);
;                         *(u32x4*)((bf16_t*)Xout + ro + bj * HALF) = o; }
;                     else { *(f32x4*)((float*)Xout + ro + bj * HALF) = x0; *(f32x4*)((float*)Xout + ro + bj * HALF + 4) = x1; } } }
; template <class Map, class Epi>
; DI void gemm_phase(LAS unsigned char* lds, const Map& MP, const Epi& E, const int nM, const int nN, const int K, const int lda, const int ldb) {
;     ...
;         if (!has_next) break;
;     ...
;     PG8_WAIT_V(0);
;     if (wr == 0) PG8_BAR;
;     PG8_BAR;
	s_nop 1
	v_mov_b32_e32 v64, v194
	v_mov_b32_e32 v65, v195
	v_mov_b32_e32 v66, v196
	v_mov_b32_e32 v67, v197
	s_mov_b64 s[8:9], 0x48000
	s_waitcnt lgkmcnt(0)
	v_lshlrev_b32_e32 v72, 16, v64
	v_and_b32_e32 v73, 0xffff0000, v64
	v_lshlrev_b32_e32 v64, 16, v65
	v_and_b32_e32 v65, 0xffff0000, v65
	v_lshlrev_b32_e32 v74, 16, v66
	v_and_b32_e32 v75, 0xffff0000, v66
	v_lshlrev_b32_e32 v66, 16, v67
	v_and_b32_e32 v67, 0xffff0000, v67
	v_pk_add_f32 v[62:63], v[62:63], v[64:65]
	v_pk_add_f32 v[60:61], v[60:61], v[72:73]
	v_lshl_add_u64 v[64:65], v[68:69], 2, s[4:5]
	v_pk_add_f32 v[58:59], v[58:59], v[66:67]
	v_pk_add_f32 v[56:57], v[56:57], v[74:75]
	global_store_dwordx4 v[64:65], v[60:63], off
	global_store_dwordx4 v[64:65], v[56:59], off offset:16
	s_waitcnt vmcnt(23)
	s_nop 1
	v_mov_b32_e32 v56, v198
	v_mov_b32_e32 v57, v199
	v_mov_b32_e32 v58, v200
	v_mov_b32_e32 v59, v201
	s_waitcnt lgkmcnt(0)
	v_lshlrev_b32_e32 v60, 16, v56
	v_and_b32_e32 v61, 0xffff0000, v56
	v_lshlrev_b32_e32 v56, 16, v57
	v_and_b32_e32 v57, 0xffff0000, v57
	v_lshlrev_b32_e32 v62, 16, v58
	v_and_b32_e32 v63, 0xffff0000, v58
	v_lshlrev_b32_e32 v58, 16, v59
	v_and_b32_e32 v59, 0xffff0000, v59
	v_pk_add_f32 v[54:55], v[54:55], v[56:57]
	v_pk_add_f32 v[52:53], v[52:53], v[60:61]
	v_pk_add_f32 v[50:51], v[50:51], v[58:59]
	v_pk_add_f32 v[48:49], v[48:49], v[62:63]
	global_store_dwordx4 v[64:65], v[52:55], off offset:512
	global_store_dwordx4 v[64:65], v[48:51], off offset:528
	s_nop 0
	v_lshl_add_u64 v[52:53], v[144:145], 0, s[8:9]
	v_lshl_add_u64 v[54:55], v[52:53], 1, s[6:7]
	s_waitcnt vmcnt(24)
	s_nop 1
	v_mov_b32_e32 v48, v202
	v_mov_b32_e32 v49, v203
	v_mov_b32_e32 v50, v204
	v_mov_b32_e32 v51, v205
	s_mov_b64 s[8:9], 0x50000
	s_waitcnt lgkmcnt(0)
	v_lshlrev_b32_e32 v56, 16, v48
	v_and_b32_e32 v57, 0xffff0000, v48
	v_lshlrev_b32_e32 v48, 16, v49
	v_and_b32_e32 v49, 0xffff0000, v49
	v_lshlrev_b32_e32 v58, 16, v50
	v_and_b32_e32 v59, 0xffff0000, v50
	v_lshlrev_b32_e32 v50, 16, v51
	v_and_b32_e32 v51, 0xffff0000, v51
	v_pk_add_f32 v[46:47], v[46:47], v[48:49]
	v_pk_add_f32 v[44:45], v[44:45], v[56:57]
	v_lshl_add_u64 v[48:49], v[52:53], 2, s[4:5]
	v_pk_add_f32 v[42:43], v[42:43], v[50:51]
	v_pk_add_f32 v[40:41], v[40:41], v[58:59]
	global_store_dwordx4 v[48:49], v[44:47], off
	global_store_dwordx4 v[48:49], v[40:43], off offset:16
	s_waitcnt vmcnt(25)
	s_nop 1
	v_mov_b32_e32 v40, v206
	v_mov_b32_e32 v41, v207
	v_mov_b32_e32 v42, v208
	v_mov_b32_e32 v43, v209
	s_waitcnt lgkmcnt(0)
	v_lshlrev_b32_e32 v44, 16, v40
	v_and_b32_e32 v45, 0xffff0000, v40
	v_lshlrev_b32_e32 v40, 16, v41
	v_and_b32_e32 v41, 0xffff0000, v41
	v_lshlrev_b32_e32 v46, 16, v42
	v_and_b32_e32 v47, 0xffff0000, v42
	v_lshlrev_b32_e32 v42, 16, v43
	v_and_b32_e32 v43, 0xffff0000, v43
	v_pk_add_f32 v[38:39], v[38:39], v[40:41]
	v_pk_add_f32 v[36:37], v[36:37], v[44:45]
	v_pk_add_f32 v[34:35], v[34:35], v[42:43]
	v_pk_add_f32 v[32:33], v[32:33], v[46:47]
	global_store_dwordx4 v[48:49], v[36:39], off offset:512
	global_store_dwordx4 v[48:49], v[32:35], off offset:528
	s_nop 0
	v_lshl_add_u64 v[36:37], v[144:145], 0, s[8:9]
	v_lshl_add_u64 v[38:39], v[36:37], 1, s[6:7]
	s_waitcnt vmcnt(26)
	s_nop 1
	v_mov_b32_e32 v32, v210
	v_mov_b32_e32 v33, v211
	v_mov_b32_e32 v34, v212
	v_mov_b32_e32 v35, v213
	s_mov_b64 s[8:9], 0x58000
	s_waitcnt lgkmcnt(0)
	v_lshlrev_b32_e32 v40, 16, v32
	v_and_b32_e32 v41, 0xffff0000, v32
	v_lshlrev_b32_e32 v32, 16, v33
	v_and_b32_e32 v33, 0xffff0000, v33
	v_lshlrev_b32_e32 v42, 16, v34
	v_and_b32_e32 v43, 0xffff0000, v34
	v_lshlrev_b32_e32 v34, 16, v35
	v_and_b32_e32 v35, 0xffff0000, v35
	v_pk_add_f32 v[30:31], v[30:31], v[32:33]
	v_pk_add_f32 v[28:29], v[28:29], v[40:41]
	v_lshl_add_u64 v[32:33], v[36:37], 2, s[4:5]
	v_pk_add_f32 v[26:27], v[26:27], v[34:35]
	v_pk_add_f32 v[24:25], v[24:25], v[42:43]
	global_store_dwordx4 v[32:33], v[28:31], off
	global_store_dwordx4 v[32:33], v[24:27], off offset:16
	s_waitcnt vmcnt(27)
	s_nop 1
	v_mov_b32_e32 v24, v248
	v_mov_b32_e32 v25, v249
	v_mov_b32_e32 v26, v250
	v_mov_b32_e32 v27, v251
	s_waitcnt lgkmcnt(0)
	v_lshlrev_b32_e32 v28, 16, v24
	v_and_b32_e32 v29, 0xffff0000, v24
	v_lshlrev_b32_e32 v24, 16, v25
	v_and_b32_e32 v25, 0xffff0000, v25
	v_lshlrev_b32_e32 v30, 16, v26
	v_and_b32_e32 v31, 0xffff0000, v26
	v_lshlrev_b32_e32 v26, 16, v27
	v_and_b32_e32 v27, 0xffff0000, v27
	v_pk_add_f32 v[22:23], v[22:23], v[24:25]
	v_pk_add_f32 v[20:21], v[20:21], v[28:29]
	v_pk_add_f32 v[18:19], v[18:19], v[26:27]
	v_pk_add_f32 v[16:17], v[16:17], v[30:31]
	global_store_dwordx4 v[32:33], v[20:23], off offset:512
	global_store_dwordx4 v[32:33], v[16:19], off offset:528
	s_nop 0
	v_lshl_add_u64 v[20:21], v[144:145], 0, s[8:9]
	v_lshl_add_u64 v[22:23], v[20:21], 1, s[6:7]
	s_waitcnt vmcnt(28)
	s_nop 1
	v_mov_b32_e32 v16, v252
	v_mov_b32_e32 v17, v253
	v_mov_b32_e32 v18, v254
	v_mov_b32_e32 v19, v255
	s_mov_b64 s[8:9], s[42:43]
	s_waitcnt lgkmcnt(0)
	v_lshlrev_b32_e32 v24, 16, v16
	v_and_b32_e32 v25, 0xffff0000, v16
	v_lshlrev_b32_e32 v16, 16, v17
	v_and_b32_e32 v17, 0xffff0000, v17
	v_lshlrev_b32_e32 v26, 16, v18
	v_and_b32_e32 v27, 0xffff0000, v18
	v_lshlrev_b32_e32 v18, 16, v19
	v_and_b32_e32 v19, 0xffff0000, v19
	v_pk_add_f32 v[14:15], v[14:15], v[16:17]
	v_pk_add_f32 v[12:13], v[12:13], v[24:25]
	v_lshl_add_u64 v[16:17], v[20:21], 2, s[4:5]
	v_pk_add_f32 v[10:11], v[10:11], v[18:19]
	v_pk_add_f32 v[8:9], v[8:9], v[26:27]
	global_store_dwordx4 v[16:17], v[12:15], off
	global_store_dwordx4 v[16:17], v[8:11], off offset:16
	global_load_dwordx4 v[8:11], v[22:23], off offset:256
	s_waitcnt vmcnt(0) lgkmcnt(0)
	v_lshlrev_b32_e32 v12, 16, v8
	v_and_b32_e32 v13, 0xffff0000, v8
	v_lshlrev_b32_e32 v8, 16, v9
	v_and_b32_e32 v9, 0xffff0000, v9
	v_lshlrev_b32_e32 v14, 16, v10
	v_and_b32_e32 v15, 0xffff0000, v10
	v_lshlrev_b32_e32 v10, 16, v11
	v_and_b32_e32 v11, 0xffff0000, v11
	v_pk_add_f32 v[6:7], v[6:7], v[8:9]
	v_pk_add_f32 v[4:5], v[4:5], v[12:13]
	v_pk_add_f32 v[2:3], v[2:3], v[10:11]
	v_pk_add_f32 v[0:1], v[0:1], v[14:15]
	global_store_dwordx4 v[16:17], v[4:7], off offset:512
	global_store_dwordx4 v[16:17], v[0:3], off offset:528
	s_cbranch_vccz .LBB1_2646
	s_waitcnt vmcnt(0)
	s_cmpk_gt_u32 s3, 0xff
	s_cbranch_scc1 .LBB1_2657
	s_barrier
